# K loops: per-segment s_setprio flips removed; one static s_setprio 1 for waves 4-7 at K-loop entry, reset to 0 at exit (on top of balanced loads)
# speedup vs baseline: 1.0192x; 1.0192x over previous
;     __device__ bool next(int i, Unit& u) const { const int L = i * G + c; if (L >= 384) return false; u.pm = L; u.pn = L / 6; return true; }
;     ...
;         const bool has_next = S.next(ui + 1, nxt);
;         const char* nA = has_next ? (const char*)g.A + (size_t)nxt.pm * tsA : cA; const char* nB = has_next ? (const char*)g.Bt + (size_t)nxt.pn * tsB : cB;
;         for (int t = 0; t < nt; t += 2) {
;             const bool last = (t == nt - 2);
;             const char* a1 = cA + (size_t)(t + 1) * kstep;
;             const char* a2 = last ? nA : cA + (size_t)(t + 2) * kstep; const char* b2 = last ? nB : cB + (size_t)(t + 2) * kstep;
;     ...
; #pragma unroll
;         for (int a = 0; a < 2; ++a)
; #pragma unroll
;             for (int b = 0; b < 2; ++b)
; #pragma unroll
;                 for (int m = 0; m < 4; ++m)
; #pragma unroll
;                     for (int n = 0; n < 2; ++n) acc[a][b][m][n] = (f32x4){0.f, 0.f, 0.f, 0.f};
.LBB0_146:
	s_ashr_i32 s23, s22, 31
	s_lshl_b64 s[24:25], s[22:23], 20
	s_add_u32 s24, s96, s24
	s_addc_u32 s25, s97, s25
	s_ashr_i32 s21, s20, 31
	s_lshl_b64 s[26:27], s[20:21], 20
	s_add_u32 s26, s12, s26
	s_addc_u32 s27, s13, s27
	v_mov_b32_e32 v127, 0
	s_and_b64 vcc, exec, s[6:7]
	v_lshl_add_u32 v210, s28, 8, v193
	s_cbranch_vccnz .LBB0_157
	s_and_b64 s[28:29], s[8:9], exec
	s_cselect_b32 s21, s25, s35
	s_cselect_b32 s23, s24, s34
	s_cselect_b32 s57, s27, s31
	s_cselect_b32 s58, s26, s30
	s_add_u32 s28, s34, 0x80080
	s_addc_u32 s29, s35, 0
	v_ashrrev_i32_e32 v211, 31, v210
	s_add_u32 s59, s30, 0x100
	v_mov_b32_e32 v0, 0
	v_lshl_add_u64 v[212:213], v[210:211], 2, s[74:75]
	s_addc_u32 s60, s31, 0
	s_mov_b32 s61, 0
	v_mov_b32_e32 v1, 0
	v_mov_b64_e32 v[2:3], 0
	v_mov_b64_e32 v[8:9], 0
	v_mov_b64_e32 v[10:11], 0
	v_mov_b64_e32 v[16:17], 0
	v_mov_b64_e32 v[18:19], 0
	v_mov_b64_e32 v[24:25], 0
	v_mov_b64_e32 v[26:27], 0
	v_mov_b64_e32 v[32:33], 0
	v_mov_b64_e32 v[34:35], 0
	v_mov_b64_e32 v[40:41], 0
	v_mov_b64_e32 v[42:43], 0
	v_mov_b64_e32 v[48:49], 0
	v_mov_b64_e32 v[50:51], 0
	v_mov_b64_e32 v[56:57], 0
	v_mov_b64_e32 v[58:59], 0
	v_mov_b64_e32 v[4:5], 0
	v_mov_b64_e32 v[6:7], 0
	v_mov_b64_e32 v[12:13], 0
	v_mov_b64_e32 v[14:15], 0
	v_mov_b64_e32 v[20:21], 0
	v_mov_b64_e32 v[22:23], 0
	v_mov_b64_e32 v[28:29], 0
	v_mov_b64_e32 v[30:31], 0
	v_mov_b64_e32 v[36:37], 0
	v_mov_b64_e32 v[38:39], 0
	v_mov_b64_e32 v[44:45], 0
	v_mov_b64_e32 v[46:47], 0
	v_mov_b64_e32 v[52:53], 0
	v_mov_b64_e32 v[54:55], 0
	v_mov_b64_e32 v[60:61], 0
	v_mov_b64_e32 v[62:63], 0
	v_mov_b64_e32 v[64:65], 0
	v_mov_b64_e32 v[66:67], 0
	v_mov_b64_e32 v[72:73], 0
	v_mov_b64_e32 v[74:75], 0
	v_mov_b64_e32 v[80:81], 0
	v_mov_b64_e32 v[82:83], 0
	v_mov_b64_e32 v[88:89], 0
	v_mov_b64_e32 v[90:91], 0
	v_mov_b64_e32 v[96:97], 0
	v_mov_b64_e32 v[98:99], 0
	v_mov_b64_e32 v[104:105], 0
	v_mov_b64_e32 v[106:107], 0
	v_mov_b64_e32 v[112:113], 0
	v_mov_b64_e32 v[114:115], 0
	v_mov_b64_e32 v[120:121], 0
	v_mov_b64_e32 v[122:123], 0
	v_mov_b64_e32 v[68:69], 0
	v_mov_b64_e32 v[70:71], 0
	v_mov_b64_e32 v[76:77], 0
	v_mov_b64_e32 v[78:79], 0
	v_mov_b64_e32 v[84:85], 0
	v_mov_b64_e32 v[86:87], 0
	v_mov_b64_e32 v[92:93], 0
	v_mov_b64_e32 v[94:95], 0
	v_mov_b64_e32 v[100:101], 0
	v_mov_b64_e32 v[102:103], 0
	v_mov_b64_e32 v[108:109], 0
	v_mov_b64_e32 v[110:111], 0
	v_mov_b64_e32 v[116:117], 0
	v_mov_b64_e32 v[118:119], 0
	v_mov_b64_e32 v[124:125], 0
	v_mov_b64_e32 v[126:127], 0
	v_readfirstlane_b32 s99, v234
	s_nop 0
	s_lshr_b32 s99, s99, 8
	s_cmp_eq_u32 s99, 0
	s_cbranch_scc1 .Lsp_0
	s_setprio 1

; #define PG8_STAGE(bufoff, gbase, voff) do { _Pragma("unroll") for (int _i = 0; _i < 2; ++_i) \
;         __builtin_amdgcn_global_load_lds((const unsigned*)((const char*)(gbase) + (voff)[_i]), (LAS unsigned*)(lds + (bufoff) + ldsw + _i * 8192), 16, 0, ((voff) == voffA ? AUXA : 0)); } while (0)
; #define PG8_LDA(dst, b, h) do { _Pragma("unroll") for (int m = 0; m < 4; ++m) _Pragma("unroll") for (int k = 0; k < 2; ++k) dst[m][k] = *(const LAS bf16x8*)(lds + PG8_SA(b, h) + aoff + m * 2048 + k * 1024); } while (0)
; #define PG8_LDB(dst, b, h) do { _Pragma("unroll") for (int n = 0; n < 2; ++n) _Pragma("unroll") for (int k = 0; k < 2; ++k) dst[n][k] = *(const LAS bf16x8*)(lds + PG8_SB(b, h) + boff + n * 2048 + k * 1024); } while (0)
; #define PG8_MMA(ai, bj, At, Bt) do { __builtin_amdgcn_s_setprio(1); _Pragma("unroll") for (int m = 0; m < 4; ++m) _Pragma("unroll") for (int n = 0; n < 2; ++n) _Pragma("unroll") for (int k = 0; k < 2; ++k) \
;         acc[ai][bj][m][n] = __builtin_amdgcn_mfma_f32_16x16x32_bf16(Bt[n][k], At[m][k], acc[ai][bj][m][n], 0, 0, 0); __builtin_amdgcn_s_setprio(0); } while (0)
; #define PG8_WAIT_V(n) asm volatile("s_waitcnt vmcnt(" #n ")" ::: "memory")
; #define PG8_WAIT_L(n) asm volatile("s_waitcnt lgkmcnt(" #n ")" ::: "memory")
; #define PG8_BAR __builtin_amdgcn_s_barrier()
; #define PG8_SCHED __builtin_amdgcn_sched_barrier(0)
;     ...
;             PG8_WAIT_L(0); PG8_BAR; PG8_MMA(1, 0, At, B0); PG8_MMA(1, 1, At, B1); PG8_BAR; PG8_SCHED;
;             PG8_LDB(B0, 1, 0); PG8_LDB(B1, 1, 1); PG8_SCHED; PG8_LDA(At, 1, 0); PG8_STAGE(PG8_SA(0, 1), a2 + hsA, voffA);
;             PG8_WAIT_V(8); PG8_WAIT_L(0); PG8_BAR; PG8_MMA(0, 0, At, B0); PG8_MMA(0, 1, At, B1); PG8_BAR; PG8_SCHED;
.Lspx_0:
	s_setprio 0
	s_branch .LBB0_158
.LBB0_148:
	s_waitcnt lgkmcnt(0)
	s_add_i32 s61, s61, 2
	s_barrier
	v_mfma_f32_16x16x32_bf16 v[60:63], v[144:147], v[184:187], v[60:63]
	v_mfma_f32_16x16x32_bf16 v[52:55], v[152:155], v[184:187], v[52:55]
	v_mfma_f32_16x16x32_bf16 v[44:47], v[144:147], v[176:179], v[44:47]
	v_mfma_f32_16x16x32_bf16 v[36:39], v[152:155], v[176:179], v[36:39]
	v_mfma_f32_16x16x32_bf16 v[28:31], v[144:147], v[168:171], v[28:31]
	v_mfma_f32_16x16x32_bf16 v[20:23], v[152:155], v[168:171], v[20:23]
	v_mfma_f32_16x16x32_bf16 v[12:15], v[144:147], v[160:163], v[12:15]
	v_mfma_f32_16x16x32_bf16 v[4:7], v[152:155], v[160:163], v[4:7]
	v_mfma_f32_16x16x32_bf16 v[60:63], v[148:151], v[188:191], v[60:63]
	v_mfma_f32_16x16x32_bf16 v[52:55], v[156:159], v[188:191], v[52:55]
	v_mfma_f32_16x16x32_bf16 v[44:47], v[148:151], v[180:183], v[44:47]
	v_mfma_f32_16x16x32_bf16 v[36:39], v[156:159], v[180:183], v[36:39]
	v_mfma_f32_16x16x32_bf16 v[28:31], v[148:151], v[172:175], v[28:31]
	v_mfma_f32_16x16x32_bf16 v[20:23], v[156:159], v[172:175], v[20:23]
	v_mfma_f32_16x16x32_bf16 v[12:15], v[148:151], v[164:167], v[12:15]
	v_mfma_f32_16x16x32_bf16 v[4:7], v[156:159], v[164:167], v[4:7]
	v_mfma_f32_16x16x32_bf16 v[56:59], v[128:131], v[184:187], v[56:59]
	v_mfma_f32_16x16x32_bf16 v[48:51], v[136:139], v[184:187], v[48:51]
	v_mfma_f32_16x16x32_bf16 v[40:43], v[128:131], v[176:179], v[40:43]
	v_mfma_f32_16x16x32_bf16 v[32:35], v[136:139], v[176:179], v[32:35]
	v_mfma_f32_16x16x32_bf16 v[24:27], v[128:131], v[168:171], v[24:27]
	v_mfma_f32_16x16x32_bf16 v[16:19], v[136:139], v[168:171], v[16:19]
	v_mfma_f32_16x16x32_bf16 v[8:11], v[128:131], v[160:163], v[8:11]
	v_mfma_f32_16x16x32_bf16 v[0:3], v[136:139], v[160:163], v[0:3]
	v_mfma_f32_16x16x32_bf16 v[56:59], v[132:135], v[188:191], v[56:59]
	v_mfma_f32_16x16x32_bf16 v[48:51], v[140:143], v[188:191], v[48:51]
	v_mfma_f32_16x16x32_bf16 v[40:43], v[132:135], v[180:183], v[40:43]
	v_mfma_f32_16x16x32_bf16 v[32:35], v[140:143], v[180:183], v[32:35]
	v_mfma_f32_16x16x32_bf16 v[24:27], v[132:135], v[172:175], v[24:27]
	v_mfma_f32_16x16x32_bf16 v[16:19], v[140:143], v[172:175], v[16:19]
	v_mfma_f32_16x16x32_bf16 v[8:11], v[132:135], v[164:167], v[8:11]
	v_mfma_f32_16x16x32_bf16 v[0:3], v[140:143], v[164:167], v[0:3]
	s_barrier
	s_mov_b32 m0, s40
	s_nop 0
	global_load_lds_dwordx4 v200, s[34:35]
	s_mov_b32 m0, s45
	s_nop 0
	global_load_lds_dwordx4 v196, s[34:35]
	s_add_i32 s36, 0, 0x18000
	s_add_i32 s37, 0, 0x1c000
	v_add_u32_e32 v140, s36, v222
	v_add_u32_e32 v156, s37, v222
	ds_read_b128 v[128:131], v140
	ds_read_b128 v[132:135], v140 offset:1024
	ds_read_b128 v[136:139], v140 offset:2048
	ds_read_b128 v[140:143], v140 offset:3072
	ds_read_b128 v[144:147], v156
	ds_read_b128 v[148:151], v156 offset:1024
	ds_read_b128 v[152:155], v156 offset:2048
	ds_read_b128 v[156:159], v156 offset:3072
	s_add_u32 s34, s34, 0x80000
	s_addc_u32 s35, s35, 0
	s_mov_b32 m0, s46
	ds_read_b128 v[160:163], v226 offset:32768
	ds_read_b128 v[164:167], v226 offset:33792
	ds_read_b128 v[168:171], v226 offset:34816
	ds_read_b128 v[172:175], v226 offset:35840
	ds_read_b128 v[176:179], v226 offset:36864
	ds_read_b128 v[180:183], v226 offset:37888
	ds_read_b128 v[184:187], v226 offset:38912
	ds_read_b128 v[188:191], v226 offset:39936
	global_load_lds_dwordx4 v200, s[34:35]
	s_mov_b32 m0, s47
	s_nop 0
	global_load_lds_dwordx4 v196, s[34:35]
	s_waitcnt vmcnt(8)
	s_waitcnt lgkmcnt(0)
	s_barrier
; #define PG8_STAGE(bufoff, gbase, voff) do { _Pragma("unroll") for (int _i = 0; _i < 2; ++_i) \
;         __builtin_amdgcn_global_load_lds((const unsigned*)((const char*)(gbase) + (voff)[_i]), (LAS unsigned*)(lds + (bufoff) + ldsw + _i * 8192), 16, 0, ((voff) == voffA ? AUXA : 0)); } while (0)
; #define PG8_LDA(dst, b, h) do { _Pragma("unroll") for (int m = 0; m < 4; ++m) _Pragma("unroll") for (int k = 0; k < 2; ++k) dst[m][k] = *(const LAS bf16x8*)(lds + PG8_SA(b, h) + aoff + m * 2048 + k * 1024); } while (0)
; #define PG8_MMA(ai, bj, At, Bt) do { __builtin_amdgcn_s_setprio(1); _Pragma("unroll") for (int m = 0; m < 4; ++m) _Pragma("unroll") for (int n = 0; n < 2; ++n) _Pragma("unroll") for (int k = 0; k < 2; ++k) \
;         acc[ai][bj][m][n] = __builtin_amdgcn_mfma_f32_16x16x32_bf16(Bt[n][k], At[m][k], acc[ai][bj][m][n], 0, 0, 0); __builtin_amdgcn_s_setprio(0); } while (0)
; #define PG8_WAIT_V(n) asm volatile("s_waitcnt vmcnt(" #n ")" ::: "memory")
; #define PG8_WAIT_L(n) asm volatile("s_waitcnt lgkmcnt(" #n ")" ::: "memory")
; #define PG8_BAR __builtin_amdgcn_s_barrier()
; #define PG8_SCHED __builtin_amdgcn_sched_barrier(0)
;     ...
;             PG8_WAIT_V(8); PG8_WAIT_L(0); PG8_BAR; PG8_MMA(0, 0, At, B0); PG8_MMA(0, 1, At, B1); PG8_BAR; PG8_SCHED;
;             PG8_LDA(At, 1, 1); PG8_STAGE(PG8_SB(1, 0), b3, voffB); PG8_STAGE(PG8_SB(1, 1), b3 + hsB, voffB); PG8_STAGE(PG8_SA(1, 0), a3, voffA);
;             PG8_WAIT_V(8); PG8_WAIT_L(0); PG8_BAR; PG8_MMA(1, 0, At, B0); PG8_MMA(1, 1, At, B1); PG8_BAR; PG8_SCHED;
;         }
	v_mfma_f32_16x16x32_bf16 v[124:127], v[128:131], v[160:163], v[124:127]
	v_mfma_f32_16x16x32_bf16 v[116:119], v[136:139], v[160:163], v[116:119]
	v_mfma_f32_16x16x32_bf16 v[108:111], v[128:131], v[168:171], v[108:111]
	v_mfma_f32_16x16x32_bf16 v[100:103], v[136:139], v[168:171], v[100:103]
	v_mfma_f32_16x16x32_bf16 v[92:95], v[128:131], v[176:179], v[92:95]
	v_mfma_f32_16x16x32_bf16 v[84:87], v[136:139], v[176:179], v[84:87]
	v_mfma_f32_16x16x32_bf16 v[76:79], v[128:131], v[184:187], v[76:79]
	v_mfma_f32_16x16x32_bf16 v[68:71], v[136:139], v[184:187], v[68:71]
	v_mfma_f32_16x16x32_bf16 v[124:127], v[132:135], v[164:167], v[124:127]
	v_mfma_f32_16x16x32_bf16 v[116:119], v[140:143], v[164:167], v[116:119]
	v_mfma_f32_16x16x32_bf16 v[108:111], v[132:135], v[172:175], v[108:111]
	v_mfma_f32_16x16x32_bf16 v[100:103], v[140:143], v[172:175], v[100:103]
	v_mfma_f32_16x16x32_bf16 v[92:95], v[132:135], v[180:183], v[92:95]
	v_mfma_f32_16x16x32_bf16 v[84:87], v[140:143], v[180:183], v[84:87]
	v_mfma_f32_16x16x32_bf16 v[76:79], v[132:135], v[188:191], v[76:79]
	v_mfma_f32_16x16x32_bf16 v[68:71], v[140:143], v[188:191], v[68:71]
	v_mfma_f32_16x16x32_bf16 v[120:123], v[144:147], v[160:163], v[120:123]
	v_mfma_f32_16x16x32_bf16 v[112:115], v[152:155], v[160:163], v[112:115]
	v_mfma_f32_16x16x32_bf16 v[104:107], v[144:147], v[168:171], v[104:107]
	v_mfma_f32_16x16x32_bf16 v[96:99], v[152:155], v[168:171], v[96:99]
	v_mfma_f32_16x16x32_bf16 v[88:91], v[144:147], v[176:179], v[88:91]
	v_mfma_f32_16x16x32_bf16 v[80:83], v[152:155], v[176:179], v[80:83]
	v_mfma_f32_16x16x32_bf16 v[72:75], v[144:147], v[184:187], v[72:75]
	v_mfma_f32_16x16x32_bf16 v[64:67], v[152:155], v[184:187], v[64:67]
	v_mfma_f32_16x16x32_bf16 v[120:123], v[148:151], v[164:167], v[120:123]
	v_mfma_f32_16x16x32_bf16 v[112:115], v[156:159], v[164:167], v[112:115]
	v_mfma_f32_16x16x32_bf16 v[104:107], v[148:151], v[172:175], v[104:107]
	v_mfma_f32_16x16x32_bf16 v[96:99], v[156:159], v[172:175], v[96:99]
	v_mfma_f32_16x16x32_bf16 v[88:91], v[148:151], v[180:183], v[88:91]
	v_mfma_f32_16x16x32_bf16 v[80:83], v[156:159], v[180:183], v[80:83]
	v_mfma_f32_16x16x32_bf16 v[72:75], v[148:151], v[188:191], v[72:75]
	v_mfma_f32_16x16x32_bf16 v[64:67], v[156:159], v[188:191], v[64:67]
	s_barrier
	s_add_i32 s34, s36, s3
	s_mov_b32 m0, s34
	ds_read_b128 v[160:163], v226 offset:49152
	ds_read_b128 v[164:167], v226 offset:50176
	ds_read_b128 v[168:171], v226 offset:51200
	ds_read_b128 v[172:175], v226 offset:52224
	ds_read_b128 v[176:179], v226 offset:53248
	ds_read_b128 v[180:183], v226 offset:54272
	ds_read_b128 v[184:187], v226 offset:55296
	ds_read_b128 v[188:191], v226 offset:56320
	global_load_lds_dwordx4 v198, s[98:99]
	s_add_i32 m0, s34, 0x2000
	s_add_u32 s30, s30, 0x80080
	s_addc_u32 s31, s31, 0
	s_add_i32 s34, s37, s3
	global_load_lds_dwordx4 v194, s[98:99]
	s_mov_b32 m0, s34
	s_nop 0
	global_load_lds_dwordx4 v198, s[30:31]
	s_add_i32 m0, s34, 0x2000
	s_nop 0
	global_load_lds_dwordx4 v194, s[30:31]
	s_waitcnt vmcnt(6)
	s_waitcnt lgkmcnt(0)
	s_barrier
	v_mfma_f32_16x16x32_bf16 v[60:63], v[128:131], v[160:163], v[60:63]
	v_mfma_f32_16x16x32_bf16 v[52:55], v[136:139], v[160:163], v[52:55]
	v_mfma_f32_16x16x32_bf16 v[44:47], v[128:131], v[168:171], v[44:47]
	v_mfma_f32_16x16x32_bf16 v[36:39], v[136:139], v[168:171], v[36:39]
	v_mfma_f32_16x16x32_bf16 v[28:31], v[128:131], v[176:179], v[28:31]
	v_mfma_f32_16x16x32_bf16 v[20:23], v[136:139], v[176:179], v[20:23]
	v_mfma_f32_16x16x32_bf16 v[12:15], v[128:131], v[184:187], v[12:15]
	v_mfma_f32_16x16x32_bf16 v[4:7], v[136:139], v[184:187], v[4:7]
	v_mfma_f32_16x16x32_bf16 v[60:63], v[132:135], v[164:167], v[60:63]
	v_mfma_f32_16x16x32_bf16 v[52:55], v[140:143], v[164:167], v[52:55]
	v_mfma_f32_16x16x32_bf16 v[44:47], v[132:135], v[172:175], v[44:47]
	v_mfma_f32_16x16x32_bf16 v[36:39], v[140:143], v[172:175], v[36:39]
	v_mfma_f32_16x16x32_bf16 v[28:31], v[132:135], v[180:183], v[28:31]
	v_mfma_f32_16x16x32_bf16 v[20:23], v[140:143], v[180:183], v[20:23]
	v_mfma_f32_16x16x32_bf16 v[12:15], v[132:135], v[188:191], v[12:15]
	v_mfma_f32_16x16x32_bf16 v[4:7], v[140:143], v[188:191], v[4:7]
	v_mfma_f32_16x16x32_bf16 v[56:59], v[144:147], v[160:163], v[56:59]
	v_mfma_f32_16x16x32_bf16 v[48:51], v[152:155], v[160:163], v[48:51]
	v_mfma_f32_16x16x32_bf16 v[40:43], v[144:147], v[168:171], v[40:43]
	v_mfma_f32_16x16x32_bf16 v[32:35], v[152:155], v[168:171], v[32:35]
	v_mfma_f32_16x16x32_bf16 v[24:27], v[144:147], v[176:179], v[24:27]
	v_mfma_f32_16x16x32_bf16 v[16:19], v[152:155], v[176:179], v[16:19]
	v_mfma_f32_16x16x32_bf16 v[8:11], v[144:147], v[184:187], v[8:11]
	v_mfma_f32_16x16x32_bf16 v[0:3], v[152:155], v[184:187], v[0:3]
	v_mfma_f32_16x16x32_bf16 v[56:59], v[148:151], v[164:167], v[56:59]
	v_mfma_f32_16x16x32_bf16 v[48:51], v[156:159], v[164:167], v[48:51]
	v_mfma_f32_16x16x32_bf16 v[40:43], v[148:151], v[172:175], v[40:43]
	v_mfma_f32_16x16x32_bf16 v[32:35], v[156:159], v[172:175], v[32:35]
	v_mfma_f32_16x16x32_bf16 v[24:27], v[148:151], v[180:183], v[24:27]
	v_mfma_f32_16x16x32_bf16 v[16:19], v[156:159], v[180:183], v[16:19]
	v_mfma_f32_16x16x32_bf16 v[8:11], v[148:151], v[188:191], v[8:11]
	v_mfma_f32_16x16x32_bf16 v[0:3], v[156:159], v[188:191], v[0:3]
	s_barrier
	s_add_u32 s28, s28, 0x100
	s_addc_u32 s29, s29, 0
	s_add_u32 s59, s59, 0x100
	s_addc_u32 s60, s60, 0
	s_cmp_ge_i32 s61, s49
	s_cbranch_scc1 .Lspx_0

; #define PG8_STAGE(bufoff, gbase, voff) do { _Pragma("unroll") for (int _i = 0; _i < 2; ++_i) \
;         __builtin_amdgcn_global_load_lds((const unsigned*)((const char*)(gbase) + (voff)[_i]), (LAS unsigned*)(lds + (bufoff) + ldsw + _i * 8192), 16, 0, ((voff) == voffA ? AUXA : 0)); } while (0)
; #define PG8_LDA(dst, b, h) do { _Pragma("unroll") for (int m = 0; m < 4; ++m) _Pragma("unroll") for (int k = 0; k < 2; ++k) dst[m][k] = *(const LAS bf16x8*)(lds + PG8_SA(b, h) + aoff + m * 2048 + k * 1024); } while (0)
; #define PG8_MMA(ai, bj, At, Bt) do { __builtin_amdgcn_s_setprio(1); _Pragma("unroll") for (int m = 0; m < 4; ++m) _Pragma("unroll") for (int n = 0; n < 2; ++n) _Pragma("unroll") for (int k = 0; k < 2; ++k) \
;         acc[ai][bj][m][n] = __builtin_amdgcn_mfma_f32_16x16x32_bf16(Bt[n][k], At[m][k], acc[ai][bj][m][n], 0, 0, 0); __builtin_amdgcn_s_setprio(0); } while (0)
; #define PG8_WAIT_V(n) asm volatile("s_waitcnt vmcnt(" #n ")" ::: "memory")
; #define PG8_WAIT_L(n) asm volatile("s_waitcnt lgkmcnt(" #n ")" ::: "memory")
; #define PG8_BAR __builtin_amdgcn_s_barrier()
; #define PG8_SCHED __builtin_amdgcn_sched_barrier(0)
;     ...
;             PG8_WAIT_L(0); PG8_BAR; PG8_MMA(0, 0, At, B0); PG8_MMA(0, 1, At, B1); PG8_BAR; PG8_SCHED;
;             PG8_LDA(At, 0, 1); PG8_STAGE(PG8_SB(0, 0), b2, voffB); PG8_STAGE(PG8_SB(0, 1), b2 + hsB, voffB); PG8_STAGE(PG8_SA(0, 0), a2, voffA);
;             if (Epi::NPRE != 0 && last) { PG8_WAIT_V(16); } else { PG8_WAIT_V(8); }
.LBB0_153:
	s_add_u32 s34, s28, 0xfff80080
	s_addc_u32 s35, s29, -1
	s_waitcnt lgkmcnt(0)
	s_and_b64 s[30:31], s[30:31], exec
	s_cselect_b32 s35, s21, s35
	s_cselect_b32 s34, s23, s34
	s_cselect_b32 s31, s57, s60
	s_cselect_b32 s30, s58, s59
	s_barrier
	v_mfma_f32_16x16x32_bf16 v[124:127], v[144:147], v[184:187], v[124:127]
	v_mfma_f32_16x16x32_bf16 v[116:119], v[152:155], v[184:187], v[116:119]
	v_mfma_f32_16x16x32_bf16 v[108:111], v[144:147], v[176:179], v[108:111]
	v_mfma_f32_16x16x32_bf16 v[100:103], v[152:155], v[176:179], v[100:103]
	v_mfma_f32_16x16x32_bf16 v[92:95], v[144:147], v[168:171], v[92:95]
	v_mfma_f32_16x16x32_bf16 v[84:87], v[152:155], v[168:171], v[84:87]
	v_mfma_f32_16x16x32_bf16 v[76:79], v[144:147], v[160:163], v[76:79]
	v_mfma_f32_16x16x32_bf16 v[68:71], v[152:155], v[160:163], v[68:71]
	v_mfma_f32_16x16x32_bf16 v[124:127], v[148:151], v[188:191], v[124:127]
	v_mfma_f32_16x16x32_bf16 v[116:119], v[156:159], v[188:191], v[116:119]
	v_mfma_f32_16x16x32_bf16 v[108:111], v[148:151], v[180:183], v[108:111]
	v_mfma_f32_16x16x32_bf16 v[100:103], v[156:159], v[180:183], v[100:103]
	v_mfma_f32_16x16x32_bf16 v[92:95], v[148:151], v[172:175], v[92:95]
	v_mfma_f32_16x16x32_bf16 v[84:87], v[156:159], v[172:175], v[84:87]
	v_mfma_f32_16x16x32_bf16 v[76:79], v[148:151], v[164:167], v[76:79]
	v_mfma_f32_16x16x32_bf16 v[68:71], v[156:159], v[164:167], v[68:71]
	v_mfma_f32_16x16x32_bf16 v[120:123], v[128:131], v[184:187], v[120:123]
	v_mfma_f32_16x16x32_bf16 v[112:115], v[136:139], v[184:187], v[112:115]
	v_mfma_f32_16x16x32_bf16 v[104:107], v[128:131], v[176:179], v[104:107]
	v_mfma_f32_16x16x32_bf16 v[96:99], v[136:139], v[176:179], v[96:99]
	v_mfma_f32_16x16x32_bf16 v[88:91], v[128:131], v[168:171], v[88:91]
	v_mfma_f32_16x16x32_bf16 v[80:83], v[136:139], v[168:171], v[80:83]
	v_mfma_f32_16x16x32_bf16 v[72:75], v[128:131], v[160:163], v[72:75]
	v_mfma_f32_16x16x32_bf16 v[64:67], v[136:139], v[160:163], v[64:67]
	v_mfma_f32_16x16x32_bf16 v[120:123], v[132:135], v[188:191], v[120:123]
	v_mfma_f32_16x16x32_bf16 v[112:115], v[140:143], v[188:191], v[112:115]
	v_mfma_f32_16x16x32_bf16 v[104:107], v[132:135], v[180:183], v[104:107]
	v_mfma_f32_16x16x32_bf16 v[96:99], v[140:143], v[180:183], v[96:99]
	v_mfma_f32_16x16x32_bf16 v[88:91], v[132:135], v[172:175], v[88:91]
	v_mfma_f32_16x16x32_bf16 v[80:83], v[140:143], v[172:175], v[80:83]
	v_mfma_f32_16x16x32_bf16 v[72:75], v[132:135], v[164:167], v[72:75]
	v_mfma_f32_16x16x32_bf16 v[64:67], v[140:143], v[164:167], v[64:67]
	s_barrier
	s_add_u32 s98, s30, s16
	s_addc_u32 s99, s31, s17
	s_add_u32 s100, s34, s16
	s_addc_u32 s101, s35, s17
	s_mov_b32 m0, s41
	s_add_u32 s38, s30, 0x80000
	ds_read_b128 v[184:187], v226 offset:16384
	ds_read_b128 v[188:191], v226 offset:17408
	ds_read_b128 v[176:179], v226 offset:18432
	ds_read_b128 v[180:183], v226 offset:19456
	ds_read_b128 v[168:171], v226 offset:20480
	ds_read_b128 v[172:175], v226 offset:21504
	ds_read_b128 v[160:163], v226 offset:22528
	ds_read_b128 v[164:167], v226 offset:23552
	global_load_lds_dwordx4 v198, s[30:31]
	s_mov_b32 m0, s42
	s_addc_u32 s39, s31, 0
	global_load_lds_dwordx4 v194, s[30:31]
	s_mov_b32 m0, s43
	s_nop 0
	global_load_lds_dwordx4 v198, s[38:39]
	s_mov_b32 m0, s44
	s_nop 0
	global_load_lds_dwordx4 v194, s[38:39]
	s_mov_b64 s[38:39], -1
	s_and_b64 vcc, exec, s[36:37]
	s_cbranch_vccz .LBB0_155
	s_waitcnt vmcnt(6)
	s_mov_b64 s[38:39], 0

; #define PG8_STAGE(bufoff, gbase, voff) do { _Pragma("unroll") for (int _i = 0; _i < 2; ++_i) \
;         __builtin_amdgcn_global_load_lds((const unsigned*)((const char*)(gbase) + (voff)[_i]), (LAS unsigned*)(lds + (bufoff) + ldsw + _i * 8192), 16, 0, ((voff) == voffA ? AUXA : 0)); } while (0)
; #define PG8_LDA(dst, b, h) do { _Pragma("unroll") for (int m = 0; m < 4; ++m) _Pragma("unroll") for (int k = 0; k < 2; ++k) dst[m][k] = *(const LAS bf16x8*)(lds + PG8_SA(b, h) + aoff + m * 2048 + k * 1024); } while (0)
; #define PG8_LDB(dst, b, h) do { _Pragma("unroll") for (int n = 0; n < 2; ++n) _Pragma("unroll") for (int k = 0; k < 2; ++k) dst[n][k] = *(const LAS bf16x8*)(lds + PG8_SB(b, h) + boff + n * 2048 + k * 1024); } while (0)
; #define PG8_MMA(ai, bj, At, Bt) do { __builtin_amdgcn_s_setprio(1); _Pragma("unroll") for (int m = 0; m < 4; ++m) _Pragma("unroll") for (int n = 0; n < 2; ++n) _Pragma("unroll") for (int k = 0; k < 2; ++k) \
;         acc[ai][bj][m][n] = __builtin_amdgcn_mfma_f32_16x16x32_bf16(Bt[n][k], At[m][k], acc[ai][bj][m][n], 0, 0, 0); __builtin_amdgcn_s_setprio(0); } while (0)
; #define PG8_WAIT_V(n) asm volatile("s_waitcnt vmcnt(" #n ")" ::: "memory")
; #define PG8_WAIT_L(n) asm volatile("s_waitcnt lgkmcnt(" #n ")" ::: "memory")
; #define PG8_BAR __builtin_amdgcn_s_barrier()
; #define PG8_SCHED __builtin_amdgcn_sched_barrier(0)
;     ...
;             PG8_LDB(B0, 0, 0); PG8_LDB(B1, 0, 1); PG8_SCHED; PG8_LDA(At, 0, 0); PG8_STAGE(PG8_SA(1, 1), a1 + hsA, voffA);
;             if (Epi::NPRE != 0 && last) { E.pre(sv, cur, wr, fr); PG8_WAIT_V(16); } else { PG8_WAIT_V(8); }
;             PG8_WAIT_L(0); PG8_BAR; PG8_MMA(0, 0, At, B0); PG8_MMA(0, 1, At, B1); PG8_BAR; PG8_SCHED;
;     ...
; #pragma unroll
;         for (int a = 0; a < 2; ++a)
; #pragma unroll
;             for (int b = 0; b < 2; ++b)
; #pragma unroll
;                 for (int m = 0; m < 4; ++m)
; #pragma unroll
;                     for (int n = 0; n < 2; ++n) acc[a][b][m][n] = (f32x4){0.f, 0.f, 0.f, 0.f};
.LBB0_244:
	v_mov_b32_e32 v179, 0
	s_andn2_b64 vcc, exec, s[18:19]
	v_mov_b32_e32 v178, 0
	v_mov_b64_e32 v[184:185], 0
	v_mov_b64_e32 v[182:183], 0
	v_mov_b64_e32 v[180:181], 0
	v_mov_b64_e32 v[168:169], 0
	v_mov_b64_e32 v[166:167], 0
	v_mov_b64_e32 v[164:165], 0
	v_mov_b64_e32 v[162:163], 0
	v_mov_b64_e32 v[152:153], 0
	v_mov_b64_e32 v[150:151], 0
	v_mov_b64_e32 v[148:149], 0
	v_mov_b64_e32 v[146:147], 0
	v_mov_b64_e32 v[120:121], 0
	v_mov_b64_e32 v[118:119], 0
	v_mov_b64_e32 v[116:117], 0
	v_mov_b64_e32 v[114:115], 0
	v_mov_b64_e32 v[194:195], 0
	v_mov_b64_e32 v[190:191], 0
	v_mov_b64_e32 v[188:189], 0
	v_mov_b64_e32 v[186:187], 0
	v_mov_b64_e32 v[176:177], 0
	v_mov_b64_e32 v[174:175], 0
	v_mov_b64_e32 v[172:173], 0
	v_mov_b64_e32 v[170:171], 0
	v_mov_b64_e32 v[160:161], 0
	v_mov_b64_e32 v[158:159], 0
	v_mov_b64_e32 v[156:157], 0
	v_mov_b64_e32 v[154:155], 0
	v_mov_b64_e32 v[144:145], 0
	v_mov_b64_e32 v[126:127], 0
	v_mov_b64_e32 v[124:125], 0
	v_mov_b64_e32 v[122:123], 0
	v_mov_b64_e32 v[102:103], 0
	v_mov_b64_e32 v[100:101], 0
	v_mov_b64_e32 v[98:99], 0
	v_mov_b64_e32 v[96:97], 0
	v_mov_b64_e32 v[86:87], 0
	v_mov_b64_e32 v[84:85], 0
	v_mov_b64_e32 v[82:83], 0
	v_mov_b64_e32 v[80:81], 0
	v_mov_b64_e32 v[70:71], 0
	v_mov_b64_e32 v[68:69], 0
	v_mov_b64_e32 v[66:67], 0
	v_mov_b64_e32 v[64:65], 0
	v_mov_b64_e32 v[54:55], 0
	v_mov_b64_e32 v[52:53], 0
	v_mov_b64_e32 v[50:51], 0
	v_mov_b64_e32 v[48:49], 0
	v_mov_b64_e32 v[110:111], 0
	v_mov_b64_e32 v[108:109], 0
	v_mov_b64_e32 v[106:107], 0
	v_mov_b64_e32 v[104:105], 0
	v_mov_b64_e32 v[94:95], 0
	v_mov_b64_e32 v[92:93], 0
	v_mov_b64_e32 v[90:91], 0
	v_mov_b64_e32 v[88:89], 0
	v_mov_b64_e32 v[78:79], 0
	v_mov_b64_e32 v[76:77], 0
	v_mov_b64_e32 v[74:75], 0
	v_mov_b64_e32 v[72:73], 0
	v_mov_b64_e32 v[62:63], 0
	v_mov_b64_e32 v[60:61], 0
	v_mov_b64_e32 v[58:59], 0
	v_mov_b64_e32 v[56:57], 0
	s_cbranch_vccnz .LBB0_248
	s_add_u32 s24, s24, 0x160080
	s_addc_u32 s25, s25, 0
	s_add_u32 s50, s26, 0x100
	v_mov_b32_e32 v0, 0
	s_addc_u32 s51, s27, 0
	s_mov_b32 s26, 0
	s_waitcnt lgkmcnt(0)
	v_mov_b32_e32 v1, 0
	v_mov_b64_e32 v[2:3], 0
	v_mov_b64_e32 v[4:5], 0
	v_mov_b64_e32 v[6:7], 0
	v_mov_b64_e32 v[8:9], 0
	v_mov_b64_e32 v[10:11], 0
	v_mov_b64_e32 v[12:13], 0
	v_mov_b64_e32 v[14:15], 0
	v_mov_b64_e32 v[20:21], 0
	v_mov_b64_e32 v[22:23], 0
	v_mov_b64_e32 v[28:29], 0
	v_mov_b64_e32 v[30:31], 0
	v_mov_b64_e32 v[36:37], 0
	v_mov_b64_e32 v[38:39], 0
	v_mov_b64_e32 v[44:45], 0
	v_mov_b64_e32 v[46:47], 0
	v_mov_b64_e32 v[16:17], 0
	v_mov_b64_e32 v[18:19], 0
	v_mov_b64_e32 v[24:25], 0
	v_mov_b64_e32 v[26:27], 0
	v_mov_b64_e32 v[32:33], 0
	v_mov_b64_e32 v[34:35], 0
	v_mov_b64_e32 v[40:41], 0
	v_mov_b64_e32 v[42:43], 0
	v_mov_b64_e32 v[48:49], 0
	v_mov_b64_e32 v[50:51], 0
	v_mov_b64_e32 v[52:53], 0
	v_mov_b64_e32 v[54:55], 0
	v_mov_b64_e32 v[56:57], 0
	v_mov_b64_e32 v[58:59], 0
	v_mov_b64_e32 v[60:61], 0
	v_mov_b64_e32 v[62:63], 0
	v_mov_b64_e32 v[64:65], 0
	v_mov_b64_e32 v[66:67], 0
	v_mov_b64_e32 v[68:69], 0
	v_mov_b64_e32 v[70:71], 0
	v_mov_b64_e32 v[72:73], 0
	v_mov_b64_e32 v[74:75], 0
	v_mov_b64_e32 v[76:77], 0
	v_mov_b64_e32 v[78:79], 0
	v_mov_b64_e32 v[84:85], 0
	v_mov_b64_e32 v[86:87], 0
	v_mov_b64_e32 v[92:93], 0
	v_mov_b64_e32 v[94:95], 0
	v_mov_b64_e32 v[100:101], 0
	v_mov_b64_e32 v[102:103], 0
	v_mov_b64_e32 v[108:109], 0
	v_mov_b64_e32 v[110:111], 0
	v_mov_b64_e32 v[80:81], 0
	v_mov_b64_e32 v[82:83], 0
	v_mov_b64_e32 v[88:89], 0
	v_mov_b64_e32 v[90:91], 0
	v_mov_b64_e32 v[96:97], 0
	v_mov_b64_e32 v[98:99], 0
	v_mov_b64_e32 v[104:105], 0
	v_mov_b64_e32 v[106:107], 0
	v_mov_b64_e32 v[112:113], 0
	v_mov_b64_e32 v[114:115], 0
	v_mov_b64_e32 v[116:117], 0
	v_mov_b64_e32 v[118:119], 0
	v_mov_b64_e32 v[120:121], 0
	v_mov_b64_e32 v[122:123], 0
	v_mov_b64_e32 v[124:125], 0
	v_mov_b64_e32 v[126:127], 0
	v_readfirstlane_b32 s99, v234
	s_nop 0
	s_lshr_b32 s99, s99, 8
	s_cmp_eq_u32 s99, 0
	s_cbranch_scc1 .Lsp_1
	s_setprio 1
.Lsp_1:
.LBB0_246:
	s_add_u32 s98, s24, 0xffea0000
	s_addc_u32 s99, s25, -1
	s_mov_b32 m0, s39
	s_nop 0
	global_load_lds_dwordx4 v128, s[98:99]
	s_mov_b32 m0, s40
	s_nop 0
	global_load_lds_dwordx4 v132, s[98:99]
	ds_read_b128 v[144:147], v208
	ds_read_b128 v[148:151], v208 offset:1024
	ds_read_b128 v[152:155], v208 offset:2048
	ds_read_b128 v[156:159], v208 offset:3072
	ds_read_b128 v[160:163], v209
	ds_read_b128 v[164:167], v209 offset:1024
	ds_read_b128 v[168:171], v209 offset:2048
	ds_read_b128 v[172:175], v209 offset:3072
	s_add_i32 s52, s26, 2
	s_add_u32 s27, s24, 0xffea0080
	s_addc_u32 s28, s25, -1
	s_cmp_eq_u32 s41, s26
	s_cselect_b32 s26, s22, s50
	s_cselect_b32 s29, s11, s28
	s_cselect_b32 s28, s10, s27
	s_cselect_b32 s27, s23, s51
	s_add_i32 m0, s30, 0xc000
	ds_read_b128 v[176:179], v210
	ds_read_b128 v[180:183], v210 offset:1024
	ds_read_b128 v[184:187], v210 offset:2048
	ds_read_b128 v[188:191], v210 offset:3072
	ds_read_b128 v[194:197], v210 offset:4096
	ds_read_b128 v[198:201], v210 offset:5120
	ds_read_b128 v[202:205], v210 offset:6144
	ds_read_b128 v[212:215], v210 offset:7168
	global_load_lds_dwordx4 v136, s[24:25]
	s_add_i32 m0, s30, 0xe000
	s_nop 0
	global_load_lds_dwordx4 v138, s[24:25]
	s_waitcnt vmcnt(8)
	s_waitcnt lgkmcnt(0)
	s_barrier
; #define PG8_STAGE(bufoff, gbase, voff) do { _Pragma("unroll") for (int _i = 0; _i < 2; ++_i) \
;         __builtin_amdgcn_global_load_lds((const unsigned*)((const char*)(gbase) + (voff)[_i]), (LAS unsigned*)(lds + (bufoff) + ldsw + _i * 8192), 16, 0, ((voff) == voffA ? AUXA : 0)); } while (0)
; #define PG8_LDA(dst, b, h) do { _Pragma("unroll") for (int m = 0; m < 4; ++m) _Pragma("unroll") for (int k = 0; k < 2; ++k) dst[m][k] = *(const LAS bf16x8*)(lds + PG8_SA(b, h) + aoff + m * 2048 + k * 1024); } while (0)
; #define PG8_MMA(ai, bj, At, Bt) do { __builtin_amdgcn_s_setprio(1); _Pragma("unroll") for (int m = 0; m < 4; ++m) _Pragma("unroll") for (int n = 0; n < 2; ++n) _Pragma("unroll") for (int k = 0; k < 2; ++k) \
;         acc[ai][bj][m][n] = __builtin_amdgcn_mfma_f32_16x16x32_bf16(Bt[n][k], At[m][k], acc[ai][bj][m][n], 0, 0, 0); __builtin_amdgcn_s_setprio(0); } while (0)
; #define PG8_WAIT_V(n) asm volatile("s_waitcnt vmcnt(" #n ")" ::: "memory")
; #define PG8_WAIT_L(n) asm volatile("s_waitcnt lgkmcnt(" #n ")" ::: "memory")
; #define PG8_BAR __builtin_amdgcn_s_barrier()
; #define PG8_SCHED __builtin_amdgcn_sched_barrier(0)
;     ...
;             PG8_WAIT_L(0); PG8_BAR; PG8_MMA(0, 0, At, B0); PG8_MMA(0, 1, At, B1); PG8_BAR; PG8_SCHED;
;             PG8_LDA(At, 0, 1); PG8_STAGE(PG8_SB(0, 0), b2, voffB); PG8_STAGE(PG8_SB(0, 1), b2 + hsB, voffB); PG8_STAGE(PG8_SA(0, 0), a2, voffA);
;             if (Epi::NPRE != 0 && last) { PG8_WAIT_V(16); } else { PG8_WAIT_V(8); }
;             PG8_WAIT_L(0); PG8_BAR; PG8_MMA(1, 0, At, B0); PG8_MMA(1, 1, At, B1); PG8_BAR; PG8_SCHED;
	v_mfma_f32_16x16x32_bf16 v[124:127], v[144:147], v[176:179], v[124:127]
	v_mfma_f32_16x16x32_bf16 v[120:123], v[152:155], v[176:179], v[120:123]
	v_mfma_f32_16x16x32_bf16 v[116:119], v[144:147], v[184:187], v[116:119]
	v_mfma_f32_16x16x32_bf16 v[112:115], v[152:155], v[184:187], v[112:115]
	v_mfma_f32_16x16x32_bf16 v[104:107], v[144:147], v[194:197], v[104:107]
	v_mfma_f32_16x16x32_bf16 v[96:99], v[152:155], v[194:197], v[96:99]
	v_mfma_f32_16x16x32_bf16 v[88:91], v[144:147], v[202:205], v[88:91]
	v_mfma_f32_16x16x32_bf16 v[80:83], v[152:155], v[202:205], v[80:83]
	v_mfma_f32_16x16x32_bf16 v[124:127], v[148:151], v[180:183], v[124:127]
	v_mfma_f32_16x16x32_bf16 v[120:123], v[156:159], v[180:183], v[120:123]
	v_mfma_f32_16x16x32_bf16 v[116:119], v[148:151], v[188:191], v[116:119]
	v_mfma_f32_16x16x32_bf16 v[112:115], v[156:159], v[188:191], v[112:115]
	v_mfma_f32_16x16x32_bf16 v[104:107], v[148:151], v[198:201], v[104:107]
	v_mfma_f32_16x16x32_bf16 v[96:99], v[156:159], v[198:201], v[96:99]
	v_mfma_f32_16x16x32_bf16 v[88:91], v[148:151], v[212:215], v[88:91]
	v_mfma_f32_16x16x32_bf16 v[80:83], v[156:159], v[212:215], v[80:83]
	v_mfma_f32_16x16x32_bf16 v[108:111], v[160:163], v[176:179], v[108:111]
	v_mfma_f32_16x16x32_bf16 v[100:103], v[168:171], v[176:179], v[100:103]
	v_mfma_f32_16x16x32_bf16 v[92:95], v[160:163], v[184:187], v[92:95]
	v_mfma_f32_16x16x32_bf16 v[84:87], v[168:171], v[184:187], v[84:87]
	v_mfma_f32_16x16x32_bf16 v[76:79], v[160:163], v[194:197], v[76:79]
	v_mfma_f32_16x16x32_bf16 v[72:75], v[168:171], v[194:197], v[72:75]
	v_mfma_f32_16x16x32_bf16 v[68:71], v[160:163], v[202:205], v[68:71]
	v_mfma_f32_16x16x32_bf16 v[64:67], v[168:171], v[202:205], v[64:67]
	v_mfma_f32_16x16x32_bf16 v[108:111], v[164:167], v[180:183], v[108:111]
	v_mfma_f32_16x16x32_bf16 v[100:103], v[172:175], v[180:183], v[100:103]
	v_mfma_f32_16x16x32_bf16 v[92:95], v[164:167], v[188:191], v[92:95]
	v_mfma_f32_16x16x32_bf16 v[84:87], v[172:175], v[188:191], v[84:87]
	v_mfma_f32_16x16x32_bf16 v[76:79], v[164:167], v[198:201], v[76:79]
	v_mfma_f32_16x16x32_bf16 v[72:75], v[172:175], v[198:201], v[72:75]
	v_mfma_f32_16x16x32_bf16 v[68:71], v[164:167], v[212:215], v[68:71]
	v_mfma_f32_16x16x32_bf16 v[64:67], v[172:175], v[212:215], v[64:67]
	s_barrier
	s_add_u32 s98, s26, s16
	s_addc_u32 s99, s27, s17
	s_add_u32 s100, s28, s16
	s_addc_u32 s101, s29, s17
	s_add_i32 s53, s44, s5
	s_mov_b32 m0, s53
	ds_read_b128 v[176:179], v210 offset:16384
	ds_read_b128 v[180:183], v210 offset:17408
	ds_read_b128 v[184:187], v210 offset:18432
	ds_read_b128 v[188:191], v210 offset:19456
	ds_read_b128 v[194:197], v210 offset:20480
	ds_read_b128 v[198:201], v210 offset:21504
	ds_read_b128 v[202:205], v210 offset:22528
	ds_read_b128 v[212:215], v210 offset:23552
	global_load_lds_dwordx4 v130, s[26:27]
	s_add_i32 m0, s53, 0x2000
	s_add_u32 s54, s26, 0x160000
	s_addc_u32 s55, s27, 0
	s_add_i32 s53, s45, s5
	global_load_lds_dwordx4 v134, s[26:27]
	s_mov_b32 m0, s53
	s_nop 0
	global_load_lds_dwordx4 v130, s[54:55]
	s_add_i32 m0, s53, 0x2000
	s_nop 0
	global_load_lds_dwordx4 v134, s[54:55]
	s_waitcnt vmcnt(6)
	s_waitcnt lgkmcnt(0)
	s_barrier
	v_mfma_f32_16x16x32_bf16 v[60:63], v[144:147], v[176:179], v[60:63]
	v_mfma_f32_16x16x32_bf16 v[56:59], v[152:155], v[176:179], v[56:59]
	v_mfma_f32_16x16x32_bf16 v[52:55], v[144:147], v[184:187], v[52:55]
	v_mfma_f32_16x16x32_bf16 v[48:51], v[152:155], v[184:187], v[48:51]
	v_mfma_f32_16x16x32_bf16 v[40:43], v[144:147], v[194:197], v[40:43]
	v_mfma_f32_16x16x32_bf16 v[32:35], v[152:155], v[194:197], v[32:35]
	v_mfma_f32_16x16x32_bf16 v[24:27], v[144:147], v[202:205], v[24:27]
	v_mfma_f32_16x16x32_bf16 v[16:19], v[152:155], v[202:205], v[16:19]
	v_mfma_f32_16x16x32_bf16 v[60:63], v[148:151], v[180:183], v[60:63]
	v_mfma_f32_16x16x32_bf16 v[56:59], v[156:159], v[180:183], v[56:59]
	v_mfma_f32_16x16x32_bf16 v[52:55], v[148:151], v[188:191], v[52:55]
	v_mfma_f32_16x16x32_bf16 v[48:51], v[156:159], v[188:191], v[48:51]
	v_mfma_f32_16x16x32_bf16 v[40:43], v[148:151], v[198:201], v[40:43]
	v_mfma_f32_16x16x32_bf16 v[32:35], v[156:159], v[198:201], v[32:35]
	v_mfma_f32_16x16x32_bf16 v[24:27], v[148:151], v[212:215], v[24:27]
	v_mfma_f32_16x16x32_bf16 v[16:19], v[156:159], v[212:215], v[16:19]
	v_mfma_f32_16x16x32_bf16 v[44:47], v[160:163], v[176:179], v[44:47]
	v_mfma_f32_16x16x32_bf16 v[36:39], v[168:171], v[176:179], v[36:39]
	v_mfma_f32_16x16x32_bf16 v[28:31], v[160:163], v[184:187], v[28:31]
	v_mfma_f32_16x16x32_bf16 v[20:23], v[168:171], v[184:187], v[20:23]
	v_mfma_f32_16x16x32_bf16 v[12:15], v[160:163], v[194:197], v[12:15]
	v_mfma_f32_16x16x32_bf16 v[8:11], v[168:171], v[194:197], v[8:11]
	v_mfma_f32_16x16x32_bf16 v[4:7], v[160:163], v[202:205], v[4:7]
	v_mfma_f32_16x16x32_bf16 v[0:3], v[168:171], v[202:205], v[0:3]
	v_mfma_f32_16x16x32_bf16 v[44:47], v[164:167], v[180:183], v[44:47]
	v_mfma_f32_16x16x32_bf16 v[36:39], v[172:175], v[180:183], v[36:39]
	v_mfma_f32_16x16x32_bf16 v[28:31], v[164:167], v[188:191], v[28:31]
	v_mfma_f32_16x16x32_bf16 v[20:23], v[172:175], v[188:191], v[20:23]
	v_mfma_f32_16x16x32_bf16 v[12:15], v[164:167], v[198:201], v[12:15]
	v_mfma_f32_16x16x32_bf16 v[8:11], v[172:175], v[198:201], v[8:11]
	v_mfma_f32_16x16x32_bf16 v[4:7], v[164:167], v[212:215], v[4:7]
	v_mfma_f32_16x16x32_bf16 v[0:3], v[172:175], v[212:215], v[0:3]
	s_barrier
; #define PG8_STAGE(bufoff, gbase, voff) do { _Pragma("unroll") for (int _i = 0; _i < 2; ++_i) \
;         __builtin_amdgcn_global_load_lds((const unsigned*)((const char*)(gbase) + (voff)[_i]), (LAS unsigned*)(lds + (bufoff) + ldsw + _i * 8192), 16, 0, ((voff) == voffA ? AUXA : 0)); } while (0)
; #define PG8_LDA(dst, b, h) do { _Pragma("unroll") for (int m = 0; m < 4; ++m) _Pragma("unroll") for (int k = 0; k < 2; ++k) dst[m][k] = *(const LAS bf16x8*)(lds + PG8_SA(b, h) + aoff + m * 2048 + k * 1024); } while (0)
; #define PG8_LDB(dst, b, h) do { _Pragma("unroll") for (int n = 0; n < 2; ++n) _Pragma("unroll") for (int k = 0; k < 2; ++k) dst[n][k] = *(const LAS bf16x8*)(lds + PG8_SB(b, h) + boff + n * 2048 + k * 1024); } while (0)
; #define PG8_MMA(ai, bj, At, Bt) do { __builtin_amdgcn_s_setprio(1); _Pragma("unroll") for (int m = 0; m < 4; ++m) _Pragma("unroll") for (int n = 0; n < 2; ++n) _Pragma("unroll") for (int k = 0; k < 2; ++k) \
;         acc[ai][bj][m][n] = __builtin_amdgcn_mfma_f32_16x16x32_bf16(Bt[n][k], At[m][k], acc[ai][bj][m][n], 0, 0, 0); __builtin_amdgcn_s_setprio(0); } while (0)
; #define PG8_WAIT_V(n) asm volatile("s_waitcnt vmcnt(" #n ")" ::: "memory")
; #define PG8_WAIT_L(n) asm volatile("s_waitcnt lgkmcnt(" #n ")" ::: "memory")
; #define PG8_BAR __builtin_amdgcn_s_barrier()
; #define PG8_SCHED __builtin_amdgcn_sched_barrier(0)
;     ...
;             PG8_LDB(B0, 1, 0); PG8_LDB(B1, 1, 1); PG8_SCHED; PG8_LDA(At, 1, 0); PG8_STAGE(PG8_SA(0, 1), a2 + hsA, voffA);
;             PG8_WAIT_V(8); PG8_WAIT_L(0); PG8_BAR; PG8_MMA(0, 0, At, B0); PG8_MMA(0, 1, At, B1); PG8_BAR; PG8_SCHED;
;             PG8_LDA(At, 1, 1); PG8_STAGE(PG8_SB(1, 0), b3, voffB); PG8_STAGE(PG8_SB(1, 1), b3 + hsB, voffB); PG8_STAGE(PG8_SA(1, 0), a3, voffA);
;             PG8_WAIT_V(8); PG8_WAIT_L(0); PG8_BAR; PG8_MMA(1, 0, At, B0); PG8_MMA(1, 1, At, B1); PG8_BAR; PG8_SCHED;
	s_mov_b32 m0, s30
	s_nop 0
	global_load_lds_dwordx4 v128, s[28:29]
	s_mov_b32 m0, s31
	s_nop 0
	global_load_lds_dwordx4 v132, s[28:29]
	s_add_i32 s53, 0, 0x18000
	s_add_i32 s54, 0, 0x1c000
	v_add_u32_e32 v156, s53, v206
	v_add_u32_e32 v172, s54, v206
	ds_read_b128 v[144:147], v156
	ds_read_b128 v[148:151], v156 offset:1024
	ds_read_b128 v[152:155], v156 offset:2048
	ds_read_b128 v[156:159], v156 offset:3072
	ds_read_b128 v[160:163], v172
	ds_read_b128 v[164:167], v172 offset:1024
	ds_read_b128 v[168:171], v172 offset:2048
	ds_read_b128 v[172:175], v172 offset:3072
	s_add_u32 s28, s28, 0x160000
	s_addc_u32 s29, s29, 0
	s_mov_b32 m0, s34
	ds_read_b128 v[176:179], v210 offset:32768
	ds_read_b128 v[180:183], v210 offset:33792
	ds_read_b128 v[184:187], v210 offset:34816
	ds_read_b128 v[188:191], v210 offset:35840
	ds_read_b128 v[194:197], v210 offset:36864
	ds_read_b128 v[198:201], v210 offset:37888
	ds_read_b128 v[202:205], v210 offset:38912
	ds_read_b128 v[212:215], v210 offset:39936
	global_load_lds_dwordx4 v128, s[28:29]
	s_mov_b32 m0, s35
	s_nop 0
	global_load_lds_dwordx4 v132, s[28:29]
	s_waitcnt vmcnt(8)
	s_waitcnt lgkmcnt(0)
	s_barrier
	v_mfma_f32_16x16x32_bf16 v[124:127], v[144:147], v[176:179], v[124:127]
	v_mfma_f32_16x16x32_bf16 v[120:123], v[152:155], v[176:179], v[120:123]
	v_mfma_f32_16x16x32_bf16 v[116:119], v[144:147], v[184:187], v[116:119]
	v_mfma_f32_16x16x32_bf16 v[112:115], v[152:155], v[184:187], v[112:115]
	v_mfma_f32_16x16x32_bf16 v[104:107], v[144:147], v[194:197], v[104:107]
	v_mfma_f32_16x16x32_bf16 v[96:99], v[152:155], v[194:197], v[96:99]
	v_mfma_f32_16x16x32_bf16 v[88:91], v[144:147], v[202:205], v[88:91]
	v_mfma_f32_16x16x32_bf16 v[80:83], v[152:155], v[202:205], v[80:83]
	v_mfma_f32_16x16x32_bf16 v[124:127], v[148:151], v[180:183], v[124:127]
	v_mfma_f32_16x16x32_bf16 v[120:123], v[156:159], v[180:183], v[120:123]
	v_mfma_f32_16x16x32_bf16 v[116:119], v[148:151], v[188:191], v[116:119]
	v_mfma_f32_16x16x32_bf16 v[112:115], v[156:159], v[188:191], v[112:115]
	v_mfma_f32_16x16x32_bf16 v[104:107], v[148:151], v[198:201], v[104:107]
	v_mfma_f32_16x16x32_bf16 v[96:99], v[156:159], v[198:201], v[96:99]
	v_mfma_f32_16x16x32_bf16 v[88:91], v[148:151], v[212:215], v[88:91]
	v_mfma_f32_16x16x32_bf16 v[80:83], v[156:159], v[212:215], v[80:83]
	v_mfma_f32_16x16x32_bf16 v[108:111], v[160:163], v[176:179], v[108:111]
	v_mfma_f32_16x16x32_bf16 v[100:103], v[168:171], v[176:179], v[100:103]
	v_mfma_f32_16x16x32_bf16 v[92:95], v[160:163], v[184:187], v[92:95]
	v_mfma_f32_16x16x32_bf16 v[84:87], v[168:171], v[184:187], v[84:87]
	v_mfma_f32_16x16x32_bf16 v[76:79], v[160:163], v[194:197], v[76:79]
	v_mfma_f32_16x16x32_bf16 v[72:75], v[168:171], v[194:197], v[72:75]
	v_mfma_f32_16x16x32_bf16 v[68:71], v[160:163], v[202:205], v[68:71]
	v_mfma_f32_16x16x32_bf16 v[64:67], v[168:171], v[202:205], v[64:67]
	v_mfma_f32_16x16x32_bf16 v[108:111], v[164:167], v[180:183], v[108:111]
	v_mfma_f32_16x16x32_bf16 v[100:103], v[172:175], v[180:183], v[100:103]
	v_mfma_f32_16x16x32_bf16 v[92:95], v[164:167], v[188:191], v[92:95]
	v_mfma_f32_16x16x32_bf16 v[84:87], v[172:175], v[188:191], v[84:87]
	v_mfma_f32_16x16x32_bf16 v[76:79], v[164:167], v[198:201], v[76:79]
	v_mfma_f32_16x16x32_bf16 v[72:75], v[172:175], v[198:201], v[72:75]
	v_mfma_f32_16x16x32_bf16 v[68:71], v[164:167], v[212:215], v[68:71]
	v_mfma_f32_16x16x32_bf16 v[64:67], v[172:175], v[212:215], v[64:67]
	s_barrier
	s_add_i32 s28, s53, s5
	s_mov_b32 m0, s28
	ds_read_b128 v[176:179], v210 offset:49152
	ds_read_b128 v[180:183], v210 offset:50176
	ds_read_b128 v[184:187], v210 offset:51200
	ds_read_b128 v[188:191], v210 offset:52224
	ds_read_b128 v[194:197], v210 offset:53248
	ds_read_b128 v[198:201], v210 offset:54272
	ds_read_b128 v[202:205], v210 offset:55296
	ds_read_b128 v[212:215], v210 offset:56320
	global_load_lds_dwordx4 v130, s[98:99]
	s_add_i32 m0, s28, 0x2000
	s_add_u32 s26, s26, 0x160080
	s_addc_u32 s27, s27, 0
	s_add_i32 s28, s54, s5
	global_load_lds_dwordx4 v134, s[98:99]
	s_mov_b32 m0, s28
	s_nop 0
	global_load_lds_dwordx4 v130, s[26:27]
	s_add_i32 m0, s28, 0x2000
	s_nop 0
	global_load_lds_dwordx4 v134, s[26:27]
	s_waitcnt vmcnt(6)
	s_waitcnt lgkmcnt(0)
	s_barrier
; #define PG8_MMA(ai, bj, At, Bt) do { __builtin_amdgcn_s_setprio(1); _Pragma("unroll") for (int m = 0; m < 4; ++m) _Pragma("unroll") for (int n = 0; n < 2; ++n) _Pragma("unroll") for (int k = 0; k < 2; ++k) \
;         acc[ai][bj][m][n] = __builtin_amdgcn_mfma_f32_16x16x32_bf16(Bt[n][k], At[m][k], acc[ai][bj][m][n], 0, 0, 0); __builtin_amdgcn_s_setprio(0); } while (0)
; #define PG8_WAIT_V(n) asm volatile("s_waitcnt vmcnt(" #n ")" ::: "memory")
; #define PG8_WAIT_L(n) asm volatile("s_waitcnt lgkmcnt(" #n ")" ::: "memory")
; #define PG8_BAR __builtin_amdgcn_s_barrier()
; #define PG8_SCHED __builtin_amdgcn_sched_barrier(0)
;     ...
;             PG8_WAIT_V(8); PG8_WAIT_L(0); PG8_BAR; PG8_MMA(1, 0, At, B0); PG8_MMA(1, 1, At, B1); PG8_BAR; PG8_SCHED;
;         }
;     __device__ __forceinline__ void operator()(const Acc& acc, const Unit& u, int wr, int wc, int fr, int fq, const float (&sv8)[8]) const {
;     ...
;                     const int col = colb + bj * 128;
;                     const f32x4 y0 = xr[m][bj][0] + acc[ai][bj][m][0] * scale, y1 = xr[m][bj][1] + acc[ai][bj][m][1] * scale;
	v_mfma_f32_16x16x32_bf16 v[60:63], v[144:147], v[176:179], v[60:63]
	v_mfma_f32_16x16x32_bf16 v[56:59], v[152:155], v[176:179], v[56:59]
	v_mfma_f32_16x16x32_bf16 v[52:55], v[144:147], v[184:187], v[52:55]
	v_mfma_f32_16x16x32_bf16 v[48:51], v[152:155], v[184:187], v[48:51]
	v_mfma_f32_16x16x32_bf16 v[40:43], v[144:147], v[194:197], v[40:43]
	v_mfma_f32_16x16x32_bf16 v[32:35], v[152:155], v[194:197], v[32:35]
	v_mfma_f32_16x16x32_bf16 v[24:27], v[144:147], v[202:205], v[24:27]
	v_mfma_f32_16x16x32_bf16 v[16:19], v[152:155], v[202:205], v[16:19]
	v_mfma_f32_16x16x32_bf16 v[60:63], v[148:151], v[180:183], v[60:63]
	v_mfma_f32_16x16x32_bf16 v[56:59], v[156:159], v[180:183], v[56:59]
	v_mfma_f32_16x16x32_bf16 v[52:55], v[148:151], v[188:191], v[52:55]
	v_mfma_f32_16x16x32_bf16 v[48:51], v[156:159], v[188:191], v[48:51]
	v_mfma_f32_16x16x32_bf16 v[40:43], v[148:151], v[198:201], v[40:43]
	v_mfma_f32_16x16x32_bf16 v[32:35], v[156:159], v[198:201], v[32:35]
	v_mfma_f32_16x16x32_bf16 v[24:27], v[148:151], v[212:215], v[24:27]
	v_mfma_f32_16x16x32_bf16 v[16:19], v[156:159], v[212:215], v[16:19]
	v_mfma_f32_16x16x32_bf16 v[44:47], v[160:163], v[176:179], v[44:47]
	v_mfma_f32_16x16x32_bf16 v[36:39], v[168:171], v[176:179], v[36:39]
	v_mfma_f32_16x16x32_bf16 v[28:31], v[160:163], v[184:187], v[28:31]
	v_mfma_f32_16x16x32_bf16 v[20:23], v[168:171], v[184:187], v[20:23]
	v_mfma_f32_16x16x32_bf16 v[12:15], v[160:163], v[194:197], v[12:15]
	v_mfma_f32_16x16x32_bf16 v[8:11], v[168:171], v[194:197], v[8:11]
	v_mfma_f32_16x16x32_bf16 v[4:7], v[160:163], v[202:205], v[4:7]
	v_mfma_f32_16x16x32_bf16 v[0:3], v[168:171], v[202:205], v[0:3]
	v_mfma_f32_16x16x32_bf16 v[44:47], v[164:167], v[180:183], v[44:47]
	v_mfma_f32_16x16x32_bf16 v[36:39], v[172:175], v[180:183], v[36:39]
	v_mfma_f32_16x16x32_bf16 v[28:31], v[164:167], v[188:191], v[28:31]
	v_mfma_f32_16x16x32_bf16 v[20:23], v[172:175], v[188:191], v[20:23]
	v_mfma_f32_16x16x32_bf16 v[12:15], v[164:167], v[198:201], v[12:15]
	v_mfma_f32_16x16x32_bf16 v[8:11], v[172:175], v[198:201], v[8:11]
	v_mfma_f32_16x16x32_bf16 v[4:7], v[164:167], v[212:215], v[4:7]
	v_mfma_f32_16x16x32_bf16 v[0:3], v[172:175], v[212:215], v[0:3]
	s_barrier
	s_add_u32 s24, s24, 0x100
	s_addc_u32 s25, s25, 0
	s_add_u32 s50, s50, 0x100
	s_addc_u32 s51, s51, 0
	s_cmp_ge_i32 s52, s38
	s_mov_b32 s26, s52
	s_cbranch_scc0 .LBB0_246
	s_setprio 0
	v_pk_mul_f32 v[178:179], v[126:127], 0.5 op_sel_hi:[1,0]
	v_pk_mul_f32 v[184:185], v[124:125], 0.5 op_sel_hi:[1,0]
	v_pk_mul_f32 v[182:183], v[122:123], 0.5 op_sel_hi:[1,0]
	v_pk_mul_f32 v[180:181], v[120:121], 0.5 op_sel_hi:[1,0]
	v_pk_mul_f32 v[194:195], v[110:111], 0.5 op_sel_hi:[1,0]
	v_pk_mul_f32 v[190:191], v[108:109], 0.5 op_sel_hi:[1,0]
	v_pk_mul_f32 v[188:189], v[102:103], 0.5 op_sel_hi:[1,0]
	v_pk_mul_f32 v[186:187], v[100:101], 0.5 op_sel_hi:[1,0]
	v_pk_mul_f32 v[168:169], v[118:119], 0.5 op_sel_hi:[1,0]
	v_pk_mul_f32 v[166:167], v[116:117], 0.5 op_sel_hi:[1,0]
	v_pk_mul_f32 v[164:165], v[114:115], 0.5 op_sel_hi:[1,0]
	v_pk_mul_f32 v[162:163], v[112:113], 0.5 op_sel_hi:[1,0]
	v_pk_mul_f32 v[176:177], v[94:95], 0.5 op_sel_hi:[1,0]
	v_pk_mul_f32 v[174:175], v[92:93], 0.5 op_sel_hi:[1,0]
	v_pk_mul_f32 v[172:173], v[86:87], 0.5 op_sel_hi:[1,0]
	v_pk_mul_f32 v[170:171], v[84:85], 0.5 op_sel_hi:[1,0]
	v_pk_mul_f32 v[152:153], v[106:107], 0.5 op_sel_hi:[1,0]
	v_pk_mul_f32 v[150:151], v[104:105], 0.5 op_sel_hi:[1,0]
	v_pk_mul_f32 v[148:149], v[98:99], 0.5 op_sel_hi:[1,0]
	v_pk_mul_f32 v[146:147], v[96:97], 0.5 op_sel_hi:[1,0]
	v_pk_mul_f32 v[160:161], v[78:79], 0.5 op_sel_hi:[1,0]
	v_pk_mul_f32 v[158:159], v[76:77], 0.5 op_sel_hi:[1,0]
	v_pk_mul_f32 v[156:157], v[74:75], 0.5 op_sel_hi:[1,0]
	v_pk_mul_f32 v[154:155], v[72:73], 0.5 op_sel_hi:[1,0]
	v_pk_mul_f32 v[120:121], v[90:91], 0.5 op_sel_hi:[1,0]
	v_pk_mul_f32 v[118:119], v[88:89], 0.5 op_sel_hi:[1,0]
	v_pk_mul_f32 v[116:117], v[82:83], 0.5 op_sel_hi:[1,0]
	v_pk_mul_f32 v[114:115], v[80:81], 0.5 op_sel_hi:[1,0]
	v_pk_mul_f32 v[144:145], v[70:71], 0.5 op_sel_hi:[1,0]
	v_pk_mul_f32 v[126:127], v[68:69], 0.5 op_sel_hi:[1,0]
	v_pk_mul_f32 v[124:125], v[66:67], 0.5 op_sel_hi:[1,0]
	v_pk_mul_f32 v[122:123], v[64:65], 0.5 op_sel_hi:[1,0]
	v_pk_mul_f32 v[102:103], v[62:63], 0.5 op_sel_hi:[1,0]
	v_pk_mul_f32 v[100:101], v[60:61], 0.5 op_sel_hi:[1,0]
	v_pk_mul_f32 v[98:99], v[58:59], 0.5 op_sel_hi:[1,0]
	v_pk_mul_f32 v[96:97], v[56:57], 0.5 op_sel_hi:[1,0]
	v_pk_mul_f32 v[110:111], v[46:47], 0.5 op_sel_hi:[1,0]
	v_pk_mul_f32 v[108:109], v[44:45], 0.5 op_sel_hi:[1,0]
	v_pk_mul_f32 v[106:107], v[38:39], 0.5 op_sel_hi:[1,0]
	v_pk_mul_f32 v[104:105], v[36:37], 0.5 op_sel_hi:[1,0]
	v_pk_mul_f32 v[86:87], v[54:55], 0.5 op_sel_hi:[1,0]
	v_pk_mul_f32 v[84:85], v[52:53], 0.5 op_sel_hi:[1,0]
	v_pk_mul_f32 v[82:83], v[50:51], 0.5 op_sel_hi:[1,0]
	v_pk_mul_f32 v[80:81], v[48:49], 0.5 op_sel_hi:[1,0]
	v_pk_mul_f32 v[94:95], v[30:31], 0.5 op_sel_hi:[1,0]
	v_pk_mul_f32 v[92:93], v[28:29], 0.5 op_sel_hi:[1,0]
	v_pk_mul_f32 v[90:91], v[22:23], 0.5 op_sel_hi:[1,0]
	v_pk_mul_f32 v[88:89], v[20:21], 0.5 op_sel_hi:[1,0]
	v_pk_mul_f32 v[70:71], v[42:43], 0.5 op_sel_hi:[1,0]
	v_pk_mul_f32 v[68:69], v[40:41], 0.5 op_sel_hi:[1,0]
	v_pk_mul_f32 v[66:67], v[34:35], 0.5 op_sel_hi:[1,0]
	v_pk_mul_f32 v[64:65], v[32:33], 0.5 op_sel_hi:[1,0]
	v_pk_mul_f32 v[78:79], v[14:15], 0.5 op_sel_hi:[1,0]
	v_pk_mul_f32 v[76:77], v[12:13], 0.5 op_sel_hi:[1,0]
	v_pk_mul_f32 v[74:75], v[10:11], 0.5 op_sel_hi:[1,0]
	v_pk_mul_f32 v[72:73], v[8:9], 0.5 op_sel_hi:[1,0]
	v_pk_mul_f32 v[54:55], v[26:27], 0.5 op_sel_hi:[1,0]
	v_pk_mul_f32 v[52:53], v[24:25], 0.5 op_sel_hi:[1,0]
	v_pk_mul_f32 v[50:51], v[18:19], 0.5 op_sel_hi:[1,0]
	v_pk_mul_f32 v[48:49], v[16:17], 0.5 op_sel_hi:[1,0]
	v_pk_mul_f32 v[62:63], v[6:7], 0.5 op_sel_hi:[1,0]
	v_pk_mul_f32 v[60:61], v[4:5], 0.5 op_sel_hi:[1,0]
	v_pk_mul_f32 v[58:59], v[2:3], 0.5 op_sel_hi:[1,0]
	v_pk_mul_f32 v[56:57], v[0:1], 0.5 op_sel_hi:[1,0]

;     __device__ bool next(int i, Unit& u) const { const int L = i * G + c; if (L >= 384) return false; u.pm = L; u.pn = L / 6; return true; }
;     ...
;         const bool has_next = S.next(ui + 1, nxt);
;         const char* nA = has_next ? (const char*)g.A + (size_t)nxt.pm * tsA : cA; const char* nB = has_next ? (const char*)g.Bt + (size_t)nxt.pn * tsB : cB;
;         for (int t = 0; t < nt; t += 2) {
;             const bool last = (t == nt - 2);
;             const char* a1 = cA + (size_t)(t + 1) * kstep;
;             const char* a2 = last ? nA : cA + (size_t)(t + 2) * kstep; const char* b2 = last ? nB : cB + (size_t)(t + 2) * kstep;
;     ...
; #pragma unroll
;         for (int a = 0; a < 2; ++a)
; #pragma unroll
;             for (int b = 0; b < 2; ++b)
; #pragma unroll
;                 for (int m = 0; m < 4; ++m)
; #pragma unroll
;                     for (int n = 0; n < 2; ++n) acc[a][b][m][n] = (f32x4){0.f, 0.f, 0.f, 0.f};
.LBB0_368:
	s_ashr_i32 s23, s22, 31
	s_lshl_b64 s[24:25], s[22:23], 20
	s_add_u32 s24, s96, s24
	s_addc_u32 s25, s97, s25
	s_ashr_i32 s21, s20, 31
	s_lshl_b64 s[26:27], s[20:21], 20
	s_add_u32 s26, s3, s26
	s_addc_u32 s27, s4, s27
	s_andn2_b64 vcc, exec, s[14:15]
	v_mov_b32_e32 v127, 0
	s_cbranch_vccnz .LBB0_379
	s_and_b64 s[34:35], s[0:1], exec
	s_cselect_b32 s7, s25, s29
	s_cselect_b32 s21, s24, s28
	s_cselect_b32 s23, s27, s31
	s_cselect_b32 s68, s26, s30
	v_lshl_add_u32 v0, s6, 8, v205
	s_add_u32 s28, s28, 0x80080
	v_ashrrev_i32_e32 v1, 31, v0
	s_addc_u32 s29, s29, 0
	v_lshl_add_u64 v[224:225], v[0:1], 2, s[88:89]
	s_add_u32 s69, s30, 0x100
	v_mov_b32_e32 v0, 0
	s_addc_u32 s70, s31, 0
	s_mov_b32 s71, 0
	v_mov_b32_e32 v1, 0
	v_mov_b64_e32 v[2:3], 0
	v_mov_b64_e32 v[4:5], 0
	v_mov_b64_e32 v[6:7], 0
	v_mov_b64_e32 v[16:17], 0
	v_mov_b64_e32 v[18:19], 0
	v_mov_b64_e32 v[20:21], 0
	v_mov_b64_e32 v[22:23], 0
	v_mov_b64_e32 v[32:33], 0
	v_mov_b64_e32 v[34:35], 0
	v_mov_b64_e32 v[36:37], 0
	v_mov_b64_e32 v[38:39], 0
	v_mov_b64_e32 v[48:49], 0
	v_mov_b64_e32 v[50:51], 0
	v_mov_b64_e32 v[52:53], 0
	v_mov_b64_e32 v[54:55], 0
	v_mov_b64_e32 v[8:9], 0
	v_mov_b64_e32 v[10:11], 0
	v_mov_b64_e32 v[12:13], 0
	v_mov_b64_e32 v[14:15], 0
	v_mov_b64_e32 v[24:25], 0
	v_mov_b64_e32 v[26:27], 0
	v_mov_b64_e32 v[28:29], 0
	v_mov_b64_e32 v[30:31], 0
	v_mov_b64_e32 v[40:41], 0
	v_mov_b64_e32 v[42:43], 0
	v_mov_b64_e32 v[44:45], 0
	v_mov_b64_e32 v[46:47], 0
	v_mov_b64_e32 v[56:57], 0
	v_mov_b64_e32 v[58:59], 0
	v_mov_b64_e32 v[60:61], 0
	v_mov_b64_e32 v[62:63], 0
	v_mov_b64_e32 v[64:65], 0
	v_mov_b64_e32 v[66:67], 0
	v_mov_b64_e32 v[68:69], 0
	v_mov_b64_e32 v[70:71], 0
	v_mov_b64_e32 v[80:81], 0
	v_mov_b64_e32 v[82:83], 0
	v_mov_b64_e32 v[84:85], 0
	v_mov_b64_e32 v[86:87], 0
	v_mov_b64_e32 v[96:97], 0
	v_mov_b64_e32 v[98:99], 0
	v_mov_b64_e32 v[100:101], 0
	v_mov_b64_e32 v[102:103], 0
	v_mov_b64_e32 v[112:113], 0
	v_mov_b64_e32 v[114:115], 0
	v_mov_b64_e32 v[116:117], 0
	v_mov_b64_e32 v[118:119], 0
	v_mov_b64_e32 v[72:73], 0
	v_mov_b64_e32 v[74:75], 0
	v_mov_b64_e32 v[76:77], 0
	v_mov_b64_e32 v[78:79], 0
	v_mov_b64_e32 v[88:89], 0
	v_mov_b64_e32 v[90:91], 0
	v_mov_b64_e32 v[92:93], 0
	v_mov_b64_e32 v[94:95], 0
	v_mov_b64_e32 v[104:105], 0
	v_mov_b64_e32 v[106:107], 0
	v_mov_b64_e32 v[108:109], 0
	v_mov_b64_e32 v[110:111], 0
	v_mov_b64_e32 v[120:121], 0
	v_mov_b64_e32 v[122:123], 0
	v_mov_b64_e32 v[124:125], 0
	v_mov_b64_e32 v[126:127], 0
	v_readfirstlane_b32 s99, v234
	s_nop 0
	s_lshr_b32 s99, s99, 8
	s_cmp_eq_u32 s99, 0
	s_cbranch_scc1 .Lsp_2
	s_setprio 1

; #define PG8_STAGE(bufoff, gbase, voff) do { _Pragma("unroll") for (int _i = 0; _i < 2; ++_i) \
;         __builtin_amdgcn_global_load_lds((const unsigned*)((const char*)(gbase) + (voff)[_i]), (LAS unsigned*)(lds + (bufoff) + ldsw + _i * 8192), 16, 0, ((voff) == voffA ? AUXA : 0)); } while (0)
; #define PG8_LDA(dst, b, h) do { _Pragma("unroll") for (int m = 0; m < 4; ++m) _Pragma("unroll") for (int k = 0; k < 2; ++k) dst[m][k] = *(const LAS bf16x8*)(lds + PG8_SA(b, h) + aoff + m * 2048 + k * 1024); } while (0)
; #define PG8_LDB(dst, b, h) do { _Pragma("unroll") for (int n = 0; n < 2; ++n) _Pragma("unroll") for (int k = 0; k < 2; ++k) dst[n][k] = *(const LAS bf16x8*)(lds + PG8_SB(b, h) + boff + n * 2048 + k * 1024); } while (0)
; #define PG8_MMA(ai, bj, At, Bt) do { __builtin_amdgcn_s_setprio(1); _Pragma("unroll") for (int m = 0; m < 4; ++m) _Pragma("unroll") for (int n = 0; n < 2; ++n) _Pragma("unroll") for (int k = 0; k < 2; ++k) \
;         acc[ai][bj][m][n] = __builtin_amdgcn_mfma_f32_16x16x32_bf16(Bt[n][k], At[m][k], acc[ai][bj][m][n], 0, 0, 0); __builtin_amdgcn_s_setprio(0); } while (0)
; #define PG8_WAIT_V(n) asm volatile("s_waitcnt vmcnt(" #n ")" ::: "memory")
; #define PG8_WAIT_L(n) asm volatile("s_waitcnt lgkmcnt(" #n ")" ::: "memory")
; #define PG8_BAR __builtin_amdgcn_s_barrier()
; #define PG8_SCHED __builtin_amdgcn_sched_barrier(0)
;     ...
;             PG8_WAIT_L(0); PG8_BAR; PG8_MMA(1, 0, At, B0); PG8_MMA(1, 1, At, B1); PG8_BAR; PG8_SCHED;
;             PG8_LDB(B0, 1, 0); PG8_LDB(B1, 1, 1); PG8_SCHED; PG8_LDA(At, 1, 0); PG8_STAGE(PG8_SA(0, 1), a2 + hsA, voffA);
;             PG8_WAIT_V(8); PG8_WAIT_L(0); PG8_BAR; PG8_MMA(0, 0, At, B0); PG8_MMA(0, 1, At, B1); PG8_BAR; PG8_SCHED;
.LBB0_370:
	s_waitcnt lgkmcnt(0)
	s_add_i32 s71, s71, 2
	s_barrier
	v_mfma_f32_16x16x32_bf16 v[60:63], v[144:147], v[184:187], v[60:63]
	v_mfma_f32_16x16x32_bf16 v[56:59], v[152:155], v[184:187], v[56:59]
	v_mfma_f32_16x16x32_bf16 v[44:47], v[144:147], v[176:179], v[44:47]
	v_mfma_f32_16x16x32_bf16 v[40:43], v[152:155], v[176:179], v[40:43]
	v_mfma_f32_16x16x32_bf16 v[28:31], v[144:147], v[168:171], v[28:31]
	v_mfma_f32_16x16x32_bf16 v[24:27], v[152:155], v[168:171], v[24:27]
	v_mfma_f32_16x16x32_bf16 v[12:15], v[144:147], v[160:163], v[12:15]
	v_mfma_f32_16x16x32_bf16 v[8:11], v[152:155], v[160:163], v[8:11]
	v_mfma_f32_16x16x32_bf16 v[60:63], v[148:151], v[188:191], v[60:63]
	v_mfma_f32_16x16x32_bf16 v[56:59], v[156:159], v[188:191], v[56:59]
	v_mfma_f32_16x16x32_bf16 v[44:47], v[148:151], v[180:183], v[44:47]
	v_mfma_f32_16x16x32_bf16 v[40:43], v[156:159], v[180:183], v[40:43]
	v_mfma_f32_16x16x32_bf16 v[28:31], v[148:151], v[172:175], v[28:31]
	v_mfma_f32_16x16x32_bf16 v[24:27], v[156:159], v[172:175], v[24:27]
	v_mfma_f32_16x16x32_bf16 v[12:15], v[148:151], v[164:167], v[12:15]
	v_mfma_f32_16x16x32_bf16 v[8:11], v[156:159], v[164:167], v[8:11]
	v_mfma_f32_16x16x32_bf16 v[52:55], v[128:131], v[184:187], v[52:55]
	v_mfma_f32_16x16x32_bf16 v[48:51], v[136:139], v[184:187], v[48:51]
	v_mfma_f32_16x16x32_bf16 v[36:39], v[128:131], v[176:179], v[36:39]
	v_mfma_f32_16x16x32_bf16 v[32:35], v[136:139], v[176:179], v[32:35]
	v_mfma_f32_16x16x32_bf16 v[20:23], v[128:131], v[168:171], v[20:23]
	v_mfma_f32_16x16x32_bf16 v[16:19], v[136:139], v[168:171], v[16:19]
	v_mfma_f32_16x16x32_bf16 v[4:7], v[128:131], v[160:163], v[4:7]
	v_mfma_f32_16x16x32_bf16 v[0:3], v[136:139], v[160:163], v[0:3]
	v_mfma_f32_16x16x32_bf16 v[52:55], v[132:135], v[188:191], v[52:55]
	v_mfma_f32_16x16x32_bf16 v[48:51], v[140:143], v[188:191], v[48:51]
	v_mfma_f32_16x16x32_bf16 v[36:39], v[132:135], v[180:183], v[36:39]
	v_mfma_f32_16x16x32_bf16 v[32:35], v[140:143], v[180:183], v[32:35]
	v_mfma_f32_16x16x32_bf16 v[20:23], v[132:135], v[172:175], v[20:23]
	v_mfma_f32_16x16x32_bf16 v[16:19], v[140:143], v[172:175], v[16:19]
	v_mfma_f32_16x16x32_bf16 v[4:7], v[132:135], v[164:167], v[4:7]
	v_mfma_f32_16x16x32_bf16 v[0:3], v[140:143], v[164:167], v[0:3]
	s_barrier
	s_mov_b32 m0, s13
	s_nop 0
	global_load_lds_dwordx4 v194, s[34:35]
	s_mov_b32 m0, s44
	s_nop 0
	global_load_lds_dwordx4 v198, s[34:35]
	s_add_i32 s36, 0, 0x18000
	s_add_i32 s37, 0, 0x1c000
	v_add_u32_e32 v140, s36, v235
	v_add_u32_e32 v156, s37, v235
	ds_read_b128 v[128:131], v140
	ds_read_b128 v[132:135], v140 offset:1024
	ds_read_b128 v[136:139], v140 offset:2048
	ds_read_b128 v[140:143], v140 offset:3072
	ds_read_b128 v[144:147], v156
	ds_read_b128 v[148:151], v156 offset:1024
	ds_read_b128 v[152:155], v156 offset:2048
	ds_read_b128 v[156:159], v156 offset:3072
	s_add_u32 s34, s34, 0x80000
	s_addc_u32 s35, s35, 0
	s_mov_b32 m0, s45
	ds_read_b128 v[160:163], v239 offset:32768
	ds_read_b128 v[164:167], v239 offset:33792
	ds_read_b128 v[168:171], v239 offset:34816
	ds_read_b128 v[172:175], v239 offset:35840
	ds_read_b128 v[176:179], v239 offset:36864
	ds_read_b128 v[180:183], v239 offset:37888
	ds_read_b128 v[184:187], v239 offset:38912
	ds_read_b128 v[188:191], v239 offset:39936
	global_load_lds_dwordx4 v194, s[34:35]
	s_mov_b32 m0, s46
	s_nop 0
	global_load_lds_dwordx4 v198, s[34:35]
	s_waitcnt vmcnt(8)
	s_waitcnt lgkmcnt(0)
	s_barrier
; #define PG8_STAGE(bufoff, gbase, voff) do { _Pragma("unroll") for (int _i = 0; _i < 2; ++_i) \
;         __builtin_amdgcn_global_load_lds((const unsigned*)((const char*)(gbase) + (voff)[_i]), (LAS unsigned*)(lds + (bufoff) + ldsw + _i * 8192), 16, 0, ((voff) == voffA ? AUXA : 0)); } while (0)
; #define PG8_LDA(dst, b, h) do { _Pragma("unroll") for (int m = 0; m < 4; ++m) _Pragma("unroll") for (int k = 0; k < 2; ++k) dst[m][k] = *(const LAS bf16x8*)(lds + PG8_SA(b, h) + aoff + m * 2048 + k * 1024); } while (0)
; #define PG8_MMA(ai, bj, At, Bt) do { __builtin_amdgcn_s_setprio(1); _Pragma("unroll") for (int m = 0; m < 4; ++m) _Pragma("unroll") for (int n = 0; n < 2; ++n) _Pragma("unroll") for (int k = 0; k < 2; ++k) \
;         acc[ai][bj][m][n] = __builtin_amdgcn_mfma_f32_16x16x32_bf16(Bt[n][k], At[m][k], acc[ai][bj][m][n], 0, 0, 0); __builtin_amdgcn_s_setprio(0); } while (0)
; #define PG8_WAIT_V(n) asm volatile("s_waitcnt vmcnt(" #n ")" ::: "memory")
; #define PG8_WAIT_L(n) asm volatile("s_waitcnt lgkmcnt(" #n ")" ::: "memory")
; #define PG8_BAR __builtin_amdgcn_s_barrier()
; #define PG8_SCHED __builtin_amdgcn_sched_barrier(0)
;     ...
;             PG8_WAIT_V(8); PG8_WAIT_L(0); PG8_BAR; PG8_MMA(0, 0, At, B0); PG8_MMA(0, 1, At, B1); PG8_BAR; PG8_SCHED;
;             PG8_LDA(At, 1, 1); PG8_STAGE(PG8_SB(1, 0), b3, voffB); PG8_STAGE(PG8_SB(1, 1), b3 + hsB, voffB); PG8_STAGE(PG8_SA(1, 0), a3, voffA);
;             PG8_WAIT_V(8); PG8_WAIT_L(0); PG8_BAR; PG8_MMA(1, 0, At, B0); PG8_MMA(1, 1, At, B1); PG8_BAR; PG8_SCHED;
;         }
	v_mfma_f32_16x16x32_bf16 v[124:127], v[128:131], v[160:163], v[124:127]
	v_mfma_f32_16x16x32_bf16 v[120:123], v[136:139], v[160:163], v[120:123]
	v_mfma_f32_16x16x32_bf16 v[108:111], v[128:131], v[168:171], v[108:111]
	v_mfma_f32_16x16x32_bf16 v[104:107], v[136:139], v[168:171], v[104:107]
	v_mfma_f32_16x16x32_bf16 v[92:95], v[128:131], v[176:179], v[92:95]
	v_mfma_f32_16x16x32_bf16 v[88:91], v[136:139], v[176:179], v[88:91]
	v_mfma_f32_16x16x32_bf16 v[76:79], v[128:131], v[184:187], v[76:79]
	v_mfma_f32_16x16x32_bf16 v[72:75], v[136:139], v[184:187], v[72:75]
	v_mfma_f32_16x16x32_bf16 v[124:127], v[132:135], v[164:167], v[124:127]
	v_mfma_f32_16x16x32_bf16 v[120:123], v[140:143], v[164:167], v[120:123]
	v_mfma_f32_16x16x32_bf16 v[108:111], v[132:135], v[172:175], v[108:111]
	v_mfma_f32_16x16x32_bf16 v[104:107], v[140:143], v[172:175], v[104:107]
	v_mfma_f32_16x16x32_bf16 v[92:95], v[132:135], v[180:183], v[92:95]
	v_mfma_f32_16x16x32_bf16 v[88:91], v[140:143], v[180:183], v[88:91]
	v_mfma_f32_16x16x32_bf16 v[76:79], v[132:135], v[188:191], v[76:79]
	v_mfma_f32_16x16x32_bf16 v[72:75], v[140:143], v[188:191], v[72:75]
	v_mfma_f32_16x16x32_bf16 v[116:119], v[144:147], v[160:163], v[116:119]
	v_mfma_f32_16x16x32_bf16 v[112:115], v[152:155], v[160:163], v[112:115]
	v_mfma_f32_16x16x32_bf16 v[100:103], v[144:147], v[168:171], v[100:103]
	v_mfma_f32_16x16x32_bf16 v[96:99], v[152:155], v[168:171], v[96:99]
	v_mfma_f32_16x16x32_bf16 v[84:87], v[144:147], v[176:179], v[84:87]
	v_mfma_f32_16x16x32_bf16 v[80:83], v[152:155], v[176:179], v[80:83]
	v_mfma_f32_16x16x32_bf16 v[68:71], v[144:147], v[184:187], v[68:71]
	v_mfma_f32_16x16x32_bf16 v[64:67], v[152:155], v[184:187], v[64:67]
	v_mfma_f32_16x16x32_bf16 v[116:119], v[148:151], v[164:167], v[116:119]
	v_mfma_f32_16x16x32_bf16 v[112:115], v[156:159], v[164:167], v[112:115]
	v_mfma_f32_16x16x32_bf16 v[100:103], v[148:151], v[172:175], v[100:103]
	v_mfma_f32_16x16x32_bf16 v[96:99], v[156:159], v[172:175], v[96:99]
	v_mfma_f32_16x16x32_bf16 v[84:87], v[148:151], v[180:183], v[84:87]
	v_mfma_f32_16x16x32_bf16 v[80:83], v[156:159], v[180:183], v[80:83]
	v_mfma_f32_16x16x32_bf16 v[68:71], v[148:151], v[188:191], v[68:71]
	v_mfma_f32_16x16x32_bf16 v[64:67], v[156:159], v[188:191], v[64:67]
	s_barrier
	s_add_i32 s34, s36, s5
	s_mov_b32 m0, s34
	ds_read_b128 v[160:163], v239 offset:49152
	ds_read_b128 v[164:167], v239 offset:50176
	ds_read_b128 v[168:171], v239 offset:51200
	ds_read_b128 v[172:175], v239 offset:52224
	ds_read_b128 v[176:179], v239 offset:53248
	ds_read_b128 v[180:183], v239 offset:54272
	ds_read_b128 v[184:187], v239 offset:55296
	ds_read_b128 v[188:191], v239 offset:56320
	global_load_lds_dwordx4 v196, s[98:99]
	s_add_i32 m0, s34, 0x2000
	s_add_u32 s30, s30, 0x80080
	s_addc_u32 s31, s31, 0
	s_add_i32 s34, s37, s5
	global_load_lds_dwordx4 v200, s[98:99]
	s_mov_b32 m0, s34
	s_nop 0
	global_load_lds_dwordx4 v196, s[30:31]
	s_add_i32 m0, s34, 0x2000
	s_nop 0
	global_load_lds_dwordx4 v200, s[30:31]
	s_waitcnt vmcnt(6)
	s_waitcnt lgkmcnt(0)
	s_barrier
	v_mfma_f32_16x16x32_bf16 v[60:63], v[128:131], v[160:163], v[60:63]
	v_mfma_f32_16x16x32_bf16 v[56:59], v[136:139], v[160:163], v[56:59]
	v_mfma_f32_16x16x32_bf16 v[44:47], v[128:131], v[168:171], v[44:47]
	v_mfma_f32_16x16x32_bf16 v[40:43], v[136:139], v[168:171], v[40:43]
	v_mfma_f32_16x16x32_bf16 v[28:31], v[128:131], v[176:179], v[28:31]
	v_mfma_f32_16x16x32_bf16 v[24:27], v[136:139], v[176:179], v[24:27]
	v_mfma_f32_16x16x32_bf16 v[12:15], v[128:131], v[184:187], v[12:15]
	v_mfma_f32_16x16x32_bf16 v[8:11], v[136:139], v[184:187], v[8:11]
	v_mfma_f32_16x16x32_bf16 v[60:63], v[132:135], v[164:167], v[60:63]
	v_mfma_f32_16x16x32_bf16 v[56:59], v[140:143], v[164:167], v[56:59]
	v_mfma_f32_16x16x32_bf16 v[44:47], v[132:135], v[172:175], v[44:47]
	v_mfma_f32_16x16x32_bf16 v[40:43], v[140:143], v[172:175], v[40:43]
	v_mfma_f32_16x16x32_bf16 v[28:31], v[132:135], v[180:183], v[28:31]
	v_mfma_f32_16x16x32_bf16 v[24:27], v[140:143], v[180:183], v[24:27]
	v_mfma_f32_16x16x32_bf16 v[12:15], v[132:135], v[188:191], v[12:15]
	v_mfma_f32_16x16x32_bf16 v[8:11], v[140:143], v[188:191], v[8:11]
	v_mfma_f32_16x16x32_bf16 v[52:55], v[144:147], v[160:163], v[52:55]
	v_mfma_f32_16x16x32_bf16 v[48:51], v[152:155], v[160:163], v[48:51]
	v_mfma_f32_16x16x32_bf16 v[36:39], v[144:147], v[168:171], v[36:39]
	v_mfma_f32_16x16x32_bf16 v[32:35], v[152:155], v[168:171], v[32:35]
	v_mfma_f32_16x16x32_bf16 v[20:23], v[144:147], v[176:179], v[20:23]
	v_mfma_f32_16x16x32_bf16 v[16:19], v[152:155], v[176:179], v[16:19]
	v_mfma_f32_16x16x32_bf16 v[4:7], v[144:147], v[184:187], v[4:7]
	v_mfma_f32_16x16x32_bf16 v[0:3], v[152:155], v[184:187], v[0:3]
	v_mfma_f32_16x16x32_bf16 v[52:55], v[148:151], v[164:167], v[52:55]
	v_mfma_f32_16x16x32_bf16 v[48:51], v[156:159], v[164:167], v[48:51]
	v_mfma_f32_16x16x32_bf16 v[36:39], v[148:151], v[172:175], v[36:39]
	v_mfma_f32_16x16x32_bf16 v[32:35], v[156:159], v[172:175], v[32:35]
	v_mfma_f32_16x16x32_bf16 v[20:23], v[148:151], v[180:183], v[20:23]
	v_mfma_f32_16x16x32_bf16 v[16:19], v[156:159], v[180:183], v[16:19]
	v_mfma_f32_16x16x32_bf16 v[4:7], v[148:151], v[188:191], v[4:7]
	v_mfma_f32_16x16x32_bf16 v[0:3], v[156:159], v[188:191], v[0:3]
	s_barrier
	s_add_u32 s28, s28, 0x100
	s_addc_u32 s29, s29, 0
	s_add_u32 s69, s69, 0x100
	s_addc_u32 s70, s70, 0
	s_cmp_ge_i32 s71, s48
	s_cbranch_scc1 .Lspx_2

; #define PG8_STAGE(bufoff, gbase, voff) do { _Pragma("unroll") for (int _i = 0; _i < 2; ++_i) \
;         __builtin_amdgcn_global_load_lds((const unsigned*)((const char*)(gbase) + (voff)[_i]), (LAS unsigned*)(lds + (bufoff) + ldsw + _i * 8192), 16, 0, ((voff) == voffA ? AUXA : 0)); } while (0)
; #define PG8_LDA(dst, b, h) do { _Pragma("unroll") for (int m = 0; m < 4; ++m) _Pragma("unroll") for (int k = 0; k < 2; ++k) dst[m][k] = *(const LAS bf16x8*)(lds + PG8_SA(b, h) + aoff + m * 2048 + k * 1024); } while (0)
; #define PG8_LDB(dst, b, h) do { _Pragma("unroll") for (int n = 0; n < 2; ++n) _Pragma("unroll") for (int k = 0; k < 2; ++k) dst[n][k] = *(const LAS bf16x8*)(lds + PG8_SB(b, h) + boff + n * 2048 + k * 1024); } while (0)
; #define PG8_MMA(ai, bj, At, Bt) do { __builtin_amdgcn_s_setprio(1); _Pragma("unroll") for (int m = 0; m < 4; ++m) _Pragma("unroll") for (int n = 0; n < 2; ++n) _Pragma("unroll") for (int k = 0; k < 2; ++k) \
;         acc[ai][bj][m][n] = __builtin_amdgcn_mfma_f32_16x16x32_bf16(Bt[n][k], At[m][k], acc[ai][bj][m][n], 0, 0, 0); __builtin_amdgcn_s_setprio(0); } while (0)
; #define PG8_WAIT_V(n) asm volatile("s_waitcnt vmcnt(" #n ")" ::: "memory")
; #define PG8_WAIT_L(n) asm volatile("s_waitcnt lgkmcnt(" #n ")" ::: "memory")
; #define PG8_BAR __builtin_amdgcn_s_barrier()
; #define PG8_SCHED __builtin_amdgcn_sched_barrier(0)
;     ...
;             const char* a2 = last ? nA : cA + (size_t)(t + 2) * kstep; const char* b2 = last ? nB : cB + (size_t)(t + 2) * kstep;
;             const char* a3 = a2 + kstep; const char* b3 = b2 + kstep;
;             PG8_LDB(B0, 0, 0); PG8_LDB(B1, 0, 1); PG8_SCHED; PG8_LDA(At, 0, 0); PG8_STAGE(PG8_SA(1, 1), a1 + hsA, voffA);
;             if (Epi::NPRE != 0 && last) { E.pre(sv, cur, wr, fr); PG8_WAIT_V(16); } else { PG8_WAIT_V(8); }
;             PG8_WAIT_L(0); PG8_BAR; PG8_MMA(0, 0, At, B0); PG8_MMA(0, 1, At, B1); PG8_BAR; PG8_SCHED;
;             PG8_LDA(At, 0, 1); PG8_STAGE(PG8_SB(0, 0), b2, voffB); PG8_STAGE(PG8_SB(0, 1), b2 + hsB, voffB); PG8_STAGE(PG8_SA(0, 0), a2, voffA);
;             if (Epi::NPRE != 0 && last) { PG8_WAIT_V(16); } else { PG8_WAIT_V(8); }
.LBB0_375:
	s_add_u32 s34, s28, 0xfff80080
	s_addc_u32 s35, s29, -1
	s_waitcnt lgkmcnt(0)
	s_and_b64 s[30:31], s[30:31], exec
	s_cselect_b32 s35, s7, s35
	s_cselect_b32 s34, s21, s34
	s_cselect_b32 s31, s23, s70
	s_cselect_b32 s30, s68, s69
	s_barrier
	v_mfma_f32_16x16x32_bf16 v[124:127], v[144:147], v[184:187], v[124:127]
	v_mfma_f32_16x16x32_bf16 v[120:123], v[152:155], v[184:187], v[120:123]
	v_mfma_f32_16x16x32_bf16 v[108:111], v[144:147], v[176:179], v[108:111]
	v_mfma_f32_16x16x32_bf16 v[104:107], v[152:155], v[176:179], v[104:107]
	v_mfma_f32_16x16x32_bf16 v[92:95], v[144:147], v[168:171], v[92:95]
	v_mfma_f32_16x16x32_bf16 v[88:91], v[152:155], v[168:171], v[88:91]
	v_mfma_f32_16x16x32_bf16 v[76:79], v[144:147], v[160:163], v[76:79]
	v_mfma_f32_16x16x32_bf16 v[72:75], v[152:155], v[160:163], v[72:75]
	v_mfma_f32_16x16x32_bf16 v[124:127], v[148:151], v[188:191], v[124:127]
	v_mfma_f32_16x16x32_bf16 v[120:123], v[156:159], v[188:191], v[120:123]
	v_mfma_f32_16x16x32_bf16 v[108:111], v[148:151], v[180:183], v[108:111]
	v_mfma_f32_16x16x32_bf16 v[104:107], v[156:159], v[180:183], v[104:107]
	v_mfma_f32_16x16x32_bf16 v[92:95], v[148:151], v[172:175], v[92:95]
	v_mfma_f32_16x16x32_bf16 v[88:91], v[156:159], v[172:175], v[88:91]
	v_mfma_f32_16x16x32_bf16 v[76:79], v[148:151], v[164:167], v[76:79]
	v_mfma_f32_16x16x32_bf16 v[72:75], v[156:159], v[164:167], v[72:75]
	v_mfma_f32_16x16x32_bf16 v[116:119], v[128:131], v[184:187], v[116:119]
	v_mfma_f32_16x16x32_bf16 v[112:115], v[136:139], v[184:187], v[112:115]
	v_mfma_f32_16x16x32_bf16 v[100:103], v[128:131], v[176:179], v[100:103]
	v_mfma_f32_16x16x32_bf16 v[96:99], v[136:139], v[176:179], v[96:99]
	v_mfma_f32_16x16x32_bf16 v[84:87], v[128:131], v[168:171], v[84:87]
	v_mfma_f32_16x16x32_bf16 v[80:83], v[136:139], v[168:171], v[80:83]
	v_mfma_f32_16x16x32_bf16 v[68:71], v[128:131], v[160:163], v[68:71]
	v_mfma_f32_16x16x32_bf16 v[64:67], v[136:139], v[160:163], v[64:67]
	v_mfma_f32_16x16x32_bf16 v[116:119], v[132:135], v[188:191], v[116:119]
	v_mfma_f32_16x16x32_bf16 v[112:115], v[140:143], v[188:191], v[112:115]
	v_mfma_f32_16x16x32_bf16 v[100:103], v[132:135], v[180:183], v[100:103]
	v_mfma_f32_16x16x32_bf16 v[96:99], v[140:143], v[180:183], v[96:99]
	v_mfma_f32_16x16x32_bf16 v[84:87], v[132:135], v[172:175], v[84:87]
	v_mfma_f32_16x16x32_bf16 v[80:83], v[140:143], v[172:175], v[80:83]
	v_mfma_f32_16x16x32_bf16 v[68:71], v[132:135], v[164:167], v[68:71]
	v_mfma_f32_16x16x32_bf16 v[64:67], v[140:143], v[164:167], v[64:67]
	s_barrier
	s_add_u32 s98, s30, s10
	s_addc_u32 s99, s31, s11
	s_add_u32 s100, s34, s10
	s_addc_u32 s101, s35, s11
	s_mov_b32 m0, s40
	s_add_u32 s38, s30, 0x80000
	ds_read_b128 v[184:187], v239 offset:16384
	ds_read_b128 v[188:191], v239 offset:17408
	ds_read_b128 v[176:179], v239 offset:18432
	ds_read_b128 v[180:183], v239 offset:19456
	ds_read_b128 v[168:171], v239 offset:20480
	ds_read_b128 v[172:175], v239 offset:21504
	ds_read_b128 v[160:163], v239 offset:22528
	ds_read_b128 v[164:167], v239 offset:23552
	global_load_lds_dwordx4 v196, s[30:31]
	s_mov_b32 m0, s41
	s_addc_u32 s39, s31, 0
	global_load_lds_dwordx4 v200, s[30:31]
	s_mov_b32 m0, s42
	s_nop 0
	global_load_lds_dwordx4 v196, s[38:39]
	s_mov_b32 m0, s43
	s_nop 0
	global_load_lds_dwordx4 v200, s[38:39]
	s_mov_b64 s[38:39], -1
	s_and_b64 vcc, exec, s[36:37]
	s_cbranch_vccz .LBB0_377
	s_waitcnt vmcnt(6)
	s_mov_b64 s[38:39], 0

;     __device__ bool next(int i, Unit& u) const { const int L = i * G + c; if (L >= 384) return false; u.pm = L; u.pn = L / 6; return true; }
;     ...
;         const bool has_next = S.next(ui + 1, nxt);
;         const char* nA = has_next ? (const char*)g.A + (size_t)nxt.pm * tsA : cA; const char* nB = has_next ? (const char*)g.Bt + (size_t)nxt.pn * tsB : cB;
;         for (int t = 0; t < nt; t += 2) {
;             const bool last = (t == nt - 2);
;             const char* a1 = cA + (size_t)(t + 1) * kstep;
;             const char* a2 = last ? nA : cA + (size_t)(t + 2) * kstep; const char* b2 = last ? nB : cB + (size_t)(t + 2) * kstep;
;             const char* a3 = a2 + kstep; const char* b3 = b2 + kstep;
;             PG8_LDB(B0, 0, 0); PG8_LDB(B1, 0, 1); PG8_SCHED; PG8_LDA(At, 0, 0); PG8_STAGE(PG8_SA(1, 1), a1 + hsA, voffA);
;             if (Epi::NPRE != 0 && last) { E.pre(sv, cur, wr, fr); PG8_WAIT_V(16); } else { PG8_WAIT_V(8); }
;             PG8_WAIT_L(0); PG8_BAR; PG8_MMA(0, 0, At, B0); PG8_MMA(0, 1, At, B1); PG8_BAR; PG8_SCHED;
;             PG8_LDA(At, 0, 1); PG8_STAGE(PG8_SB(0, 0), b2, voffB); PG8_STAGE(PG8_SB(0, 1), b2 + hsB, voffB); PG8_STAGE(PG8_SA(0, 0), a2, voffA);
;             if (Epi::NPRE != 0 && last) { PG8_WAIT_V(16); } else { PG8_WAIT_V(8); }
;             PG8_WAIT_L(0); PG8_BAR; PG8_MMA(1, 0, At, B0); PG8_MMA(1, 1, At, B1); PG8_BAR; PG8_SCHED;
;             PG8_LDB(B0, 1, 0); PG8_LDB(B1, 1, 1); PG8_SCHED; PG8_LDA(At, 1, 0); PG8_STAGE(PG8_SA(0, 1), a2 + hsA, voffA);
;             PG8_WAIT_V(8); PG8_WAIT_L(0); PG8_BAR; PG8_MMA(0, 0, At, B0); PG8_MMA(0, 1, At, B1); PG8_BAR; PG8_SCHED;
;             PG8_LDA(At, 1, 1); PG8_STAGE(PG8_SB(1, 0), b3, voffB); PG8_STAGE(PG8_SB(1, 1), b3 + hsB, voffB); PG8_STAGE(PG8_SA(1, 0), a3, voffA);
;             PG8_WAIT_V(8); PG8_WAIT_L(0); PG8_BAR; PG8_MMA(1, 0, At, B0); PG8_MMA(1, 1, At, B1); PG8_BAR; PG8_SCHED;
;         }
;         if constexpr (ALIGN_EPI) { if (wr == 0) PG8_BAR; }
;         E(acc, cur, wr, wc, fr, fq, sv);
;         if (!has_next) break;
; #pragma unroll
;         for (int a = 0; a < 2; ++a)
; #pragma unroll
;             for (int b = 0; b < 2; ++b)
; #pragma unroll
;                 for (int m = 0; m < 4; ++m)
; #pragma unroll
;                     for (int n = 0; n < 2; ++n) acc[a][b][m][n] = (f32x4){0.f, 0.f, 0.f, 0.f};
;         cur = nxt; cA = nA; cB = nB; ++ui;
.LBB0_646:
	s_add_i32 s34, s34, 1
	s_mul_i32 s16, s34, s33
	s_mov_b32 s19, s47
	s_add_i32 s47, s16, s2
	s_mul_hi_i32 s16, s47, 0x2aaaaaab
	s_lshr_b32 s17, s16, 31
	s_mov_b32 s18, s48
	s_add_i32 s48, s16, s17
	s_cmpk_lt_i32 s47, 0x180
	s_cselect_b64 s[20:21], -1, 0
	s_and_b64 s[16:17], s[20:21], exec
	s_cselect_b32 s16, s47, s19
	s_cselect_b32 s18, s48, s18
	s_ashr_i32 s17, s16, 31
	s_lshl_b64 s[16:17], s[16:17], 18
	s_add_u32 s16, s8, s16
	s_addc_u32 s17, s9, s17
	s_ashr_i32 s19, s18, 31
	s_lshl_b64 s[18:19], s[18:19], 17
	s_add_u32 s18, s4, s18
	v_mov_b32_e32 v127, 0
	s_addc_u32 s19, s5, s19
	s_and_b64 vcc, exec, s[0:1]
	v_mov_b32_e32 v126, 0
	v_mov_b64_e32 v[124:125], 0
	v_mov_b64_e32 v[122:123], 0
	v_mov_b64_e32 v[120:121], 0
	v_mov_b64_e32 v[110:111], 0
	v_mov_b64_e32 v[108:109], 0
	v_mov_b64_e32 v[106:107], 0
	v_mov_b64_e32 v[104:105], 0
	v_mov_b64_e32 v[94:95], 0
	v_mov_b64_e32 v[92:93], 0
	v_mov_b64_e32 v[90:91], 0
	v_mov_b64_e32 v[88:89], 0
	v_mov_b64_e32 v[78:79], 0
	v_mov_b64_e32 v[76:77], 0
	v_mov_b64_e32 v[74:75], 0
	v_mov_b64_e32 v[72:73], 0
	v_mov_b64_e32 v[118:119], 0
	v_mov_b64_e32 v[116:117], 0
	v_mov_b64_e32 v[114:115], 0
	v_mov_b64_e32 v[112:113], 0
	v_mov_b64_e32 v[102:103], 0
	v_mov_b64_e32 v[100:101], 0
	v_mov_b64_e32 v[98:99], 0
	v_mov_b64_e32 v[96:97], 0
	v_mov_b64_e32 v[86:87], 0
	v_mov_b64_e32 v[84:85], 0
	v_mov_b64_e32 v[82:83], 0
	v_mov_b64_e32 v[80:81], 0
	v_mov_b64_e32 v[70:71], 0
	v_mov_b64_e32 v[68:69], 0
	v_mov_b64_e32 v[66:67], 0
	v_mov_b64_e32 v[64:65], 0
	v_mov_b64_e32 v[62:63], 0
	v_mov_b64_e32 v[60:61], 0
	v_mov_b64_e32 v[58:59], 0
	v_mov_b64_e32 v[56:57], 0
	v_mov_b64_e32 v[46:47], 0
	v_mov_b64_e32 v[44:45], 0
	v_mov_b64_e32 v[42:43], 0
	v_mov_b64_e32 v[40:41], 0
	v_mov_b64_e32 v[30:31], 0
	v_mov_b64_e32 v[28:29], 0
	v_mov_b64_e32 v[26:27], 0
	v_mov_b64_e32 v[24:25], 0
	v_mov_b64_e32 v[14:15], 0
	v_mov_b64_e32 v[12:13], 0
	v_mov_b64_e32 v[10:11], 0
	v_mov_b64_e32 v[8:9], 0
	v_mov_b64_e32 v[54:55], 0
	v_mov_b64_e32 v[52:53], 0
	v_mov_b64_e32 v[50:51], 0
	v_mov_b64_e32 v[48:49], 0
	v_mov_b64_e32 v[38:39], 0
	v_mov_b64_e32 v[36:37], 0
	v_mov_b64_e32 v[34:35], 0
	v_mov_b64_e32 v[32:33], 0
	v_mov_b64_e32 v[22:23], 0
	v_mov_b64_e32 v[20:21], 0
	v_mov_b64_e32 v[18:19], 0
	v_mov_b64_e32 v[16:17], 0
	v_mov_b64_e32 v[6:7], 0
	v_mov_b64_e32 v[4:5], 0
	v_mov_b64_e32 v[2:3], 0
	v_mov_b64_e32 v[0:1], 0
	s_cbranch_vccnz .LBB0_649
	s_and_b64 s[26:27], s[20:21], exec
	s_cselect_b32 s50, s17, s23
	s_cselect_b32 s51, s16, s22
	s_cselect_b32 s52, s19, s25
	s_cselect_b32 s53, s18, s24
	s_add_u32 s22, s22, 0x20080
	s_addc_u32 s23, s23, 0
	s_add_u32 s54, s24, 0x100
	v_mov_b32_e32 v0, 0
	s_addc_u32 s55, s25, 0
	s_mov_b32 s24, 0
	v_mov_b32_e32 v1, 0
	v_mov_b64_e32 v[2:3], 0
	v_mov_b64_e32 v[4:5], 0
	v_mov_b64_e32 v[6:7], 0
	v_mov_b64_e32 v[16:17], 0
	v_mov_b64_e32 v[18:19], 0
	v_mov_b64_e32 v[20:21], 0
	v_mov_b64_e32 v[22:23], 0
	v_mov_b64_e32 v[32:33], 0
	v_mov_b64_e32 v[34:35], 0
	v_mov_b64_e32 v[36:37], 0
	v_mov_b64_e32 v[38:39], 0
	v_mov_b64_e32 v[48:49], 0
	v_mov_b64_e32 v[50:51], 0
	v_mov_b64_e32 v[52:53], 0
	v_mov_b64_e32 v[54:55], 0
	v_mov_b64_e32 v[8:9], 0
	v_mov_b64_e32 v[10:11], 0
	v_mov_b64_e32 v[12:13], 0
	v_mov_b64_e32 v[14:15], 0
	v_mov_b64_e32 v[24:25], 0
	v_mov_b64_e32 v[26:27], 0
	v_mov_b64_e32 v[28:29], 0
	v_mov_b64_e32 v[30:31], 0
	v_mov_b64_e32 v[40:41], 0
	v_mov_b64_e32 v[42:43], 0
	v_mov_b64_e32 v[44:45], 0
	v_mov_b64_e32 v[46:47], 0
	v_mov_b64_e32 v[56:57], 0
	v_mov_b64_e32 v[58:59], 0
	v_mov_b64_e32 v[60:61], 0
	v_mov_b64_e32 v[62:63], 0
	v_mov_b64_e32 v[64:65], 0
	v_mov_b64_e32 v[66:67], 0
	v_mov_b64_e32 v[68:69], 0
	v_mov_b64_e32 v[70:71], 0
	v_mov_b64_e32 v[80:81], 0
	v_mov_b64_e32 v[82:83], 0
	v_mov_b64_e32 v[84:85], 0
	v_mov_b64_e32 v[86:87], 0
	v_mov_b64_e32 v[96:97], 0
	v_mov_b64_e32 v[98:99], 0
	v_mov_b64_e32 v[100:101], 0
	v_mov_b64_e32 v[102:103], 0
	v_mov_b64_e32 v[112:113], 0
	v_mov_b64_e32 v[114:115], 0
	v_mov_b64_e32 v[116:117], 0
	v_mov_b64_e32 v[118:119], 0
	v_mov_b64_e32 v[72:73], 0
	v_mov_b64_e32 v[74:75], 0
	v_mov_b64_e32 v[76:77], 0
	v_mov_b64_e32 v[78:79], 0
	v_mov_b64_e32 v[88:89], 0
	v_mov_b64_e32 v[90:91], 0
	v_mov_b64_e32 v[92:93], 0
	v_mov_b64_e32 v[94:95], 0
	v_mov_b64_e32 v[104:105], 0
	v_mov_b64_e32 v[106:107], 0
	v_mov_b64_e32 v[108:109], 0
	v_mov_b64_e32 v[110:111], 0
	v_mov_b64_e32 v[120:121], 0
	v_mov_b64_e32 v[122:123], 0
	v_mov_b64_e32 v[124:125], 0
	v_mov_b64_e32 v[126:127], 0
	v_readfirstlane_b32 s99, v234
	s_nop 0
	s_lshr_b32 s99, s99, 8
	s_cmp_eq_u32 s99, 0
	s_cbranch_scc1 .Lsp_3
	s_setprio 1
; #define PG8_STAGE(bufoff, gbase, voff) do { _Pragma("unroll") for (int _i = 0; _i < 2; ++_i) \
;         __builtin_amdgcn_global_load_lds((const unsigned*)((const char*)(gbase) + (voff)[_i]), (LAS unsigned*)(lds + (bufoff) + ldsw + _i * 8192), 16, 0, ((voff) == voffA ? AUXA : 0)); } while (0)
; #define PG8_LDA(dst, b, h) do { _Pragma("unroll") for (int m = 0; m < 4; ++m) _Pragma("unroll") for (int k = 0; k < 2; ++k) dst[m][k] = *(const LAS bf16x8*)(lds + PG8_SA(b, h) + aoff + m * 2048 + k * 1024); } while (0)
; #define PG8_LDB(dst, b, h) do { _Pragma("unroll") for (int n = 0; n < 2; ++n) _Pragma("unroll") for (int k = 0; k < 2; ++k) dst[n][k] = *(const LAS bf16x8*)(lds + PG8_SB(b, h) + boff + n * 2048 + k * 1024); } while (0)
; #define PG8_MMA(ai, bj, At, Bt) do { __builtin_amdgcn_s_setprio(1); _Pragma("unroll") for (int m = 0; m < 4; ++m) _Pragma("unroll") for (int n = 0; n < 2; ++n) _Pragma("unroll") for (int k = 0; k < 2; ++k) \
;         acc[ai][bj][m][n] = __builtin_amdgcn_mfma_f32_16x16x32_bf16(Bt[n][k], At[m][k], acc[ai][bj][m][n], 0, 0, 0); __builtin_amdgcn_s_setprio(0); } while (0)
; #define PG8_WAIT_V(n) asm volatile("s_waitcnt vmcnt(" #n ")" ::: "memory")
; #define PG8_WAIT_L(n) asm volatile("s_waitcnt lgkmcnt(" #n ")" ::: "memory")
; #define PG8_BAR __builtin_amdgcn_s_barrier()
; #define PG8_SCHED __builtin_amdgcn_sched_barrier(0)
;     ...
;         for (int t = 0; t < nt; t += 2) {
;             const bool last = (t == nt - 2);
;             const char* a1 = cA + (size_t)(t + 1) * kstep;
;             const char* a2 = last ? nA : cA + (size_t)(t + 2) * kstep; const char* b2 = last ? nB : cB + (size_t)(t + 2) * kstep;
;             const char* a3 = a2 + kstep; const char* b3 = b2 + kstep;
;             PG8_LDB(B0, 0, 0); PG8_LDB(B1, 0, 1); PG8_SCHED; PG8_LDA(At, 0, 0); PG8_STAGE(PG8_SA(1, 1), a1 + hsA, voffA);
;             if (Epi::NPRE != 0 && last) { E.pre(sv, cur, wr, fr); PG8_WAIT_V(16); } else { PG8_WAIT_V(8); }
;             PG8_WAIT_L(0); PG8_BAR; PG8_MMA(0, 0, At, B0); PG8_MMA(0, 1, At, B1); PG8_BAR; PG8_SCHED;
;             PG8_LDA(At, 0, 1); PG8_STAGE(PG8_SB(0, 0), b2, voffB); PG8_STAGE(PG8_SB(0, 1), b2 + hsB, voffB); PG8_STAGE(PG8_SA(0, 0), a2, voffA);
;             if (Epi::NPRE != 0 && last) { PG8_WAIT_V(16); } else { PG8_WAIT_V(8); }
;             PG8_WAIT_L(0); PG8_BAR; PG8_MMA(1, 0, At, B0); PG8_MMA(1, 1, At, B1); PG8_BAR; PG8_SCHED;
.Lsp_3:
.LBB0_648:
	s_add_u32 s98, s22, 0xfffe0000
	s_addc_u32 s99, s23, -1
	s_mov_b32 m0, s36
	s_nop 0
	global_load_lds_dwordx4 v134, s[98:99]
	s_mov_b32 m0, s37
	s_nop 0
	global_load_lds_dwordx4 v130, s[98:99]
	ds_read_b128 v[148:151], v143
	ds_read_b128 v[152:155], v143 offset:1024
	ds_read_b128 v[156:159], v143 offset:2048
	ds_read_b128 v[160:163], v143 offset:3072
	ds_read_b128 v[164:167], v144
	ds_read_b128 v[168:171], v144 offset:1024
	ds_read_b128 v[172:175], v144 offset:2048
	ds_read_b128 v[176:179], v144 offset:3072
	s_add_i32 s56, s24, 2
	s_add_u32 s25, s22, 0xfffe0080
	s_addc_u32 s26, s23, -1
	s_cmp_eq_u32 s38, s24
	s_cselect_b32 s24, s53, s54
	s_cselect_b32 s27, s50, s26
	s_cselect_b32 s26, s51, s25
	s_cselect_b32 s25, s52, s55
	s_mov_b32 m0, s39
	ds_read_b128 v[180:183], v145
	ds_read_b128 v[184:187], v145 offset:1024
	ds_read_b128 v[188:191], v145 offset:2048
	ds_read_b128 v[194:197], v145 offset:3072
	ds_read_b128 v[198:201], v145 offset:4096
	ds_read_b128 v[202:205], v145 offset:5120
	ds_read_b128 v[206:209], v145 offset:6144
	ds_read_b128 v[210:213], v145 offset:7168
	global_load_lds_dwordx4 v138, s[22:23]
	s_mov_b32 m0, s40
	s_nop 0
	global_load_lds_dwordx4 v140, s[22:23]
	s_waitcnt vmcnt(8)
	s_waitcnt lgkmcnt(0)
	s_barrier
	v_mfma_f32_16x16x32_bf16 v[124:127], v[148:151], v[180:183], v[124:127]
	v_mfma_f32_16x16x32_bf16 v[120:123], v[156:159], v[180:183], v[120:123]
	v_mfma_f32_16x16x32_bf16 v[108:111], v[148:151], v[188:191], v[108:111]
	v_mfma_f32_16x16x32_bf16 v[104:107], v[156:159], v[188:191], v[104:107]
	v_mfma_f32_16x16x32_bf16 v[92:95], v[148:151], v[198:201], v[92:95]
	v_mfma_f32_16x16x32_bf16 v[88:91], v[156:159], v[198:201], v[88:91]
	v_mfma_f32_16x16x32_bf16 v[76:79], v[148:151], v[206:209], v[76:79]
	v_mfma_f32_16x16x32_bf16 v[72:75], v[156:159], v[206:209], v[72:75]
	v_mfma_f32_16x16x32_bf16 v[124:127], v[152:155], v[184:187], v[124:127]
	v_mfma_f32_16x16x32_bf16 v[120:123], v[160:163], v[184:187], v[120:123]
	v_mfma_f32_16x16x32_bf16 v[108:111], v[152:155], v[194:197], v[108:111]
	v_mfma_f32_16x16x32_bf16 v[104:107], v[160:163], v[194:197], v[104:107]
	v_mfma_f32_16x16x32_bf16 v[92:95], v[152:155], v[202:205], v[92:95]
	v_mfma_f32_16x16x32_bf16 v[88:91], v[160:163], v[202:205], v[88:91]
	v_mfma_f32_16x16x32_bf16 v[76:79], v[152:155], v[210:213], v[76:79]
	v_mfma_f32_16x16x32_bf16 v[72:75], v[160:163], v[210:213], v[72:75]
	v_mfma_f32_16x16x32_bf16 v[116:119], v[164:167], v[180:183], v[116:119]
	v_mfma_f32_16x16x32_bf16 v[112:115], v[172:175], v[180:183], v[112:115]
	v_mfma_f32_16x16x32_bf16 v[100:103], v[164:167], v[188:191], v[100:103]
	v_mfma_f32_16x16x32_bf16 v[96:99], v[172:175], v[188:191], v[96:99]
	v_mfma_f32_16x16x32_bf16 v[84:87], v[164:167], v[198:201], v[84:87]
	v_mfma_f32_16x16x32_bf16 v[80:83], v[172:175], v[198:201], v[80:83]
	v_mfma_f32_16x16x32_bf16 v[68:71], v[164:167], v[206:209], v[68:71]
	v_mfma_f32_16x16x32_bf16 v[64:67], v[172:175], v[206:209], v[64:67]
	v_mfma_f32_16x16x32_bf16 v[116:119], v[168:171], v[184:187], v[116:119]
	v_mfma_f32_16x16x32_bf16 v[112:115], v[176:179], v[184:187], v[112:115]
	v_mfma_f32_16x16x32_bf16 v[100:103], v[168:171], v[194:197], v[100:103]
	v_mfma_f32_16x16x32_bf16 v[96:99], v[176:179], v[194:197], v[96:99]
	v_mfma_f32_16x16x32_bf16 v[84:87], v[168:171], v[202:205], v[84:87]
	v_mfma_f32_16x16x32_bf16 v[80:83], v[176:179], v[202:205], v[80:83]
	v_mfma_f32_16x16x32_bf16 v[68:71], v[168:171], v[210:213], v[68:71]
	v_mfma_f32_16x16x32_bf16 v[64:67], v[176:179], v[210:213], v[64:67]
	s_barrier
	s_add_u32 s98, s24, s12
	s_addc_u32 s99, s25, s13
	s_add_u32 s100, s26, s12
	s_addc_u32 s101, s27, s13
	s_mov_b32 m0, s41
	s_add_u32 s66, s24, 0x10000
	ds_read_b128 v[180:183], v145 offset:16384
	ds_read_b128 v[184:187], v145 offset:17408
	ds_read_b128 v[188:191], v145 offset:18432
	ds_read_b128 v[194:197], v145 offset:19456
	ds_read_b128 v[198:201], v145 offset:20480
	ds_read_b128 v[202:205], v145 offset:21504
	ds_read_b128 v[206:209], v145 offset:22528
	ds_read_b128 v[210:213], v145 offset:23552
	global_load_lds_dwordx4 v132, s[24:25]
	s_mov_b32 m0, s42
	s_addc_u32 s67, s25, 0
	global_load_lds_dwordx4 v128, s[24:25]
	s_mov_b32 m0, s43
	s_nop 0
	global_load_lds_dwordx4 v132, s[66:67]
	s_mov_b32 m0, s44
	s_nop 0
	global_load_lds_dwordx4 v128, s[66:67]
	s_waitcnt vmcnt(6)
	s_waitcnt lgkmcnt(0)
	s_barrier
	v_mfma_f32_16x16x32_bf16 v[60:63], v[148:151], v[180:183], v[60:63]
	v_mfma_f32_16x16x32_bf16 v[56:59], v[156:159], v[180:183], v[56:59]
	v_mfma_f32_16x16x32_bf16 v[44:47], v[148:151], v[188:191], v[44:47]
	v_mfma_f32_16x16x32_bf16 v[40:43], v[156:159], v[188:191], v[40:43]
	v_mfma_f32_16x16x32_bf16 v[28:31], v[148:151], v[198:201], v[28:31]
	v_mfma_f32_16x16x32_bf16 v[24:27], v[156:159], v[198:201], v[24:27]
	v_mfma_f32_16x16x32_bf16 v[12:15], v[148:151], v[206:209], v[12:15]
	v_mfma_f32_16x16x32_bf16 v[8:11], v[156:159], v[206:209], v[8:11]
	v_mfma_f32_16x16x32_bf16 v[60:63], v[152:155], v[184:187], v[60:63]
	v_mfma_f32_16x16x32_bf16 v[56:59], v[160:163], v[184:187], v[56:59]
	v_mfma_f32_16x16x32_bf16 v[44:47], v[152:155], v[194:197], v[44:47]
	v_mfma_f32_16x16x32_bf16 v[40:43], v[160:163], v[194:197], v[40:43]
	v_mfma_f32_16x16x32_bf16 v[28:31], v[152:155], v[202:205], v[28:31]
	v_mfma_f32_16x16x32_bf16 v[24:27], v[160:163], v[202:205], v[24:27]
	v_mfma_f32_16x16x32_bf16 v[12:15], v[152:155], v[210:213], v[12:15]
	v_mfma_f32_16x16x32_bf16 v[8:11], v[160:163], v[210:213], v[8:11]
	v_mfma_f32_16x16x32_bf16 v[52:55], v[164:167], v[180:183], v[52:55]
	v_mfma_f32_16x16x32_bf16 v[48:51], v[172:175], v[180:183], v[48:51]
	v_mfma_f32_16x16x32_bf16 v[36:39], v[164:167], v[188:191], v[36:39]
	v_mfma_f32_16x16x32_bf16 v[32:35], v[172:175], v[188:191], v[32:35]
	v_mfma_f32_16x16x32_bf16 v[20:23], v[164:167], v[198:201], v[20:23]
	v_mfma_f32_16x16x32_bf16 v[16:19], v[172:175], v[198:201], v[16:19]
	v_mfma_f32_16x16x32_bf16 v[4:7], v[164:167], v[206:209], v[4:7]
	v_mfma_f32_16x16x32_bf16 v[0:3], v[172:175], v[206:209], v[0:3]
	v_mfma_f32_16x16x32_bf16 v[52:55], v[168:171], v[184:187], v[52:55]
	v_mfma_f32_16x16x32_bf16 v[48:51], v[176:179], v[184:187], v[48:51]
	v_mfma_f32_16x16x32_bf16 v[36:39], v[168:171], v[194:197], v[36:39]
	v_mfma_f32_16x16x32_bf16 v[32:35], v[176:179], v[194:197], v[32:35]
	v_mfma_f32_16x16x32_bf16 v[20:23], v[168:171], v[202:205], v[20:23]
	v_mfma_f32_16x16x32_bf16 v[16:19], v[176:179], v[202:205], v[16:19]
	v_mfma_f32_16x16x32_bf16 v[4:7], v[168:171], v[210:213], v[4:7]
	v_mfma_f32_16x16x32_bf16 v[0:3], v[176:179], v[210:213], v[0:3]
	s_barrier
; #define PG8_STAGE(bufoff, gbase, voff) do { _Pragma("unroll") for (int _i = 0; _i < 2; ++_i) \
;         __builtin_amdgcn_global_load_lds((const unsigned*)((const char*)(gbase) + (voff)[_i]), (LAS unsigned*)(lds + (bufoff) + ldsw + _i * 8192), 16, 0, ((voff) == voffA ? AUXA : 0)); } while (0)
; #define PG8_LDA(dst, b, h) do { _Pragma("unroll") for (int m = 0; m < 4; ++m) _Pragma("unroll") for (int k = 0; k < 2; ++k) dst[m][k] = *(const LAS bf16x8*)(lds + PG8_SA(b, h) + aoff + m * 2048 + k * 1024); } while (0)
; #define PG8_LDB(dst, b, h) do { _Pragma("unroll") for (int n = 0; n < 2; ++n) _Pragma("unroll") for (int k = 0; k < 2; ++k) dst[n][k] = *(const LAS bf16x8*)(lds + PG8_SB(b, h) + boff + n * 2048 + k * 1024); } while (0)
; #define PG8_MMA(ai, bj, At, Bt) do { __builtin_amdgcn_s_setprio(1); _Pragma("unroll") for (int m = 0; m < 4; ++m) _Pragma("unroll") for (int n = 0; n < 2; ++n) _Pragma("unroll") for (int k = 0; k < 2; ++k) \
;         acc[ai][bj][m][n] = __builtin_amdgcn_mfma_f32_16x16x32_bf16(Bt[n][k], At[m][k], acc[ai][bj][m][n], 0, 0, 0); __builtin_amdgcn_s_setprio(0); } while (0)
; #define PG8_WAIT_V(n) asm volatile("s_waitcnt vmcnt(" #n ")" ::: "memory")
; #define PG8_WAIT_L(n) asm volatile("s_waitcnt lgkmcnt(" #n ")" ::: "memory")
; #define PG8_BAR __builtin_amdgcn_s_barrier()
; #define PG8_SCHED __builtin_amdgcn_sched_barrier(0)
;     ...
;             PG8_LDB(B0, 1, 0); PG8_LDB(B1, 1, 1); PG8_SCHED; PG8_LDA(At, 1, 0); PG8_STAGE(PG8_SA(0, 1), a2 + hsA, voffA);
;             PG8_WAIT_V(8); PG8_WAIT_L(0); PG8_BAR; PG8_MMA(0, 0, At, B0); PG8_MMA(0, 1, At, B1); PG8_BAR; PG8_SCHED;
;             PG8_LDA(At, 1, 1); PG8_STAGE(PG8_SB(1, 0), b3, voffB); PG8_STAGE(PG8_SB(1, 1), b3 + hsB, voffB); PG8_STAGE(PG8_SA(1, 0), a3, voffA);
;             PG8_WAIT_V(8); PG8_WAIT_L(0); PG8_BAR; PG8_MMA(1, 0, At, B0); PG8_MMA(1, 1, At, B1); PG8_BAR; PG8_SCHED;
;         }
	s_mov_b32 m0, s3
	s_nop 0
	global_load_lds_dwordx4 v134, s[26:27]
	s_mov_b32 m0, s29
	s_nop 0
	global_load_lds_dwordx4 v130, s[26:27]
	ds_read_b128 v[148:151], v146
	ds_read_b128 v[152:155], v146 offset:1024
	ds_read_b128 v[156:159], v146 offset:2048
	ds_read_b128 v[160:163], v146 offset:3072
	ds_read_b128 v[164:167], v147
	ds_read_b128 v[168:171], v147 offset:1024
	ds_read_b128 v[172:175], v147 offset:2048
	ds_read_b128 v[176:179], v147 offset:3072
	s_add_u32 s26, s26, 0x20000
	s_addc_u32 s27, s27, 0
	s_mov_b32 m0, s30
	ds_read_b128 v[180:183], v145 offset:32768
	ds_read_b128 v[184:187], v145 offset:33792
	ds_read_b128 v[188:191], v145 offset:34816
	ds_read_b128 v[194:197], v145 offset:35840
	ds_read_b128 v[198:201], v145 offset:36864
	ds_read_b128 v[202:205], v145 offset:37888
	ds_read_b128 v[206:209], v145 offset:38912
	ds_read_b128 v[210:213], v145 offset:39936
	global_load_lds_dwordx4 v134, s[26:27]
	s_mov_b32 m0, s31
	s_nop 0
	global_load_lds_dwordx4 v130, s[26:27]
	s_waitcnt vmcnt(8)
	s_waitcnt lgkmcnt(0)
	s_barrier
	v_mfma_f32_16x16x32_bf16 v[124:127], v[148:151], v[180:183], v[124:127]
	v_mfma_f32_16x16x32_bf16 v[120:123], v[156:159], v[180:183], v[120:123]
	v_mfma_f32_16x16x32_bf16 v[108:111], v[148:151], v[188:191], v[108:111]
	v_mfma_f32_16x16x32_bf16 v[104:107], v[156:159], v[188:191], v[104:107]
	v_mfma_f32_16x16x32_bf16 v[92:95], v[148:151], v[198:201], v[92:95]
	v_mfma_f32_16x16x32_bf16 v[88:91], v[156:159], v[198:201], v[88:91]
	v_mfma_f32_16x16x32_bf16 v[76:79], v[148:151], v[206:209], v[76:79]
	v_mfma_f32_16x16x32_bf16 v[72:75], v[156:159], v[206:209], v[72:75]
	v_mfma_f32_16x16x32_bf16 v[124:127], v[152:155], v[184:187], v[124:127]
	v_mfma_f32_16x16x32_bf16 v[120:123], v[160:163], v[184:187], v[120:123]
	v_mfma_f32_16x16x32_bf16 v[108:111], v[152:155], v[194:197], v[108:111]
	v_mfma_f32_16x16x32_bf16 v[104:107], v[160:163], v[194:197], v[104:107]
	v_mfma_f32_16x16x32_bf16 v[92:95], v[152:155], v[202:205], v[92:95]
	v_mfma_f32_16x16x32_bf16 v[88:91], v[160:163], v[202:205], v[88:91]
	v_mfma_f32_16x16x32_bf16 v[76:79], v[152:155], v[210:213], v[76:79]
	v_mfma_f32_16x16x32_bf16 v[72:75], v[160:163], v[210:213], v[72:75]
	v_mfma_f32_16x16x32_bf16 v[116:119], v[164:167], v[180:183], v[116:119]
	v_mfma_f32_16x16x32_bf16 v[112:115], v[172:175], v[180:183], v[112:115]
	v_mfma_f32_16x16x32_bf16 v[100:103], v[164:167], v[188:191], v[100:103]
	v_mfma_f32_16x16x32_bf16 v[96:99], v[172:175], v[188:191], v[96:99]
	v_mfma_f32_16x16x32_bf16 v[84:87], v[164:167], v[198:201], v[84:87]
	v_mfma_f32_16x16x32_bf16 v[80:83], v[172:175], v[198:201], v[80:83]
	v_mfma_f32_16x16x32_bf16 v[68:71], v[164:167], v[206:209], v[68:71]
	v_mfma_f32_16x16x32_bf16 v[64:67], v[172:175], v[206:209], v[64:67]
	v_mfma_f32_16x16x32_bf16 v[116:119], v[168:171], v[184:187], v[116:119]
	v_mfma_f32_16x16x32_bf16 v[112:115], v[176:179], v[184:187], v[112:115]
	v_mfma_f32_16x16x32_bf16 v[100:103], v[168:171], v[194:197], v[100:103]
	v_mfma_f32_16x16x32_bf16 v[96:99], v[176:179], v[194:197], v[96:99]
	v_mfma_f32_16x16x32_bf16 v[84:87], v[168:171], v[202:205], v[84:87]
	v_mfma_f32_16x16x32_bf16 v[80:83], v[176:179], v[202:205], v[80:83]
	v_mfma_f32_16x16x32_bf16 v[68:71], v[168:171], v[210:213], v[68:71]
	v_mfma_f32_16x16x32_bf16 v[64:67], v[176:179], v[210:213], v[64:67]
	s_barrier
	s_add_i32 s26, s45, s28
	s_mov_b32 m0, s26
	ds_read_b128 v[180:183], v145 offset:49152
	ds_read_b128 v[184:187], v145 offset:50176
	ds_read_b128 v[188:191], v145 offset:51200
	ds_read_b128 v[194:197], v145 offset:52224
	ds_read_b128 v[198:201], v145 offset:53248
	ds_read_b128 v[202:205], v145 offset:54272
	ds_read_b128 v[206:209], v145 offset:55296
	ds_read_b128 v[210:213], v145 offset:56320
	global_load_lds_dwordx4 v132, s[98:99]
	s_add_i32 m0, s26, 0x2000
	s_add_u32 s24, s24, 0x10080
	s_addc_u32 s25, s25, 0
	s_add_i32 s26, s46, s28
	global_load_lds_dwordx4 v128, s[98:99]
	s_mov_b32 m0, s26
	s_nop 0
	global_load_lds_dwordx4 v132, s[24:25]
	s_add_i32 m0, s26, 0x2000
	s_nop 0
	global_load_lds_dwordx4 v128, s[24:25]
	s_waitcnt vmcnt(6)
	s_waitcnt lgkmcnt(0)
	s_barrier
	v_mfma_f32_16x16x32_bf16 v[60:63], v[148:151], v[180:183], v[60:63]
	v_mfma_f32_16x16x32_bf16 v[56:59], v[156:159], v[180:183], v[56:59]
	v_mfma_f32_16x16x32_bf16 v[44:47], v[148:151], v[188:191], v[44:47]
	v_mfma_f32_16x16x32_bf16 v[40:43], v[156:159], v[188:191], v[40:43]
	v_mfma_f32_16x16x32_bf16 v[28:31], v[148:151], v[198:201], v[28:31]
	v_mfma_f32_16x16x32_bf16 v[24:27], v[156:159], v[198:201], v[24:27]
	v_mfma_f32_16x16x32_bf16 v[12:15], v[148:151], v[206:209], v[12:15]
	v_mfma_f32_16x16x32_bf16 v[8:11], v[156:159], v[206:209], v[8:11]
	v_mfma_f32_16x16x32_bf16 v[60:63], v[152:155], v[184:187], v[60:63]
	v_mfma_f32_16x16x32_bf16 v[56:59], v[160:163], v[184:187], v[56:59]
	v_mfma_f32_16x16x32_bf16 v[44:47], v[152:155], v[194:197], v[44:47]
	v_mfma_f32_16x16x32_bf16 v[40:43], v[160:163], v[194:197], v[40:43]
	v_mfma_f32_16x16x32_bf16 v[28:31], v[152:155], v[202:205], v[28:31]
	v_mfma_f32_16x16x32_bf16 v[24:27], v[160:163], v[202:205], v[24:27]
	v_mfma_f32_16x16x32_bf16 v[12:15], v[152:155], v[210:213], v[12:15]
	v_mfma_f32_16x16x32_bf16 v[8:11], v[160:163], v[210:213], v[8:11]
	v_mfma_f32_16x16x32_bf16 v[52:55], v[164:167], v[180:183], v[52:55]
	v_mfma_f32_16x16x32_bf16 v[48:51], v[172:175], v[180:183], v[48:51]
	v_mfma_f32_16x16x32_bf16 v[36:39], v[164:167], v[188:191], v[36:39]
	v_mfma_f32_16x16x32_bf16 v[32:35], v[172:175], v[188:191], v[32:35]
	v_mfma_f32_16x16x32_bf16 v[20:23], v[164:167], v[198:201], v[20:23]
	v_mfma_f32_16x16x32_bf16 v[16:19], v[172:175], v[198:201], v[16:19]
	v_mfma_f32_16x16x32_bf16 v[4:7], v[164:167], v[206:209], v[4:7]
	v_mfma_f32_16x16x32_bf16 v[0:3], v[172:175], v[206:209], v[0:3]
	v_mfma_f32_16x16x32_bf16 v[52:55], v[168:171], v[184:187], v[52:55]
	v_mfma_f32_16x16x32_bf16 v[48:51], v[176:179], v[184:187], v[48:51]
	v_mfma_f32_16x16x32_bf16 v[36:39], v[168:171], v[194:197], v[36:39]
	v_mfma_f32_16x16x32_bf16 v[32:35], v[176:179], v[194:197], v[32:35]
	v_mfma_f32_16x16x32_bf16 v[20:23], v[168:171], v[202:205], v[20:23]
	v_mfma_f32_16x16x32_bf16 v[16:19], v[176:179], v[202:205], v[16:19]
	v_mfma_f32_16x16x32_bf16 v[4:7], v[168:171], v[210:213], v[4:7]
	v_mfma_f32_16x16x32_bf16 v[0:3], v[176:179], v[210:213], v[0:3]
	s_barrier
	s_add_u32 s22, s22, 0x100
	s_addc_u32 s23, s23, 0
	s_add_u32 s54, s54, 0x100
	s_addc_u32 s55, s55, 0
	s_cmp_ge_i32 s56, s35
	s_mov_b32 s24, s56
	s_cbranch_scc0 .LBB0_648
	s_setprio 0

;     __device__ bool next(int i, Unit& u) const { const int L = i * G + c; if (L >= 384) return false; u.pm = L; u.pn = L / 6; return true; }
;     ...
;         const bool has_next = S.next(ui + 1, nxt);
;         const char* nA = has_next ? (const char*)g.A + (size_t)nxt.pm * tsA : cA; const char* nB = has_next ? (const char*)g.Bt + (size_t)nxt.pn * tsB : cB;
;         for (int t = 0; t < nt; t += 2) {
;             const bool last = (t == nt - 2);
;             const char* a1 = cA + (size_t)(t + 1) * kstep;
;             const char* a2 = last ? nA : cA + (size_t)(t + 2) * kstep; const char* b2 = last ? nB : cB + (size_t)(t + 2) * kstep;
;             const char* a3 = a2 + kstep; const char* b3 = b2 + kstep;
;             PG8_LDB(B0, 0, 0); PG8_LDB(B1, 0, 1); PG8_SCHED; PG8_LDA(At, 0, 0); PG8_STAGE(PG8_SA(1, 1), a1 + hsA, voffA);
;             if (Epi::NPRE != 0 && last) { E.pre(sv, cur, wr, fr); PG8_WAIT_V(16); } else { PG8_WAIT_V(8); }
;             PG8_WAIT_L(0); PG8_BAR; PG8_MMA(0, 0, At, B0); PG8_MMA(0, 1, At, B1); PG8_BAR; PG8_SCHED;
;             PG8_LDA(At, 0, 1); PG8_STAGE(PG8_SB(0, 0), b2, voffB); PG8_STAGE(PG8_SB(0, 1), b2 + hsB, voffB); PG8_STAGE(PG8_SA(0, 0), a2, voffA);
;             if (Epi::NPRE != 0 && last) { PG8_WAIT_V(16); } else { PG8_WAIT_V(8); }
;             PG8_WAIT_L(0); PG8_BAR; PG8_MMA(1, 0, At, B0); PG8_MMA(1, 1, At, B1); PG8_BAR; PG8_SCHED;
;             PG8_LDB(B0, 1, 0); PG8_LDB(B1, 1, 1); PG8_SCHED; PG8_LDA(At, 1, 0); PG8_STAGE(PG8_SA(0, 1), a2 + hsA, voffA);
;             PG8_WAIT_V(8); PG8_WAIT_L(0); PG8_BAR; PG8_MMA(0, 0, At, B0); PG8_MMA(0, 1, At, B1); PG8_BAR; PG8_SCHED;
;             PG8_LDA(At, 1, 1); PG8_STAGE(PG8_SB(1, 0), b3, voffB); PG8_STAGE(PG8_SB(1, 1), b3 + hsB, voffB); PG8_STAGE(PG8_SA(1, 0), a3, voffA);
;             PG8_WAIT_V(8); PG8_WAIT_L(0); PG8_BAR; PG8_MMA(1, 0, At, B0); PG8_MMA(1, 1, At, B1); PG8_BAR; PG8_SCHED;
;         }
;         if constexpr (ALIGN_EPI) { if (wr == 0) PG8_BAR; }
;         E(acc, cur, wr, wc, fr, fq, sv);
;         if (!has_next) break;
; #pragma unroll
;         for (int a = 0; a < 2; ++a)
; #pragma unroll
;             for (int b = 0; b < 2; ++b)
; #pragma unroll
;                 for (int m = 0; m < 4; ++m)
; #pragma unroll
;                     for (int n = 0; n < 2; ++n) acc[a][b][m][n] = (f32x4){0.f, 0.f, 0.f, 0.f};
;         cur = nxt; cA = nA; cB = nB; ++ui;
.LBB0_885:
	s_add_i32 s38, s38, 1
	s_mul_i32 s16, s38, s33
	s_mov_b32 s19, s45
	s_add_i32 s45, s16, s2
	s_mul_hi_i32 s16, s45, 0x2aaaaaab
	s_lshr_b32 s17, s16, 31
	s_mov_b32 s18, s46
	s_add_i32 s46, s16, s17
	s_cmpk_lt_i32 s45, 0x180
	s_cselect_b64 s[20:21], -1, 0
	s_and_b64 s[16:17], s[20:21], exec
	s_cselect_b32 s16, s45, s19
	s_cselect_b32 s18, s46, s18
	s_ashr_i32 s17, s16, 31
	s_lshl_b64 s[16:17], s[16:17], 18
	s_add_u32 s16, s4, s16
	s_addc_u32 s17, s5, s17
	s_ashr_i32 s19, s18, 31
	s_lshl_b64 s[18:19], s[18:19], 18
	s_add_u32 s18, s30, s18
	v_mov_b32_e32 v127, 0
	s_addc_u32 s19, s31, s19
	s_and_b64 vcc, exec, s[0:1]
	v_mov_b32_e32 v126, 0
	v_mov_b64_e32 v[124:125], 0
	v_mov_b64_e32 v[122:123], 0
	v_mov_b64_e32 v[120:121], 0
	v_mov_b64_e32 v[110:111], 0
	v_mov_b64_e32 v[108:109], 0
	v_mov_b64_e32 v[106:107], 0
	v_mov_b64_e32 v[104:105], 0
	v_mov_b64_e32 v[94:95], 0
	v_mov_b64_e32 v[92:93], 0
	v_mov_b64_e32 v[90:91], 0
	v_mov_b64_e32 v[88:89], 0
	v_mov_b64_e32 v[78:79], 0
	v_mov_b64_e32 v[76:77], 0
	v_mov_b64_e32 v[74:75], 0
	v_mov_b64_e32 v[72:73], 0
	v_mov_b64_e32 v[118:119], 0
	v_mov_b64_e32 v[116:117], 0
	v_mov_b64_e32 v[114:115], 0
	v_mov_b64_e32 v[112:113], 0
	v_mov_b64_e32 v[102:103], 0
	v_mov_b64_e32 v[100:101], 0
	v_mov_b64_e32 v[98:99], 0
	v_mov_b64_e32 v[96:97], 0
	v_mov_b64_e32 v[86:87], 0
	v_mov_b64_e32 v[84:85], 0
	v_mov_b64_e32 v[82:83], 0
	v_mov_b64_e32 v[80:81], 0
	v_mov_b64_e32 v[70:71], 0
	v_mov_b64_e32 v[68:69], 0
	v_mov_b64_e32 v[66:67], 0
	v_mov_b64_e32 v[64:65], 0
	v_mov_b64_e32 v[62:63], 0
	v_mov_b64_e32 v[60:61], 0
	v_mov_b64_e32 v[58:59], 0
	v_mov_b64_e32 v[56:57], 0
	v_mov_b64_e32 v[46:47], 0
	v_mov_b64_e32 v[44:45], 0
	v_mov_b64_e32 v[42:43], 0
	v_mov_b64_e32 v[40:41], 0
	v_mov_b64_e32 v[30:31], 0
	v_mov_b64_e32 v[28:29], 0
	v_mov_b64_e32 v[26:27], 0
	v_mov_b64_e32 v[24:25], 0
	v_mov_b64_e32 v[14:15], 0
	v_mov_b64_e32 v[12:13], 0
	v_mov_b64_e32 v[10:11], 0
	v_mov_b64_e32 v[8:9], 0
	v_mov_b64_e32 v[54:55], 0
	v_mov_b64_e32 v[52:53], 0
	v_mov_b64_e32 v[50:51], 0
	v_mov_b64_e32 v[48:49], 0
	v_mov_b64_e32 v[38:39], 0
	v_mov_b64_e32 v[36:37], 0
	v_mov_b64_e32 v[34:35], 0
	v_mov_b64_e32 v[32:33], 0
	v_mov_b64_e32 v[22:23], 0
	v_mov_b64_e32 v[20:21], 0
	v_mov_b64_e32 v[18:19], 0
	v_mov_b64_e32 v[16:17], 0
	v_mov_b64_e32 v[6:7], 0
	v_mov_b64_e32 v[4:5], 0
	v_mov_b64_e32 v[2:3], 0
	v_mov_b64_e32 v[0:1], 0
	s_cbranch_vccnz .LBB0_888
	s_and_b64 s[28:29], s[20:21], exec
	s_cselect_b32 s23, s17, s25
	s_cselect_b32 s48, s16, s24
	s_cselect_b32 s49, s19, s27
	s_cselect_b32 s50, s18, s26
	s_add_u32 s24, s24, 0x20080
	s_addc_u32 s25, s25, 0
	s_add_u32 s51, s26, 0x100
	v_mov_b32_e32 v0, 0
	s_addc_u32 s52, s27, 0
	s_mov_b32 s26, 0
	v_mov_b32_e32 v1, 0
	v_mov_b64_e32 v[2:3], 0
	v_mov_b64_e32 v[4:5], 0
	v_mov_b64_e32 v[6:7], 0
	v_mov_b64_e32 v[16:17], 0
	v_mov_b64_e32 v[18:19], 0
	v_mov_b64_e32 v[20:21], 0
	v_mov_b64_e32 v[22:23], 0
	v_mov_b64_e32 v[32:33], 0
	v_mov_b64_e32 v[34:35], 0
	v_mov_b64_e32 v[36:37], 0
	v_mov_b64_e32 v[38:39], 0
	v_mov_b64_e32 v[48:49], 0
	v_mov_b64_e32 v[50:51], 0
	v_mov_b64_e32 v[52:53], 0
	v_mov_b64_e32 v[54:55], 0
	v_mov_b64_e32 v[8:9], 0
	v_mov_b64_e32 v[10:11], 0
	v_mov_b64_e32 v[12:13], 0
	v_mov_b64_e32 v[14:15], 0
	v_mov_b64_e32 v[24:25], 0
	v_mov_b64_e32 v[26:27], 0
	v_mov_b64_e32 v[28:29], 0
	v_mov_b64_e32 v[30:31], 0
	v_mov_b64_e32 v[40:41], 0
	v_mov_b64_e32 v[42:43], 0
	v_mov_b64_e32 v[44:45], 0
	v_mov_b64_e32 v[46:47], 0
	v_mov_b64_e32 v[56:57], 0
	v_mov_b64_e32 v[58:59], 0
	v_mov_b64_e32 v[60:61], 0
	v_mov_b64_e32 v[62:63], 0
	v_mov_b64_e32 v[64:65], 0
	v_mov_b64_e32 v[66:67], 0
	v_mov_b64_e32 v[68:69], 0
	v_mov_b64_e32 v[70:71], 0
	v_mov_b64_e32 v[80:81], 0
	v_mov_b64_e32 v[82:83], 0
	v_mov_b64_e32 v[84:85], 0
	v_mov_b64_e32 v[86:87], 0
	v_mov_b64_e32 v[96:97], 0
	v_mov_b64_e32 v[98:99], 0
	v_mov_b64_e32 v[100:101], 0
	v_mov_b64_e32 v[102:103], 0
	v_mov_b64_e32 v[112:113], 0
	v_mov_b64_e32 v[114:115], 0
	v_mov_b64_e32 v[116:117], 0
	v_mov_b64_e32 v[118:119], 0
	v_mov_b64_e32 v[72:73], 0
	v_mov_b64_e32 v[74:75], 0
	v_mov_b64_e32 v[76:77], 0
	v_mov_b64_e32 v[78:79], 0
	v_mov_b64_e32 v[88:89], 0
	v_mov_b64_e32 v[90:91], 0
	v_mov_b64_e32 v[92:93], 0
	v_mov_b64_e32 v[94:95], 0
	v_mov_b64_e32 v[104:105], 0
	v_mov_b64_e32 v[106:107], 0
	v_mov_b64_e32 v[108:109], 0
	v_mov_b64_e32 v[110:111], 0
	v_mov_b64_e32 v[120:121], 0
	v_mov_b64_e32 v[122:123], 0
	v_mov_b64_e32 v[124:125], 0
	v_mov_b64_e32 v[126:127], 0
	v_readfirstlane_b32 s99, v234
	s_nop 0
	s_lshr_b32 s99, s99, 8
	s_cmp_eq_u32 s99, 0
	s_cbranch_scc1 .Lsp_4
	s_setprio 1
; #define PG8_STAGE(bufoff, gbase, voff) do { _Pragma("unroll") for (int _i = 0; _i < 2; ++_i) \
;         __builtin_amdgcn_global_load_lds((const unsigned*)((const char*)(gbase) + (voff)[_i]), (LAS unsigned*)(lds + (bufoff) + ldsw + _i * 8192), 16, 0, ((voff) == voffA ? AUXA : 0)); } while (0)
; #define PG8_LDA(dst, b, h) do { _Pragma("unroll") for (int m = 0; m < 4; ++m) _Pragma("unroll") for (int k = 0; k < 2; ++k) dst[m][k] = *(const LAS bf16x8*)(lds + PG8_SA(b, h) + aoff + m * 2048 + k * 1024); } while (0)
; #define PG8_LDB(dst, b, h) do { _Pragma("unroll") for (int n = 0; n < 2; ++n) _Pragma("unroll") for (int k = 0; k < 2; ++k) dst[n][k] = *(const LAS bf16x8*)(lds + PG8_SB(b, h) + boff + n * 2048 + k * 1024); } while (0)
; #define PG8_MMA(ai, bj, At, Bt) do { __builtin_amdgcn_s_setprio(1); _Pragma("unroll") for (int m = 0; m < 4; ++m) _Pragma("unroll") for (int n = 0; n < 2; ++n) _Pragma("unroll") for (int k = 0; k < 2; ++k) \
;         acc[ai][bj][m][n] = __builtin_amdgcn_mfma_f32_16x16x32_bf16(Bt[n][k], At[m][k], acc[ai][bj][m][n], 0, 0, 0); __builtin_amdgcn_s_setprio(0); } while (0)
; #define PG8_WAIT_V(n) asm volatile("s_waitcnt vmcnt(" #n ")" ::: "memory")
; #define PG8_WAIT_L(n) asm volatile("s_waitcnt lgkmcnt(" #n ")" ::: "memory")
; #define PG8_BAR __builtin_amdgcn_s_barrier()
; #define PG8_SCHED __builtin_amdgcn_sched_barrier(0)
;     ...
;         for (int t = 0; t < nt; t += 2) {
;             const bool last = (t == nt - 2);
;             const char* a1 = cA + (size_t)(t + 1) * kstep;
;             const char* a2 = last ? nA : cA + (size_t)(t + 2) * kstep; const char* b2 = last ? nB : cB + (size_t)(t + 2) * kstep;
;             const char* a3 = a2 + kstep; const char* b3 = b2 + kstep;
;             PG8_LDB(B0, 0, 0); PG8_LDB(B1, 0, 1); PG8_SCHED; PG8_LDA(At, 0, 0); PG8_STAGE(PG8_SA(1, 1), a1 + hsA, voffA);
;             if (Epi::NPRE != 0 && last) { E.pre(sv, cur, wr, fr); PG8_WAIT_V(16); } else { PG8_WAIT_V(8); }
;             PG8_WAIT_L(0); PG8_BAR; PG8_MMA(0, 0, At, B0); PG8_MMA(0, 1, At, B1); PG8_BAR; PG8_SCHED;
;             PG8_LDA(At, 0, 1); PG8_STAGE(PG8_SB(0, 0), b2, voffB); PG8_STAGE(PG8_SB(0, 1), b2 + hsB, voffB); PG8_STAGE(PG8_SA(0, 0), a2, voffA);
;             if (Epi::NPRE != 0 && last) { PG8_WAIT_V(16); } else { PG8_WAIT_V(8); }
;             PG8_WAIT_L(0); PG8_BAR; PG8_MMA(1, 0, At, B0); PG8_MMA(1, 1, At, B1); PG8_BAR; PG8_SCHED;
.Lsp_4:
.LBB0_887:
	s_add_u32 s98, s24, 0xfffe0000
	s_addc_u32 s99, s25, -1
	s_mov_b32 m0, s40
	s_nop 0
	global_load_lds_dwordx4 v134, s[98:99]
	s_mov_b32 m0, s41
	s_nop 0
	global_load_lds_dwordx4 v130, s[98:99]
	ds_read_b128 v[150:153], v146
	ds_read_b128 v[154:157], v146 offset:1024
	ds_read_b128 v[158:161], v146 offset:2048
	ds_read_b128 v[162:165], v146 offset:3072
	ds_read_b128 v[166:169], v147
	ds_read_b128 v[170:173], v147 offset:1024
	ds_read_b128 v[174:177], v147 offset:2048
	ds_read_b128 v[178:181], v147 offset:3072
	s_add_i32 s53, s26, 2
	s_add_u32 s27, s24, 0xfffe0080
	s_addc_u32 s28, s25, -1
	s_cmp_eq_u32 s42, s26
	s_cselect_b32 s26, s50, s51
	s_cselect_b32 s29, s23, s28
	s_cselect_b32 s28, s48, s27
	s_cselect_b32 s27, s49, s52
	s_add_i32 m0, s3, 0xc000
	ds_read_b128 v[182:185], v148
	ds_read_b128 v[186:189], v148 offset:1024
	ds_read_b128 v[194:197], v148 offset:2048
	ds_read_b128 v[198:201], v148 offset:3072
	ds_read_b128 v[202:205], v148 offset:4096
	ds_read_b128 v[206:209], v148 offset:5120
	ds_read_b128 v[210:213], v148 offset:6144
	ds_read_b128 v[214:217], v148 offset:7168
	global_load_lds_dwordx4 v138, s[24:25]
	s_add_i32 m0, s3, 0xe000
	s_nop 0
	global_load_lds_dwordx4 v140, s[24:25]
	s_waitcnt vmcnt(8)
	s_waitcnt lgkmcnt(0)
	s_barrier
	v_mfma_f32_16x16x32_bf16 v[124:127], v[150:153], v[182:185], v[124:127]
	v_mfma_f32_16x16x32_bf16 v[120:123], v[158:161], v[182:185], v[120:123]
	v_mfma_f32_16x16x32_bf16 v[108:111], v[150:153], v[194:197], v[108:111]
	v_mfma_f32_16x16x32_bf16 v[104:107], v[158:161], v[194:197], v[104:107]
	v_mfma_f32_16x16x32_bf16 v[92:95], v[150:153], v[202:205], v[92:95]
	v_mfma_f32_16x16x32_bf16 v[88:91], v[158:161], v[202:205], v[88:91]
	v_mfma_f32_16x16x32_bf16 v[76:79], v[150:153], v[210:213], v[76:79]
	v_mfma_f32_16x16x32_bf16 v[72:75], v[158:161], v[210:213], v[72:75]
	v_mfma_f32_16x16x32_bf16 v[124:127], v[154:157], v[186:189], v[124:127]
	v_mfma_f32_16x16x32_bf16 v[120:123], v[162:165], v[186:189], v[120:123]
	v_mfma_f32_16x16x32_bf16 v[108:111], v[154:157], v[198:201], v[108:111]
	v_mfma_f32_16x16x32_bf16 v[104:107], v[162:165], v[198:201], v[104:107]
	v_mfma_f32_16x16x32_bf16 v[92:95], v[154:157], v[206:209], v[92:95]
	v_mfma_f32_16x16x32_bf16 v[88:91], v[162:165], v[206:209], v[88:91]
	v_mfma_f32_16x16x32_bf16 v[76:79], v[154:157], v[214:217], v[76:79]
	v_mfma_f32_16x16x32_bf16 v[72:75], v[162:165], v[214:217], v[72:75]
	v_mfma_f32_16x16x32_bf16 v[116:119], v[166:169], v[182:185], v[116:119]
	v_mfma_f32_16x16x32_bf16 v[112:115], v[174:177], v[182:185], v[112:115]
	v_mfma_f32_16x16x32_bf16 v[100:103], v[166:169], v[194:197], v[100:103]
	v_mfma_f32_16x16x32_bf16 v[96:99], v[174:177], v[194:197], v[96:99]
	v_mfma_f32_16x16x32_bf16 v[84:87], v[166:169], v[202:205], v[84:87]
	v_mfma_f32_16x16x32_bf16 v[80:83], v[174:177], v[202:205], v[80:83]
	v_mfma_f32_16x16x32_bf16 v[68:71], v[166:169], v[210:213], v[68:71]
	v_mfma_f32_16x16x32_bf16 v[64:67], v[174:177], v[210:213], v[64:67]
	v_mfma_f32_16x16x32_bf16 v[116:119], v[170:173], v[186:189], v[116:119]
	v_mfma_f32_16x16x32_bf16 v[112:115], v[178:181], v[186:189], v[112:115]
	v_mfma_f32_16x16x32_bf16 v[100:103], v[170:173], v[198:201], v[100:103]
	v_mfma_f32_16x16x32_bf16 v[96:99], v[178:181], v[198:201], v[96:99]
	v_mfma_f32_16x16x32_bf16 v[84:87], v[170:173], v[206:209], v[84:87]
	v_mfma_f32_16x16x32_bf16 v[80:83], v[178:181], v[206:209], v[80:83]
	v_mfma_f32_16x16x32_bf16 v[68:71], v[170:173], v[214:217], v[68:71]
	v_mfma_f32_16x16x32_bf16 v[64:67], v[178:181], v[214:217], v[64:67]
	s_barrier
	s_add_u32 s98, s26, s12
	s_addc_u32 s99, s27, s13
	s_add_u32 s100, s28, s12
	s_addc_u32 s101, s29, s13
	s_add_i32 s54, s43, s34
	s_mov_b32 m0, s54
	ds_read_b128 v[182:185], v148 offset:16384
	ds_read_b128 v[186:189], v148 offset:17408
	ds_read_b128 v[194:197], v148 offset:18432
	ds_read_b128 v[198:201], v148 offset:19456
	ds_read_b128 v[202:205], v148 offset:20480
	ds_read_b128 v[206:209], v148 offset:21504
	ds_read_b128 v[210:213], v148 offset:22528
	ds_read_b128 v[214:217], v148 offset:23552
	global_load_lds_dwordx4 v132, s[26:27]
	s_add_i32 m0, s54, 0x2000
	s_add_u32 s54, s26, 0x20000
	s_addc_u32 s55, s27, 0
	s_add_i32 s56, s44, s34
	global_load_lds_dwordx4 v128, s[26:27]
	s_mov_b32 m0, s56
	s_nop 0
	global_load_lds_dwordx4 v132, s[54:55]
	s_add_i32 m0, s56, 0x2000
	s_nop 0
	global_load_lds_dwordx4 v128, s[54:55]
	s_waitcnt vmcnt(6)
	s_waitcnt lgkmcnt(0)
	s_barrier
	v_mfma_f32_16x16x32_bf16 v[60:63], v[150:153], v[182:185], v[60:63]
	v_mfma_f32_16x16x32_bf16 v[56:59], v[158:161], v[182:185], v[56:59]
	v_mfma_f32_16x16x32_bf16 v[44:47], v[150:153], v[194:197], v[44:47]
	v_mfma_f32_16x16x32_bf16 v[40:43], v[158:161], v[194:197], v[40:43]
	v_mfma_f32_16x16x32_bf16 v[28:31], v[150:153], v[202:205], v[28:31]
	v_mfma_f32_16x16x32_bf16 v[24:27], v[158:161], v[202:205], v[24:27]
	v_mfma_f32_16x16x32_bf16 v[12:15], v[150:153], v[210:213], v[12:15]
	v_mfma_f32_16x16x32_bf16 v[8:11], v[158:161], v[210:213], v[8:11]
	v_mfma_f32_16x16x32_bf16 v[60:63], v[154:157], v[186:189], v[60:63]
	v_mfma_f32_16x16x32_bf16 v[56:59], v[162:165], v[186:189], v[56:59]
	v_mfma_f32_16x16x32_bf16 v[44:47], v[154:157], v[198:201], v[44:47]
	v_mfma_f32_16x16x32_bf16 v[40:43], v[162:165], v[198:201], v[40:43]
	v_mfma_f32_16x16x32_bf16 v[28:31], v[154:157], v[206:209], v[28:31]
	v_mfma_f32_16x16x32_bf16 v[24:27], v[162:165], v[206:209], v[24:27]
	v_mfma_f32_16x16x32_bf16 v[12:15], v[154:157], v[214:217], v[12:15]
	v_mfma_f32_16x16x32_bf16 v[8:11], v[162:165], v[214:217], v[8:11]
	v_mfma_f32_16x16x32_bf16 v[52:55], v[166:169], v[182:185], v[52:55]
	v_mfma_f32_16x16x32_bf16 v[48:51], v[174:177], v[182:185], v[48:51]
	v_mfma_f32_16x16x32_bf16 v[36:39], v[166:169], v[194:197], v[36:39]
	v_mfma_f32_16x16x32_bf16 v[32:35], v[174:177], v[194:197], v[32:35]
	v_mfma_f32_16x16x32_bf16 v[20:23], v[166:169], v[202:205], v[20:23]
	v_mfma_f32_16x16x32_bf16 v[16:19], v[174:177], v[202:205], v[16:19]
	v_mfma_f32_16x16x32_bf16 v[4:7], v[166:169], v[210:213], v[4:7]
	v_mfma_f32_16x16x32_bf16 v[0:3], v[174:177], v[210:213], v[0:3]
	v_mfma_f32_16x16x32_bf16 v[52:55], v[170:173], v[186:189], v[52:55]
	v_mfma_f32_16x16x32_bf16 v[48:51], v[178:181], v[186:189], v[48:51]
	v_mfma_f32_16x16x32_bf16 v[36:39], v[170:173], v[198:201], v[36:39]
	v_mfma_f32_16x16x32_bf16 v[32:35], v[178:181], v[198:201], v[32:35]
	v_mfma_f32_16x16x32_bf16 v[20:23], v[170:173], v[206:209], v[20:23]
	v_mfma_f32_16x16x32_bf16 v[16:19], v[178:181], v[206:209], v[16:19]
	v_mfma_f32_16x16x32_bf16 v[4:7], v[170:173], v[214:217], v[4:7]
	v_mfma_f32_16x16x32_bf16 v[0:3], v[178:181], v[214:217], v[0:3]
	s_barrier
; #define PG8_STAGE(bufoff, gbase, voff) do { _Pragma("unroll") for (int _i = 0; _i < 2; ++_i) \
;         __builtin_amdgcn_global_load_lds((const unsigned*)((const char*)(gbase) + (voff)[_i]), (LAS unsigned*)(lds + (bufoff) + ldsw + _i * 8192), 16, 0, ((voff) == voffA ? AUXA : 0)); } while (0)
; #define PG8_LDA(dst, b, h) do { _Pragma("unroll") for (int m = 0; m < 4; ++m) _Pragma("unroll") for (int k = 0; k < 2; ++k) dst[m][k] = *(const LAS bf16x8*)(lds + PG8_SA(b, h) + aoff + m * 2048 + k * 1024); } while (0)
; #define PG8_LDB(dst, b, h) do { _Pragma("unroll") for (int n = 0; n < 2; ++n) _Pragma("unroll") for (int k = 0; k < 2; ++k) dst[n][k] = *(const LAS bf16x8*)(lds + PG8_SB(b, h) + boff + n * 2048 + k * 1024); } while (0)
; #define PG8_MMA(ai, bj, At, Bt) do { __builtin_amdgcn_s_setprio(1); _Pragma("unroll") for (int m = 0; m < 4; ++m) _Pragma("unroll") for (int n = 0; n < 2; ++n) _Pragma("unroll") for (int k = 0; k < 2; ++k) \
;         acc[ai][bj][m][n] = __builtin_amdgcn_mfma_f32_16x16x32_bf16(Bt[n][k], At[m][k], acc[ai][bj][m][n], 0, 0, 0); __builtin_amdgcn_s_setprio(0); } while (0)
; #define PG8_WAIT_V(n) asm volatile("s_waitcnt vmcnt(" #n ")" ::: "memory")
; #define PG8_WAIT_L(n) asm volatile("s_waitcnt lgkmcnt(" #n ")" ::: "memory")
; #define PG8_BAR __builtin_amdgcn_s_barrier()
; #define PG8_SCHED __builtin_amdgcn_sched_barrier(0)
;     ...
;             PG8_LDB(B0, 1, 0); PG8_LDB(B1, 1, 1); PG8_SCHED; PG8_LDA(At, 1, 0); PG8_STAGE(PG8_SA(0, 1), a2 + hsA, voffA);
;             PG8_WAIT_V(8); PG8_WAIT_L(0); PG8_BAR; PG8_MMA(0, 0, At, B0); PG8_MMA(0, 1, At, B1); PG8_BAR; PG8_SCHED;
;             PG8_LDA(At, 1, 1); PG8_STAGE(PG8_SB(1, 0), b3, voffB); PG8_STAGE(PG8_SB(1, 1), b3 + hsB, voffB); PG8_STAGE(PG8_SA(1, 0), a3, voffA);
;             PG8_WAIT_V(8); PG8_WAIT_L(0); PG8_BAR; PG8_MMA(1, 0, At, B0); PG8_MMA(1, 1, At, B1); PG8_BAR; PG8_SCHED;
;         }
	s_mov_b32 m0, s3
	s_nop 0
	global_load_lds_dwordx4 v134, s[28:29]
	s_mov_b32 m0, s35
	s_nop 0
	global_load_lds_dwordx4 v130, s[28:29]
	s_add_i32 s54, 0, 0x18000
	v_add_u32_e32 v149, s54, v143
	s_add_i32 s55, 0, 0x1c000
	ds_read_b128 v[150:153], v149
	ds_read_b128 v[154:157], v149 offset:1024
	ds_read_b128 v[158:161], v149 offset:2048
	ds_read_b128 v[162:165], v149 offset:3072
	v_add_u32_e32 v149, s55, v143
	ds_read_b128 v[166:169], v149
	ds_read_b128 v[170:173], v149 offset:1024
	ds_read_b128 v[174:177], v149 offset:2048
	ds_read_b128 v[178:181], v149 offset:3072
	s_add_u32 s28, s28, 0x20000
	s_addc_u32 s29, s29, 0
	s_mov_b32 m0, s36
	ds_read_b128 v[182:185], v148 offset:32768
	ds_read_b128 v[186:189], v148 offset:33792
	ds_read_b128 v[194:197], v148 offset:34816
	ds_read_b128 v[198:201], v148 offset:35840
	ds_read_b128 v[202:205], v148 offset:36864
	ds_read_b128 v[206:209], v148 offset:37888
	ds_read_b128 v[210:213], v148 offset:38912
	ds_read_b128 v[214:217], v148 offset:39936
	global_load_lds_dwordx4 v134, s[28:29]
	s_mov_b32 m0, s37
	s_nop 0
	global_load_lds_dwordx4 v130, s[28:29]
	s_waitcnt vmcnt(8)
	s_waitcnt lgkmcnt(0)
	s_barrier
	v_mfma_f32_16x16x32_bf16 v[124:127], v[150:153], v[182:185], v[124:127]
	v_mfma_f32_16x16x32_bf16 v[120:123], v[158:161], v[182:185], v[120:123]
	v_mfma_f32_16x16x32_bf16 v[108:111], v[150:153], v[194:197], v[108:111]
	v_mfma_f32_16x16x32_bf16 v[104:107], v[158:161], v[194:197], v[104:107]
	v_mfma_f32_16x16x32_bf16 v[92:95], v[150:153], v[202:205], v[92:95]
	v_mfma_f32_16x16x32_bf16 v[88:91], v[158:161], v[202:205], v[88:91]
	v_mfma_f32_16x16x32_bf16 v[76:79], v[150:153], v[210:213], v[76:79]
	v_mfma_f32_16x16x32_bf16 v[72:75], v[158:161], v[210:213], v[72:75]
	v_mfma_f32_16x16x32_bf16 v[124:127], v[154:157], v[186:189], v[124:127]
	v_mfma_f32_16x16x32_bf16 v[120:123], v[162:165], v[186:189], v[120:123]
	v_mfma_f32_16x16x32_bf16 v[108:111], v[154:157], v[198:201], v[108:111]
	v_mfma_f32_16x16x32_bf16 v[104:107], v[162:165], v[198:201], v[104:107]
	v_mfma_f32_16x16x32_bf16 v[92:95], v[154:157], v[206:209], v[92:95]
	v_mfma_f32_16x16x32_bf16 v[88:91], v[162:165], v[206:209], v[88:91]
	v_mfma_f32_16x16x32_bf16 v[76:79], v[154:157], v[214:217], v[76:79]
	v_mfma_f32_16x16x32_bf16 v[72:75], v[162:165], v[214:217], v[72:75]
	v_mfma_f32_16x16x32_bf16 v[116:119], v[166:169], v[182:185], v[116:119]
	v_mfma_f32_16x16x32_bf16 v[112:115], v[174:177], v[182:185], v[112:115]
	v_mfma_f32_16x16x32_bf16 v[100:103], v[166:169], v[194:197], v[100:103]
	v_mfma_f32_16x16x32_bf16 v[96:99], v[174:177], v[194:197], v[96:99]
	v_mfma_f32_16x16x32_bf16 v[84:87], v[166:169], v[202:205], v[84:87]
	v_mfma_f32_16x16x32_bf16 v[80:83], v[174:177], v[202:205], v[80:83]
	v_mfma_f32_16x16x32_bf16 v[68:71], v[166:169], v[210:213], v[68:71]
	v_mfma_f32_16x16x32_bf16 v[64:67], v[174:177], v[210:213], v[64:67]
	v_mfma_f32_16x16x32_bf16 v[116:119], v[170:173], v[186:189], v[116:119]
	v_mfma_f32_16x16x32_bf16 v[112:115], v[178:181], v[186:189], v[112:115]
	v_mfma_f32_16x16x32_bf16 v[100:103], v[170:173], v[198:201], v[100:103]
	v_mfma_f32_16x16x32_bf16 v[96:99], v[178:181], v[198:201], v[96:99]
	v_mfma_f32_16x16x32_bf16 v[84:87], v[170:173], v[206:209], v[84:87]
	v_mfma_f32_16x16x32_bf16 v[80:83], v[178:181], v[206:209], v[80:83]
	v_mfma_f32_16x16x32_bf16 v[68:71], v[170:173], v[214:217], v[68:71]
	v_mfma_f32_16x16x32_bf16 v[64:67], v[178:181], v[214:217], v[64:67]
	s_barrier
	s_add_i32 s28, s54, s34
	s_mov_b32 m0, s28
	ds_read_b128 v[182:185], v148 offset:49152
	ds_read_b128 v[186:189], v148 offset:50176
	ds_read_b128 v[194:197], v148 offset:51200
	ds_read_b128 v[198:201], v148 offset:52224
	ds_read_b128 v[202:205], v148 offset:53248
	ds_read_b128 v[206:209], v148 offset:54272
	ds_read_b128 v[210:213], v148 offset:55296
	ds_read_b128 v[214:217], v148 offset:56320
	global_load_lds_dwordx4 v132, s[98:99]
	s_add_i32 m0, s28, 0x2000
	s_add_u32 s26, s26, 0x20080
	s_addc_u32 s27, s27, 0
	s_add_i32 s28, s55, s34
	global_load_lds_dwordx4 v128, s[98:99]
	s_mov_b32 m0, s28
	s_nop 0
	global_load_lds_dwordx4 v132, s[26:27]
	s_add_i32 m0, s28, 0x2000
	s_nop 0
	global_load_lds_dwordx4 v128, s[26:27]
	s_waitcnt vmcnt(6)
	s_waitcnt lgkmcnt(0)
	s_barrier
	v_mfma_f32_16x16x32_bf16 v[60:63], v[150:153], v[182:185], v[60:63]
	v_mfma_f32_16x16x32_bf16 v[56:59], v[158:161], v[182:185], v[56:59]
	v_mfma_f32_16x16x32_bf16 v[44:47], v[150:153], v[194:197], v[44:47]
	v_mfma_f32_16x16x32_bf16 v[40:43], v[158:161], v[194:197], v[40:43]
	v_mfma_f32_16x16x32_bf16 v[28:31], v[150:153], v[202:205], v[28:31]
	v_mfma_f32_16x16x32_bf16 v[24:27], v[158:161], v[202:205], v[24:27]
	v_mfma_f32_16x16x32_bf16 v[12:15], v[150:153], v[210:213], v[12:15]
	v_mfma_f32_16x16x32_bf16 v[8:11], v[158:161], v[210:213], v[8:11]
	v_mfma_f32_16x16x32_bf16 v[60:63], v[154:157], v[186:189], v[60:63]
	v_mfma_f32_16x16x32_bf16 v[56:59], v[162:165], v[186:189], v[56:59]
	v_mfma_f32_16x16x32_bf16 v[44:47], v[154:157], v[198:201], v[44:47]
	v_mfma_f32_16x16x32_bf16 v[40:43], v[162:165], v[198:201], v[40:43]
	v_mfma_f32_16x16x32_bf16 v[28:31], v[154:157], v[206:209], v[28:31]
	v_mfma_f32_16x16x32_bf16 v[24:27], v[162:165], v[206:209], v[24:27]
	v_mfma_f32_16x16x32_bf16 v[12:15], v[154:157], v[214:217], v[12:15]
	v_mfma_f32_16x16x32_bf16 v[8:11], v[162:165], v[214:217], v[8:11]
	v_mfma_f32_16x16x32_bf16 v[52:55], v[166:169], v[182:185], v[52:55]
	v_mfma_f32_16x16x32_bf16 v[48:51], v[174:177], v[182:185], v[48:51]
	v_mfma_f32_16x16x32_bf16 v[36:39], v[166:169], v[194:197], v[36:39]
	v_mfma_f32_16x16x32_bf16 v[32:35], v[174:177], v[194:197], v[32:35]
	v_mfma_f32_16x16x32_bf16 v[20:23], v[166:169], v[202:205], v[20:23]
	v_mfma_f32_16x16x32_bf16 v[16:19], v[174:177], v[202:205], v[16:19]
	v_mfma_f32_16x16x32_bf16 v[4:7], v[166:169], v[210:213], v[4:7]
	v_mfma_f32_16x16x32_bf16 v[0:3], v[174:177], v[210:213], v[0:3]
	v_mfma_f32_16x16x32_bf16 v[52:55], v[170:173], v[186:189], v[52:55]
	v_mfma_f32_16x16x32_bf16 v[48:51], v[178:181], v[186:189], v[48:51]
	v_mfma_f32_16x16x32_bf16 v[36:39], v[170:173], v[198:201], v[36:39]
	v_mfma_f32_16x16x32_bf16 v[32:35], v[178:181], v[198:201], v[32:35]
	v_mfma_f32_16x16x32_bf16 v[20:23], v[170:173], v[206:209], v[20:23]
	v_mfma_f32_16x16x32_bf16 v[16:19], v[178:181], v[206:209], v[16:19]
	v_mfma_f32_16x16x32_bf16 v[4:7], v[170:173], v[214:217], v[4:7]
	v_mfma_f32_16x16x32_bf16 v[0:3], v[178:181], v[214:217], v[0:3]
	s_barrier
	s_add_u32 s24, s24, 0x100
	s_addc_u32 s25, s25, 0
	s_add_u32 s51, s51, 0x100
	s_addc_u32 s52, s52, 0
	s_cmp_ge_i32 s53, s39
	s_mov_b32 s26, s53
	s_cbranch_scc0 .LBB0_887
	s_setprio 0

; #define PG8_WAIT_V(n) asm volatile("s_waitcnt vmcnt(" #n ")" ::: "memory")
; #define PG8_WAIT_L(n) asm volatile("s_waitcnt lgkmcnt(" #n ")" ::: "memory")
; #define PG8_BAR __builtin_amdgcn_s_barrier()
;     ...
;         const char* nA = has_next ? (const char*)g.A + (size_t)nxt.pm * tsA : cA; const char* nB = has_next ? (const char*)g.Bt + (size_t)nxt.pn * tsB : cB;
;         for (int t = 0; t < nt; t += 2) {
;             const bool last = (t == nt - 2);
;             const char* a1 = cA + (size_t)(t + 1) * kstep;
;             const char* a2 = last ? nA : cA + (size_t)(t + 2) * kstep; const char* b2 = last ? nB : cB + (size_t)(t + 2) * kstep;
;             const char* a3 = a2 + kstep; const char* b3 = b2 + kstep;
;             PG8_LDB(B0, 0, 0); PG8_LDB(B1, 0, 1); PG8_SCHED; PG8_LDA(At, 0, 0); PG8_STAGE(PG8_SA(1, 1), a1 + hsA, voffA);
;             if (Epi::NPRE != 0 && last) { E.pre(sv, cur, wr, fr); PG8_WAIT_V(16); } else { PG8_WAIT_V(8); }
;             PG8_WAIT_L(0); PG8_BAR; PG8_MMA(0, 0, At, B0); PG8_MMA(0, 1, At, B1); PG8_BAR; PG8_SCHED;
;             PG8_LDA(At, 0, 1); PG8_STAGE(PG8_SB(0, 0), b2, voffB); PG8_STAGE(PG8_SB(0, 1), b2 + hsB, voffB); PG8_STAGE(PG8_SA(0, 0), a2, voffA);
;             if (Epi::NPRE != 0 && last) { PG8_WAIT_V(16); } else { PG8_WAIT_V(8); }
;             PG8_WAIT_L(0); PG8_BAR; PG8_MMA(1, 0, At, B0); PG8_MMA(1, 1, At, B1); PG8_BAR; PG8_SCHED;
;             PG8_LDB(B0, 1, 0); PG8_LDB(B1, 1, 1); PG8_SCHED; PG8_LDA(At, 1, 0); PG8_STAGE(PG8_SA(0, 1), a2 + hsA, voffA);
;             PG8_WAIT_V(8); PG8_WAIT_L(0); PG8_BAR; PG8_MMA(0, 0, At, B0); PG8_MMA(0, 1, At, B1); PG8_BAR; PG8_SCHED;
;             PG8_LDA(At, 1, 1); PG8_STAGE(PG8_SB(1, 0), b3, voffB); PG8_STAGE(PG8_SB(1, 1), b3 + hsB, voffB); PG8_STAGE(PG8_SA(1, 0), a3, voffA);
;             PG8_WAIT_V(8); PG8_WAIT_L(0); PG8_BAR; PG8_MMA(1, 0, At, B0); PG8_MMA(1, 1, At, B1); PG8_BAR; PG8_SCHED;
;         }
;         if constexpr (ALIGN_EPI) { if (wr == 0) PG8_BAR; }
;         E(acc, cur, wr, wc, fr, fq, sv);
;         if (!has_next) break;
; #pragma unroll
;         for (int a = 0; a < 2; ++a)
; #pragma unroll
;             for (int b = 0; b < 2; ++b)
; #pragma unroll
;                 for (int m = 0; m < 4; ++m)
; #pragma unroll
;                     for (int n = 0; n < 2; ++n) acc[a][b][m][n] = (f32x4){0.f, 0.f, 0.f, 0.f};
;         cur = nxt; cA = nA; cB = nB; ++ui;
.LBB0_957:
	s_ashr_i32 s21, s20, 31
	s_lshl_b64 s[22:23], s[20:21], 19
	s_add_u32 s22, s8, s22
	s_addc_u32 s23, s9, s23
	s_ashr_i32 s19, s18, 31
	s_lshl_b64 s[24:25], s[18:19], 19
	s_add_u32 s24, s6, s24
	v_mov_b32_e32 v139, 0
	s_addc_u32 s25, s7, s25
	s_andn2_b64 vcc, exec, s[14:15]
	v_mov_b32_e32 v138, v139
	v_mov_b32_e32 v137, v139
	v_mov_b32_e32 v136, v139
	v_mov_b32_e32 v143, v139
	v_mov_b32_e32 v142, v139
	v_mov_b32_e32 v141, v139
	v_mov_b32_e32 v140, v139
	v_mov_b32_e32 v127, v139
	v_mov_b32_e32 v126, v139
	v_mov_b32_e32 v125, v139
	v_mov_b32_e32 v124, v139
	v_mov_b32_e32 v123, v139
	v_mov_b32_e32 v122, v139
	v_mov_b32_e32 v121, v139
	v_mov_b32_e32 v120, v139
	v_mov_b32_e32 v103, v139
	v_mov_b32_e32 v102, v139
	v_mov_b32_e32 v101, v139
	v_mov_b32_e32 v100, v139
	v_mov_b32_e32 v99, v139
	v_mov_b32_e32 v98, v139
	v_mov_b32_e32 v97, v139
	v_mov_b32_e32 v96, v139
	v_mov_b32_e32 v79, v139
	v_mov_b32_e32 v78, v139
	v_mov_b32_e32 v77, v139
	v_mov_b32_e32 v76, v139
	v_mov_b32_e32 v75, v139
	v_mov_b32_e32 v74, v139
	v_mov_b32_e32 v73, v139
	v_mov_b32_e32 v72, v139
	v_mov_b32_e32 v135, v139
	v_mov_b32_e32 v134, v139
	v_mov_b32_e32 v133, v139
	v_mov_b32_e32 v132, v139
	v_mov_b32_e32 v131, v139
	v_mov_b32_e32 v130, v139
	v_mov_b32_e32 v129, v139
	v_mov_b32_e32 v128, v139
	v_mov_b32_e32 v119, v139
	v_mov_b32_e32 v118, v139
	v_mov_b32_e32 v117, v139
	v_mov_b32_e32 v116, v139
	v_mov_b32_e32 v115, v139
	v_mov_b32_e32 v114, v139
	v_mov_b32_e32 v113, v139
	v_mov_b32_e32 v112, v139
	v_mov_b32_e32 v87, v139
	v_mov_b32_e32 v86, v139
	v_mov_b32_e32 v85, v139
	v_mov_b32_e32 v84, v139
	v_mov_b32_e32 v83, v139
	v_mov_b32_e32 v82, v139
	v_mov_b32_e32 v81, v139
	v_mov_b32_e32 v80, v139
	v_mov_b32_e32 v71, v139
	v_mov_b32_e32 v70, v139
	v_mov_b32_e32 v69, v139
	v_mov_b32_e32 v68, v139
	v_mov_b32_e32 v67, v139
	v_mov_b32_e32 v66, v139
	v_mov_b32_e32 v65, v139
	v_mov_b32_e32 v64, v139
	v_mov_b32_e32 v63, v139
	v_mov_b32_e32 v62, v139
	v_mov_b32_e32 v61, v139
	v_mov_b32_e32 v60, v139
	v_mov_b32_e32 v59, v139
	v_mov_b32_e32 v58, v139
	v_mov_b32_e32 v57, v139
	v_mov_b32_e32 v56, v139
	v_mov_b32_e32 v47, v139
	v_mov_b32_e32 v46, v139
	v_mov_b32_e32 v45, v139
	v_mov_b32_e32 v44, v139
	v_mov_b32_e32 v43, v139
	v_mov_b32_e32 v42, v139
	v_mov_b32_e32 v41, v139
	v_mov_b32_e32 v40, v139
	v_mov_b32_e32 v31, v139
	v_mov_b32_e32 v30, v139
	v_mov_b32_e32 v29, v139
	v_mov_b32_e32 v28, v139
	v_mov_b32_e32 v27, v139
	v_mov_b32_e32 v26, v139
	v_mov_b32_e32 v25, v139
	v_mov_b32_e32 v24, v139
	v_mov_b32_e32 v15, v139
	v_mov_b32_e32 v14, v139
	v_mov_b32_e32 v13, v139
	v_mov_b32_e32 v12, v139
	v_mov_b32_e32 v11, v139
	v_mov_b32_e32 v10, v139
	v_mov_b32_e32 v9, v139
	v_mov_b32_e32 v8, v139
	v_mov_b32_e32 v55, v139
	v_mov_b32_e32 v54, v139
	v_mov_b32_e32 v53, v139
	v_mov_b32_e32 v52, v139
	v_mov_b32_e32 v51, v139
	v_mov_b32_e32 v50, v139
	v_mov_b32_e32 v49, v139
	v_mov_b32_e32 v48, v139
	v_mov_b32_e32 v39, v139
	v_mov_b32_e32 v38, v139
	v_mov_b32_e32 v37, v139
	v_mov_b32_e32 v36, v139
	v_mov_b32_e32 v35, v139
	v_mov_b32_e32 v34, v139
	v_mov_b32_e32 v33, v139
	v_mov_b32_e32 v32, v139
	v_mov_b32_e32 v23, v139
	v_mov_b32_e32 v22, v139
	v_mov_b32_e32 v21, v139
	v_mov_b32_e32 v20, v139
	v_mov_b32_e32 v19, v139
	v_mov_b32_e32 v18, v139
	v_mov_b32_e32 v17, v139
	v_mov_b32_e32 v16, v139
	v_mov_b32_e32 v7, v139
	v_mov_b32_e32 v6, v139
	v_mov_b32_e32 v5, v139
	v_mov_b32_e32 v4, v139
	v_mov_b32_e32 v3, v139
	v_mov_b32_e32 v2, v139
	v_mov_b32_e32 v1, v139
	v_mov_b32_e32 v0, v139
	s_cbranch_vccnz .LBB0_960
	s_and_b64 s[34:35], s[0:1], exec
	s_cselect_b32 s19, s23, s29
	s_cselect_b32 s21, s22, s28
	s_cselect_b32 s47, s25, s31
	s_cselect_b32 s48, s24, s30
	s_add_u32 s28, s28, 0x40080
	s_addc_u32 s29, s29, 0
	s_add_u32 s49, s30, 0x100
	v_mov_b32_e32 v0, 0
	s_addc_u32 s50, s31, 0
	s_mov_b32 s30, 0
	v_mov_b32_e32 v1, 0
	v_mov_b64_e32 v[2:3], 0
	v_mov_b64_e32 v[4:5], 0
	v_mov_b64_e32 v[6:7], 0
	v_mov_b64_e32 v[16:17], 0
	v_mov_b64_e32 v[18:19], 0
	v_mov_b64_e32 v[20:21], 0
	v_mov_b64_e32 v[22:23], 0
	v_mov_b64_e32 v[32:33], 0
	v_mov_b64_e32 v[34:35], 0
	v_mov_b64_e32 v[36:37], 0
	v_mov_b64_e32 v[38:39], 0
	v_mov_b64_e32 v[48:49], 0
	v_mov_b64_e32 v[50:51], 0
	v_mov_b64_e32 v[52:53], 0
	v_mov_b64_e32 v[54:55], 0
	v_mov_b64_e32 v[8:9], 0
	v_mov_b64_e32 v[10:11], 0
	v_mov_b64_e32 v[12:13], 0
	v_mov_b64_e32 v[14:15], 0
	v_mov_b64_e32 v[24:25], 0
	v_mov_b64_e32 v[26:27], 0
	v_mov_b64_e32 v[28:29], 0
	v_mov_b64_e32 v[30:31], 0
	v_mov_b64_e32 v[40:41], 0
	v_mov_b64_e32 v[42:43], 0
	v_mov_b64_e32 v[44:45], 0
	v_mov_b64_e32 v[46:47], 0
	v_mov_b64_e32 v[56:57], 0
	v_mov_b64_e32 v[58:59], 0
	v_mov_b64_e32 v[60:61], 0
	v_mov_b64_e32 v[62:63], 0
	v_mov_b64_e32 v[64:65], 0
	v_mov_b64_e32 v[66:67], 0
	v_mov_b64_e32 v[68:69], 0
	v_mov_b64_e32 v[70:71], 0
	v_mov_b64_e32 v[80:81], 0
	v_mov_b64_e32 v[82:83], 0
	v_mov_b64_e32 v[84:85], 0
	v_mov_b64_e32 v[86:87], 0
	v_mov_b64_e32 v[112:113], 0
	v_mov_b64_e32 v[114:115], 0
	v_mov_b64_e32 v[116:117], 0
	v_mov_b64_e32 v[118:119], 0
	v_mov_b64_e32 v[128:129], 0
	v_mov_b64_e32 v[130:131], 0
	v_mov_b64_e32 v[132:133], 0
	v_mov_b64_e32 v[134:135], 0
	v_mov_b64_e32 v[72:73], 0
	v_mov_b64_e32 v[74:75], 0
	v_mov_b64_e32 v[76:77], 0
	v_mov_b64_e32 v[78:79], 0
	v_mov_b64_e32 v[96:97], 0
	v_mov_b64_e32 v[98:99], 0
	v_mov_b64_e32 v[100:101], 0
	v_mov_b64_e32 v[102:103], 0
	v_mov_b64_e32 v[120:121], 0
	v_mov_b64_e32 v[122:123], 0
	v_mov_b64_e32 v[124:125], 0
	v_mov_b64_e32 v[126:127], 0
	v_mov_b64_e32 v[140:141], 0
	v_mov_b64_e32 v[142:143], 0
	v_mov_b64_e32 v[136:137], 0
	v_mov_b64_e32 v[138:139], 0
	v_readfirstlane_b32 s99, v234
	s_nop 0
	s_lshr_b32 s99, s99, 8
	s_cmp_eq_u32 s99, 0
	s_cbranch_scc1 .Lsp_5
	s_setprio 1
; #define PG8_STAGE(bufoff, gbase, voff) do { _Pragma("unroll") for (int _i = 0; _i < 2; ++_i) \
;         __builtin_amdgcn_global_load_lds((const unsigned*)((const char*)(gbase) + (voff)[_i]), (LAS unsigned*)(lds + (bufoff) + ldsw + _i * 8192), 16, 0, ((voff) == voffA ? AUXA : 0)); } while (0)
; #define PG8_LDA(dst, b, h) do { _Pragma("unroll") for (int m = 0; m < 4; ++m) _Pragma("unroll") for (int k = 0; k < 2; ++k) dst[m][k] = *(const LAS bf16x8*)(lds + PG8_SA(b, h) + aoff + m * 2048 + k * 1024); } while (0)
; #define PG8_LDB(dst, b, h) do { _Pragma("unroll") for (int n = 0; n < 2; ++n) _Pragma("unroll") for (int k = 0; k < 2; ++k) dst[n][k] = *(const LAS bf16x8*)(lds + PG8_SB(b, h) + boff + n * 2048 + k * 1024); } while (0)
; #define PG8_MMA(ai, bj, At, Bt) do { __builtin_amdgcn_s_setprio(1); _Pragma("unroll") for (int m = 0; m < 4; ++m) _Pragma("unroll") for (int n = 0; n < 2; ++n) _Pragma("unroll") for (int k = 0; k < 2; ++k) \
;         acc[ai][bj][m][n] = __builtin_amdgcn_mfma_f32_16x16x32_bf16(Bt[n][k], At[m][k], acc[ai][bj][m][n], 0, 0, 0); __builtin_amdgcn_s_setprio(0); } while (0)
; #define PG8_WAIT_V(n) asm volatile("s_waitcnt vmcnt(" #n ")" ::: "memory")
; #define PG8_WAIT_L(n) asm volatile("s_waitcnt lgkmcnt(" #n ")" ::: "memory")
; #define PG8_BAR __builtin_amdgcn_s_barrier()
; #define PG8_SCHED __builtin_amdgcn_sched_barrier(0)
;     ...
;         for (int t = 0; t < nt; t += 2) {
;             const bool last = (t == nt - 2);
;             const char* a1 = cA + (size_t)(t + 1) * kstep;
;             const char* a2 = last ? nA : cA + (size_t)(t + 2) * kstep; const char* b2 = last ? nB : cB + (size_t)(t + 2) * kstep;
;             const char* a3 = a2 + kstep; const char* b3 = b2 + kstep;
;             PG8_LDB(B0, 0, 0); PG8_LDB(B1, 0, 1); PG8_SCHED; PG8_LDA(At, 0, 0); PG8_STAGE(PG8_SA(1, 1), a1 + hsA, voffA);
;             if (Epi::NPRE != 0 && last) { E.pre(sv, cur, wr, fr); PG8_WAIT_V(16); } else { PG8_WAIT_V(8); }
;             PG8_WAIT_L(0); PG8_BAR; PG8_MMA(0, 0, At, B0); PG8_MMA(0, 1, At, B1); PG8_BAR; PG8_SCHED;
;             PG8_LDA(At, 0, 1); PG8_STAGE(PG8_SB(0, 0), b2, voffB); PG8_STAGE(PG8_SB(0, 1), b2 + hsB, voffB); PG8_STAGE(PG8_SA(0, 0), a2, voffA);
;             if (Epi::NPRE != 0 && last) { PG8_WAIT_V(16); } else { PG8_WAIT_V(8); }
;             PG8_WAIT_L(0); PG8_BAR; PG8_MMA(1, 0, At, B0); PG8_MMA(1, 1, At, B1); PG8_BAR; PG8_SCHED;
.Lsp_5:
.LBB0_959:
	s_add_u32 s98, s28, 0xfffc0000
	s_addc_u32 s99, s29, -1
	s_mov_b32 m0, s40
	s_nop 0
	global_load_lds_dwordx4 v170, s[98:99]
	s_mov_b32 m0, s41
	s_nop 0
	global_load_lds_dwordx4 v166, s[98:99]
	ds_read_b128 v[88:91], v196
	ds_read_b128 v[92:95], v196 offset:1024
	ds_read_b128 v[104:107], v196 offset:2048
	ds_read_b128 v[108:111], v196 offset:3072
	ds_read_b128 v[144:147], v197
	ds_read_b128 v[148:151], v197 offset:1024
	ds_read_b128 v[152:155], v197 offset:2048
	ds_read_b128 v[156:159], v197 offset:3072
	s_add_i32 s51, s30, 2
	s_add_u32 s31, s28, 0xfffc0080
	s_addc_u32 s34, s29, -1
	s_cmp_eq_u32 s42, s30
	s_cselect_b32 s30, s48, s49
	s_cselect_b32 s35, s19, s34
	s_cselect_b32 s34, s21, s31
	s_cselect_b32 s31, s47, s50
	s_add_i32 m0, s5, 0xc000
	ds_read_b128 v[160:163], v198
	ds_read_b128 v[180:183], v198 offset:1024
	ds_read_b128 v[184:187], v198 offset:2048
	ds_read_b128 v[188:191], v198 offset:3072
	ds_read_b128 v[200:203], v198 offset:4096
	ds_read_b128 v[204:207], v198 offset:5120
	ds_read_b128 v[208:211], v198 offset:6144
	ds_read_b128 v[212:215], v198 offset:7168
	global_load_lds_dwordx4 v172, s[28:29]
	s_add_i32 m0, s5, 0xe000
	s_nop 0
	global_load_lds_dwordx4 v174, s[28:29]
	s_waitcnt vmcnt(8)
	s_waitcnt lgkmcnt(0)
	s_barrier
	v_mfma_f32_16x16x32_bf16 v[136:139], v[88:91], v[160:163], v[136:139]
	v_mfma_f32_16x16x32_bf16 v[140:143], v[104:107], v[160:163], v[140:143]
	v_mfma_f32_16x16x32_bf16 v[124:127], v[88:91], v[184:187], v[124:127]
	v_mfma_f32_16x16x32_bf16 v[120:123], v[104:107], v[184:187], v[120:123]
	v_mfma_f32_16x16x32_bf16 v[100:103], v[88:91], v[200:203], v[100:103]
	v_mfma_f32_16x16x32_bf16 v[96:99], v[104:107], v[200:203], v[96:99]
	v_mfma_f32_16x16x32_bf16 v[76:79], v[88:91], v[208:211], v[76:79]
	v_mfma_f32_16x16x32_bf16 v[72:75], v[104:107], v[208:211], v[72:75]
	v_mfma_f32_16x16x32_bf16 v[136:139], v[92:95], v[180:183], v[136:139]
	v_mfma_f32_16x16x32_bf16 v[140:143], v[108:111], v[180:183], v[140:143]
	v_mfma_f32_16x16x32_bf16 v[124:127], v[92:95], v[188:191], v[124:127]
	v_mfma_f32_16x16x32_bf16 v[120:123], v[108:111], v[188:191], v[120:123]
	v_mfma_f32_16x16x32_bf16 v[100:103], v[92:95], v[204:207], v[100:103]
	v_mfma_f32_16x16x32_bf16 v[96:99], v[108:111], v[204:207], v[96:99]
	v_mfma_f32_16x16x32_bf16 v[76:79], v[92:95], v[212:215], v[76:79]
	v_mfma_f32_16x16x32_bf16 v[72:75], v[108:111], v[212:215], v[72:75]
	v_mfma_f32_16x16x32_bf16 v[132:135], v[144:147], v[160:163], v[132:135]
	v_mfma_f32_16x16x32_bf16 v[128:131], v[152:155], v[160:163], v[128:131]
	v_mfma_f32_16x16x32_bf16 v[116:119], v[144:147], v[184:187], v[116:119]
	v_mfma_f32_16x16x32_bf16 v[112:115], v[152:155], v[184:187], v[112:115]
	v_mfma_f32_16x16x32_bf16 v[84:87], v[144:147], v[200:203], v[84:87]
	v_mfma_f32_16x16x32_bf16 v[80:83], v[152:155], v[200:203], v[80:83]
	v_mfma_f32_16x16x32_bf16 v[68:71], v[144:147], v[208:211], v[68:71]
	v_mfma_f32_16x16x32_bf16 v[64:67], v[152:155], v[208:211], v[64:67]
	v_mfma_f32_16x16x32_bf16 v[132:135], v[148:151], v[180:183], v[132:135]
	v_mfma_f32_16x16x32_bf16 v[128:131], v[156:159], v[180:183], v[128:131]
	v_mfma_f32_16x16x32_bf16 v[116:119], v[148:151], v[188:191], v[116:119]
	v_mfma_f32_16x16x32_bf16 v[112:115], v[156:159], v[188:191], v[112:115]
	v_mfma_f32_16x16x32_bf16 v[84:87], v[148:151], v[204:207], v[84:87]
	v_mfma_f32_16x16x32_bf16 v[80:83], v[156:159], v[204:207], v[80:83]
	v_mfma_f32_16x16x32_bf16 v[68:71], v[148:151], v[212:215], v[68:71]
	v_mfma_f32_16x16x32_bf16 v[64:67], v[156:159], v[212:215], v[64:67]
	s_barrier
	s_add_u32 s98, s30, s12
	s_addc_u32 s99, s31, s13
	s_add_u32 s100, s34, s12
	s_addc_u32 s101, s35, s13
	s_add_i32 s52, s44, s3
	s_mov_b32 m0, s52
	ds_read_b128 v[160:163], v198 offset:16384
	ds_read_b128 v[180:183], v198 offset:17408
	ds_read_b128 v[184:187], v198 offset:18432
	ds_read_b128 v[188:191], v198 offset:19456
	ds_read_b128 v[200:203], v198 offset:20480
	ds_read_b128 v[204:207], v198 offset:21504
	ds_read_b128 v[208:211], v198 offset:22528
	ds_read_b128 v[212:215], v198 offset:23552
	global_load_lds_dwordx4 v168, s[30:31]
	s_add_i32 m0, s52, 0x2000
	s_add_u32 s52, s30, 0x40000
	s_addc_u32 s53, s31, 0
	s_add_i32 s54, s45, s3
	global_load_lds_dwordx4 v164, s[30:31]
	s_mov_b32 m0, s54
	s_nop 0
	global_load_lds_dwordx4 v168, s[52:53]
	s_add_i32 m0, s54, 0x2000
	s_nop 0
	global_load_lds_dwordx4 v164, s[52:53]
	s_waitcnt vmcnt(6)
	s_waitcnt lgkmcnt(0)
	s_barrier
	v_mfma_f32_16x16x32_bf16 v[60:63], v[88:91], v[160:163], v[60:63]
	v_mfma_f32_16x16x32_bf16 v[56:59], v[104:107], v[160:163], v[56:59]
	v_mfma_f32_16x16x32_bf16 v[44:47], v[88:91], v[184:187], v[44:47]
	v_mfma_f32_16x16x32_bf16 v[40:43], v[104:107], v[184:187], v[40:43]
	v_mfma_f32_16x16x32_bf16 v[28:31], v[88:91], v[200:203], v[28:31]
	v_mfma_f32_16x16x32_bf16 v[24:27], v[104:107], v[200:203], v[24:27]
	v_mfma_f32_16x16x32_bf16 v[12:15], v[88:91], v[208:211], v[12:15]
	v_mfma_f32_16x16x32_bf16 v[8:11], v[104:107], v[208:211], v[8:11]
	v_mfma_f32_16x16x32_bf16 v[60:63], v[92:95], v[180:183], v[60:63]
	v_mfma_f32_16x16x32_bf16 v[56:59], v[108:111], v[180:183], v[56:59]
	v_mfma_f32_16x16x32_bf16 v[44:47], v[92:95], v[188:191], v[44:47]
	v_mfma_f32_16x16x32_bf16 v[40:43], v[108:111], v[188:191], v[40:43]
	v_mfma_f32_16x16x32_bf16 v[28:31], v[92:95], v[204:207], v[28:31]
	v_mfma_f32_16x16x32_bf16 v[24:27], v[108:111], v[204:207], v[24:27]
	v_mfma_f32_16x16x32_bf16 v[12:15], v[92:95], v[212:215], v[12:15]
	v_mfma_f32_16x16x32_bf16 v[8:11], v[108:111], v[212:215], v[8:11]
	v_mfma_f32_16x16x32_bf16 v[52:55], v[144:147], v[160:163], v[52:55]
	v_mfma_f32_16x16x32_bf16 v[48:51], v[152:155], v[160:163], v[48:51]
	v_mfma_f32_16x16x32_bf16 v[36:39], v[144:147], v[184:187], v[36:39]
	v_mfma_f32_16x16x32_bf16 v[32:35], v[152:155], v[184:187], v[32:35]
	v_mfma_f32_16x16x32_bf16 v[20:23], v[144:147], v[200:203], v[20:23]
	v_mfma_f32_16x16x32_bf16 v[16:19], v[152:155], v[200:203], v[16:19]
	v_mfma_f32_16x16x32_bf16 v[4:7], v[144:147], v[208:211], v[4:7]
	v_mfma_f32_16x16x32_bf16 v[0:3], v[152:155], v[208:211], v[0:3]
	v_mfma_f32_16x16x32_bf16 v[52:55], v[148:151], v[180:183], v[52:55]
	v_mfma_f32_16x16x32_bf16 v[48:51], v[156:159], v[180:183], v[48:51]
	v_mfma_f32_16x16x32_bf16 v[36:39], v[148:151], v[188:191], v[36:39]
	v_mfma_f32_16x16x32_bf16 v[32:35], v[156:159], v[188:191], v[32:35]
	v_mfma_f32_16x16x32_bf16 v[20:23], v[148:151], v[204:207], v[20:23]
	v_mfma_f32_16x16x32_bf16 v[16:19], v[156:159], v[204:207], v[16:19]
	v_mfma_f32_16x16x32_bf16 v[4:7], v[148:151], v[212:215], v[4:7]
	v_mfma_f32_16x16x32_bf16 v[0:3], v[156:159], v[212:215], v[0:3]
	s_barrier
; #define PG8_STAGE(bufoff, gbase, voff) do { _Pragma("unroll") for (int _i = 0; _i < 2; ++_i) \
;         __builtin_amdgcn_global_load_lds((const unsigned*)((const char*)(gbase) + (voff)[_i]), (LAS unsigned*)(lds + (bufoff) + ldsw + _i * 8192), 16, 0, ((voff) == voffA ? AUXA : 0)); } while (0)
; #define PG8_LDA(dst, b, h) do { _Pragma("unroll") for (int m = 0; m < 4; ++m) _Pragma("unroll") for (int k = 0; k < 2; ++k) dst[m][k] = *(const LAS bf16x8*)(lds + PG8_SA(b, h) + aoff + m * 2048 + k * 1024); } while (0)
; #define PG8_LDB(dst, b, h) do { _Pragma("unroll") for (int n = 0; n < 2; ++n) _Pragma("unroll") for (int k = 0; k < 2; ++k) dst[n][k] = *(const LAS bf16x8*)(lds + PG8_SB(b, h) + boff + n * 2048 + k * 1024); } while (0)
; #define PG8_MMA(ai, bj, At, Bt) do { __builtin_amdgcn_s_setprio(1); _Pragma("unroll") for (int m = 0; m < 4; ++m) _Pragma("unroll") for (int n = 0; n < 2; ++n) _Pragma("unroll") for (int k = 0; k < 2; ++k) \
;         acc[ai][bj][m][n] = __builtin_amdgcn_mfma_f32_16x16x32_bf16(Bt[n][k], At[m][k], acc[ai][bj][m][n], 0, 0, 0); __builtin_amdgcn_s_setprio(0); } while (0)
; #define PG8_WAIT_V(n) asm volatile("s_waitcnt vmcnt(" #n ")" ::: "memory")
; #define PG8_WAIT_L(n) asm volatile("s_waitcnt lgkmcnt(" #n ")" ::: "memory")
; #define PG8_BAR __builtin_amdgcn_s_barrier()
; #define PG8_SCHED __builtin_amdgcn_sched_barrier(0)
;     ...
;             PG8_LDB(B0, 1, 0); PG8_LDB(B1, 1, 1); PG8_SCHED; PG8_LDA(At, 1, 0); PG8_STAGE(PG8_SA(0, 1), a2 + hsA, voffA);
;             PG8_WAIT_V(8); PG8_WAIT_L(0); PG8_BAR; PG8_MMA(0, 0, At, B0); PG8_MMA(0, 1, At, B1); PG8_BAR; PG8_SCHED;
;             PG8_LDA(At, 1, 1); PG8_STAGE(PG8_SB(1, 0), b3, voffB); PG8_STAGE(PG8_SB(1, 1), b3 + hsB, voffB); PG8_STAGE(PG8_SA(1, 0), a3, voffA);
;             PG8_WAIT_V(8); PG8_WAIT_L(0); PG8_BAR; PG8_MMA(1, 0, At, B0); PG8_MMA(1, 1, At, B1); PG8_BAR; PG8_SCHED;
;         }
	s_mov_b32 m0, s5
	s_nop 0
	global_load_lds_dwordx4 v170, s[34:35]
	s_mov_b32 m0, s27
	s_nop 0
	global_load_lds_dwordx4 v166, s[34:35]
	s_add_i32 s52, 0, 0x18000
	s_add_i32 s53, 0, 0x1c000
	v_add_u32_e32 v108, s52, v194
	v_add_u32_e32 v156, s53, v194
	ds_read_b128 v[88:91], v108
	ds_read_b128 v[92:95], v108 offset:1024
	ds_read_b128 v[104:107], v108 offset:2048
	ds_read_b128 v[108:111], v108 offset:3072
	ds_read_b128 v[144:147], v156
	ds_read_b128 v[148:151], v156 offset:1024
	ds_read_b128 v[152:155], v156 offset:2048
	ds_read_b128 v[156:159], v156 offset:3072
	s_add_u32 s34, s34, 0x40000
	s_addc_u32 s35, s35, 0
	s_mov_b32 m0, s36
	ds_read_b128 v[160:163], v198 offset:32768
	ds_read_b128 v[180:183], v198 offset:33792
	ds_read_b128 v[184:187], v198 offset:34816
	ds_read_b128 v[188:191], v198 offset:35840
	ds_read_b128 v[200:203], v198 offset:36864
	ds_read_b128 v[204:207], v198 offset:37888
	ds_read_b128 v[208:211], v198 offset:38912
	ds_read_b128 v[212:215], v198 offset:39936
	global_load_lds_dwordx4 v170, s[34:35]
	s_mov_b32 m0, s37
	s_nop 0
	global_load_lds_dwordx4 v166, s[34:35]
	s_waitcnt vmcnt(8)
	s_waitcnt lgkmcnt(0)
	s_barrier
	v_mfma_f32_16x16x32_bf16 v[136:139], v[88:91], v[160:163], v[136:139]
	v_mfma_f32_16x16x32_bf16 v[140:143], v[104:107], v[160:163], v[140:143]
	v_mfma_f32_16x16x32_bf16 v[124:127], v[88:91], v[184:187], v[124:127]
	v_mfma_f32_16x16x32_bf16 v[120:123], v[104:107], v[184:187], v[120:123]
	v_mfma_f32_16x16x32_bf16 v[100:103], v[88:91], v[200:203], v[100:103]
	v_mfma_f32_16x16x32_bf16 v[96:99], v[104:107], v[200:203], v[96:99]
	v_mfma_f32_16x16x32_bf16 v[76:79], v[88:91], v[208:211], v[76:79]
	v_mfma_f32_16x16x32_bf16 v[72:75], v[104:107], v[208:211], v[72:75]
	v_mfma_f32_16x16x32_bf16 v[136:139], v[92:95], v[180:183], v[136:139]
	v_mfma_f32_16x16x32_bf16 v[140:143], v[108:111], v[180:183], v[140:143]
	v_mfma_f32_16x16x32_bf16 v[124:127], v[92:95], v[188:191], v[124:127]
	v_mfma_f32_16x16x32_bf16 v[120:123], v[108:111], v[188:191], v[120:123]
	v_mfma_f32_16x16x32_bf16 v[100:103], v[92:95], v[204:207], v[100:103]
	v_mfma_f32_16x16x32_bf16 v[96:99], v[108:111], v[204:207], v[96:99]
	v_mfma_f32_16x16x32_bf16 v[76:79], v[92:95], v[212:215], v[76:79]
	v_mfma_f32_16x16x32_bf16 v[72:75], v[108:111], v[212:215], v[72:75]
	v_mfma_f32_16x16x32_bf16 v[132:135], v[144:147], v[160:163], v[132:135]
	v_mfma_f32_16x16x32_bf16 v[128:131], v[152:155], v[160:163], v[128:131]
	v_mfma_f32_16x16x32_bf16 v[116:119], v[144:147], v[184:187], v[116:119]
	v_mfma_f32_16x16x32_bf16 v[112:115], v[152:155], v[184:187], v[112:115]
	v_mfma_f32_16x16x32_bf16 v[84:87], v[144:147], v[200:203], v[84:87]
	v_mfma_f32_16x16x32_bf16 v[80:83], v[152:155], v[200:203], v[80:83]
	v_mfma_f32_16x16x32_bf16 v[68:71], v[144:147], v[208:211], v[68:71]
	v_mfma_f32_16x16x32_bf16 v[64:67], v[152:155], v[208:211], v[64:67]
	v_mfma_f32_16x16x32_bf16 v[132:135], v[148:151], v[180:183], v[132:135]
	v_mfma_f32_16x16x32_bf16 v[128:131], v[156:159], v[180:183], v[128:131]
	v_mfma_f32_16x16x32_bf16 v[116:119], v[148:151], v[188:191], v[116:119]
	v_mfma_f32_16x16x32_bf16 v[112:115], v[156:159], v[188:191], v[112:115]
	v_mfma_f32_16x16x32_bf16 v[84:87], v[148:151], v[204:207], v[84:87]
	v_mfma_f32_16x16x32_bf16 v[80:83], v[156:159], v[204:207], v[80:83]
	v_mfma_f32_16x16x32_bf16 v[68:71], v[148:151], v[212:215], v[68:71]
	v_mfma_f32_16x16x32_bf16 v[64:67], v[156:159], v[212:215], v[64:67]
	s_barrier
	s_add_i32 s34, s52, s3
	s_mov_b32 m0, s34
	ds_read_b128 v[160:163], v198 offset:49152
	ds_read_b128 v[180:183], v198 offset:50176
	ds_read_b128 v[184:187], v198 offset:51200
	ds_read_b128 v[188:191], v198 offset:52224
	ds_read_b128 v[200:203], v198 offset:53248
	ds_read_b128 v[204:207], v198 offset:54272
	ds_read_b128 v[208:211], v198 offset:55296
	ds_read_b128 v[212:215], v198 offset:56320
	global_load_lds_dwordx4 v168, s[98:99]
	s_add_i32 m0, s34, 0x2000
	s_add_u32 s30, s30, 0x40080
	s_addc_u32 s31, s31, 0
	s_add_i32 s34, s53, s3
	global_load_lds_dwordx4 v164, s[98:99]
	s_mov_b32 m0, s34
	s_nop 0
	global_load_lds_dwordx4 v168, s[30:31]
	s_add_i32 m0, s34, 0x2000
	s_nop 0
	global_load_lds_dwordx4 v164, s[30:31]
	s_waitcnt vmcnt(6)
	s_waitcnt lgkmcnt(0)
	s_barrier
	v_mfma_f32_16x16x32_bf16 v[60:63], v[88:91], v[160:163], v[60:63]
	v_mfma_f32_16x16x32_bf16 v[56:59], v[104:107], v[160:163], v[56:59]
	v_mfma_f32_16x16x32_bf16 v[44:47], v[88:91], v[184:187], v[44:47]
	v_mfma_f32_16x16x32_bf16 v[40:43], v[104:107], v[184:187], v[40:43]
	v_mfma_f32_16x16x32_bf16 v[28:31], v[88:91], v[200:203], v[28:31]
	v_mfma_f32_16x16x32_bf16 v[24:27], v[104:107], v[200:203], v[24:27]
	v_mfma_f32_16x16x32_bf16 v[12:15], v[88:91], v[208:211], v[12:15]
	v_mfma_f32_16x16x32_bf16 v[8:11], v[104:107], v[208:211], v[8:11]
	v_mfma_f32_16x16x32_bf16 v[60:63], v[92:95], v[180:183], v[60:63]
	v_mfma_f32_16x16x32_bf16 v[56:59], v[108:111], v[180:183], v[56:59]
	v_mfma_f32_16x16x32_bf16 v[44:47], v[92:95], v[188:191], v[44:47]
	v_mfma_f32_16x16x32_bf16 v[40:43], v[108:111], v[188:191], v[40:43]
	v_mfma_f32_16x16x32_bf16 v[28:31], v[92:95], v[204:207], v[28:31]
	v_mfma_f32_16x16x32_bf16 v[24:27], v[108:111], v[204:207], v[24:27]
	v_mfma_f32_16x16x32_bf16 v[12:15], v[92:95], v[212:215], v[12:15]
	v_mfma_f32_16x16x32_bf16 v[8:11], v[108:111], v[212:215], v[8:11]
	v_mfma_f32_16x16x32_bf16 v[52:55], v[144:147], v[160:163], v[52:55]
	v_mfma_f32_16x16x32_bf16 v[48:51], v[152:155], v[160:163], v[48:51]
	v_mfma_f32_16x16x32_bf16 v[36:39], v[144:147], v[184:187], v[36:39]
	v_mfma_f32_16x16x32_bf16 v[32:35], v[152:155], v[184:187], v[32:35]
	v_mfma_f32_16x16x32_bf16 v[20:23], v[144:147], v[200:203], v[20:23]
	v_mfma_f32_16x16x32_bf16 v[16:19], v[152:155], v[200:203], v[16:19]
	v_mfma_f32_16x16x32_bf16 v[4:7], v[144:147], v[208:211], v[4:7]
	v_mfma_f32_16x16x32_bf16 v[0:3], v[152:155], v[208:211], v[0:3]
	v_mfma_f32_16x16x32_bf16 v[52:55], v[148:151], v[180:183], v[52:55]
	v_mfma_f32_16x16x32_bf16 v[48:51], v[156:159], v[180:183], v[48:51]
	v_mfma_f32_16x16x32_bf16 v[36:39], v[148:151], v[188:191], v[36:39]
	v_mfma_f32_16x16x32_bf16 v[32:35], v[156:159], v[188:191], v[32:35]
	v_mfma_f32_16x16x32_bf16 v[20:23], v[148:151], v[204:207], v[20:23]
	v_mfma_f32_16x16x32_bf16 v[16:19], v[156:159], v[204:207], v[16:19]
	v_mfma_f32_16x16x32_bf16 v[4:7], v[148:151], v[212:215], v[4:7]
	v_mfma_f32_16x16x32_bf16 v[0:3], v[156:159], v[212:215], v[0:3]
	s_barrier
	s_add_u32 s28, s28, 0x100
	s_addc_u32 s29, s29, 0
	s_add_u32 s49, s49, 0x100
	s_addc_u32 s50, s50, 0
	s_cmp_ge_i32 s51, s39
	s_mov_b32 s30, s51
	s_cbranch_scc0 .LBB0_959
	s_setprio 0

; #define PG8_STAGE(bufoff, gbase, voff) do { _Pragma("unroll") for (int _i = 0; _i < 2; ++_i) \
;         __builtin_amdgcn_global_load_lds((const unsigned*)((const char*)(gbase) + (voff)[_i]), (LAS unsigned*)(lds + (bufoff) + ldsw + _i * 8192), 16, 0, ((voff) == voffA ? AUXA : 0)); } while (0)
; #define PG8_LDA(dst, b, h) do { _Pragma("unroll") for (int m = 0; m < 4; ++m) _Pragma("unroll") for (int k = 0; k < 2; ++k) dst[m][k] = *(const LAS bf16x8*)(lds + PG8_SA(b, h) + aoff + m * 2048 + k * 1024); } while (0)
; #define PG8_LDB(dst, b, h) do { _Pragma("unroll") for (int n = 0; n < 2; ++n) _Pragma("unroll") for (int k = 0; k < 2; ++k) dst[n][k] = *(const LAS bf16x8*)(lds + PG8_SB(b, h) + boff + n * 2048 + k * 1024); } while (0)
; #define PG8_MMA(ai, bj, At, Bt) do { __builtin_amdgcn_s_setprio(1); _Pragma("unroll") for (int m = 0; m < 4; ++m) _Pragma("unroll") for (int n = 0; n < 2; ++n) _Pragma("unroll") for (int k = 0; k < 2; ++k) \
;         acc[ai][bj][m][n] = __builtin_amdgcn_mfma_f32_16x16x32_bf16(Bt[n][k], At[m][k], acc[ai][bj][m][n], 0, 0, 0); __builtin_amdgcn_s_setprio(0); } while (0)
; #define PG8_WAIT_V(n) asm volatile("s_waitcnt vmcnt(" #n ")" ::: "memory")
; #define PG8_WAIT_L(n) asm volatile("s_waitcnt lgkmcnt(" #n ")" ::: "memory")
; #define PG8_BAR __builtin_amdgcn_s_barrier()
; #define PG8_SCHED __builtin_amdgcn_sched_barrier(0)
;     ...
;         for (int t = 0; t < nt; t += 2) {
;             const bool last = (t == nt - 2);
;             const char* a1 = cA + (size_t)(t + 1) * kstep;
;             const char* a2 = last ? nA : cA + (size_t)(t + 2) * kstep; const char* b2 = last ? nB : cB + (size_t)(t + 2) * kstep;
;             const char* a3 = a2 + kstep; const char* b3 = b2 + kstep;
;             PG8_LDB(B0, 0, 0); PG8_LDB(B1, 0, 1); PG8_SCHED; PG8_LDA(At, 0, 0); PG8_STAGE(PG8_SA(1, 1), a1 + hsA, voffA);
;             if (Epi::NPRE != 0 && last) { E.pre(sv, cur, wr, fr); PG8_WAIT_V(16); } else { PG8_WAIT_V(8); }
;             PG8_WAIT_L(0); PG8_BAR; PG8_MMA(0, 0, At, B0); PG8_MMA(0, 1, At, B1); PG8_BAR; PG8_SCHED;
;     ...
; #pragma unroll
;         for (int a = 0; a < 2; ++a)
; #pragma unroll
;             for (int b = 0; b < 2; ++b)
; #pragma unroll
;                 for (int m = 0; m < 4; ++m)
; #pragma unroll
;                     for (int n = 0; n < 2; ++n) acc[a][b][m][n] = (f32x4){0.f, 0.f, 0.f, 0.f};
;         cur = nxt; cA = nA; cB = nB; ++ui;
.LBB0_1038:
	s_ashr_i32 s23, s22, 31
	s_lshl_b64 s[24:25], s[22:23], 19
	s_add_u32 s24, s3, s24
	s_addc_u32 s25, s4, s25
	s_ashr_i32 s21, s20, 31
	s_lshl_b64 s[26:27], s[20:21], 19
	s_add_u32 s26, s5, s26
	v_mov_b32_e32 v127, 0
	s_addc_u32 s27, s36, s27
	s_and_b64 vcc, exec, s[0:1]
	v_mov_b32_e32 v126, 0
	v_mov_b64_e32 v[124:125], 0
	v_mov_b64_e32 v[122:123], 0
	v_mov_b64_e32 v[120:121], 0
	v_mov_b64_e32 v[110:111], 0
	v_mov_b64_e32 v[108:109], 0
	v_mov_b64_e32 v[106:107], 0
	v_mov_b64_e32 v[104:105], 0
	v_mov_b64_e32 v[94:95], 0
	v_mov_b64_e32 v[92:93], 0
	v_mov_b64_e32 v[90:91], 0
	v_mov_b64_e32 v[88:89], 0
	v_mov_b64_e32 v[78:79], 0
	v_mov_b64_e32 v[76:77], 0
	v_mov_b64_e32 v[74:75], 0
	v_mov_b64_e32 v[72:73], 0
	v_mov_b64_e32 v[118:119], 0
	v_mov_b64_e32 v[116:117], 0
	v_mov_b64_e32 v[114:115], 0
	v_mov_b64_e32 v[112:113], 0
	v_mov_b64_e32 v[102:103], 0
	v_mov_b64_e32 v[100:101], 0
	v_mov_b64_e32 v[98:99], 0
	v_mov_b64_e32 v[96:97], 0
	v_mov_b64_e32 v[86:87], 0
	v_mov_b64_e32 v[84:85], 0
	v_mov_b64_e32 v[82:83], 0
	v_mov_b64_e32 v[80:81], 0
	v_mov_b64_e32 v[70:71], 0
	v_mov_b64_e32 v[68:69], 0
	v_mov_b64_e32 v[66:67], 0
	v_mov_b64_e32 v[64:65], 0
	v_mov_b64_e32 v[62:63], 0
	v_mov_b64_e32 v[60:61], 0
	v_mov_b64_e32 v[58:59], 0
	v_mov_b64_e32 v[56:57], 0
	v_mov_b64_e32 v[46:47], 0
	v_mov_b64_e32 v[44:45], 0
	v_mov_b64_e32 v[42:43], 0
	v_mov_b64_e32 v[40:41], 0
	v_mov_b64_e32 v[30:31], 0
	v_mov_b64_e32 v[28:29], 0
	v_mov_b64_e32 v[26:27], 0
	v_mov_b64_e32 v[24:25], 0
	v_mov_b64_e32 v[14:15], 0
	v_mov_b64_e32 v[12:13], 0
	v_mov_b64_e32 v[10:11], 0
	v_mov_b64_e32 v[8:9], 0
	v_mov_b64_e32 v[54:55], 0
	v_mov_b64_e32 v[52:53], 0
	v_mov_b64_e32 v[50:51], 0
	v_mov_b64_e32 v[48:49], 0
	v_mov_b64_e32 v[38:39], 0
	v_mov_b64_e32 v[36:37], 0
	v_mov_b64_e32 v[34:35], 0
	v_mov_b64_e32 v[32:33], 0
	v_mov_b64_e32 v[22:23], 0
	v_mov_b64_e32 v[20:21], 0
	v_mov_b64_e32 v[18:19], 0
	v_mov_b64_e32 v[16:17], 0
	v_mov_b64_e32 v[6:7], 0
	v_mov_b64_e32 v[4:5], 0
	v_mov_b64_e32 v[2:3], 0
	v_mov_b64_e32 v[0:1], 0
	s_cbranch_vccnz .LBB0_1041
	s_and_b64 s[34:35], s[6:7], exec
	s_cselect_b32 s21, s25, s29
	s_cselect_b32 s23, s24, s28
	s_cselect_b32 s52, s27, s31
	s_cselect_b32 s53, s26, s30
	s_add_u32 s28, s28, 0x40080
	s_addc_u32 s29, s29, 0
	s_add_u32 s54, s30, 0x100
	v_mov_b32_e32 v0, 0
	s_addc_u32 s55, s31, 0
	s_mov_b32 s30, 0
	v_mov_b32_e32 v1, 0
	v_mov_b64_e32 v[2:3], 0
	v_mov_b64_e32 v[4:5], 0
	v_mov_b64_e32 v[6:7], 0
	v_mov_b64_e32 v[16:17], 0
	v_mov_b64_e32 v[18:19], 0
	v_mov_b64_e32 v[20:21], 0
	v_mov_b64_e32 v[22:23], 0
	v_mov_b64_e32 v[32:33], 0
	v_mov_b64_e32 v[34:35], 0
	v_mov_b64_e32 v[36:37], 0
	v_mov_b64_e32 v[38:39], 0
	v_mov_b64_e32 v[48:49], 0
	v_mov_b64_e32 v[50:51], 0
	v_mov_b64_e32 v[52:53], 0
	v_mov_b64_e32 v[54:55], 0
	v_mov_b64_e32 v[8:9], 0
	v_mov_b64_e32 v[10:11], 0
	v_mov_b64_e32 v[12:13], 0
	v_mov_b64_e32 v[14:15], 0
	v_mov_b64_e32 v[24:25], 0
	v_mov_b64_e32 v[26:27], 0
	v_mov_b64_e32 v[28:29], 0
	v_mov_b64_e32 v[30:31], 0
	v_mov_b64_e32 v[40:41], 0
	v_mov_b64_e32 v[42:43], 0
	v_mov_b64_e32 v[44:45], 0
	v_mov_b64_e32 v[46:47], 0
	v_mov_b64_e32 v[56:57], 0
	v_mov_b64_e32 v[58:59], 0
	v_mov_b64_e32 v[60:61], 0
	v_mov_b64_e32 v[62:63], 0
	v_mov_b64_e32 v[64:65], 0
	v_mov_b64_e32 v[66:67], 0
	v_mov_b64_e32 v[68:69], 0
	v_mov_b64_e32 v[70:71], 0
	v_mov_b64_e32 v[80:81], 0
	v_mov_b64_e32 v[82:83], 0
	v_mov_b64_e32 v[84:85], 0
	v_mov_b64_e32 v[86:87], 0
	v_mov_b64_e32 v[96:97], 0
	v_mov_b64_e32 v[98:99], 0
	v_mov_b64_e32 v[100:101], 0
	v_mov_b64_e32 v[102:103], 0
	v_mov_b64_e32 v[112:113], 0
	v_mov_b64_e32 v[114:115], 0
	v_mov_b64_e32 v[116:117], 0
	v_mov_b64_e32 v[118:119], 0
	v_mov_b64_e32 v[72:73], 0
	v_mov_b64_e32 v[74:75], 0
	v_mov_b64_e32 v[76:77], 0
	v_mov_b64_e32 v[78:79], 0
	v_mov_b64_e32 v[88:89], 0
	v_mov_b64_e32 v[90:91], 0
	v_mov_b64_e32 v[92:93], 0
	v_mov_b64_e32 v[94:95], 0
	v_mov_b64_e32 v[104:105], 0
	v_mov_b64_e32 v[106:107], 0
	v_mov_b64_e32 v[108:109], 0
	v_mov_b64_e32 v[110:111], 0
	v_mov_b64_e32 v[120:121], 0
	v_mov_b64_e32 v[122:123], 0
	v_mov_b64_e32 v[124:125], 0
	v_mov_b64_e32 v[126:127], 0
	v_readfirstlane_b32 s99, v234
	s_nop 0
	s_lshr_b32 s99, s99, 8
	s_cmp_eq_u32 s99, 0
	s_cbranch_scc1 .Lsp_6
	s_setprio 1
.Lsp_6:
.LBB0_1040:
	s_add_u32 s98, s28, 0xfffc0000
	s_addc_u32 s99, s29, -1
	s_mov_b32 m0, s45
	s_nop 0
	global_load_lds_dwordx4 v134, s[98:99]
	s_mov_b32 m0, s46
	s_nop 0
	global_load_lds_dwordx4 v130, s[98:99]
	ds_read_b128 v[150:153], v147
	ds_read_b128 v[154:157], v147 offset:1024
	ds_read_b128 v[158:161], v147 offset:2048
	ds_read_b128 v[162:165], v147 offset:3072
	ds_read_b128 v[166:169], v148
	ds_read_b128 v[170:173], v148 offset:1024
	ds_read_b128 v[174:177], v148 offset:2048
	ds_read_b128 v[178:181], v148 offset:3072
	s_add_i32 s56, s30, 2
	s_add_u32 s31, s28, 0xfffc0080
	s_addc_u32 s34, s29, -1
	s_cmp_eq_u32 s47, s30
	s_cselect_b32 s30, s53, s54
	s_cselect_b32 s35, s21, s34
	s_cselect_b32 s34, s23, s31
	s_cselect_b32 s31, s52, s55
	s_add_i32 m0, s19, 0xc000
	ds_read_b128 v[182:185], v149
	ds_read_b128 v[186:189], v149 offset:1024
	ds_read_b128 v[190:193], v149 offset:2048
	ds_read_b128 v[194:197], v149 offset:3072
	ds_read_b128 v[198:201], v149 offset:4096
	ds_read_b128 v[202:205], v149 offset:5120
	ds_read_b128 v[206:209], v149 offset:6144
	ds_read_b128 v[210:213], v149 offset:7168
	global_load_lds_dwordx4 v136, s[28:29]
	s_add_i32 m0, s19, 0xe000
	s_nop 0
	global_load_lds_dwordx4 v138, s[28:29]
	s_waitcnt vmcnt(8)
	s_waitcnt lgkmcnt(0)
	s_barrier
; #define PG8_STAGE(bufoff, gbase, voff) do { _Pragma("unroll") for (int _i = 0; _i < 2; ++_i) \
;         __builtin_amdgcn_global_load_lds((const unsigned*)((const char*)(gbase) + (voff)[_i]), (LAS unsigned*)(lds + (bufoff) + ldsw + _i * 8192), 16, 0, ((voff) == voffA ? AUXA : 0)); } while (0)
; #define PG8_LDA(dst, b, h) do { _Pragma("unroll") for (int m = 0; m < 4; ++m) _Pragma("unroll") for (int k = 0; k < 2; ++k) dst[m][k] = *(const LAS bf16x8*)(lds + PG8_SA(b, h) + aoff + m * 2048 + k * 1024); } while (0)
; #define PG8_MMA(ai, bj, At, Bt) do { __builtin_amdgcn_s_setprio(1); _Pragma("unroll") for (int m = 0; m < 4; ++m) _Pragma("unroll") for (int n = 0; n < 2; ++n) _Pragma("unroll") for (int k = 0; k < 2; ++k) \
;         acc[ai][bj][m][n] = __builtin_amdgcn_mfma_f32_16x16x32_bf16(Bt[n][k], At[m][k], acc[ai][bj][m][n], 0, 0, 0); __builtin_amdgcn_s_setprio(0); } while (0)
; #define PG8_WAIT_V(n) asm volatile("s_waitcnt vmcnt(" #n ")" ::: "memory")
; #define PG8_WAIT_L(n) asm volatile("s_waitcnt lgkmcnt(" #n ")" ::: "memory")
; #define PG8_BAR __builtin_amdgcn_s_barrier()
; #define PG8_SCHED __builtin_amdgcn_sched_barrier(0)
;     ...
;             PG8_WAIT_L(0); PG8_BAR; PG8_MMA(0, 0, At, B0); PG8_MMA(0, 1, At, B1); PG8_BAR; PG8_SCHED;
;             PG8_LDA(At, 0, 1); PG8_STAGE(PG8_SB(0, 0), b2, voffB); PG8_STAGE(PG8_SB(0, 1), b2 + hsB, voffB); PG8_STAGE(PG8_SA(0, 0), a2, voffA);
;             if (Epi::NPRE != 0 && last) { PG8_WAIT_V(16); } else { PG8_WAIT_V(8); }
;             PG8_WAIT_L(0); PG8_BAR; PG8_MMA(1, 0, At, B0); PG8_MMA(1, 1, At, B1); PG8_BAR; PG8_SCHED;
	v_mfma_f32_16x16x32_bf16 v[124:127], v[150:153], v[182:185], v[124:127]
	v_mfma_f32_16x16x32_bf16 v[120:123], v[158:161], v[182:185], v[120:123]
	v_mfma_f32_16x16x32_bf16 v[108:111], v[150:153], v[190:193], v[108:111]
	v_mfma_f32_16x16x32_bf16 v[104:107], v[158:161], v[190:193], v[104:107]
	v_mfma_f32_16x16x32_bf16 v[92:95], v[150:153], v[198:201], v[92:95]
	v_mfma_f32_16x16x32_bf16 v[88:91], v[158:161], v[198:201], v[88:91]
	v_mfma_f32_16x16x32_bf16 v[76:79], v[150:153], v[206:209], v[76:79]
	v_mfma_f32_16x16x32_bf16 v[72:75], v[158:161], v[206:209], v[72:75]
	v_mfma_f32_16x16x32_bf16 v[124:127], v[154:157], v[186:189], v[124:127]
	v_mfma_f32_16x16x32_bf16 v[120:123], v[162:165], v[186:189], v[120:123]
	v_mfma_f32_16x16x32_bf16 v[108:111], v[154:157], v[194:197], v[108:111]
	v_mfma_f32_16x16x32_bf16 v[104:107], v[162:165], v[194:197], v[104:107]
	v_mfma_f32_16x16x32_bf16 v[92:95], v[154:157], v[202:205], v[92:95]
	v_mfma_f32_16x16x32_bf16 v[88:91], v[162:165], v[202:205], v[88:91]
	v_mfma_f32_16x16x32_bf16 v[76:79], v[154:157], v[210:213], v[76:79]
	v_mfma_f32_16x16x32_bf16 v[72:75], v[162:165], v[210:213], v[72:75]
	v_mfma_f32_16x16x32_bf16 v[116:119], v[166:169], v[182:185], v[116:119]
	v_mfma_f32_16x16x32_bf16 v[112:115], v[174:177], v[182:185], v[112:115]
	v_mfma_f32_16x16x32_bf16 v[100:103], v[166:169], v[190:193], v[100:103]
	v_mfma_f32_16x16x32_bf16 v[96:99], v[174:177], v[190:193], v[96:99]
	v_mfma_f32_16x16x32_bf16 v[84:87], v[166:169], v[198:201], v[84:87]
	v_mfma_f32_16x16x32_bf16 v[80:83], v[174:177], v[198:201], v[80:83]
	v_mfma_f32_16x16x32_bf16 v[68:71], v[166:169], v[206:209], v[68:71]
	v_mfma_f32_16x16x32_bf16 v[64:67], v[174:177], v[206:209], v[64:67]
	v_mfma_f32_16x16x32_bf16 v[116:119], v[170:173], v[186:189], v[116:119]
	v_mfma_f32_16x16x32_bf16 v[112:115], v[178:181], v[186:189], v[112:115]
	v_mfma_f32_16x16x32_bf16 v[100:103], v[170:173], v[194:197], v[100:103]
	v_mfma_f32_16x16x32_bf16 v[96:99], v[178:181], v[194:197], v[96:99]
	v_mfma_f32_16x16x32_bf16 v[84:87], v[170:173], v[202:205], v[84:87]
	v_mfma_f32_16x16x32_bf16 v[80:83], v[178:181], v[202:205], v[80:83]
	v_mfma_f32_16x16x32_bf16 v[68:71], v[170:173], v[210:213], v[68:71]
	v_mfma_f32_16x16x32_bf16 v[64:67], v[178:181], v[210:213], v[64:67]
	s_barrier
	s_add_u32 s98, s30, s14
	s_addc_u32 s99, s31, s15
	s_add_u32 s100, s34, s14
	s_addc_u32 s101, s35, s15
	s_add_i32 s57, s49, s37
	s_mov_b32 m0, s57
	ds_read_b128 v[182:185], v149 offset:16384
	ds_read_b128 v[186:189], v149 offset:17408
	ds_read_b128 v[190:193], v149 offset:18432
	ds_read_b128 v[194:197], v149 offset:19456
	ds_read_b128 v[198:201], v149 offset:20480
	ds_read_b128 v[202:205], v149 offset:21504
	ds_read_b128 v[206:209], v149 offset:22528
	ds_read_b128 v[210:213], v149 offset:23552
	global_load_lds_dwordx4 v132, s[30:31]
	s_add_i32 m0, s57, 0x2000
	s_add_u32 s58, s30, 0x40000
	s_addc_u32 s59, s31, 0
	s_add_i32 s57, s50, s37
	global_load_lds_dwordx4 v128, s[30:31]
	s_mov_b32 m0, s57
	s_nop 0
	global_load_lds_dwordx4 v132, s[58:59]
	s_add_i32 m0, s57, 0x2000
	s_nop 0
	global_load_lds_dwordx4 v128, s[58:59]
	s_waitcnt vmcnt(6)
	s_waitcnt lgkmcnt(0)
	s_barrier
	v_mfma_f32_16x16x32_bf16 v[60:63], v[150:153], v[182:185], v[60:63]
	v_mfma_f32_16x16x32_bf16 v[56:59], v[158:161], v[182:185], v[56:59]
	v_mfma_f32_16x16x32_bf16 v[44:47], v[150:153], v[190:193], v[44:47]
	v_mfma_f32_16x16x32_bf16 v[40:43], v[158:161], v[190:193], v[40:43]
	v_mfma_f32_16x16x32_bf16 v[28:31], v[150:153], v[198:201], v[28:31]
	v_mfma_f32_16x16x32_bf16 v[24:27], v[158:161], v[198:201], v[24:27]
	v_mfma_f32_16x16x32_bf16 v[12:15], v[150:153], v[206:209], v[12:15]
	v_mfma_f32_16x16x32_bf16 v[8:11], v[158:161], v[206:209], v[8:11]
	v_mfma_f32_16x16x32_bf16 v[60:63], v[154:157], v[186:189], v[60:63]
	v_mfma_f32_16x16x32_bf16 v[56:59], v[162:165], v[186:189], v[56:59]
	v_mfma_f32_16x16x32_bf16 v[44:47], v[154:157], v[194:197], v[44:47]
	v_mfma_f32_16x16x32_bf16 v[40:43], v[162:165], v[194:197], v[40:43]
	v_mfma_f32_16x16x32_bf16 v[28:31], v[154:157], v[202:205], v[28:31]
	v_mfma_f32_16x16x32_bf16 v[24:27], v[162:165], v[202:205], v[24:27]
	v_mfma_f32_16x16x32_bf16 v[12:15], v[154:157], v[210:213], v[12:15]
	v_mfma_f32_16x16x32_bf16 v[8:11], v[162:165], v[210:213], v[8:11]
	v_mfma_f32_16x16x32_bf16 v[52:55], v[166:169], v[182:185], v[52:55]
	v_mfma_f32_16x16x32_bf16 v[48:51], v[174:177], v[182:185], v[48:51]
	v_mfma_f32_16x16x32_bf16 v[36:39], v[166:169], v[190:193], v[36:39]
	v_mfma_f32_16x16x32_bf16 v[32:35], v[174:177], v[190:193], v[32:35]
	v_mfma_f32_16x16x32_bf16 v[20:23], v[166:169], v[198:201], v[20:23]
	v_mfma_f32_16x16x32_bf16 v[16:19], v[174:177], v[198:201], v[16:19]
	v_mfma_f32_16x16x32_bf16 v[4:7], v[166:169], v[206:209], v[4:7]
	v_mfma_f32_16x16x32_bf16 v[0:3], v[174:177], v[206:209], v[0:3]
	v_mfma_f32_16x16x32_bf16 v[52:55], v[170:173], v[186:189], v[52:55]
	v_mfma_f32_16x16x32_bf16 v[48:51], v[178:181], v[186:189], v[48:51]
	v_mfma_f32_16x16x32_bf16 v[36:39], v[170:173], v[194:197], v[36:39]
	v_mfma_f32_16x16x32_bf16 v[32:35], v[178:181], v[194:197], v[32:35]
	v_mfma_f32_16x16x32_bf16 v[20:23], v[170:173], v[202:205], v[20:23]
	v_mfma_f32_16x16x32_bf16 v[16:19], v[178:181], v[202:205], v[16:19]
	v_mfma_f32_16x16x32_bf16 v[4:7], v[170:173], v[210:213], v[4:7]
	v_mfma_f32_16x16x32_bf16 v[0:3], v[178:181], v[210:213], v[0:3]
	s_barrier
; #define PG8_STAGE(bufoff, gbase, voff) do { _Pragma("unroll") for (int _i = 0; _i < 2; ++_i) \
;         __builtin_amdgcn_global_load_lds((const unsigned*)((const char*)(gbase) + (voff)[_i]), (LAS unsigned*)(lds + (bufoff) + ldsw + _i * 8192), 16, 0, ((voff) == voffA ? AUXA : 0)); } while (0)
; #define PG8_LDA(dst, b, h) do { _Pragma("unroll") for (int m = 0; m < 4; ++m) _Pragma("unroll") for (int k = 0; k < 2; ++k) dst[m][k] = *(const LAS bf16x8*)(lds + PG8_SA(b, h) + aoff + m * 2048 + k * 1024); } while (0)
; #define PG8_LDB(dst, b, h) do { _Pragma("unroll") for (int n = 0; n < 2; ++n) _Pragma("unroll") for (int k = 0; k < 2; ++k) dst[n][k] = *(const LAS bf16x8*)(lds + PG8_SB(b, h) + boff + n * 2048 + k * 1024); } while (0)
; #define PG8_MMA(ai, bj, At, Bt) do { __builtin_amdgcn_s_setprio(1); _Pragma("unroll") for (int m = 0; m < 4; ++m) _Pragma("unroll") for (int n = 0; n < 2; ++n) _Pragma("unroll") for (int k = 0; k < 2; ++k) \
;         acc[ai][bj][m][n] = __builtin_amdgcn_mfma_f32_16x16x32_bf16(Bt[n][k], At[m][k], acc[ai][bj][m][n], 0, 0, 0); __builtin_amdgcn_s_setprio(0); } while (0)
; #define PG8_WAIT_V(n) asm volatile("s_waitcnt vmcnt(" #n ")" ::: "memory")
; #define PG8_WAIT_L(n) asm volatile("s_waitcnt lgkmcnt(" #n ")" ::: "memory")
; #define PG8_BAR __builtin_amdgcn_s_barrier()
; #define PG8_SCHED __builtin_amdgcn_sched_barrier(0)
;     ...
;             PG8_LDB(B0, 1, 0); PG8_LDB(B1, 1, 1); PG8_SCHED; PG8_LDA(At, 1, 0); PG8_STAGE(PG8_SA(0, 1), a2 + hsA, voffA);
;             PG8_WAIT_V(8); PG8_WAIT_L(0); PG8_BAR; PG8_MMA(0, 0, At, B0); PG8_MMA(0, 1, At, B1); PG8_BAR; PG8_SCHED;
;             PG8_LDA(At, 1, 1); PG8_STAGE(PG8_SB(1, 0), b3, voffB); PG8_STAGE(PG8_SB(1, 1), b3 + hsB, voffB); PG8_STAGE(PG8_SA(1, 0), a3, voffA);
;             PG8_WAIT_V(8); PG8_WAIT_L(0); PG8_BAR; PG8_MMA(1, 0, At, B0); PG8_MMA(1, 1, At, B1); PG8_BAR; PG8_SCHED;
;         }
	s_mov_b32 m0, s19
	s_nop 0
	global_load_lds_dwordx4 v134, s[34:35]
	s_mov_b32 m0, s40
	s_nop 0
	global_load_lds_dwordx4 v130, s[34:35]
	s_add_i32 s57, 0, 0x18000
	s_add_i32 s58, 0, 0x1c000
	v_add_u32_e32 v162, s57, v145
	v_add_u32_e32 v178, s58, v145
	ds_read_b128 v[150:153], v162
	ds_read_b128 v[154:157], v162 offset:1024
	ds_read_b128 v[158:161], v162 offset:2048
	ds_read_b128 v[162:165], v162 offset:3072
	ds_read_b128 v[166:169], v178
	ds_read_b128 v[170:173], v178 offset:1024
	ds_read_b128 v[174:177], v178 offset:2048
	ds_read_b128 v[178:181], v178 offset:3072
	s_add_u32 s34, s34, 0x40000
	s_addc_u32 s35, s35, 0
	s_mov_b32 m0, s41
	ds_read_b128 v[182:185], v149 offset:32768
	ds_read_b128 v[186:189], v149 offset:33792
	ds_read_b128 v[190:193], v149 offset:34816
	ds_read_b128 v[194:197], v149 offset:35840
	ds_read_b128 v[198:201], v149 offset:36864
	ds_read_b128 v[202:205], v149 offset:37888
	ds_read_b128 v[206:209], v149 offset:38912
	ds_read_b128 v[210:213], v149 offset:39936
	global_load_lds_dwordx4 v134, s[34:35]
	s_mov_b32 m0, s42
	s_nop 0
	global_load_lds_dwordx4 v130, s[34:35]
	s_waitcnt vmcnt(8)
	s_waitcnt lgkmcnt(0)
	s_barrier
	v_mfma_f32_16x16x32_bf16 v[124:127], v[150:153], v[182:185], v[124:127]
	v_mfma_f32_16x16x32_bf16 v[120:123], v[158:161], v[182:185], v[120:123]
	v_mfma_f32_16x16x32_bf16 v[108:111], v[150:153], v[190:193], v[108:111]
	v_mfma_f32_16x16x32_bf16 v[104:107], v[158:161], v[190:193], v[104:107]
	v_mfma_f32_16x16x32_bf16 v[92:95], v[150:153], v[198:201], v[92:95]
	v_mfma_f32_16x16x32_bf16 v[88:91], v[158:161], v[198:201], v[88:91]
	v_mfma_f32_16x16x32_bf16 v[76:79], v[150:153], v[206:209], v[76:79]
	v_mfma_f32_16x16x32_bf16 v[72:75], v[158:161], v[206:209], v[72:75]
	v_mfma_f32_16x16x32_bf16 v[124:127], v[154:157], v[186:189], v[124:127]
	v_mfma_f32_16x16x32_bf16 v[120:123], v[162:165], v[186:189], v[120:123]
	v_mfma_f32_16x16x32_bf16 v[108:111], v[154:157], v[194:197], v[108:111]
	v_mfma_f32_16x16x32_bf16 v[104:107], v[162:165], v[194:197], v[104:107]
	v_mfma_f32_16x16x32_bf16 v[92:95], v[154:157], v[202:205], v[92:95]
	v_mfma_f32_16x16x32_bf16 v[88:91], v[162:165], v[202:205], v[88:91]
	v_mfma_f32_16x16x32_bf16 v[76:79], v[154:157], v[210:213], v[76:79]
	v_mfma_f32_16x16x32_bf16 v[72:75], v[162:165], v[210:213], v[72:75]
	v_mfma_f32_16x16x32_bf16 v[116:119], v[166:169], v[182:185], v[116:119]
	v_mfma_f32_16x16x32_bf16 v[112:115], v[174:177], v[182:185], v[112:115]
	v_mfma_f32_16x16x32_bf16 v[100:103], v[166:169], v[190:193], v[100:103]
	v_mfma_f32_16x16x32_bf16 v[96:99], v[174:177], v[190:193], v[96:99]
	v_mfma_f32_16x16x32_bf16 v[84:87], v[166:169], v[198:201], v[84:87]
	v_mfma_f32_16x16x32_bf16 v[80:83], v[174:177], v[198:201], v[80:83]
	v_mfma_f32_16x16x32_bf16 v[68:71], v[166:169], v[206:209], v[68:71]
	v_mfma_f32_16x16x32_bf16 v[64:67], v[174:177], v[206:209], v[64:67]
	v_mfma_f32_16x16x32_bf16 v[116:119], v[170:173], v[186:189], v[116:119]
	v_mfma_f32_16x16x32_bf16 v[112:115], v[178:181], v[186:189], v[112:115]
	v_mfma_f32_16x16x32_bf16 v[100:103], v[170:173], v[194:197], v[100:103]
	v_mfma_f32_16x16x32_bf16 v[96:99], v[178:181], v[194:197], v[96:99]
	v_mfma_f32_16x16x32_bf16 v[84:87], v[170:173], v[202:205], v[84:87]
	v_mfma_f32_16x16x32_bf16 v[80:83], v[178:181], v[202:205], v[80:83]
	v_mfma_f32_16x16x32_bf16 v[68:71], v[170:173], v[210:213], v[68:71]
	v_mfma_f32_16x16x32_bf16 v[64:67], v[178:181], v[210:213], v[64:67]
	s_barrier
	s_add_i32 s34, s57, s37
	s_mov_b32 m0, s34
	ds_read_b128 v[182:185], v149 offset:49152
	ds_read_b128 v[186:189], v149 offset:50176
	ds_read_b128 v[190:193], v149 offset:51200
	ds_read_b128 v[194:197], v149 offset:52224
	ds_read_b128 v[198:201], v149 offset:53248
	ds_read_b128 v[202:205], v149 offset:54272
	ds_read_b128 v[206:209], v149 offset:55296
	ds_read_b128 v[210:213], v149 offset:56320
	global_load_lds_dwordx4 v132, s[98:99]
	s_add_i32 m0, s34, 0x2000
	s_add_u32 s30, s30, 0x40080
	s_addc_u32 s31, s31, 0
	s_add_i32 s34, s58, s37
	global_load_lds_dwordx4 v128, s[98:99]
	s_mov_b32 m0, s34
	s_nop 0
	global_load_lds_dwordx4 v132, s[30:31]
	s_add_i32 m0, s34, 0x2000
	s_nop 0
	global_load_lds_dwordx4 v128, s[30:31]
	s_waitcnt vmcnt(6)
	s_waitcnt lgkmcnt(0)
	s_barrier
	v_mfma_f32_16x16x32_bf16 v[60:63], v[150:153], v[182:185], v[60:63]
	v_mfma_f32_16x16x32_bf16 v[56:59], v[158:161], v[182:185], v[56:59]
	v_mfma_f32_16x16x32_bf16 v[44:47], v[150:153], v[190:193], v[44:47]
	v_mfma_f32_16x16x32_bf16 v[40:43], v[158:161], v[190:193], v[40:43]
	v_mfma_f32_16x16x32_bf16 v[28:31], v[150:153], v[198:201], v[28:31]
	v_mfma_f32_16x16x32_bf16 v[24:27], v[158:161], v[198:201], v[24:27]
	v_mfma_f32_16x16x32_bf16 v[12:15], v[150:153], v[206:209], v[12:15]
	v_mfma_f32_16x16x32_bf16 v[8:11], v[158:161], v[206:209], v[8:11]
	v_mfma_f32_16x16x32_bf16 v[60:63], v[154:157], v[186:189], v[60:63]
	v_mfma_f32_16x16x32_bf16 v[56:59], v[162:165], v[186:189], v[56:59]
	v_mfma_f32_16x16x32_bf16 v[44:47], v[154:157], v[194:197], v[44:47]
	v_mfma_f32_16x16x32_bf16 v[40:43], v[162:165], v[194:197], v[40:43]
	v_mfma_f32_16x16x32_bf16 v[28:31], v[154:157], v[202:205], v[28:31]
	v_mfma_f32_16x16x32_bf16 v[24:27], v[162:165], v[202:205], v[24:27]
	v_mfma_f32_16x16x32_bf16 v[12:15], v[154:157], v[210:213], v[12:15]
	v_mfma_f32_16x16x32_bf16 v[8:11], v[162:165], v[210:213], v[8:11]
	v_mfma_f32_16x16x32_bf16 v[52:55], v[166:169], v[182:185], v[52:55]
	v_mfma_f32_16x16x32_bf16 v[48:51], v[174:177], v[182:185], v[48:51]
	v_mfma_f32_16x16x32_bf16 v[36:39], v[166:169], v[190:193], v[36:39]
	v_mfma_f32_16x16x32_bf16 v[32:35], v[174:177], v[190:193], v[32:35]
	v_mfma_f32_16x16x32_bf16 v[20:23], v[166:169], v[198:201], v[20:23]
	v_mfma_f32_16x16x32_bf16 v[16:19], v[174:177], v[198:201], v[16:19]
	v_mfma_f32_16x16x32_bf16 v[4:7], v[166:169], v[206:209], v[4:7]
	v_mfma_f32_16x16x32_bf16 v[0:3], v[174:177], v[206:209], v[0:3]
	v_mfma_f32_16x16x32_bf16 v[52:55], v[170:173], v[186:189], v[52:55]
	v_mfma_f32_16x16x32_bf16 v[48:51], v[178:181], v[186:189], v[48:51]
	v_mfma_f32_16x16x32_bf16 v[36:39], v[170:173], v[194:197], v[36:39]
	v_mfma_f32_16x16x32_bf16 v[32:35], v[178:181], v[194:197], v[32:35]
	v_mfma_f32_16x16x32_bf16 v[20:23], v[170:173], v[202:205], v[20:23]
	v_mfma_f32_16x16x32_bf16 v[16:19], v[178:181], v[202:205], v[16:19]
	v_mfma_f32_16x16x32_bf16 v[4:7], v[170:173], v[210:213], v[4:7]
	v_mfma_f32_16x16x32_bf16 v[0:3], v[178:181], v[210:213], v[0:3]
	s_barrier
	s_add_u32 s28, s28, 0x100
	s_addc_u32 s29, s29, 0
	s_add_u32 s54, s54, 0x100
	s_addc_u32 s55, s55, 0
	s_cmp_ge_i32 s56, s44
	s_mov_b32 s30, s56
	s_cbranch_scc0 .LBB0_1040
	s_setprio 0

; #define PG8_STAGE(bufoff, gbase, voff) do { _Pragma("unroll") for (int _i = 0; _i < 2; ++_i) \
;         __builtin_amdgcn_global_load_lds((const unsigned*)((const char*)(gbase) + (voff)[_i]), (LAS unsigned*)(lds + (bufoff) + ldsw + _i * 8192), 16, 0, ((voff) == voffA ? AUXA : 0)); } while (0)
; #define PG8_LDA(dst, b, h) do { _Pragma("unroll") for (int m = 0; m < 4; ++m) _Pragma("unroll") for (int k = 0; k < 2; ++k) dst[m][k] = *(const LAS bf16x8*)(lds + PG8_SA(b, h) + aoff + m * 2048 + k * 1024); } while (0)
; #define PG8_LDB(dst, b, h) do { _Pragma("unroll") for (int n = 0; n < 2; ++n) _Pragma("unroll") for (int k = 0; k < 2; ++k) dst[n][k] = *(const LAS bf16x8*)(lds + PG8_SB(b, h) + boff + n * 2048 + k * 1024); } while (0)
; #define PG8_MMA(ai, bj, At, Bt) do { __builtin_amdgcn_s_setprio(1); _Pragma("unroll") for (int m = 0; m < 4; ++m) _Pragma("unroll") for (int n = 0; n < 2; ++n) _Pragma("unroll") for (int k = 0; k < 2; ++k) \
;         acc[ai][bj][m][n] = __builtin_amdgcn_mfma_f32_16x16x32_bf16(Bt[n][k], At[m][k], acc[ai][bj][m][n], 0, 0, 0); __builtin_amdgcn_s_setprio(0); } while (0)
; #define PG8_WAIT_V(n) asm volatile("s_waitcnt vmcnt(" #n ")" ::: "memory")
; #define PG8_WAIT_L(n) asm volatile("s_waitcnt lgkmcnt(" #n ")" ::: "memory")
; #define PG8_BAR __builtin_amdgcn_s_barrier()
; #define PG8_SCHED __builtin_amdgcn_sched_barrier(0)
;     ...
;         for (int t = 0; t < nt; t += 2) {
;             const bool last = (t == nt - 2);
;             const char* a1 = cA + (size_t)(t + 1) * kstep;
;             const char* a2 = last ? nA : cA + (size_t)(t + 2) * kstep; const char* b2 = last ? nB : cB + (size_t)(t + 2) * kstep;
;             const char* a3 = a2 + kstep; const char* b3 = b2 + kstep;
;             PG8_LDB(B0, 0, 0); PG8_LDB(B1, 0, 1); PG8_SCHED; PG8_LDA(At, 0, 0); PG8_STAGE(PG8_SA(1, 1), a1 + hsA, voffA);
;             if (Epi::NPRE != 0 && last) { E.pre(sv, cur, wr, fr); PG8_WAIT_V(16); } else { PG8_WAIT_V(8); }
;             PG8_WAIT_L(0); PG8_BAR; PG8_MMA(0, 0, At, B0); PG8_MMA(0, 1, At, B1); PG8_BAR; PG8_SCHED;
;     ...
; #pragma unroll
;         for (int a = 0; a < 2; ++a)
; #pragma unroll
;             for (int b = 0; b < 2; ++b)
; #pragma unroll
;                 for (int m = 0; m < 4; ++m)
; #pragma unroll
;                     for (int n = 0; n < 2; ++n) acc[a][b][m][n] = (f32x4){0.f, 0.f, 0.f, 0.f};
;         cur = nxt; cA = nA; cB = nB; ++ui;
.LBB0_1110:
	s_ashr_i32 s23, s22, 31
	s_lshl_b64 s[24:25], s[22:23], 19
	s_add_u32 s24, s94, s24
	s_addc_u32 s25, s95, s25
	s_ashr_i32 s21, s20, 31
	s_lshl_b64 s[26:27], s[20:21], 19
	s_add_u32 s26, s3, s26
	v_mov_b32_e32 v127, 0
	s_addc_u32 s27, s4, s27
	s_and_b64 vcc, exec, s[0:1]
	v_mov_b32_e32 v126, 0
	v_mov_b64_e32 v[124:125], 0
	v_mov_b64_e32 v[122:123], 0
	v_mov_b64_e32 v[120:121], 0
	v_mov_b64_e32 v[110:111], 0
	v_mov_b64_e32 v[108:109], 0
	v_mov_b64_e32 v[106:107], 0
	v_mov_b64_e32 v[104:105], 0
	v_mov_b64_e32 v[94:95], 0
	v_mov_b64_e32 v[92:93], 0
	v_mov_b64_e32 v[90:91], 0
	v_mov_b64_e32 v[88:89], 0
	v_mov_b64_e32 v[78:79], 0
	v_mov_b64_e32 v[76:77], 0
	v_mov_b64_e32 v[74:75], 0
	v_mov_b64_e32 v[72:73], 0
	v_mov_b64_e32 v[118:119], 0
	v_mov_b64_e32 v[116:117], 0
	v_mov_b64_e32 v[114:115], 0
	v_mov_b64_e32 v[112:113], 0
	v_mov_b64_e32 v[102:103], 0
	v_mov_b64_e32 v[100:101], 0
	v_mov_b64_e32 v[98:99], 0
	v_mov_b64_e32 v[96:97], 0
	v_mov_b64_e32 v[86:87], 0
	v_mov_b64_e32 v[84:85], 0
	v_mov_b64_e32 v[82:83], 0
	v_mov_b64_e32 v[80:81], 0
	v_mov_b64_e32 v[70:71], 0
	v_mov_b64_e32 v[68:69], 0
	v_mov_b64_e32 v[66:67], 0
	v_mov_b64_e32 v[64:65], 0
	v_mov_b64_e32 v[62:63], 0
	v_mov_b64_e32 v[60:61], 0
	v_mov_b64_e32 v[58:59], 0
	v_mov_b64_e32 v[56:57], 0
	v_mov_b64_e32 v[46:47], 0
	v_mov_b64_e32 v[44:45], 0
	v_mov_b64_e32 v[42:43], 0
	v_mov_b64_e32 v[40:41], 0
	v_mov_b64_e32 v[30:31], 0
	v_mov_b64_e32 v[28:29], 0
	v_mov_b64_e32 v[26:27], 0
	v_mov_b64_e32 v[24:25], 0
	v_mov_b64_e32 v[14:15], 0
	v_mov_b64_e32 v[12:13], 0
	v_mov_b64_e32 v[10:11], 0
	v_mov_b64_e32 v[8:9], 0
	v_mov_b64_e32 v[54:55], 0
	v_mov_b64_e32 v[52:53], 0
	v_mov_b64_e32 v[50:51], 0
	v_mov_b64_e32 v[48:49], 0
	v_mov_b64_e32 v[38:39], 0
	v_mov_b64_e32 v[36:37], 0
	v_mov_b64_e32 v[34:35], 0
	v_mov_b64_e32 v[32:33], 0
	v_mov_b64_e32 v[22:23], 0
	v_mov_b64_e32 v[20:21], 0
	v_mov_b64_e32 v[18:19], 0
	v_mov_b64_e32 v[16:17], 0
	v_mov_b64_e32 v[6:7], 0
	v_mov_b64_e32 v[4:5], 0
	v_mov_b64_e32 v[2:3], 0
	v_mov_b64_e32 v[0:1], 0
	s_cbranch_vccnz .LBB0_1113
	s_and_b64 s[34:35], s[6:7], exec
	s_cselect_b32 s21, s25, s29
	s_cselect_b32 s23, s24, s28
	s_cselect_b32 s50, s27, s31
	s_cselect_b32 s51, s26, s30
	s_add_u32 s28, s28, 0x40080
	s_addc_u32 s29, s29, 0
	s_add_u32 s52, s30, 0x100
	v_mov_b32_e32 v0, 0
	s_addc_u32 s53, s31, 0
	s_mov_b32 s30, 0
	v_mov_b32_e32 v1, 0
	v_mov_b64_e32 v[2:3], 0
	v_mov_b64_e32 v[4:5], 0
	v_mov_b64_e32 v[6:7], 0
	v_mov_b64_e32 v[16:17], 0
	v_mov_b64_e32 v[18:19], 0
	v_mov_b64_e32 v[20:21], 0
	v_mov_b64_e32 v[22:23], 0
	v_mov_b64_e32 v[32:33], 0
	v_mov_b64_e32 v[34:35], 0
	v_mov_b64_e32 v[36:37], 0
	v_mov_b64_e32 v[38:39], 0
	v_mov_b64_e32 v[48:49], 0
	v_mov_b64_e32 v[50:51], 0
	v_mov_b64_e32 v[52:53], 0
	v_mov_b64_e32 v[54:55], 0
	v_mov_b64_e32 v[8:9], 0
	v_mov_b64_e32 v[10:11], 0
	v_mov_b64_e32 v[12:13], 0
	v_mov_b64_e32 v[14:15], 0
	v_mov_b64_e32 v[24:25], 0
	v_mov_b64_e32 v[26:27], 0
	v_mov_b64_e32 v[28:29], 0
	v_mov_b64_e32 v[30:31], 0
	v_mov_b64_e32 v[40:41], 0
	v_mov_b64_e32 v[42:43], 0
	v_mov_b64_e32 v[44:45], 0
	v_mov_b64_e32 v[46:47], 0
	v_mov_b64_e32 v[56:57], 0
	v_mov_b64_e32 v[58:59], 0
	v_mov_b64_e32 v[60:61], 0
	v_mov_b64_e32 v[62:63], 0
	v_mov_b64_e32 v[64:65], 0
	v_mov_b64_e32 v[66:67], 0
	v_mov_b64_e32 v[68:69], 0
	v_mov_b64_e32 v[70:71], 0
	v_mov_b64_e32 v[80:81], 0
	v_mov_b64_e32 v[82:83], 0
	v_mov_b64_e32 v[84:85], 0
	v_mov_b64_e32 v[86:87], 0
	v_mov_b64_e32 v[96:97], 0
	v_mov_b64_e32 v[98:99], 0
	v_mov_b64_e32 v[100:101], 0
	v_mov_b64_e32 v[102:103], 0
	v_mov_b64_e32 v[112:113], 0
	v_mov_b64_e32 v[114:115], 0
	v_mov_b64_e32 v[116:117], 0
	v_mov_b64_e32 v[118:119], 0
	v_mov_b64_e32 v[72:73], 0
	v_mov_b64_e32 v[74:75], 0
	v_mov_b64_e32 v[76:77], 0
	v_mov_b64_e32 v[78:79], 0
	v_mov_b64_e32 v[88:89], 0
	v_mov_b64_e32 v[90:91], 0
	v_mov_b64_e32 v[92:93], 0
	v_mov_b64_e32 v[94:95], 0
	v_mov_b64_e32 v[104:105], 0
	v_mov_b64_e32 v[106:107], 0
	v_mov_b64_e32 v[108:109], 0
	v_mov_b64_e32 v[110:111], 0
	v_mov_b64_e32 v[120:121], 0
	v_mov_b64_e32 v[122:123], 0
	v_mov_b64_e32 v[124:125], 0
	v_mov_b64_e32 v[126:127], 0
	v_readfirstlane_b32 s99, v234
	s_nop 0
	s_lshr_b32 s99, s99, 8
	s_cmp_eq_u32 s99, 0
	s_cbranch_scc1 .Lsp_7
	s_setprio 1
.Lsp_7:
.LBB0_1112:
	s_add_u32 s98, s28, 0xfffc0000
	s_addc_u32 s99, s29, -1
	s_mov_b32 m0, s43
	s_nop 0
	global_load_lds_dwordx4 v134, s[98:99]
	s_mov_b32 m0, s44
	s_nop 0
	global_load_lds_dwordx4 v130, s[98:99]
	ds_read_b128 v[150:153], v147
	ds_read_b128 v[154:157], v147 offset:1024
	ds_read_b128 v[158:161], v147 offset:2048
	ds_read_b128 v[162:165], v147 offset:3072
	ds_read_b128 v[166:169], v148
	ds_read_b128 v[170:173], v148 offset:1024
	ds_read_b128 v[174:177], v148 offset:2048
	ds_read_b128 v[178:181], v148 offset:3072
	s_add_i32 s54, s30, 2
	s_add_u32 s31, s28, 0xfffc0080
	s_addc_u32 s34, s29, -1
	s_cmp_eq_u32 s45, s30
	s_cselect_b32 s30, s51, s52
	s_cselect_b32 s35, s21, s34
	s_cselect_b32 s34, s23, s31
	s_cselect_b32 s31, s50, s53
	s_add_i32 m0, s19, 0xc000
	ds_read_b128 v[182:185], v149
	ds_read_b128 v[186:189], v149 offset:1024
	ds_read_b128 v[190:193], v149 offset:2048
	ds_read_b128 v[194:197], v149 offset:3072
	ds_read_b128 v[198:201], v149 offset:4096
	ds_read_b128 v[202:205], v149 offset:5120
	ds_read_b128 v[206:209], v149 offset:6144
	ds_read_b128 v[210:213], v149 offset:7168
	global_load_lds_dwordx4 v136, s[28:29]
	s_add_i32 m0, s19, 0xe000
	s_nop 0
	global_load_lds_dwordx4 v138, s[28:29]
	s_waitcnt vmcnt(8)
	s_waitcnt lgkmcnt(0)
	s_barrier
; #define PG8_STAGE(bufoff, gbase, voff) do { _Pragma("unroll") for (int _i = 0; _i < 2; ++_i) \
;         __builtin_amdgcn_global_load_lds((const unsigned*)((const char*)(gbase) + (voff)[_i]), (LAS unsigned*)(lds + (bufoff) + ldsw + _i * 8192), 16, 0, ((voff) == voffA ? AUXA : 0)); } while (0)
; #define PG8_LDA(dst, b, h) do { _Pragma("unroll") for (int m = 0; m < 4; ++m) _Pragma("unroll") for (int k = 0; k < 2; ++k) dst[m][k] = *(const LAS bf16x8*)(lds + PG8_SA(b, h) + aoff + m * 2048 + k * 1024); } while (0)
; #define PG8_MMA(ai, bj, At, Bt) do { __builtin_amdgcn_s_setprio(1); _Pragma("unroll") for (int m = 0; m < 4; ++m) _Pragma("unroll") for (int n = 0; n < 2; ++n) _Pragma("unroll") for (int k = 0; k < 2; ++k) \
;         acc[ai][bj][m][n] = __builtin_amdgcn_mfma_f32_16x16x32_bf16(Bt[n][k], At[m][k], acc[ai][bj][m][n], 0, 0, 0); __builtin_amdgcn_s_setprio(0); } while (0)
; #define PG8_WAIT_V(n) asm volatile("s_waitcnt vmcnt(" #n ")" ::: "memory")
; #define PG8_WAIT_L(n) asm volatile("s_waitcnt lgkmcnt(" #n ")" ::: "memory")
; #define PG8_BAR __builtin_amdgcn_s_barrier()
; #define PG8_SCHED __builtin_amdgcn_sched_barrier(0)
;     ...
;             PG8_WAIT_L(0); PG8_BAR; PG8_MMA(0, 0, At, B0); PG8_MMA(0, 1, At, B1); PG8_BAR; PG8_SCHED;
;             PG8_LDA(At, 0, 1); PG8_STAGE(PG8_SB(0, 0), b2, voffB); PG8_STAGE(PG8_SB(0, 1), b2 + hsB, voffB); PG8_STAGE(PG8_SA(0, 0), a2, voffA);
;             if (Epi::NPRE != 0 && last) { PG8_WAIT_V(16); } else { PG8_WAIT_V(8); }
;             PG8_WAIT_L(0); PG8_BAR; PG8_MMA(1, 0, At, B0); PG8_MMA(1, 1, At, B1); PG8_BAR; PG8_SCHED;
	v_mfma_f32_16x16x32_bf16 v[124:127], v[150:153], v[182:185], v[124:127]
	v_mfma_f32_16x16x32_bf16 v[120:123], v[158:161], v[182:185], v[120:123]
	v_mfma_f32_16x16x32_bf16 v[108:111], v[150:153], v[190:193], v[108:111]
	v_mfma_f32_16x16x32_bf16 v[104:107], v[158:161], v[190:193], v[104:107]
	v_mfma_f32_16x16x32_bf16 v[92:95], v[150:153], v[198:201], v[92:95]
	v_mfma_f32_16x16x32_bf16 v[88:91], v[158:161], v[198:201], v[88:91]
	v_mfma_f32_16x16x32_bf16 v[76:79], v[150:153], v[206:209], v[76:79]
	v_mfma_f32_16x16x32_bf16 v[72:75], v[158:161], v[206:209], v[72:75]
	v_mfma_f32_16x16x32_bf16 v[124:127], v[154:157], v[186:189], v[124:127]
	v_mfma_f32_16x16x32_bf16 v[120:123], v[162:165], v[186:189], v[120:123]
	v_mfma_f32_16x16x32_bf16 v[108:111], v[154:157], v[194:197], v[108:111]
	v_mfma_f32_16x16x32_bf16 v[104:107], v[162:165], v[194:197], v[104:107]
	v_mfma_f32_16x16x32_bf16 v[92:95], v[154:157], v[202:205], v[92:95]
	v_mfma_f32_16x16x32_bf16 v[88:91], v[162:165], v[202:205], v[88:91]
	v_mfma_f32_16x16x32_bf16 v[76:79], v[154:157], v[210:213], v[76:79]
	v_mfma_f32_16x16x32_bf16 v[72:75], v[162:165], v[210:213], v[72:75]
	v_mfma_f32_16x16x32_bf16 v[116:119], v[166:169], v[182:185], v[116:119]
	v_mfma_f32_16x16x32_bf16 v[112:115], v[174:177], v[182:185], v[112:115]
	v_mfma_f32_16x16x32_bf16 v[100:103], v[166:169], v[190:193], v[100:103]
	v_mfma_f32_16x16x32_bf16 v[96:99], v[174:177], v[190:193], v[96:99]
	v_mfma_f32_16x16x32_bf16 v[84:87], v[166:169], v[198:201], v[84:87]
	v_mfma_f32_16x16x32_bf16 v[80:83], v[174:177], v[198:201], v[80:83]
	v_mfma_f32_16x16x32_bf16 v[68:71], v[166:169], v[206:209], v[68:71]
	v_mfma_f32_16x16x32_bf16 v[64:67], v[174:177], v[206:209], v[64:67]
	v_mfma_f32_16x16x32_bf16 v[116:119], v[170:173], v[186:189], v[116:119]
	v_mfma_f32_16x16x32_bf16 v[112:115], v[178:181], v[186:189], v[112:115]
	v_mfma_f32_16x16x32_bf16 v[100:103], v[170:173], v[194:197], v[100:103]
	v_mfma_f32_16x16x32_bf16 v[96:99], v[178:181], v[194:197], v[96:99]
	v_mfma_f32_16x16x32_bf16 v[84:87], v[170:173], v[202:205], v[84:87]
	v_mfma_f32_16x16x32_bf16 v[80:83], v[178:181], v[202:205], v[80:83]
	v_mfma_f32_16x16x32_bf16 v[68:71], v[170:173], v[210:213], v[68:71]
	v_mfma_f32_16x16x32_bf16 v[64:67], v[178:181], v[210:213], v[64:67]
	s_barrier
	s_add_u32 s98, s30, s14
	s_addc_u32 s99, s31, s15
	s_add_u32 s100, s34, s14
	s_addc_u32 s101, s35, s15
	s_add_i32 s55, s47, s5
	s_mov_b32 m0, s55
	ds_read_b128 v[182:185], v149 offset:16384
	ds_read_b128 v[186:189], v149 offset:17408
	ds_read_b128 v[190:193], v149 offset:18432
	ds_read_b128 v[194:197], v149 offset:19456
	ds_read_b128 v[198:201], v149 offset:20480
	ds_read_b128 v[202:205], v149 offset:21504
	ds_read_b128 v[206:209], v149 offset:22528
	ds_read_b128 v[210:213], v149 offset:23552
	global_load_lds_dwordx4 v132, s[30:31]
	s_add_i32 m0, s55, 0x2000
	s_add_u32 s56, s30, 0x40000
	s_addc_u32 s57, s31, 0
	s_add_i32 s55, s48, s5
	global_load_lds_dwordx4 v128, s[30:31]
	s_mov_b32 m0, s55
	s_nop 0
	global_load_lds_dwordx4 v132, s[56:57]
	s_add_i32 m0, s55, 0x2000
	s_nop 0
	global_load_lds_dwordx4 v128, s[56:57]
	s_waitcnt vmcnt(6)
	s_waitcnt lgkmcnt(0)
	s_barrier
	v_mfma_f32_16x16x32_bf16 v[60:63], v[150:153], v[182:185], v[60:63]
	v_mfma_f32_16x16x32_bf16 v[56:59], v[158:161], v[182:185], v[56:59]
	v_mfma_f32_16x16x32_bf16 v[44:47], v[150:153], v[190:193], v[44:47]
	v_mfma_f32_16x16x32_bf16 v[40:43], v[158:161], v[190:193], v[40:43]
	v_mfma_f32_16x16x32_bf16 v[28:31], v[150:153], v[198:201], v[28:31]
	v_mfma_f32_16x16x32_bf16 v[24:27], v[158:161], v[198:201], v[24:27]
	v_mfma_f32_16x16x32_bf16 v[12:15], v[150:153], v[206:209], v[12:15]
	v_mfma_f32_16x16x32_bf16 v[8:11], v[158:161], v[206:209], v[8:11]
	v_mfma_f32_16x16x32_bf16 v[60:63], v[154:157], v[186:189], v[60:63]
	v_mfma_f32_16x16x32_bf16 v[56:59], v[162:165], v[186:189], v[56:59]
	v_mfma_f32_16x16x32_bf16 v[44:47], v[154:157], v[194:197], v[44:47]
	v_mfma_f32_16x16x32_bf16 v[40:43], v[162:165], v[194:197], v[40:43]
	v_mfma_f32_16x16x32_bf16 v[28:31], v[154:157], v[202:205], v[28:31]
	v_mfma_f32_16x16x32_bf16 v[24:27], v[162:165], v[202:205], v[24:27]
	v_mfma_f32_16x16x32_bf16 v[12:15], v[154:157], v[210:213], v[12:15]
	v_mfma_f32_16x16x32_bf16 v[8:11], v[162:165], v[210:213], v[8:11]
	v_mfma_f32_16x16x32_bf16 v[52:55], v[166:169], v[182:185], v[52:55]
	v_mfma_f32_16x16x32_bf16 v[48:51], v[174:177], v[182:185], v[48:51]
	v_mfma_f32_16x16x32_bf16 v[36:39], v[166:169], v[190:193], v[36:39]
	v_mfma_f32_16x16x32_bf16 v[32:35], v[174:177], v[190:193], v[32:35]
	v_mfma_f32_16x16x32_bf16 v[20:23], v[166:169], v[198:201], v[20:23]
	v_mfma_f32_16x16x32_bf16 v[16:19], v[174:177], v[198:201], v[16:19]
	v_mfma_f32_16x16x32_bf16 v[4:7], v[166:169], v[206:209], v[4:7]
	v_mfma_f32_16x16x32_bf16 v[0:3], v[174:177], v[206:209], v[0:3]
	v_mfma_f32_16x16x32_bf16 v[52:55], v[170:173], v[186:189], v[52:55]
	v_mfma_f32_16x16x32_bf16 v[48:51], v[178:181], v[186:189], v[48:51]
	v_mfma_f32_16x16x32_bf16 v[36:39], v[170:173], v[194:197], v[36:39]
	v_mfma_f32_16x16x32_bf16 v[32:35], v[178:181], v[194:197], v[32:35]
	v_mfma_f32_16x16x32_bf16 v[20:23], v[170:173], v[202:205], v[20:23]
	v_mfma_f32_16x16x32_bf16 v[16:19], v[178:181], v[202:205], v[16:19]
	v_mfma_f32_16x16x32_bf16 v[4:7], v[170:173], v[210:213], v[4:7]
	v_mfma_f32_16x16x32_bf16 v[0:3], v[178:181], v[210:213], v[0:3]
	s_barrier
; #define PG8_STAGE(bufoff, gbase, voff) do { _Pragma("unroll") for (int _i = 0; _i < 2; ++_i) \
;         __builtin_amdgcn_global_load_lds((const unsigned*)((const char*)(gbase) + (voff)[_i]), (LAS unsigned*)(lds + (bufoff) + ldsw + _i * 8192), 16, 0, ((voff) == voffA ? AUXA : 0)); } while (0)
; #define PG8_LDA(dst, b, h) do { _Pragma("unroll") for (int m = 0; m < 4; ++m) _Pragma("unroll") for (int k = 0; k < 2; ++k) dst[m][k] = *(const LAS bf16x8*)(lds + PG8_SA(b, h) + aoff + m * 2048 + k * 1024); } while (0)
; #define PG8_LDB(dst, b, h) do { _Pragma("unroll") for (int n = 0; n < 2; ++n) _Pragma("unroll") for (int k = 0; k < 2; ++k) dst[n][k] = *(const LAS bf16x8*)(lds + PG8_SB(b, h) + boff + n * 2048 + k * 1024); } while (0)
; #define PG8_MMA(ai, bj, At, Bt) do { __builtin_amdgcn_s_setprio(1); _Pragma("unroll") for (int m = 0; m < 4; ++m) _Pragma("unroll") for (int n = 0; n < 2; ++n) _Pragma("unroll") for (int k = 0; k < 2; ++k) \
;         acc[ai][bj][m][n] = __builtin_amdgcn_mfma_f32_16x16x32_bf16(Bt[n][k], At[m][k], acc[ai][bj][m][n], 0, 0, 0); __builtin_amdgcn_s_setprio(0); } while (0)
; #define PG8_WAIT_V(n) asm volatile("s_waitcnt vmcnt(" #n ")" ::: "memory")
; #define PG8_WAIT_L(n) asm volatile("s_waitcnt lgkmcnt(" #n ")" ::: "memory")
; #define PG8_BAR __builtin_amdgcn_s_barrier()
; #define PG8_SCHED __builtin_amdgcn_sched_barrier(0)
;     ...
;             PG8_LDB(B0, 1, 0); PG8_LDB(B1, 1, 1); PG8_SCHED; PG8_LDA(At, 1, 0); PG8_STAGE(PG8_SA(0, 1), a2 + hsA, voffA);
;             PG8_WAIT_V(8); PG8_WAIT_L(0); PG8_BAR; PG8_MMA(0, 0, At, B0); PG8_MMA(0, 1, At, B1); PG8_BAR; PG8_SCHED;
;             PG8_LDA(At, 1, 1); PG8_STAGE(PG8_SB(1, 0), b3, voffB); PG8_STAGE(PG8_SB(1, 1), b3 + hsB, voffB); PG8_STAGE(PG8_SA(1, 0), a3, voffA);
;             PG8_WAIT_V(8); PG8_WAIT_L(0); PG8_BAR; PG8_MMA(1, 0, At, B0); PG8_MMA(1, 1, At, B1); PG8_BAR; PG8_SCHED;
;         }
	s_mov_b32 m0, s19
	s_nop 0
	global_load_lds_dwordx4 v134, s[34:35]
	s_mov_b32 m0, s38
	s_nop 0
	global_load_lds_dwordx4 v130, s[34:35]
	s_add_i32 s55, 0, 0x18000
	s_add_i32 s56, 0, 0x1c000
	v_add_u32_e32 v162, s55, v145
	v_add_u32_e32 v178, s56, v145
	ds_read_b128 v[150:153], v162
	ds_read_b128 v[154:157], v162 offset:1024
	ds_read_b128 v[158:161], v162 offset:2048
	ds_read_b128 v[162:165], v162 offset:3072
	ds_read_b128 v[166:169], v178
	ds_read_b128 v[170:173], v178 offset:1024
	ds_read_b128 v[174:177], v178 offset:2048
	ds_read_b128 v[178:181], v178 offset:3072
	s_add_u32 s34, s34, 0x40000
	s_addc_u32 s35, s35, 0
	s_mov_b32 m0, s39
	ds_read_b128 v[182:185], v149 offset:32768
	ds_read_b128 v[186:189], v149 offset:33792
	ds_read_b128 v[190:193], v149 offset:34816
	ds_read_b128 v[194:197], v149 offset:35840
	ds_read_b128 v[198:201], v149 offset:36864
	ds_read_b128 v[202:205], v149 offset:37888
	ds_read_b128 v[206:209], v149 offset:38912
	ds_read_b128 v[210:213], v149 offset:39936
	global_load_lds_dwordx4 v134, s[34:35]
	s_mov_b32 m0, s40
	s_nop 0
	global_load_lds_dwordx4 v130, s[34:35]
	s_waitcnt vmcnt(8)
	s_waitcnt lgkmcnt(0)
	s_barrier
	v_mfma_f32_16x16x32_bf16 v[124:127], v[150:153], v[182:185], v[124:127]
	v_mfma_f32_16x16x32_bf16 v[120:123], v[158:161], v[182:185], v[120:123]
	v_mfma_f32_16x16x32_bf16 v[108:111], v[150:153], v[190:193], v[108:111]
	v_mfma_f32_16x16x32_bf16 v[104:107], v[158:161], v[190:193], v[104:107]
	v_mfma_f32_16x16x32_bf16 v[92:95], v[150:153], v[198:201], v[92:95]
	v_mfma_f32_16x16x32_bf16 v[88:91], v[158:161], v[198:201], v[88:91]
	v_mfma_f32_16x16x32_bf16 v[76:79], v[150:153], v[206:209], v[76:79]
	v_mfma_f32_16x16x32_bf16 v[72:75], v[158:161], v[206:209], v[72:75]
	v_mfma_f32_16x16x32_bf16 v[124:127], v[154:157], v[186:189], v[124:127]
	v_mfma_f32_16x16x32_bf16 v[120:123], v[162:165], v[186:189], v[120:123]
	v_mfma_f32_16x16x32_bf16 v[108:111], v[154:157], v[194:197], v[108:111]
	v_mfma_f32_16x16x32_bf16 v[104:107], v[162:165], v[194:197], v[104:107]
	v_mfma_f32_16x16x32_bf16 v[92:95], v[154:157], v[202:205], v[92:95]
	v_mfma_f32_16x16x32_bf16 v[88:91], v[162:165], v[202:205], v[88:91]
	v_mfma_f32_16x16x32_bf16 v[76:79], v[154:157], v[210:213], v[76:79]
	v_mfma_f32_16x16x32_bf16 v[72:75], v[162:165], v[210:213], v[72:75]
	v_mfma_f32_16x16x32_bf16 v[116:119], v[166:169], v[182:185], v[116:119]
	v_mfma_f32_16x16x32_bf16 v[112:115], v[174:177], v[182:185], v[112:115]
	v_mfma_f32_16x16x32_bf16 v[100:103], v[166:169], v[190:193], v[100:103]
	v_mfma_f32_16x16x32_bf16 v[96:99], v[174:177], v[190:193], v[96:99]
	v_mfma_f32_16x16x32_bf16 v[84:87], v[166:169], v[198:201], v[84:87]
	v_mfma_f32_16x16x32_bf16 v[80:83], v[174:177], v[198:201], v[80:83]
	v_mfma_f32_16x16x32_bf16 v[68:71], v[166:169], v[206:209], v[68:71]
	v_mfma_f32_16x16x32_bf16 v[64:67], v[174:177], v[206:209], v[64:67]
	v_mfma_f32_16x16x32_bf16 v[116:119], v[170:173], v[186:189], v[116:119]
	v_mfma_f32_16x16x32_bf16 v[112:115], v[178:181], v[186:189], v[112:115]
	v_mfma_f32_16x16x32_bf16 v[100:103], v[170:173], v[194:197], v[100:103]
	v_mfma_f32_16x16x32_bf16 v[96:99], v[178:181], v[194:197], v[96:99]
	v_mfma_f32_16x16x32_bf16 v[84:87], v[170:173], v[202:205], v[84:87]
	v_mfma_f32_16x16x32_bf16 v[80:83], v[178:181], v[202:205], v[80:83]
	v_mfma_f32_16x16x32_bf16 v[68:71], v[170:173], v[210:213], v[68:71]
	v_mfma_f32_16x16x32_bf16 v[64:67], v[178:181], v[210:213], v[64:67]
	s_barrier
	s_add_i32 s34, s55, s5
	s_mov_b32 m0, s34
	ds_read_b128 v[182:185], v149 offset:49152
	ds_read_b128 v[186:189], v149 offset:50176
	ds_read_b128 v[190:193], v149 offset:51200
	ds_read_b128 v[194:197], v149 offset:52224
	ds_read_b128 v[198:201], v149 offset:53248
	ds_read_b128 v[202:205], v149 offset:54272
	ds_read_b128 v[206:209], v149 offset:55296
	ds_read_b128 v[210:213], v149 offset:56320
	global_load_lds_dwordx4 v132, s[98:99]
	s_add_i32 m0, s34, 0x2000
	s_add_u32 s30, s30, 0x40080
	s_addc_u32 s31, s31, 0
	s_add_i32 s34, s56, s5
	global_load_lds_dwordx4 v128, s[98:99]
	s_mov_b32 m0, s34
	s_nop 0
	global_load_lds_dwordx4 v132, s[30:31]
	s_add_i32 m0, s34, 0x2000
	s_nop 0
	global_load_lds_dwordx4 v128, s[30:31]
	s_waitcnt vmcnt(6)
	s_waitcnt lgkmcnt(0)
	s_barrier
	v_mfma_f32_16x16x32_bf16 v[60:63], v[150:153], v[182:185], v[60:63]
	v_mfma_f32_16x16x32_bf16 v[56:59], v[158:161], v[182:185], v[56:59]
	v_mfma_f32_16x16x32_bf16 v[44:47], v[150:153], v[190:193], v[44:47]
	v_mfma_f32_16x16x32_bf16 v[40:43], v[158:161], v[190:193], v[40:43]
	v_mfma_f32_16x16x32_bf16 v[28:31], v[150:153], v[198:201], v[28:31]
	v_mfma_f32_16x16x32_bf16 v[24:27], v[158:161], v[198:201], v[24:27]
	v_mfma_f32_16x16x32_bf16 v[12:15], v[150:153], v[206:209], v[12:15]
	v_mfma_f32_16x16x32_bf16 v[8:11], v[158:161], v[206:209], v[8:11]
	v_mfma_f32_16x16x32_bf16 v[60:63], v[154:157], v[186:189], v[60:63]
	v_mfma_f32_16x16x32_bf16 v[56:59], v[162:165], v[186:189], v[56:59]
	v_mfma_f32_16x16x32_bf16 v[44:47], v[154:157], v[194:197], v[44:47]
	v_mfma_f32_16x16x32_bf16 v[40:43], v[162:165], v[194:197], v[40:43]
	v_mfma_f32_16x16x32_bf16 v[28:31], v[154:157], v[202:205], v[28:31]
	v_mfma_f32_16x16x32_bf16 v[24:27], v[162:165], v[202:205], v[24:27]
	v_mfma_f32_16x16x32_bf16 v[12:15], v[154:157], v[210:213], v[12:15]
	v_mfma_f32_16x16x32_bf16 v[8:11], v[162:165], v[210:213], v[8:11]
	v_mfma_f32_16x16x32_bf16 v[52:55], v[166:169], v[182:185], v[52:55]
	v_mfma_f32_16x16x32_bf16 v[48:51], v[174:177], v[182:185], v[48:51]
	v_mfma_f32_16x16x32_bf16 v[36:39], v[166:169], v[190:193], v[36:39]
	v_mfma_f32_16x16x32_bf16 v[32:35], v[174:177], v[190:193], v[32:35]
	v_mfma_f32_16x16x32_bf16 v[20:23], v[166:169], v[198:201], v[20:23]
	v_mfma_f32_16x16x32_bf16 v[16:19], v[174:177], v[198:201], v[16:19]
	v_mfma_f32_16x16x32_bf16 v[4:7], v[166:169], v[206:209], v[4:7]
	v_mfma_f32_16x16x32_bf16 v[0:3], v[174:177], v[206:209], v[0:3]
	v_mfma_f32_16x16x32_bf16 v[52:55], v[170:173], v[186:189], v[52:55]
	v_mfma_f32_16x16x32_bf16 v[48:51], v[178:181], v[186:189], v[48:51]
	v_mfma_f32_16x16x32_bf16 v[36:39], v[170:173], v[194:197], v[36:39]
	v_mfma_f32_16x16x32_bf16 v[32:35], v[178:181], v[194:197], v[32:35]
	v_mfma_f32_16x16x32_bf16 v[20:23], v[170:173], v[202:205], v[20:23]
	v_mfma_f32_16x16x32_bf16 v[16:19], v[178:181], v[202:205], v[16:19]
	v_mfma_f32_16x16x32_bf16 v[4:7], v[170:173], v[210:213], v[4:7]
	v_mfma_f32_16x16x32_bf16 v[0:3], v[178:181], v[210:213], v[0:3]
	s_barrier
	s_add_u32 s28, s28, 0x100
	s_addc_u32 s29, s29, 0
	s_add_u32 s52, s52, 0x100
	s_addc_u32 s53, s53, 0
	s_cmp_ge_i32 s54, s42
	s_mov_b32 s30, s54
	s_cbranch_scc0 .LBB0_1112
	s_setprio 0

; #define PG8_WAIT_V(n) asm volatile("s_waitcnt vmcnt(" #n ")" ::: "memory")
; #define PG8_WAIT_L(n) asm volatile("s_waitcnt lgkmcnt(" #n ")" ::: "memory")
; #define PG8_BAR __builtin_amdgcn_s_barrier()
;     ...
;         const char* nA = has_next ? (const char*)g.A + (size_t)nxt.pm * tsA : cA; const char* nB = has_next ? (const char*)g.Bt + (size_t)nxt.pn * tsB : cB;
;         for (int t = 0; t < nt; t += 2) {
;             const bool last = (t == nt - 2);
;             const char* a1 = cA + (size_t)(t + 1) * kstep;
;             const char* a2 = last ? nA : cA + (size_t)(t + 2) * kstep; const char* b2 = last ? nB : cB + (size_t)(t + 2) * kstep;
;             const char* a3 = a2 + kstep; const char* b3 = b2 + kstep;
;             PG8_LDB(B0, 0, 0); PG8_LDB(B1, 0, 1); PG8_SCHED; PG8_LDA(At, 0, 0); PG8_STAGE(PG8_SA(1, 1), a1 + hsA, voffA);
;             if (Epi::NPRE != 0 && last) { E.pre(sv, cur, wr, fr); PG8_WAIT_V(16); } else { PG8_WAIT_V(8); }
;             PG8_WAIT_L(0); PG8_BAR; PG8_MMA(0, 0, At, B0); PG8_MMA(0, 1, At, B1); PG8_BAR; PG8_SCHED;
;             PG8_LDA(At, 0, 1); PG8_STAGE(PG8_SB(0, 0), b2, voffB); PG8_STAGE(PG8_SB(0, 1), b2 + hsB, voffB); PG8_STAGE(PG8_SA(0, 0), a2, voffA);
;             if (Epi::NPRE != 0 && last) { PG8_WAIT_V(16); } else { PG8_WAIT_V(8); }
;             PG8_WAIT_L(0); PG8_BAR; PG8_MMA(1, 0, At, B0); PG8_MMA(1, 1, At, B1); PG8_BAR; PG8_SCHED;
;             PG8_LDB(B0, 1, 0); PG8_LDB(B1, 1, 1); PG8_SCHED; PG8_LDA(At, 1, 0); PG8_STAGE(PG8_SA(0, 1), a2 + hsA, voffA);
;             PG8_WAIT_V(8); PG8_WAIT_L(0); PG8_BAR; PG8_MMA(0, 0, At, B0); PG8_MMA(0, 1, At, B1); PG8_BAR; PG8_SCHED;
;             PG8_LDA(At, 1, 1); PG8_STAGE(PG8_SB(1, 0), b3, voffB); PG8_STAGE(PG8_SB(1, 1), b3 + hsB, voffB); PG8_STAGE(PG8_SA(1, 0), a3, voffA);
;             PG8_WAIT_V(8); PG8_WAIT_L(0); PG8_BAR; PG8_MMA(1, 0, At, B0); PG8_MMA(1, 1, At, B1); PG8_BAR; PG8_SCHED;
;         }
;         if constexpr (ALIGN_EPI) { if (wr == 0) PG8_BAR; }
;         E(acc, cur, wr, wc, fr, fq, sv);
;         if (!has_next) break;
; #pragma unroll
;         for (int a = 0; a < 2; ++a)
; #pragma unroll
;             for (int b = 0; b < 2; ++b)
; #pragma unroll
;                 for (int m = 0; m < 4; ++m)
; #pragma unroll
;                     for (int n = 0; n < 2; ++n) acc[a][b][m][n] = (f32x4){0.f, 0.f, 0.f, 0.f};
;         cur = nxt; cA = nA; cB = nB; ++ui;
.LBB0_1182:
	s_ashr_i32 s23, s22, 31
	s_lshl_b64 s[24:25], s[22:23], 20
	s_add_u32 s24, s96, s24
	s_addc_u32 s25, s97, s25
	s_ashr_i32 s21, s20, 31
	s_lshl_b64 s[26:27], s[20:21], 20
	s_add_u32 s26, s3, s26
	s_addc_u32 s27, s4, s27
	v_mov_b32_e32 v127, 0
	s_and_b64 vcc, exec, s[0:1]
	v_lshl_add_u32 v208, s28, 8, v220
	s_cbranch_vccnz .LBB0_1193
	s_and_b64 s[28:29], s[6:7], exec
	s_cselect_b32 s21, s25, s35
	s_cselect_b32 s23, s24, s34
	s_cselect_b32 s58, s27, s31
	s_cselect_b32 s59, s26, s30
	s_add_u32 s28, s34, 0x80080
	s_addc_u32 s29, s35, 0
	v_ashrrev_i32_e32 v209, 31, v208
	s_add_u32 s60, s30, 0x100
	v_mov_b32_e32 v0, 0
	v_lshl_add_u64 v[210:211], v[208:209], 2, s[88:89]
	s_addc_u32 s61, s31, 0
	s_mov_b32 s62, 0
	v_mov_b32_e32 v1, 0
	v_mov_b64_e32 v[2:3], 0
	v_mov_b64_e32 v[8:9], 0
	v_mov_b64_e32 v[10:11], 0
	v_mov_b64_e32 v[16:17], 0
	v_mov_b64_e32 v[18:19], 0
	v_mov_b64_e32 v[24:25], 0
	v_mov_b64_e32 v[26:27], 0
	v_mov_b64_e32 v[32:33], 0
	v_mov_b64_e32 v[34:35], 0
	v_mov_b64_e32 v[40:41], 0
	v_mov_b64_e32 v[42:43], 0
	v_mov_b64_e32 v[48:49], 0
	v_mov_b64_e32 v[50:51], 0
	v_mov_b64_e32 v[56:57], 0
	v_mov_b64_e32 v[58:59], 0
	v_mov_b64_e32 v[4:5], 0
	v_mov_b64_e32 v[6:7], 0
	v_mov_b64_e32 v[12:13], 0
	v_mov_b64_e32 v[14:15], 0
	v_mov_b64_e32 v[20:21], 0
	v_mov_b64_e32 v[22:23], 0
	v_mov_b64_e32 v[28:29], 0
	v_mov_b64_e32 v[30:31], 0
	v_mov_b64_e32 v[36:37], 0
	v_mov_b64_e32 v[38:39], 0
	v_mov_b64_e32 v[44:45], 0
	v_mov_b64_e32 v[46:47], 0
	v_mov_b64_e32 v[52:53], 0
	v_mov_b64_e32 v[54:55], 0
	v_mov_b64_e32 v[60:61], 0
	v_mov_b64_e32 v[62:63], 0
	v_mov_b64_e32 v[64:65], 0
	v_mov_b64_e32 v[66:67], 0
	v_mov_b64_e32 v[72:73], 0
	v_mov_b64_e32 v[74:75], 0
	v_mov_b64_e32 v[80:81], 0
	v_mov_b64_e32 v[82:83], 0
	v_mov_b64_e32 v[88:89], 0
	v_mov_b64_e32 v[90:91], 0
	v_mov_b64_e32 v[96:97], 0
	v_mov_b64_e32 v[98:99], 0
	v_mov_b64_e32 v[104:105], 0
	v_mov_b64_e32 v[106:107], 0
	v_mov_b64_e32 v[112:113], 0
	v_mov_b64_e32 v[114:115], 0
	v_mov_b64_e32 v[120:121], 0
	v_mov_b64_e32 v[122:123], 0
	v_mov_b64_e32 v[68:69], 0
	v_mov_b64_e32 v[70:71], 0
	v_mov_b64_e32 v[76:77], 0
	v_mov_b64_e32 v[78:79], 0
	v_mov_b64_e32 v[84:85], 0
	v_mov_b64_e32 v[86:87], 0
	v_mov_b64_e32 v[92:93], 0
	v_mov_b64_e32 v[94:95], 0
	v_mov_b64_e32 v[100:101], 0
	v_mov_b64_e32 v[102:103], 0
	v_mov_b64_e32 v[108:109], 0
	v_mov_b64_e32 v[110:111], 0
	v_mov_b64_e32 v[116:117], 0
	v_mov_b64_e32 v[118:119], 0
	v_mov_b64_e32 v[124:125], 0
	v_mov_b64_e32 v[126:127], 0
	v_readfirstlane_b32 s99, v234
	s_nop 0
	s_lshr_b32 s99, s99, 8
	s_cmp_eq_u32 s99, 0
	s_cbranch_scc1 .Lsp_8
	s_setprio 1

; #define PG8_STAGE(bufoff, gbase, voff) do { _Pragma("unroll") for (int _i = 0; _i < 2; ++_i) \
;         __builtin_amdgcn_global_load_lds((const unsigned*)((const char*)(gbase) + (voff)[_i]), (LAS unsigned*)(lds + (bufoff) + ldsw + _i * 8192), 16, 0, ((voff) == voffA ? AUXA : 0)); } while (0)
; #define PG8_LDA(dst, b, h) do { _Pragma("unroll") for (int m = 0; m < 4; ++m) _Pragma("unroll") for (int k = 0; k < 2; ++k) dst[m][k] = *(const LAS bf16x8*)(lds + PG8_SA(b, h) + aoff + m * 2048 + k * 1024); } while (0)
; #define PG8_LDB(dst, b, h) do { _Pragma("unroll") for (int n = 0; n < 2; ++n) _Pragma("unroll") for (int k = 0; k < 2; ++k) dst[n][k] = *(const LAS bf16x8*)(lds + PG8_SB(b, h) + boff + n * 2048 + k * 1024); } while (0)
; #define PG8_MMA(ai, bj, At, Bt) do { __builtin_amdgcn_s_setprio(1); _Pragma("unroll") for (int m = 0; m < 4; ++m) _Pragma("unroll") for (int n = 0; n < 2; ++n) _Pragma("unroll") for (int k = 0; k < 2; ++k) \
;         acc[ai][bj][m][n] = __builtin_amdgcn_mfma_f32_16x16x32_bf16(Bt[n][k], At[m][k], acc[ai][bj][m][n], 0, 0, 0); __builtin_amdgcn_s_setprio(0); } while (0)
; #define PG8_WAIT_V(n) asm volatile("s_waitcnt vmcnt(" #n ")" ::: "memory")
; #define PG8_WAIT_L(n) asm volatile("s_waitcnt lgkmcnt(" #n ")" ::: "memory")
; #define PG8_BAR __builtin_amdgcn_s_barrier()
; #define PG8_SCHED __builtin_amdgcn_sched_barrier(0)
;     ...
;             PG8_WAIT_L(0); PG8_BAR; PG8_MMA(1, 0, At, B0); PG8_MMA(1, 1, At, B1); PG8_BAR; PG8_SCHED;
;             PG8_LDB(B0, 1, 0); PG8_LDB(B1, 1, 1); PG8_SCHED; PG8_LDA(At, 1, 0); PG8_STAGE(PG8_SA(0, 1), a2 + hsA, voffA);
;             PG8_WAIT_V(8); PG8_WAIT_L(0); PG8_BAR; PG8_MMA(0, 0, At, B0); PG8_MMA(0, 1, At, B1); PG8_BAR; PG8_SCHED;
.LBB0_1184:
	s_waitcnt lgkmcnt(0)
	s_add_i32 s62, s62, 2
	s_barrier
	v_mfma_f32_16x16x32_bf16 v[60:63], v[144:147], v[184:187], v[60:63]
	v_mfma_f32_16x16x32_bf16 v[52:55], v[152:155], v[184:187], v[52:55]
	v_mfma_f32_16x16x32_bf16 v[44:47], v[144:147], v[176:179], v[44:47]
	v_mfma_f32_16x16x32_bf16 v[36:39], v[152:155], v[176:179], v[36:39]
	v_mfma_f32_16x16x32_bf16 v[28:31], v[144:147], v[168:171], v[28:31]
	v_mfma_f32_16x16x32_bf16 v[20:23], v[152:155], v[168:171], v[20:23]
	v_mfma_f32_16x16x32_bf16 v[12:15], v[144:147], v[160:163], v[12:15]
	v_mfma_f32_16x16x32_bf16 v[4:7], v[152:155], v[160:163], v[4:7]
	v_mfma_f32_16x16x32_bf16 v[60:63], v[148:151], v[188:191], v[60:63]
	v_mfma_f32_16x16x32_bf16 v[52:55], v[156:159], v[188:191], v[52:55]
	v_mfma_f32_16x16x32_bf16 v[44:47], v[148:151], v[180:183], v[44:47]
	v_mfma_f32_16x16x32_bf16 v[36:39], v[156:159], v[180:183], v[36:39]
	v_mfma_f32_16x16x32_bf16 v[28:31], v[148:151], v[172:175], v[28:31]
	v_mfma_f32_16x16x32_bf16 v[20:23], v[156:159], v[172:175], v[20:23]
	v_mfma_f32_16x16x32_bf16 v[12:15], v[148:151], v[164:167], v[12:15]
	v_mfma_f32_16x16x32_bf16 v[4:7], v[156:159], v[164:167], v[4:7]
	v_mfma_f32_16x16x32_bf16 v[56:59], v[128:131], v[184:187], v[56:59]
	v_mfma_f32_16x16x32_bf16 v[48:51], v[136:139], v[184:187], v[48:51]
	v_mfma_f32_16x16x32_bf16 v[40:43], v[128:131], v[176:179], v[40:43]
	v_mfma_f32_16x16x32_bf16 v[32:35], v[136:139], v[176:179], v[32:35]
	v_mfma_f32_16x16x32_bf16 v[24:27], v[128:131], v[168:171], v[24:27]
	v_mfma_f32_16x16x32_bf16 v[16:19], v[136:139], v[168:171], v[16:19]
	v_mfma_f32_16x16x32_bf16 v[8:11], v[128:131], v[160:163], v[8:11]
	v_mfma_f32_16x16x32_bf16 v[0:3], v[136:139], v[160:163], v[0:3]
	v_mfma_f32_16x16x32_bf16 v[56:59], v[132:135], v[188:191], v[56:59]
	v_mfma_f32_16x16x32_bf16 v[48:51], v[140:143], v[188:191], v[48:51]
	v_mfma_f32_16x16x32_bf16 v[40:43], v[132:135], v[180:183], v[40:43]
	v_mfma_f32_16x16x32_bf16 v[32:35], v[140:143], v[180:183], v[32:35]
	v_mfma_f32_16x16x32_bf16 v[24:27], v[132:135], v[172:175], v[24:27]
	v_mfma_f32_16x16x32_bf16 v[16:19], v[140:143], v[172:175], v[16:19]
	v_mfma_f32_16x16x32_bf16 v[8:11], v[132:135], v[164:167], v[8:11]
	v_mfma_f32_16x16x32_bf16 v[0:3], v[140:143], v[164:167], v[0:3]
	s_barrier
	s_mov_b32 m0, s42
	s_nop 0
	global_load_lds_dwordx4 v198, s[34:35]
	s_mov_b32 m0, s47
	s_nop 0
	global_load_lds_dwordx4 v194, s[34:35]
	s_add_i32 s36, 0, 0x18000
	s_add_i32 s37, 0, 0x1c000
	v_add_u32_e32 v140, s36, v221
	v_add_u32_e32 v156, s37, v221
	ds_read_b128 v[128:131], v140
	ds_read_b128 v[132:135], v140 offset:1024
	ds_read_b128 v[136:139], v140 offset:2048
	ds_read_b128 v[140:143], v140 offset:3072
	ds_read_b128 v[144:147], v156
	ds_read_b128 v[148:151], v156 offset:1024
	ds_read_b128 v[152:155], v156 offset:2048
	ds_read_b128 v[156:159], v156 offset:3072
	s_add_u32 s34, s34, 0x80000
	s_addc_u32 s35, s35, 0
	s_mov_b32 m0, s48
	ds_read_b128 v[160:163], v225 offset:32768
	ds_read_b128 v[164:167], v225 offset:33792
	ds_read_b128 v[168:171], v225 offset:34816
	ds_read_b128 v[172:175], v225 offset:35840
	ds_read_b128 v[176:179], v225 offset:36864
	ds_read_b128 v[180:183], v225 offset:37888
	ds_read_b128 v[184:187], v225 offset:38912
	ds_read_b128 v[188:191], v225 offset:39936
	global_load_lds_dwordx4 v198, s[34:35]
	s_mov_b32 m0, s49
	s_nop 0
	global_load_lds_dwordx4 v194, s[34:35]
	s_waitcnt vmcnt(8)
	s_waitcnt lgkmcnt(0)
	s_barrier
; #define PG8_STAGE(bufoff, gbase, voff) do { _Pragma("unroll") for (int _i = 0; _i < 2; ++_i) \
;         __builtin_amdgcn_global_load_lds((const unsigned*)((const char*)(gbase) + (voff)[_i]), (LAS unsigned*)(lds + (bufoff) + ldsw + _i * 8192), 16, 0, ((voff) == voffA ? AUXA : 0)); } while (0)
; #define PG8_LDA(dst, b, h) do { _Pragma("unroll") for (int m = 0; m < 4; ++m) _Pragma("unroll") for (int k = 0; k < 2; ++k) dst[m][k] = *(const LAS bf16x8*)(lds + PG8_SA(b, h) + aoff + m * 2048 + k * 1024); } while (0)
; #define PG8_MMA(ai, bj, At, Bt) do { __builtin_amdgcn_s_setprio(1); _Pragma("unroll") for (int m = 0; m < 4; ++m) _Pragma("unroll") for (int n = 0; n < 2; ++n) _Pragma("unroll") for (int k = 0; k < 2; ++k) \
;         acc[ai][bj][m][n] = __builtin_amdgcn_mfma_f32_16x16x32_bf16(Bt[n][k], At[m][k], acc[ai][bj][m][n], 0, 0, 0); __builtin_amdgcn_s_setprio(0); } while (0)
; #define PG8_WAIT_V(n) asm volatile("s_waitcnt vmcnt(" #n ")" ::: "memory")
; #define PG8_WAIT_L(n) asm volatile("s_waitcnt lgkmcnt(" #n ")" ::: "memory")
; #define PG8_BAR __builtin_amdgcn_s_barrier()
; #define PG8_SCHED __builtin_amdgcn_sched_barrier(0)
;     ...
;             PG8_WAIT_V(8); PG8_WAIT_L(0); PG8_BAR; PG8_MMA(0, 0, At, B0); PG8_MMA(0, 1, At, B1); PG8_BAR; PG8_SCHED;
;             PG8_LDA(At, 1, 1); PG8_STAGE(PG8_SB(1, 0), b3, voffB); PG8_STAGE(PG8_SB(1, 1), b3 + hsB, voffB); PG8_STAGE(PG8_SA(1, 0), a3, voffA);
;             PG8_WAIT_V(8); PG8_WAIT_L(0); PG8_BAR; PG8_MMA(1, 0, At, B0); PG8_MMA(1, 1, At, B1); PG8_BAR; PG8_SCHED;
;         }
	v_mfma_f32_16x16x32_bf16 v[124:127], v[128:131], v[160:163], v[124:127]
	v_mfma_f32_16x16x32_bf16 v[116:119], v[136:139], v[160:163], v[116:119]
	v_mfma_f32_16x16x32_bf16 v[108:111], v[128:131], v[168:171], v[108:111]
	v_mfma_f32_16x16x32_bf16 v[100:103], v[136:139], v[168:171], v[100:103]
	v_mfma_f32_16x16x32_bf16 v[92:95], v[128:131], v[176:179], v[92:95]
	v_mfma_f32_16x16x32_bf16 v[84:87], v[136:139], v[176:179], v[84:87]
	v_mfma_f32_16x16x32_bf16 v[76:79], v[128:131], v[184:187], v[76:79]
	v_mfma_f32_16x16x32_bf16 v[68:71], v[136:139], v[184:187], v[68:71]
	v_mfma_f32_16x16x32_bf16 v[124:127], v[132:135], v[164:167], v[124:127]
	v_mfma_f32_16x16x32_bf16 v[116:119], v[140:143], v[164:167], v[116:119]
	v_mfma_f32_16x16x32_bf16 v[108:111], v[132:135], v[172:175], v[108:111]
	v_mfma_f32_16x16x32_bf16 v[100:103], v[140:143], v[172:175], v[100:103]
	v_mfma_f32_16x16x32_bf16 v[92:95], v[132:135], v[180:183], v[92:95]
	v_mfma_f32_16x16x32_bf16 v[84:87], v[140:143], v[180:183], v[84:87]
	v_mfma_f32_16x16x32_bf16 v[76:79], v[132:135], v[188:191], v[76:79]
	v_mfma_f32_16x16x32_bf16 v[68:71], v[140:143], v[188:191], v[68:71]
	v_mfma_f32_16x16x32_bf16 v[120:123], v[144:147], v[160:163], v[120:123]
	v_mfma_f32_16x16x32_bf16 v[112:115], v[152:155], v[160:163], v[112:115]
	v_mfma_f32_16x16x32_bf16 v[104:107], v[144:147], v[168:171], v[104:107]
	v_mfma_f32_16x16x32_bf16 v[96:99], v[152:155], v[168:171], v[96:99]
	v_mfma_f32_16x16x32_bf16 v[88:91], v[144:147], v[176:179], v[88:91]
	v_mfma_f32_16x16x32_bf16 v[80:83], v[152:155], v[176:179], v[80:83]
	v_mfma_f32_16x16x32_bf16 v[72:75], v[144:147], v[184:187], v[72:75]
	v_mfma_f32_16x16x32_bf16 v[64:67], v[152:155], v[184:187], v[64:67]
	v_mfma_f32_16x16x32_bf16 v[120:123], v[148:151], v[164:167], v[120:123]
	v_mfma_f32_16x16x32_bf16 v[112:115], v[156:159], v[164:167], v[112:115]
	v_mfma_f32_16x16x32_bf16 v[104:107], v[148:151], v[172:175], v[104:107]
	v_mfma_f32_16x16x32_bf16 v[96:99], v[156:159], v[172:175], v[96:99]
	v_mfma_f32_16x16x32_bf16 v[88:91], v[148:151], v[180:183], v[88:91]
	v_mfma_f32_16x16x32_bf16 v[80:83], v[156:159], v[180:183], v[80:83]
	v_mfma_f32_16x16x32_bf16 v[72:75], v[148:151], v[188:191], v[72:75]
	v_mfma_f32_16x16x32_bf16 v[64:67], v[156:159], v[188:191], v[64:67]
	s_barrier
	s_add_i32 s34, s36, s5
	s_mov_b32 m0, s34
	ds_read_b128 v[160:163], v225 offset:49152
	ds_read_b128 v[164:167], v225 offset:50176
	ds_read_b128 v[168:171], v225 offset:51200
	ds_read_b128 v[172:175], v225 offset:52224
	ds_read_b128 v[176:179], v225 offset:53248
	ds_read_b128 v[180:183], v225 offset:54272
	ds_read_b128 v[184:187], v225 offset:55296
	ds_read_b128 v[188:191], v225 offset:56320
	global_load_lds_dwordx4 v196, s[98:99]
	s_add_i32 m0, s34, 0x2000
	s_add_u32 s30, s30, 0x80080
	s_addc_u32 s31, s31, 0
	s_add_i32 s34, s37, s5
	global_load_lds_dwordx4 v192, s[98:99]
	s_mov_b32 m0, s34
	s_nop 0
	global_load_lds_dwordx4 v196, s[30:31]
	s_add_i32 m0, s34, 0x2000
	s_nop 0
	global_load_lds_dwordx4 v192, s[30:31]
	s_waitcnt vmcnt(6)
	s_waitcnt lgkmcnt(0)
	s_barrier
	v_mfma_f32_16x16x32_bf16 v[60:63], v[128:131], v[160:163], v[60:63]
	v_mfma_f32_16x16x32_bf16 v[52:55], v[136:139], v[160:163], v[52:55]
	v_mfma_f32_16x16x32_bf16 v[44:47], v[128:131], v[168:171], v[44:47]
	v_mfma_f32_16x16x32_bf16 v[36:39], v[136:139], v[168:171], v[36:39]
	v_mfma_f32_16x16x32_bf16 v[28:31], v[128:131], v[176:179], v[28:31]
	v_mfma_f32_16x16x32_bf16 v[20:23], v[136:139], v[176:179], v[20:23]
	v_mfma_f32_16x16x32_bf16 v[12:15], v[128:131], v[184:187], v[12:15]
	v_mfma_f32_16x16x32_bf16 v[4:7], v[136:139], v[184:187], v[4:7]
	v_mfma_f32_16x16x32_bf16 v[60:63], v[132:135], v[164:167], v[60:63]
	v_mfma_f32_16x16x32_bf16 v[52:55], v[140:143], v[164:167], v[52:55]
	v_mfma_f32_16x16x32_bf16 v[44:47], v[132:135], v[172:175], v[44:47]
	v_mfma_f32_16x16x32_bf16 v[36:39], v[140:143], v[172:175], v[36:39]
	v_mfma_f32_16x16x32_bf16 v[28:31], v[132:135], v[180:183], v[28:31]
	v_mfma_f32_16x16x32_bf16 v[20:23], v[140:143], v[180:183], v[20:23]
	v_mfma_f32_16x16x32_bf16 v[12:15], v[132:135], v[188:191], v[12:15]
	v_mfma_f32_16x16x32_bf16 v[4:7], v[140:143], v[188:191], v[4:7]
	v_mfma_f32_16x16x32_bf16 v[56:59], v[144:147], v[160:163], v[56:59]
	v_mfma_f32_16x16x32_bf16 v[48:51], v[152:155], v[160:163], v[48:51]
	v_mfma_f32_16x16x32_bf16 v[40:43], v[144:147], v[168:171], v[40:43]
	v_mfma_f32_16x16x32_bf16 v[32:35], v[152:155], v[168:171], v[32:35]
	v_mfma_f32_16x16x32_bf16 v[24:27], v[144:147], v[176:179], v[24:27]
	v_mfma_f32_16x16x32_bf16 v[16:19], v[152:155], v[176:179], v[16:19]
	v_mfma_f32_16x16x32_bf16 v[8:11], v[144:147], v[184:187], v[8:11]
	v_mfma_f32_16x16x32_bf16 v[0:3], v[152:155], v[184:187], v[0:3]
	v_mfma_f32_16x16x32_bf16 v[56:59], v[148:151], v[164:167], v[56:59]
	v_mfma_f32_16x16x32_bf16 v[48:51], v[156:159], v[164:167], v[48:51]
	v_mfma_f32_16x16x32_bf16 v[40:43], v[148:151], v[172:175], v[40:43]
	v_mfma_f32_16x16x32_bf16 v[32:35], v[156:159], v[172:175], v[32:35]
	v_mfma_f32_16x16x32_bf16 v[24:27], v[148:151], v[180:183], v[24:27]
	v_mfma_f32_16x16x32_bf16 v[16:19], v[156:159], v[180:183], v[16:19]
	v_mfma_f32_16x16x32_bf16 v[8:11], v[148:151], v[188:191], v[8:11]
	v_mfma_f32_16x16x32_bf16 v[0:3], v[156:159], v[188:191], v[0:3]
	s_barrier
	s_add_u32 s28, s28, 0x100
	s_addc_u32 s29, s29, 0
	s_add_u32 s60, s60, 0x100
	s_addc_u32 s61, s61, 0
	s_cmp_ge_i32 s62, s51
	s_cbranch_scc1 .Lspx_8

; #define PG8_STAGE(bufoff, gbase, voff) do { _Pragma("unroll") for (int _i = 0; _i < 2; ++_i) \
;         __builtin_amdgcn_global_load_lds((const unsigned*)((const char*)(gbase) + (voff)[_i]), (LAS unsigned*)(lds + (bufoff) + ldsw + _i * 8192), 16, 0, ((voff) == voffA ? AUXA : 0)); } while (0)
; #define PG8_LDA(dst, b, h) do { _Pragma("unroll") for (int m = 0; m < 4; ++m) _Pragma("unroll") for (int k = 0; k < 2; ++k) dst[m][k] = *(const LAS bf16x8*)(lds + PG8_SA(b, h) + aoff + m * 2048 + k * 1024); } while (0)
; #define PG8_LDB(dst, b, h) do { _Pragma("unroll") for (int n = 0; n < 2; ++n) _Pragma("unroll") for (int k = 0; k < 2; ++k) dst[n][k] = *(const LAS bf16x8*)(lds + PG8_SB(b, h) + boff + n * 2048 + k * 1024); } while (0)
; #define PG8_MMA(ai, bj, At, Bt) do { __builtin_amdgcn_s_setprio(1); _Pragma("unroll") for (int m = 0; m < 4; ++m) _Pragma("unroll") for (int n = 0; n < 2; ++n) _Pragma("unroll") for (int k = 0; k < 2; ++k) \
;         acc[ai][bj][m][n] = __builtin_amdgcn_mfma_f32_16x16x32_bf16(Bt[n][k], At[m][k], acc[ai][bj][m][n], 0, 0, 0); __builtin_amdgcn_s_setprio(0); } while (0)
; #define PG8_WAIT_V(n) asm volatile("s_waitcnt vmcnt(" #n ")" ::: "memory")
; #define PG8_WAIT_L(n) asm volatile("s_waitcnt lgkmcnt(" #n ")" ::: "memory")
; #define PG8_BAR __builtin_amdgcn_s_barrier()
; #define PG8_SCHED __builtin_amdgcn_sched_barrier(0)
;     ...
;             const char* a2 = last ? nA : cA + (size_t)(t + 2) * kstep; const char* b2 = last ? nB : cB + (size_t)(t + 2) * kstep;
;             const char* a3 = a2 + kstep; const char* b3 = b2 + kstep;
;             PG8_LDB(B0, 0, 0); PG8_LDB(B1, 0, 1); PG8_SCHED; PG8_LDA(At, 0, 0); PG8_STAGE(PG8_SA(1, 1), a1 + hsA, voffA);
;             if (Epi::NPRE != 0 && last) { E.pre(sv, cur, wr, fr); PG8_WAIT_V(16); } else { PG8_WAIT_V(8); }
;             PG8_WAIT_L(0); PG8_BAR; PG8_MMA(0, 0, At, B0); PG8_MMA(0, 1, At, B1); PG8_BAR; PG8_SCHED;
;             PG8_LDA(At, 0, 1); PG8_STAGE(PG8_SB(0, 0), b2, voffB); PG8_STAGE(PG8_SB(0, 1), b2 + hsB, voffB); PG8_STAGE(PG8_SA(0, 0), a2, voffA);
;             if (Epi::NPRE != 0 && last) { PG8_WAIT_V(16); } else { PG8_WAIT_V(8); }
.LBB0_1189:
	s_add_u32 s34, s28, 0xfff80080
	s_addc_u32 s35, s29, -1
	s_waitcnt lgkmcnt(0)
	s_and_b64 s[30:31], s[30:31], exec
	s_cselect_b32 s35, s21, s35
	s_cselect_b32 s34, s23, s34
	s_cselect_b32 s31, s58, s61
	s_cselect_b32 s30, s59, s60
	s_barrier
	v_mfma_f32_16x16x32_bf16 v[124:127], v[144:147], v[184:187], v[124:127]
	v_mfma_f32_16x16x32_bf16 v[116:119], v[152:155], v[184:187], v[116:119]
	v_mfma_f32_16x16x32_bf16 v[108:111], v[144:147], v[176:179], v[108:111]
	v_mfma_f32_16x16x32_bf16 v[100:103], v[152:155], v[176:179], v[100:103]
	v_mfma_f32_16x16x32_bf16 v[92:95], v[144:147], v[168:171], v[92:95]
	v_mfma_f32_16x16x32_bf16 v[84:87], v[152:155], v[168:171], v[84:87]
	v_mfma_f32_16x16x32_bf16 v[76:79], v[144:147], v[160:163], v[76:79]
	v_mfma_f32_16x16x32_bf16 v[68:71], v[152:155], v[160:163], v[68:71]
	v_mfma_f32_16x16x32_bf16 v[124:127], v[148:151], v[188:191], v[124:127]
	v_mfma_f32_16x16x32_bf16 v[116:119], v[156:159], v[188:191], v[116:119]
	v_mfma_f32_16x16x32_bf16 v[108:111], v[148:151], v[180:183], v[108:111]
	v_mfma_f32_16x16x32_bf16 v[100:103], v[156:159], v[180:183], v[100:103]
	v_mfma_f32_16x16x32_bf16 v[92:95], v[148:151], v[172:175], v[92:95]
	v_mfma_f32_16x16x32_bf16 v[84:87], v[156:159], v[172:175], v[84:87]
	v_mfma_f32_16x16x32_bf16 v[76:79], v[148:151], v[164:167], v[76:79]
	v_mfma_f32_16x16x32_bf16 v[68:71], v[156:159], v[164:167], v[68:71]
	v_mfma_f32_16x16x32_bf16 v[120:123], v[128:131], v[184:187], v[120:123]
	v_mfma_f32_16x16x32_bf16 v[112:115], v[136:139], v[184:187], v[112:115]
	v_mfma_f32_16x16x32_bf16 v[104:107], v[128:131], v[176:179], v[104:107]
	v_mfma_f32_16x16x32_bf16 v[96:99], v[136:139], v[176:179], v[96:99]
	v_mfma_f32_16x16x32_bf16 v[88:91], v[128:131], v[168:171], v[88:91]
	v_mfma_f32_16x16x32_bf16 v[80:83], v[136:139], v[168:171], v[80:83]
	v_mfma_f32_16x16x32_bf16 v[72:75], v[128:131], v[160:163], v[72:75]
	v_mfma_f32_16x16x32_bf16 v[64:67], v[136:139], v[160:163], v[64:67]
	v_mfma_f32_16x16x32_bf16 v[120:123], v[132:135], v[188:191], v[120:123]
	v_mfma_f32_16x16x32_bf16 v[112:115], v[140:143], v[188:191], v[112:115]
	v_mfma_f32_16x16x32_bf16 v[104:107], v[132:135], v[180:183], v[104:107]
	v_mfma_f32_16x16x32_bf16 v[96:99], v[140:143], v[180:183], v[96:99]
	v_mfma_f32_16x16x32_bf16 v[88:91], v[132:135], v[172:175], v[88:91]
	v_mfma_f32_16x16x32_bf16 v[80:83], v[140:143], v[172:175], v[80:83]
	v_mfma_f32_16x16x32_bf16 v[72:75], v[132:135], v[164:167], v[72:75]
	v_mfma_f32_16x16x32_bf16 v[64:67], v[140:143], v[164:167], v[64:67]
	s_barrier
	s_add_u32 s98, s30, s16
	s_addc_u32 s99, s31, s17
	s_add_u32 s100, s34, s16
	s_addc_u32 s101, s35, s17
	s_mov_b32 m0, s43
	s_add_u32 s38, s30, 0x80000
	ds_read_b128 v[184:187], v225 offset:16384
	ds_read_b128 v[188:191], v225 offset:17408
	ds_read_b128 v[176:179], v225 offset:18432
	ds_read_b128 v[180:183], v225 offset:19456
	ds_read_b128 v[168:171], v225 offset:20480
	ds_read_b128 v[172:175], v225 offset:21504
	ds_read_b128 v[160:163], v225 offset:22528
	ds_read_b128 v[164:167], v225 offset:23552
	global_load_lds_dwordx4 v196, s[30:31]
	s_mov_b32 m0, s44
	s_addc_u32 s39, s31, 0
	global_load_lds_dwordx4 v192, s[30:31]
	s_mov_b32 m0, s45
	s_nop 0
	global_load_lds_dwordx4 v196, s[38:39]
	s_mov_b32 m0, s46
	s_nop 0
	global_load_lds_dwordx4 v192, s[38:39]
	s_mov_b64 s[38:39], -1
	s_and_b64 vcc, exec, s[36:37]
	s_cbranch_vccz .LBB0_1191
	s_waitcnt vmcnt(6)
	s_mov_b64 s[38:39], 0

; #define PG8_WAIT_V(n) asm volatile("s_waitcnt vmcnt(" #n ")" ::: "memory")
; #define PG8_WAIT_L(n) asm volatile("s_waitcnt lgkmcnt(" #n ")" ::: "memory")
; #define PG8_BAR __builtin_amdgcn_s_barrier()
;     ...
;         const char* nA = has_next ? (const char*)g.A + (size_t)nxt.pm * tsA : cA; const char* nB = has_next ? (const char*)g.Bt + (size_t)nxt.pn * tsB : cB;
;         for (int t = 0; t < nt; t += 2) {
;             const bool last = (t == nt - 2);
;             const char* a1 = cA + (size_t)(t + 1) * kstep;
;             const char* a2 = last ? nA : cA + (size_t)(t + 2) * kstep; const char* b2 = last ? nB : cB + (size_t)(t + 2) * kstep;
;             const char* a3 = a2 + kstep; const char* b3 = b2 + kstep;
;             PG8_LDB(B0, 0, 0); PG8_LDB(B1, 0, 1); PG8_SCHED; PG8_LDA(At, 0, 0); PG8_STAGE(PG8_SA(1, 1), a1 + hsA, voffA);
;             if (Epi::NPRE != 0 && last) { E.pre(sv, cur, wr, fr); PG8_WAIT_V(16); } else { PG8_WAIT_V(8); }
;             PG8_WAIT_L(0); PG8_BAR; PG8_MMA(0, 0, At, B0); PG8_MMA(0, 1, At, B1); PG8_BAR; PG8_SCHED;
;             PG8_LDA(At, 0, 1); PG8_STAGE(PG8_SB(0, 0), b2, voffB); PG8_STAGE(PG8_SB(0, 1), b2 + hsB, voffB); PG8_STAGE(PG8_SA(0, 0), a2, voffA);
;             if (Epi::NPRE != 0 && last) { PG8_WAIT_V(16); } else { PG8_WAIT_V(8); }
;             PG8_WAIT_L(0); PG8_BAR; PG8_MMA(1, 0, At, B0); PG8_MMA(1, 1, At, B1); PG8_BAR; PG8_SCHED;
;             PG8_LDB(B0, 1, 0); PG8_LDB(B1, 1, 1); PG8_SCHED; PG8_LDA(At, 1, 0); PG8_STAGE(PG8_SA(0, 1), a2 + hsA, voffA);
;             PG8_WAIT_V(8); PG8_WAIT_L(0); PG8_BAR; PG8_MMA(0, 0, At, B0); PG8_MMA(0, 1, At, B1); PG8_BAR; PG8_SCHED;
;             PG8_LDA(At, 1, 1); PG8_STAGE(PG8_SB(1, 0), b3, voffB); PG8_STAGE(PG8_SB(1, 1), b3 + hsB, voffB); PG8_STAGE(PG8_SA(1, 0), a3, voffA);
;             PG8_WAIT_V(8); PG8_WAIT_L(0); PG8_BAR; PG8_MMA(1, 0, At, B0); PG8_MMA(1, 1, At, B1); PG8_BAR; PG8_SCHED;
;         }
;         if constexpr (ALIGN_EPI) { if (wr == 0) PG8_BAR; }
;         E(acc, cur, wr, wc, fr, fq, sv);
;         if (!has_next) break;
; #pragma unroll
;         for (int a = 0; a < 2; ++a)
; #pragma unroll
;             for (int b = 0; b < 2; ++b)
; #pragma unroll
;                 for (int m = 0; m < 4; ++m)
; #pragma unroll
;                     for (int n = 0; n < 2; ++n) acc[a][b][m][n] = (f32x4){0.f, 0.f, 0.f, 0.f};
;         cur = nxt; cA = nA; cB = nB; ++ui;
.LBB0_1265:
	s_ashr_i32 s23, s22, 31
	s_lshl_b64 s[24:25], s[22:23], 20
	s_add_u32 s24, s3, s24
	s_addc_u32 s25, s4, s25
	s_ashr_i32 s21, s20, 31
	s_lshl_b64 s[26:27], s[20:21], 20
	s_add_u32 s26, s5, s26
	v_mov_b32_e32 v127, 0
	s_addc_u32 s27, s40, s27
	s_and_b64 vcc, exec, s[6:7]
	v_mov_b32_e32 v126, 0
	v_mov_b64_e32 v[124:125], 0
	v_mov_b64_e32 v[122:123], 0
	v_mov_b64_e32 v[120:121], 0
	v_mov_b64_e32 v[110:111], 0
	v_mov_b64_e32 v[108:109], 0
	v_mov_b64_e32 v[106:107], 0
	v_mov_b64_e32 v[104:105], 0
	v_mov_b64_e32 v[94:95], 0
	v_mov_b64_e32 v[92:93], 0
	v_mov_b64_e32 v[90:91], 0
	v_mov_b64_e32 v[88:89], 0
	v_mov_b64_e32 v[78:79], 0
	v_mov_b64_e32 v[76:77], 0
	v_mov_b64_e32 v[74:75], 0
	v_mov_b64_e32 v[72:73], 0
	v_mov_b64_e32 v[118:119], 0
	v_mov_b64_e32 v[116:117], 0
	v_mov_b64_e32 v[114:115], 0
	v_mov_b64_e32 v[112:113], 0
	v_mov_b64_e32 v[102:103], 0
	v_mov_b64_e32 v[100:101], 0
	v_mov_b64_e32 v[98:99], 0
	v_mov_b64_e32 v[96:97], 0
	v_mov_b64_e32 v[86:87], 0
	v_mov_b64_e32 v[84:85], 0
	v_mov_b64_e32 v[82:83], 0
	v_mov_b64_e32 v[80:81], 0
	v_mov_b64_e32 v[70:71], 0
	v_mov_b64_e32 v[68:69], 0
	v_mov_b64_e32 v[66:67], 0
	v_mov_b64_e32 v[64:65], 0
	v_mov_b64_e32 v[62:63], 0
	v_mov_b64_e32 v[60:61], 0
	v_mov_b64_e32 v[58:59], 0
	v_mov_b64_e32 v[56:57], 0
	v_mov_b64_e32 v[46:47], 0
	v_mov_b64_e32 v[44:45], 0
	v_mov_b64_e32 v[42:43], 0
	v_mov_b64_e32 v[40:41], 0
	v_mov_b64_e32 v[30:31], 0
	v_mov_b64_e32 v[28:29], 0
	v_mov_b64_e32 v[26:27], 0
	v_mov_b64_e32 v[24:25], 0
	v_mov_b64_e32 v[14:15], 0
	v_mov_b64_e32 v[12:13], 0
	v_mov_b64_e32 v[10:11], 0
	v_mov_b64_e32 v[8:9], 0
	v_mov_b64_e32 v[54:55], 0
	v_mov_b64_e32 v[52:53], 0
	v_mov_b64_e32 v[50:51], 0
	v_mov_b64_e32 v[48:49], 0
	v_mov_b64_e32 v[38:39], 0
	v_mov_b64_e32 v[36:37], 0
	v_mov_b64_e32 v[34:35], 0
	v_mov_b64_e32 v[32:33], 0
	v_mov_b64_e32 v[22:23], 0
	v_mov_b64_e32 v[20:21], 0
	v_mov_b64_e32 v[18:19], 0
	v_mov_b64_e32 v[16:17], 0
	v_mov_b64_e32 v[6:7], 0
	v_mov_b64_e32 v[4:5], 0
	v_mov_b64_e32 v[2:3], 0
	s_waitcnt lgkmcnt(0)
	v_mov_b32_e32 v1, v127
	v_mov_b32_e32 v0, v127
	s_cbranch_vccnz .LBB0_1268
	s_and_b64 s[38:39], s[8:9], exec
	s_cselect_b32 s21, s25, s35
	s_cselect_b32 s23, s24, s34
	s_cselect_b32 s29, s27, s37
	s_cselect_b32 s55, s26, s36
	s_add_u32 s34, s34, 0x80080
	s_addc_u32 s35, s35, 0
	s_add_u32 s56, s36, 0x100
	v_mov_b32_e32 v0, 0
	s_addc_u32 s57, s37, 0
	s_mov_b32 s36, 0
	v_mov_b32_e32 v1, 0
	v_mov_b64_e32 v[2:3], 0
	v_mov_b64_e32 v[4:5], 0
	v_mov_b64_e32 v[6:7], 0
	v_mov_b64_e32 v[16:17], 0
	v_mov_b64_e32 v[18:19], 0
	v_mov_b64_e32 v[20:21], 0
	v_mov_b64_e32 v[22:23], 0
	v_mov_b64_e32 v[32:33], 0
	v_mov_b64_e32 v[34:35], 0
	v_mov_b64_e32 v[36:37], 0
	v_mov_b64_e32 v[38:39], 0
	v_mov_b64_e32 v[48:49], 0
	v_mov_b64_e32 v[50:51], 0
	v_mov_b64_e32 v[52:53], 0
	v_mov_b64_e32 v[54:55], 0
	v_mov_b64_e32 v[8:9], 0
	v_mov_b64_e32 v[10:11], 0
	v_mov_b64_e32 v[12:13], 0
	v_mov_b64_e32 v[14:15], 0
	v_mov_b64_e32 v[24:25], 0
	v_mov_b64_e32 v[26:27], 0
	v_mov_b64_e32 v[28:29], 0
	v_mov_b64_e32 v[30:31], 0
	v_mov_b64_e32 v[40:41], 0
	v_mov_b64_e32 v[42:43], 0
	v_mov_b64_e32 v[44:45], 0
	v_mov_b64_e32 v[46:47], 0
	v_mov_b64_e32 v[56:57], 0
	v_mov_b64_e32 v[58:59], 0
	v_mov_b64_e32 v[60:61], 0
	v_mov_b64_e32 v[62:63], 0
	v_mov_b64_e32 v[64:65], 0
	v_mov_b64_e32 v[66:67], 0
	v_mov_b64_e32 v[68:69], 0
	v_mov_b64_e32 v[70:71], 0
	v_mov_b64_e32 v[80:81], 0
	v_mov_b64_e32 v[82:83], 0
	v_mov_b64_e32 v[84:85], 0
	v_mov_b64_e32 v[86:87], 0
	v_mov_b64_e32 v[96:97], 0
	v_mov_b64_e32 v[98:99], 0
	v_mov_b64_e32 v[100:101], 0
	v_mov_b64_e32 v[102:103], 0
	v_mov_b64_e32 v[112:113], 0
	v_mov_b64_e32 v[114:115], 0
	v_mov_b64_e32 v[116:117], 0
	v_mov_b64_e32 v[118:119], 0
	v_mov_b64_e32 v[72:73], 0
	v_mov_b64_e32 v[74:75], 0
	v_mov_b64_e32 v[76:77], 0
	v_mov_b64_e32 v[78:79], 0
	v_mov_b64_e32 v[88:89], 0
	v_mov_b64_e32 v[90:91], 0
	v_mov_b64_e32 v[92:93], 0
	v_mov_b64_e32 v[94:95], 0
	v_mov_b64_e32 v[104:105], 0
	v_mov_b64_e32 v[106:107], 0
	v_mov_b64_e32 v[108:109], 0
	v_mov_b64_e32 v[110:111], 0
	v_mov_b64_e32 v[120:121], 0
	v_mov_b64_e32 v[122:123], 0
	v_mov_b64_e32 v[124:125], 0
	v_mov_b64_e32 v[126:127], 0
	v_readfirstlane_b32 s99, v234
	s_nop 0
	s_lshr_b32 s99, s99, 8
	s_cmp_eq_u32 s99, 0
	s_cbranch_scc1 .Lsp_9
	s_setprio 1
; #define PG8_STAGE(bufoff, gbase, voff) do { _Pragma("unroll") for (int _i = 0; _i < 2; ++_i) \
;         __builtin_amdgcn_global_load_lds((const unsigned*)((const char*)(gbase) + (voff)[_i]), (LAS unsigned*)(lds + (bufoff) + ldsw + _i * 8192), 16, 0, ((voff) == voffA ? AUXA : 0)); } while (0)
; #define PG8_LDA(dst, b, h) do { _Pragma("unroll") for (int m = 0; m < 4; ++m) _Pragma("unroll") for (int k = 0; k < 2; ++k) dst[m][k] = *(const LAS bf16x8*)(lds + PG8_SA(b, h) + aoff + m * 2048 + k * 1024); } while (0)
; #define PG8_LDB(dst, b, h) do { _Pragma("unroll") for (int n = 0; n < 2; ++n) _Pragma("unroll") for (int k = 0; k < 2; ++k) dst[n][k] = *(const LAS bf16x8*)(lds + PG8_SB(b, h) + boff + n * 2048 + k * 1024); } while (0)
; #define PG8_MMA(ai, bj, At, Bt) do { __builtin_amdgcn_s_setprio(1); _Pragma("unroll") for (int m = 0; m < 4; ++m) _Pragma("unroll") for (int n = 0; n < 2; ++n) _Pragma("unroll") for (int k = 0; k < 2; ++k) \
;         acc[ai][bj][m][n] = __builtin_amdgcn_mfma_f32_16x16x32_bf16(Bt[n][k], At[m][k], acc[ai][bj][m][n], 0, 0, 0); __builtin_amdgcn_s_setprio(0); } while (0)
; #define PG8_WAIT_V(n) asm volatile("s_waitcnt vmcnt(" #n ")" ::: "memory")
; #define PG8_WAIT_L(n) asm volatile("s_waitcnt lgkmcnt(" #n ")" ::: "memory")
; #define PG8_BAR __builtin_amdgcn_s_barrier()
; #define PG8_SCHED __builtin_amdgcn_sched_barrier(0)
;     ...
;         for (int t = 0; t < nt; t += 2) {
;             const bool last = (t == nt - 2);
;             const char* a1 = cA + (size_t)(t + 1) * kstep;
;             const char* a2 = last ? nA : cA + (size_t)(t + 2) * kstep; const char* b2 = last ? nB : cB + (size_t)(t + 2) * kstep;
;             const char* a3 = a2 + kstep; const char* b3 = b2 + kstep;
;             PG8_LDB(B0, 0, 0); PG8_LDB(B1, 0, 1); PG8_SCHED; PG8_LDA(At, 0, 0); PG8_STAGE(PG8_SA(1, 1), a1 + hsA, voffA);
;             if (Epi::NPRE != 0 && last) { E.pre(sv, cur, wr, fr); PG8_WAIT_V(16); } else { PG8_WAIT_V(8); }
;             PG8_WAIT_L(0); PG8_BAR; PG8_MMA(0, 0, At, B0); PG8_MMA(0, 1, At, B1); PG8_BAR; PG8_SCHED;
;             PG8_LDA(At, 0, 1); PG8_STAGE(PG8_SB(0, 0), b2, voffB); PG8_STAGE(PG8_SB(0, 1), b2 + hsB, voffB); PG8_STAGE(PG8_SA(0, 0), a2, voffA);
;             if (Epi::NPRE != 0 && last) { PG8_WAIT_V(16); } else { PG8_WAIT_V(8); }
;             PG8_WAIT_L(0); PG8_BAR; PG8_MMA(1, 0, At, B0); PG8_MMA(1, 1, At, B1); PG8_BAR; PG8_SCHED;
.Lsp_9:
.LBB0_1267:
	s_add_u32 s98, s34, 0xfff80000
	s_addc_u32 s99, s35, -1
	s_mov_b32 m0, s47
	s_nop 0
	global_load_lds_dwordx4 v152, s[98:99]
	s_mov_b32 m0, s48
	s_nop 0
	global_load_lds_dwordx4 v156, s[98:99]
	ds_read_b128 v[128:131], v189
	ds_read_b128 v[132:135], v189 offset:1024
	ds_read_b128 v[136:139], v189 offset:2048
	ds_read_b128 v[140:143], v189 offset:3072
	ds_read_b128 v[144:147], v190
	ds_read_b128 v[148:151], v190 offset:1024
	ds_read_b128 v[168:171], v190 offset:2048
	ds_read_b128 v[172:175], v190 offset:3072
	s_add_i32 s58, s36, 2
	s_add_u32 s37, s34, 0xfff80080
	s_addc_u32 s38, s35, -1
	s_cmp_eq_u32 s49, s36
	s_cselect_b32 s36, s55, s56
	s_cselect_b32 s39, s21, s38
	s_cselect_b32 s38, s23, s37
	s_cselect_b32 s37, s29, s57
	s_add_i32 m0, s31, 0xc000
	ds_read_b128 v[176:179], v191
	ds_read_b128 v[180:183], v191 offset:1024
	ds_read_b128 v[194:197], v191 offset:2048
	ds_read_b128 v[198:201], v191 offset:3072
	ds_read_b128 v[202:205], v191 offset:4096
	ds_read_b128 v[206:209], v191 offset:5120
	ds_read_b128 v[210:213], v191 offset:6144
	ds_read_b128 v[214:217], v191 offset:7168
	global_load_lds_dwordx4 v160, s[34:35]
	s_add_i32 m0, s31, 0xe000
	s_nop 0
	global_load_lds_dwordx4 v162, s[34:35]
	s_waitcnt vmcnt(8)
	s_waitcnt lgkmcnt(0)
	s_barrier
	v_mfma_f32_16x16x32_bf16 v[124:127], v[128:131], v[176:179], v[124:127]
	v_mfma_f32_16x16x32_bf16 v[120:123], v[136:139], v[176:179], v[120:123]
	v_mfma_f32_16x16x32_bf16 v[108:111], v[128:131], v[194:197], v[108:111]
	v_mfma_f32_16x16x32_bf16 v[104:107], v[136:139], v[194:197], v[104:107]
	v_mfma_f32_16x16x32_bf16 v[92:95], v[128:131], v[202:205], v[92:95]
	v_mfma_f32_16x16x32_bf16 v[88:91], v[136:139], v[202:205], v[88:91]
	v_mfma_f32_16x16x32_bf16 v[76:79], v[128:131], v[210:213], v[76:79]
	v_mfma_f32_16x16x32_bf16 v[72:75], v[136:139], v[210:213], v[72:75]
	v_mfma_f32_16x16x32_bf16 v[124:127], v[132:135], v[180:183], v[124:127]
	v_mfma_f32_16x16x32_bf16 v[120:123], v[140:143], v[180:183], v[120:123]
	v_mfma_f32_16x16x32_bf16 v[108:111], v[132:135], v[198:201], v[108:111]
	v_mfma_f32_16x16x32_bf16 v[104:107], v[140:143], v[198:201], v[104:107]
	v_mfma_f32_16x16x32_bf16 v[92:95], v[132:135], v[206:209], v[92:95]
	v_mfma_f32_16x16x32_bf16 v[88:91], v[140:143], v[206:209], v[88:91]
	v_mfma_f32_16x16x32_bf16 v[76:79], v[132:135], v[214:217], v[76:79]
	v_mfma_f32_16x16x32_bf16 v[72:75], v[140:143], v[214:217], v[72:75]
	v_mfma_f32_16x16x32_bf16 v[116:119], v[144:147], v[176:179], v[116:119]
	v_mfma_f32_16x16x32_bf16 v[112:115], v[168:171], v[176:179], v[112:115]
	v_mfma_f32_16x16x32_bf16 v[100:103], v[144:147], v[194:197], v[100:103]
	v_mfma_f32_16x16x32_bf16 v[96:99], v[168:171], v[194:197], v[96:99]
	v_mfma_f32_16x16x32_bf16 v[84:87], v[144:147], v[202:205], v[84:87]
	v_mfma_f32_16x16x32_bf16 v[80:83], v[168:171], v[202:205], v[80:83]
	v_mfma_f32_16x16x32_bf16 v[68:71], v[144:147], v[210:213], v[68:71]
	v_mfma_f32_16x16x32_bf16 v[64:67], v[168:171], v[210:213], v[64:67]
	v_mfma_f32_16x16x32_bf16 v[116:119], v[148:151], v[180:183], v[116:119]
	v_mfma_f32_16x16x32_bf16 v[112:115], v[172:175], v[180:183], v[112:115]
	v_mfma_f32_16x16x32_bf16 v[100:103], v[148:151], v[198:201], v[100:103]
	v_mfma_f32_16x16x32_bf16 v[96:99], v[172:175], v[198:201], v[96:99]
	v_mfma_f32_16x16x32_bf16 v[84:87], v[148:151], v[206:209], v[84:87]
	v_mfma_f32_16x16x32_bf16 v[80:83], v[172:175], v[206:209], v[80:83]
	v_mfma_f32_16x16x32_bf16 v[68:71], v[148:151], v[214:217], v[68:71]
	v_mfma_f32_16x16x32_bf16 v[64:67], v[172:175], v[214:217], v[64:67]
	s_barrier
	s_add_u32 s98, s36, s16
	s_addc_u32 s99, s37, s17
	s_add_u32 s100, s38, s16
	s_addc_u32 s101, s39, s17
	s_add_i32 s59, s53, s41
	s_mov_b32 m0, s59
	ds_read_b128 v[176:179], v191 offset:16384
	ds_read_b128 v[180:183], v191 offset:17408
	ds_read_b128 v[194:197], v191 offset:18432
	ds_read_b128 v[198:201], v191 offset:19456
	ds_read_b128 v[202:205], v191 offset:20480
	ds_read_b128 v[206:209], v191 offset:21504
	ds_read_b128 v[210:213], v191 offset:22528
	ds_read_b128 v[214:217], v191 offset:23552
	global_load_lds_dwordx4 v154, s[36:37]
	s_add_i32 m0, s59, 0x2000
	s_add_u32 s60, s36, 0x80000
	s_addc_u32 s61, s37, 0
	s_add_i32 s59, s54, s41
	global_load_lds_dwordx4 v158, s[36:37]
	s_mov_b32 m0, s59
	s_nop 0
	global_load_lds_dwordx4 v154, s[60:61]
	s_add_i32 m0, s59, 0x2000
	s_nop 0
	global_load_lds_dwordx4 v158, s[60:61]
	s_waitcnt vmcnt(6)
	s_waitcnt lgkmcnt(0)
	s_barrier
	v_mfma_f32_16x16x32_bf16 v[60:63], v[128:131], v[176:179], v[60:63]
	v_mfma_f32_16x16x32_bf16 v[56:59], v[136:139], v[176:179], v[56:59]
	v_mfma_f32_16x16x32_bf16 v[44:47], v[128:131], v[194:197], v[44:47]
	v_mfma_f32_16x16x32_bf16 v[40:43], v[136:139], v[194:197], v[40:43]
	v_mfma_f32_16x16x32_bf16 v[28:31], v[128:131], v[202:205], v[28:31]
	v_mfma_f32_16x16x32_bf16 v[24:27], v[136:139], v[202:205], v[24:27]
	v_mfma_f32_16x16x32_bf16 v[12:15], v[128:131], v[210:213], v[12:15]
	v_mfma_f32_16x16x32_bf16 v[8:11], v[136:139], v[210:213], v[8:11]
	v_mfma_f32_16x16x32_bf16 v[60:63], v[132:135], v[180:183], v[60:63]
	v_mfma_f32_16x16x32_bf16 v[56:59], v[140:143], v[180:183], v[56:59]
	v_mfma_f32_16x16x32_bf16 v[44:47], v[132:135], v[198:201], v[44:47]
	v_mfma_f32_16x16x32_bf16 v[40:43], v[140:143], v[198:201], v[40:43]
	v_mfma_f32_16x16x32_bf16 v[28:31], v[132:135], v[206:209], v[28:31]
	v_mfma_f32_16x16x32_bf16 v[24:27], v[140:143], v[206:209], v[24:27]
	v_mfma_f32_16x16x32_bf16 v[12:15], v[132:135], v[214:217], v[12:15]
	v_mfma_f32_16x16x32_bf16 v[8:11], v[140:143], v[214:217], v[8:11]
	v_mfma_f32_16x16x32_bf16 v[52:55], v[144:147], v[176:179], v[52:55]
	v_mfma_f32_16x16x32_bf16 v[48:51], v[168:171], v[176:179], v[48:51]
	v_mfma_f32_16x16x32_bf16 v[36:39], v[144:147], v[194:197], v[36:39]
	v_mfma_f32_16x16x32_bf16 v[32:35], v[168:171], v[194:197], v[32:35]
	v_mfma_f32_16x16x32_bf16 v[20:23], v[144:147], v[202:205], v[20:23]
	v_mfma_f32_16x16x32_bf16 v[16:19], v[168:171], v[202:205], v[16:19]
	v_mfma_f32_16x16x32_bf16 v[4:7], v[144:147], v[210:213], v[4:7]
	v_mfma_f32_16x16x32_bf16 v[0:3], v[168:171], v[210:213], v[0:3]
	v_mfma_f32_16x16x32_bf16 v[52:55], v[148:151], v[180:183], v[52:55]
	v_mfma_f32_16x16x32_bf16 v[48:51], v[172:175], v[180:183], v[48:51]
	v_mfma_f32_16x16x32_bf16 v[36:39], v[148:151], v[198:201], v[36:39]
	v_mfma_f32_16x16x32_bf16 v[32:35], v[172:175], v[198:201], v[32:35]
	v_mfma_f32_16x16x32_bf16 v[20:23], v[148:151], v[206:209], v[20:23]
	v_mfma_f32_16x16x32_bf16 v[16:19], v[172:175], v[206:209], v[16:19]
	v_mfma_f32_16x16x32_bf16 v[4:7], v[148:151], v[214:217], v[4:7]
	v_mfma_f32_16x16x32_bf16 v[0:3], v[172:175], v[214:217], v[0:3]
	s_barrier
; #define PG8_STAGE(bufoff, gbase, voff) do { _Pragma("unroll") for (int _i = 0; _i < 2; ++_i) \
;         __builtin_amdgcn_global_load_lds((const unsigned*)((const char*)(gbase) + (voff)[_i]), (LAS unsigned*)(lds + (bufoff) + ldsw + _i * 8192), 16, 0, ((voff) == voffA ? AUXA : 0)); } while (0)
; #define PG8_LDA(dst, b, h) do { _Pragma("unroll") for (int m = 0; m < 4; ++m) _Pragma("unroll") for (int k = 0; k < 2; ++k) dst[m][k] = *(const LAS bf16x8*)(lds + PG8_SA(b, h) + aoff + m * 2048 + k * 1024); } while (0)
; #define PG8_LDB(dst, b, h) do { _Pragma("unroll") for (int n = 0; n < 2; ++n) _Pragma("unroll") for (int k = 0; k < 2; ++k) dst[n][k] = *(const LAS bf16x8*)(lds + PG8_SB(b, h) + boff + n * 2048 + k * 1024); } while (0)
; #define PG8_MMA(ai, bj, At, Bt) do { __builtin_amdgcn_s_setprio(1); _Pragma("unroll") for (int m = 0; m < 4; ++m) _Pragma("unroll") for (int n = 0; n < 2; ++n) _Pragma("unroll") for (int k = 0; k < 2; ++k) \
;         acc[ai][bj][m][n] = __builtin_amdgcn_mfma_f32_16x16x32_bf16(Bt[n][k], At[m][k], acc[ai][bj][m][n], 0, 0, 0); __builtin_amdgcn_s_setprio(0); } while (0)
; #define PG8_WAIT_V(n) asm volatile("s_waitcnt vmcnt(" #n ")" ::: "memory")
;     ...
;             PG8_LDB(B0, 0, 0); PG8_LDB(B1, 0, 1); PG8_SCHED; PG8_LDA(At, 0, 0); PG8_STAGE(PG8_SA(1, 1), a1 + hsA, voffA);
;             if (Epi::NPRE != 0 && last) { E.pre(sv, cur, wr, fr); PG8_WAIT_V(16); } else { PG8_WAIT_V(8); }
;             PG8_WAIT_L(0); PG8_BAR; PG8_MMA(0, 0, At, B0); PG8_MMA(0, 1, At, B1); PG8_BAR; PG8_SCHED;
;             PG8_LDA(At, 0, 1); PG8_STAGE(PG8_SB(0, 0), b2, voffB); PG8_STAGE(PG8_SB(0, 1), b2 + hsB, voffB); PG8_STAGE(PG8_SA(0, 0), a2, voffA);
;             if (Epi::NPRE != 0 && last) { PG8_WAIT_V(16); } else { PG8_WAIT_V(8); }
;             PG8_WAIT_L(0); PG8_BAR; PG8_MMA(1, 0, At, B0); PG8_MMA(1, 1, At, B1); PG8_BAR; PG8_SCHED;
;             PG8_LDB(B0, 1, 0); PG8_LDB(B1, 1, 1); PG8_SCHED; PG8_LDA(At, 1, 0); PG8_STAGE(PG8_SA(0, 1), a2 + hsA, voffA);
;             PG8_WAIT_V(8); PG8_WAIT_L(0); PG8_BAR; PG8_MMA(0, 0, At, B0); PG8_MMA(0, 1, At, B1); PG8_BAR; PG8_SCHED;
;             PG8_LDA(At, 1, 1); PG8_STAGE(PG8_SB(1, 0), b3, voffB); PG8_STAGE(PG8_SB(1, 1), b3 + hsB, voffB); PG8_STAGE(PG8_SA(1, 0), a3, voffA);
;             PG8_WAIT_V(8); PG8_WAIT_L(0); PG8_BAR; PG8_MMA(1, 0, At, B0); PG8_MMA(1, 1, At, B1); PG8_BAR; PG8_SCHED;
;         }
	s_mov_b32 m0, s31
	s_nop 0
	global_load_lds_dwordx4 v152, s[38:39]
	s_mov_b32 m0, s42
	s_nop 0
	global_load_lds_dwordx4 v156, s[38:39]
	s_add_i32 s59, 0, 0x18000
	s_add_i32 s60, 0, 0x1c000
	v_add_u32_e32 v140, s59, v187
	v_add_u32_e32 v172, s60, v187
	ds_read_b128 v[128:131], v140
	ds_read_b128 v[132:135], v140 offset:1024
	ds_read_b128 v[136:139], v140 offset:2048
	ds_read_b128 v[140:143], v140 offset:3072
	ds_read_b128 v[144:147], v172
	ds_read_b128 v[148:151], v172 offset:1024
	ds_read_b128 v[168:171], v172 offset:2048
	ds_read_b128 v[172:175], v172 offset:3072
	s_add_u32 s38, s38, 0x80000
	s_addc_u32 s39, s39, 0
	s_mov_b32 m0, s43
	ds_read_b128 v[176:179], v191 offset:32768
	ds_read_b128 v[180:183], v191 offset:33792
	ds_read_b128 v[194:197], v191 offset:34816
	ds_read_b128 v[198:201], v191 offset:35840
	ds_read_b128 v[202:205], v191 offset:36864
	ds_read_b128 v[206:209], v191 offset:37888
	ds_read_b128 v[210:213], v191 offset:38912
	ds_read_b128 v[214:217], v191 offset:39936
	global_load_lds_dwordx4 v152, s[38:39]
	s_mov_b32 m0, s44
	s_nop 0
	global_load_lds_dwordx4 v156, s[38:39]
	s_waitcnt vmcnt(8)
	s_waitcnt lgkmcnt(0)
	s_barrier
	v_mfma_f32_16x16x32_bf16 v[124:127], v[128:131], v[176:179], v[124:127]
	v_mfma_f32_16x16x32_bf16 v[120:123], v[136:139], v[176:179], v[120:123]
	v_mfma_f32_16x16x32_bf16 v[108:111], v[128:131], v[194:197], v[108:111]
	v_mfma_f32_16x16x32_bf16 v[104:107], v[136:139], v[194:197], v[104:107]
	v_mfma_f32_16x16x32_bf16 v[92:95], v[128:131], v[202:205], v[92:95]
	v_mfma_f32_16x16x32_bf16 v[88:91], v[136:139], v[202:205], v[88:91]
	v_mfma_f32_16x16x32_bf16 v[76:79], v[128:131], v[210:213], v[76:79]
	v_mfma_f32_16x16x32_bf16 v[72:75], v[136:139], v[210:213], v[72:75]
	v_mfma_f32_16x16x32_bf16 v[124:127], v[132:135], v[180:183], v[124:127]
	v_mfma_f32_16x16x32_bf16 v[120:123], v[140:143], v[180:183], v[120:123]
	v_mfma_f32_16x16x32_bf16 v[108:111], v[132:135], v[198:201], v[108:111]
	v_mfma_f32_16x16x32_bf16 v[104:107], v[140:143], v[198:201], v[104:107]
	v_mfma_f32_16x16x32_bf16 v[92:95], v[132:135], v[206:209], v[92:95]
	v_mfma_f32_16x16x32_bf16 v[88:91], v[140:143], v[206:209], v[88:91]
	v_mfma_f32_16x16x32_bf16 v[76:79], v[132:135], v[214:217], v[76:79]
	v_mfma_f32_16x16x32_bf16 v[72:75], v[140:143], v[214:217], v[72:75]
	v_mfma_f32_16x16x32_bf16 v[116:119], v[144:147], v[176:179], v[116:119]
	v_mfma_f32_16x16x32_bf16 v[112:115], v[168:171], v[176:179], v[112:115]
	v_mfma_f32_16x16x32_bf16 v[100:103], v[144:147], v[194:197], v[100:103]
	v_mfma_f32_16x16x32_bf16 v[96:99], v[168:171], v[194:197], v[96:99]
	v_mfma_f32_16x16x32_bf16 v[84:87], v[144:147], v[202:205], v[84:87]
	v_mfma_f32_16x16x32_bf16 v[80:83], v[168:171], v[202:205], v[80:83]
	v_mfma_f32_16x16x32_bf16 v[68:71], v[144:147], v[210:213], v[68:71]
	v_mfma_f32_16x16x32_bf16 v[64:67], v[168:171], v[210:213], v[64:67]
	v_mfma_f32_16x16x32_bf16 v[116:119], v[148:151], v[180:183], v[116:119]
	v_mfma_f32_16x16x32_bf16 v[112:115], v[172:175], v[180:183], v[112:115]
	v_mfma_f32_16x16x32_bf16 v[100:103], v[148:151], v[198:201], v[100:103]
	v_mfma_f32_16x16x32_bf16 v[96:99], v[172:175], v[198:201], v[96:99]
	v_mfma_f32_16x16x32_bf16 v[84:87], v[148:151], v[206:209], v[84:87]
	v_mfma_f32_16x16x32_bf16 v[80:83], v[172:175], v[206:209], v[80:83]
	v_mfma_f32_16x16x32_bf16 v[68:71], v[148:151], v[214:217], v[68:71]
	v_mfma_f32_16x16x32_bf16 v[64:67], v[172:175], v[214:217], v[64:67]
	s_barrier
	s_add_i32 s38, s59, s41
	s_mov_b32 m0, s38
	ds_read_b128 v[176:179], v191 offset:49152
	ds_read_b128 v[180:183], v191 offset:50176
	ds_read_b128 v[194:197], v191 offset:51200
	ds_read_b128 v[198:201], v191 offset:52224
	ds_read_b128 v[202:205], v191 offset:53248
	ds_read_b128 v[206:209], v191 offset:54272
	ds_read_b128 v[210:213], v191 offset:55296
	ds_read_b128 v[214:217], v191 offset:56320
	global_load_lds_dwordx4 v154, s[98:99]
	s_add_i32 m0, s38, 0x2000
	s_add_u32 s36, s36, 0x80080
	s_addc_u32 s37, s37, 0
	s_add_i32 s38, s60, s41
	global_load_lds_dwordx4 v158, s[98:99]
	s_mov_b32 m0, s38
	s_nop 0
	global_load_lds_dwordx4 v154, s[36:37]
	s_add_i32 m0, s38, 0x2000
	s_nop 0
	global_load_lds_dwordx4 v158, s[36:37]
	s_waitcnt vmcnt(6)
	s_waitcnt lgkmcnt(0)
	s_barrier
	v_mfma_f32_16x16x32_bf16 v[60:63], v[128:131], v[176:179], v[60:63]
	v_mfma_f32_16x16x32_bf16 v[56:59], v[136:139], v[176:179], v[56:59]
	v_mfma_f32_16x16x32_bf16 v[44:47], v[128:131], v[194:197], v[44:47]
	v_mfma_f32_16x16x32_bf16 v[40:43], v[136:139], v[194:197], v[40:43]
	v_mfma_f32_16x16x32_bf16 v[28:31], v[128:131], v[202:205], v[28:31]
	v_mfma_f32_16x16x32_bf16 v[24:27], v[136:139], v[202:205], v[24:27]
	v_mfma_f32_16x16x32_bf16 v[12:15], v[128:131], v[210:213], v[12:15]
	v_mfma_f32_16x16x32_bf16 v[8:11], v[136:139], v[210:213], v[8:11]
	v_mfma_f32_16x16x32_bf16 v[60:63], v[132:135], v[180:183], v[60:63]
	v_mfma_f32_16x16x32_bf16 v[56:59], v[140:143], v[180:183], v[56:59]
	v_mfma_f32_16x16x32_bf16 v[44:47], v[132:135], v[198:201], v[44:47]
	v_mfma_f32_16x16x32_bf16 v[40:43], v[140:143], v[198:201], v[40:43]
	v_mfma_f32_16x16x32_bf16 v[28:31], v[132:135], v[206:209], v[28:31]
	v_mfma_f32_16x16x32_bf16 v[24:27], v[140:143], v[206:209], v[24:27]
	v_mfma_f32_16x16x32_bf16 v[12:15], v[132:135], v[214:217], v[12:15]
	v_mfma_f32_16x16x32_bf16 v[8:11], v[140:143], v[214:217], v[8:11]
	v_mfma_f32_16x16x32_bf16 v[52:55], v[144:147], v[176:179], v[52:55]
	v_mfma_f32_16x16x32_bf16 v[48:51], v[168:171], v[176:179], v[48:51]
	v_mfma_f32_16x16x32_bf16 v[36:39], v[144:147], v[194:197], v[36:39]
	v_mfma_f32_16x16x32_bf16 v[32:35], v[168:171], v[194:197], v[32:35]
	v_mfma_f32_16x16x32_bf16 v[20:23], v[144:147], v[202:205], v[20:23]
	v_mfma_f32_16x16x32_bf16 v[16:19], v[168:171], v[202:205], v[16:19]
	v_mfma_f32_16x16x32_bf16 v[4:7], v[144:147], v[210:213], v[4:7]
	v_mfma_f32_16x16x32_bf16 v[0:3], v[168:171], v[210:213], v[0:3]
	v_mfma_f32_16x16x32_bf16 v[52:55], v[148:151], v[180:183], v[52:55]
	v_mfma_f32_16x16x32_bf16 v[48:51], v[172:175], v[180:183], v[48:51]
	v_mfma_f32_16x16x32_bf16 v[36:39], v[148:151], v[198:201], v[36:39]
	v_mfma_f32_16x16x32_bf16 v[32:35], v[172:175], v[198:201], v[32:35]
	v_mfma_f32_16x16x32_bf16 v[20:23], v[148:151], v[206:209], v[20:23]
	v_mfma_f32_16x16x32_bf16 v[16:19], v[172:175], v[206:209], v[16:19]
	v_mfma_f32_16x16x32_bf16 v[4:7], v[148:151], v[214:217], v[4:7]
	v_mfma_f32_16x16x32_bf16 v[0:3], v[172:175], v[214:217], v[0:3]
	s_barrier
	s_add_u32 s34, s34, 0x100
	s_addc_u32 s35, s35, 0
	s_add_u32 s56, s56, 0x100
	s_addc_u32 s57, s57, 0
	s_cmp_ge_i32 s58, s46
	s_mov_b32 s36, s58
	s_cbranch_scc0 .LBB0_1267
	s_setprio 0

;     __device__ bool next(int i, Unit& u) const { const int L = i * G + c; if (L >= 384) return false; u.pm = L; u.pn = L / 6; return true; }
;     ...
;         const bool has_next = S.next(ui + 1, nxt);
;         const char* nA = has_next ? (const char*)g.A + (size_t)nxt.pm * tsA : cA; const char* nB = has_next ? (const char*)g.Bt + (size_t)nxt.pn * tsB : cB;
;         for (int t = 0; t < nt; t += 2) {
;             const bool last = (t == nt - 2);
;             const char* a1 = cA + (size_t)(t + 1) * kstep;
;             const char* a2 = last ? nA : cA + (size_t)(t + 2) * kstep; const char* b2 = last ? nB : cB + (size_t)(t + 2) * kstep;
;     ...
; #pragma unroll
;         for (int a = 0; a < 2; ++a)
; #pragma unroll
;             for (int b = 0; b < 2; ++b)
; #pragma unroll
;                 for (int m = 0; m < 4; ++m)
; #pragma unroll
;                     for (int n = 0; n < 2; ++n) acc[a][b][m][n] = (f32x4){0.f, 0.f, 0.f, 0.f};
;         cur = nxt; cA = nA; cB = nB; ++ui;
.LBB0_1353:
	s_ashr_i32 s21, s20, 31
	s_lshl_b64 s[22:23], s[20:21], 20
	s_add_u32 s22, s96, s22
	s_addc_u32 s23, s97, s23
	s_ashr_i32 s19, s18, 31
	s_lshl_b64 s[24:25], s[18:19], 20
	s_add_u32 s24, s3, s24
	s_addc_u32 s25, s4, s25
	v_mov_b32_e32 v127, 0
	s_and_b64 vcc, exec, s[0:1]
	v_lshl_add_u32 v208, s26, 8, v220
	s_cbranch_vccnz .LBB0_1364
	s_and_b64 s[26:27], s[6:7], exec
	s_cselect_b32 s19, s23, s31
	s_cselect_b32 s21, s22, s30
	s_cselect_b32 s57, s25, s29
	s_cselect_b32 s58, s24, s28
	s_add_u32 s26, s30, 0x80080
	s_addc_u32 s27, s31, 0
	v_ashrrev_i32_e32 v209, 31, v208
	s_add_u32 s59, s28, 0x100
	v_mov_b32_e32 v0, 0
	v_lshl_add_u64 v[210:211], v[208:209], 2, s[10:11]
	s_addc_u32 s60, s29, 0
	s_mov_b32 s61, 0
	v_mov_b32_e32 v1, 0
	v_mov_b64_e32 v[2:3], 0
	v_mov_b64_e32 v[8:9], 0
	v_mov_b64_e32 v[10:11], 0
	v_mov_b64_e32 v[16:17], 0
	v_mov_b64_e32 v[18:19], 0
	v_mov_b64_e32 v[24:25], 0
	v_mov_b64_e32 v[26:27], 0
	v_mov_b64_e32 v[32:33], 0
	v_mov_b64_e32 v[34:35], 0
	v_mov_b64_e32 v[40:41], 0
	v_mov_b64_e32 v[42:43], 0
	v_mov_b64_e32 v[48:49], 0
	v_mov_b64_e32 v[50:51], 0
	v_mov_b64_e32 v[56:57], 0
	v_mov_b64_e32 v[58:59], 0
	v_mov_b64_e32 v[4:5], 0
	v_mov_b64_e32 v[6:7], 0
	v_mov_b64_e32 v[12:13], 0
	v_mov_b64_e32 v[14:15], 0
	v_mov_b64_e32 v[20:21], 0
	v_mov_b64_e32 v[22:23], 0
	v_mov_b64_e32 v[28:29], 0
	v_mov_b64_e32 v[30:31], 0
	v_mov_b64_e32 v[36:37], 0
	v_mov_b64_e32 v[38:39], 0
	v_mov_b64_e32 v[44:45], 0
	v_mov_b64_e32 v[46:47], 0
	v_mov_b64_e32 v[52:53], 0
	v_mov_b64_e32 v[54:55], 0
	v_mov_b64_e32 v[60:61], 0
	v_mov_b64_e32 v[62:63], 0
	v_mov_b64_e32 v[64:65], 0
	v_mov_b64_e32 v[66:67], 0
	v_mov_b64_e32 v[72:73], 0
	v_mov_b64_e32 v[74:75], 0
	v_mov_b64_e32 v[80:81], 0
	v_mov_b64_e32 v[82:83], 0
	v_mov_b64_e32 v[88:89], 0
	v_mov_b64_e32 v[90:91], 0
	v_mov_b64_e32 v[96:97], 0
	v_mov_b64_e32 v[98:99], 0
	v_mov_b64_e32 v[104:105], 0
	v_mov_b64_e32 v[106:107], 0
	v_mov_b64_e32 v[112:113], 0
	v_mov_b64_e32 v[114:115], 0
	v_mov_b64_e32 v[120:121], 0
	v_mov_b64_e32 v[122:123], 0
	v_mov_b64_e32 v[68:69], 0
	v_mov_b64_e32 v[70:71], 0
	v_mov_b64_e32 v[76:77], 0
	v_mov_b64_e32 v[78:79], 0
	v_mov_b64_e32 v[84:85], 0
	v_mov_b64_e32 v[86:87], 0
	v_mov_b64_e32 v[92:93], 0
	v_mov_b64_e32 v[94:95], 0
	v_mov_b64_e32 v[100:101], 0
	v_mov_b64_e32 v[102:103], 0
	v_mov_b64_e32 v[108:109], 0
	v_mov_b64_e32 v[110:111], 0
	v_mov_b64_e32 v[116:117], 0
	v_mov_b64_e32 v[118:119], 0
	v_mov_b64_e32 v[124:125], 0
	v_mov_b64_e32 v[126:127], 0
	v_readfirstlane_b32 s99, v234
	s_nop 0
	s_lshr_b32 s99, s99, 8
	s_cmp_eq_u32 s99, 0
	s_cbranch_scc1 .Lsp_10
	s_setprio 1

; #define PG8_STAGE(bufoff, gbase, voff) do { _Pragma("unroll") for (int _i = 0; _i < 2; ++_i) \
;         __builtin_amdgcn_global_load_lds((const unsigned*)((const char*)(gbase) + (voff)[_i]), (LAS unsigned*)(lds + (bufoff) + ldsw + _i * 8192), 16, 0, ((voff) == voffA ? AUXA : 0)); } while (0)
; #define PG8_LDA(dst, b, h) do { _Pragma("unroll") for (int m = 0; m < 4; ++m) _Pragma("unroll") for (int k = 0; k < 2; ++k) dst[m][k] = *(const LAS bf16x8*)(lds + PG8_SA(b, h) + aoff + m * 2048 + k * 1024); } while (0)
; #define PG8_LDB(dst, b, h) do { _Pragma("unroll") for (int n = 0; n < 2; ++n) _Pragma("unroll") for (int k = 0; k < 2; ++k) dst[n][k] = *(const LAS bf16x8*)(lds + PG8_SB(b, h) + boff + n * 2048 + k * 1024); } while (0)
; #define PG8_MMA(ai, bj, At, Bt) do { __builtin_amdgcn_s_setprio(1); _Pragma("unroll") for (int m = 0; m < 4; ++m) _Pragma("unroll") for (int n = 0; n < 2; ++n) _Pragma("unroll") for (int k = 0; k < 2; ++k) \
;         acc[ai][bj][m][n] = __builtin_amdgcn_mfma_f32_16x16x32_bf16(Bt[n][k], At[m][k], acc[ai][bj][m][n], 0, 0, 0); __builtin_amdgcn_s_setprio(0); } while (0)
; #define PG8_WAIT_V(n) asm volatile("s_waitcnt vmcnt(" #n ")" ::: "memory")
; #define PG8_WAIT_L(n) asm volatile("s_waitcnt lgkmcnt(" #n ")" ::: "memory")
; #define PG8_BAR __builtin_amdgcn_s_barrier()
; #define PG8_SCHED __builtin_amdgcn_sched_barrier(0)
;     ...
;             PG8_WAIT_L(0); PG8_BAR; PG8_MMA(0, 0, At, B0); PG8_MMA(0, 1, At, B1); PG8_BAR; PG8_SCHED;
;             PG8_LDA(At, 0, 1); PG8_STAGE(PG8_SB(0, 0), b2, voffB); PG8_STAGE(PG8_SB(0, 1), b2 + hsB, voffB); PG8_STAGE(PG8_SA(0, 0), a2, voffA);
;             if (Epi::NPRE != 0 && last) { PG8_WAIT_V(16); } else { PG8_WAIT_V(8); }
;             PG8_WAIT_L(0); PG8_BAR; PG8_MMA(1, 0, At, B0); PG8_MMA(1, 1, At, B1); PG8_BAR; PG8_SCHED;
;             PG8_LDB(B0, 1, 0); PG8_LDB(B1, 1, 1); PG8_SCHED; PG8_LDA(At, 1, 0); PG8_STAGE(PG8_SA(0, 1), a2 + hsA, voffA);
;             PG8_WAIT_V(8); PG8_WAIT_L(0); PG8_BAR; PG8_MMA(0, 0, At, B0); PG8_MMA(0, 1, At, B1); PG8_BAR; PG8_SCHED;
;             PG8_LDA(At, 1, 1); PG8_STAGE(PG8_SB(1, 0), b3, voffB); PG8_STAGE(PG8_SB(1, 1), b3 + hsB, voffB); PG8_STAGE(PG8_SA(1, 0), a3, voffA);
.LBB0_1355:
	s_waitcnt lgkmcnt(0)
	s_add_i32 s61, s61, 2
	s_barrier
	v_mfma_f32_16x16x32_bf16 v[60:63], v[144:147], v[184:187], v[60:63]
	v_mfma_f32_16x16x32_bf16 v[52:55], v[152:155], v[184:187], v[52:55]
	v_mfma_f32_16x16x32_bf16 v[44:47], v[144:147], v[176:179], v[44:47]
	v_mfma_f32_16x16x32_bf16 v[36:39], v[152:155], v[176:179], v[36:39]
	v_mfma_f32_16x16x32_bf16 v[28:31], v[144:147], v[168:171], v[28:31]
	v_mfma_f32_16x16x32_bf16 v[20:23], v[152:155], v[168:171], v[20:23]
	v_mfma_f32_16x16x32_bf16 v[12:15], v[144:147], v[160:163], v[12:15]
	v_mfma_f32_16x16x32_bf16 v[4:7], v[152:155], v[160:163], v[4:7]
	v_mfma_f32_16x16x32_bf16 v[60:63], v[148:151], v[188:191], v[60:63]
	v_mfma_f32_16x16x32_bf16 v[52:55], v[156:159], v[188:191], v[52:55]
	v_mfma_f32_16x16x32_bf16 v[44:47], v[148:151], v[180:183], v[44:47]
	v_mfma_f32_16x16x32_bf16 v[36:39], v[156:159], v[180:183], v[36:39]
	v_mfma_f32_16x16x32_bf16 v[28:31], v[148:151], v[172:175], v[28:31]
	v_mfma_f32_16x16x32_bf16 v[20:23], v[156:159], v[172:175], v[20:23]
	v_mfma_f32_16x16x32_bf16 v[12:15], v[148:151], v[164:167], v[12:15]
	v_mfma_f32_16x16x32_bf16 v[4:7], v[156:159], v[164:167], v[4:7]
	v_mfma_f32_16x16x32_bf16 v[56:59], v[128:131], v[184:187], v[56:59]
	v_mfma_f32_16x16x32_bf16 v[48:51], v[136:139], v[184:187], v[48:51]
	v_mfma_f32_16x16x32_bf16 v[40:43], v[128:131], v[176:179], v[40:43]
	v_mfma_f32_16x16x32_bf16 v[32:35], v[136:139], v[176:179], v[32:35]
	v_mfma_f32_16x16x32_bf16 v[24:27], v[128:131], v[168:171], v[24:27]
	v_mfma_f32_16x16x32_bf16 v[16:19], v[136:139], v[168:171], v[16:19]
	v_mfma_f32_16x16x32_bf16 v[8:11], v[128:131], v[160:163], v[8:11]
	v_mfma_f32_16x16x32_bf16 v[0:3], v[136:139], v[160:163], v[0:3]
	v_mfma_f32_16x16x32_bf16 v[56:59], v[132:135], v[188:191], v[56:59]
	v_mfma_f32_16x16x32_bf16 v[48:51], v[140:143], v[188:191], v[48:51]
	v_mfma_f32_16x16x32_bf16 v[40:43], v[132:135], v[180:183], v[40:43]
	v_mfma_f32_16x16x32_bf16 v[32:35], v[140:143], v[180:183], v[32:35]
	v_mfma_f32_16x16x32_bf16 v[24:27], v[132:135], v[172:175], v[24:27]
	v_mfma_f32_16x16x32_bf16 v[16:19], v[140:143], v[172:175], v[16:19]
	v_mfma_f32_16x16x32_bf16 v[8:11], v[132:135], v[164:167], v[8:11]
	v_mfma_f32_16x16x32_bf16 v[0:3], v[140:143], v[164:167], v[0:3]
	s_barrier
	s_mov_b32 m0, s40
	s_nop 0
	global_load_lds_dwordx4 v198, s[30:31]
	s_mov_b32 m0, s45
	s_nop 0
	global_load_lds_dwordx4 v194, s[30:31]
	s_add_i32 s34, 0, 0x18000
	s_add_i32 s35, 0, 0x1c000
	v_add_u32_e32 v140, s34, v221
	v_add_u32_e32 v156, s35, v221
	ds_read_b128 v[128:131], v140
	ds_read_b128 v[132:135], v140 offset:1024
	ds_read_b128 v[136:139], v140 offset:2048
	ds_read_b128 v[140:143], v140 offset:3072
	ds_read_b128 v[144:147], v156
	ds_read_b128 v[148:151], v156 offset:1024
	ds_read_b128 v[152:155], v156 offset:2048
	ds_read_b128 v[156:159], v156 offset:3072
	s_add_u32 s30, s30, 0x80000
	s_addc_u32 s31, s31, 0
	s_mov_b32 m0, s46
	ds_read_b128 v[160:163], v225 offset:32768
	ds_read_b128 v[164:167], v225 offset:33792
	ds_read_b128 v[168:171], v225 offset:34816
	ds_read_b128 v[172:175], v225 offset:35840
	ds_read_b128 v[176:179], v225 offset:36864
	ds_read_b128 v[180:183], v225 offset:37888
	ds_read_b128 v[184:187], v225 offset:38912
	ds_read_b128 v[188:191], v225 offset:39936
	global_load_lds_dwordx4 v198, s[30:31]
	s_mov_b32 m0, s47
	s_nop 0
	global_load_lds_dwordx4 v194, s[30:31]
	s_waitcnt vmcnt(8)
	s_waitcnt lgkmcnt(0)
	s_barrier
; #define PG8_STAGE(bufoff, gbase, voff) do { _Pragma("unroll") for (int _i = 0; _i < 2; ++_i) \
;         __builtin_amdgcn_global_load_lds((const unsigned*)((const char*)(gbase) + (voff)[_i]), (LAS unsigned*)(lds + (bufoff) + ldsw + _i * 8192), 16, 0, ((voff) == voffA ? AUXA : 0)); } while (0)
; #define PG8_LDA(dst, b, h) do { _Pragma("unroll") for (int m = 0; m < 4; ++m) _Pragma("unroll") for (int k = 0; k < 2; ++k) dst[m][k] = *(const LAS bf16x8*)(lds + PG8_SA(b, h) + aoff + m * 2048 + k * 1024); } while (0)
; #define PG8_LDB(dst, b, h) do { _Pragma("unroll") for (int n = 0; n < 2; ++n) _Pragma("unroll") for (int k = 0; k < 2; ++k) dst[n][k] = *(const LAS bf16x8*)(lds + PG8_SB(b, h) + boff + n * 2048 + k * 1024); } while (0)
; #define PG8_MMA(ai, bj, At, Bt) do { __builtin_amdgcn_s_setprio(1); _Pragma("unroll") for (int m = 0; m < 4; ++m) _Pragma("unroll") for (int n = 0; n < 2; ++n) _Pragma("unroll") for (int k = 0; k < 2; ++k) \
;         acc[ai][bj][m][n] = __builtin_amdgcn_mfma_f32_16x16x32_bf16(Bt[n][k], At[m][k], acc[ai][bj][m][n], 0, 0, 0); __builtin_amdgcn_s_setprio(0); } while (0)
; #define PG8_WAIT_V(n) asm volatile("s_waitcnt vmcnt(" #n ")" ::: "memory")
; #define PG8_WAIT_L(n) asm volatile("s_waitcnt lgkmcnt(" #n ")" ::: "memory")
; #define PG8_BAR __builtin_amdgcn_s_barrier()
; #define PG8_SCHED __builtin_amdgcn_sched_barrier(0)
;     ...
;             PG8_LDB(B0, 1, 0); PG8_LDB(B1, 1, 1); PG8_SCHED; PG8_LDA(At, 1, 0); PG8_STAGE(PG8_SA(0, 1), a2 + hsA, voffA);
;             PG8_WAIT_V(8); PG8_WAIT_L(0); PG8_BAR; PG8_MMA(0, 0, At, B0); PG8_MMA(0, 1, At, B1); PG8_BAR; PG8_SCHED;
;             PG8_LDA(At, 1, 1); PG8_STAGE(PG8_SB(1, 0), b3, voffB); PG8_STAGE(PG8_SB(1, 1), b3 + hsB, voffB); PG8_STAGE(PG8_SA(1, 0), a3, voffA);
;             PG8_WAIT_V(8); PG8_WAIT_L(0); PG8_BAR; PG8_MMA(1, 0, At, B0); PG8_MMA(1, 1, At, B1); PG8_BAR; PG8_SCHED;
;         }
	v_mfma_f32_16x16x32_bf16 v[124:127], v[128:131], v[160:163], v[124:127]
	v_mfma_f32_16x16x32_bf16 v[116:119], v[136:139], v[160:163], v[116:119]
	v_mfma_f32_16x16x32_bf16 v[108:111], v[128:131], v[168:171], v[108:111]
	v_mfma_f32_16x16x32_bf16 v[100:103], v[136:139], v[168:171], v[100:103]
	v_mfma_f32_16x16x32_bf16 v[92:95], v[128:131], v[176:179], v[92:95]
	v_mfma_f32_16x16x32_bf16 v[84:87], v[136:139], v[176:179], v[84:87]
	v_mfma_f32_16x16x32_bf16 v[76:79], v[128:131], v[184:187], v[76:79]
	v_mfma_f32_16x16x32_bf16 v[68:71], v[136:139], v[184:187], v[68:71]
	v_mfma_f32_16x16x32_bf16 v[124:127], v[132:135], v[164:167], v[124:127]
	v_mfma_f32_16x16x32_bf16 v[116:119], v[140:143], v[164:167], v[116:119]
	v_mfma_f32_16x16x32_bf16 v[108:111], v[132:135], v[172:175], v[108:111]
	v_mfma_f32_16x16x32_bf16 v[100:103], v[140:143], v[172:175], v[100:103]
	v_mfma_f32_16x16x32_bf16 v[92:95], v[132:135], v[180:183], v[92:95]
	v_mfma_f32_16x16x32_bf16 v[84:87], v[140:143], v[180:183], v[84:87]
	v_mfma_f32_16x16x32_bf16 v[76:79], v[132:135], v[188:191], v[76:79]
	v_mfma_f32_16x16x32_bf16 v[68:71], v[140:143], v[188:191], v[68:71]
	v_mfma_f32_16x16x32_bf16 v[120:123], v[144:147], v[160:163], v[120:123]
	v_mfma_f32_16x16x32_bf16 v[112:115], v[152:155], v[160:163], v[112:115]
	v_mfma_f32_16x16x32_bf16 v[104:107], v[144:147], v[168:171], v[104:107]
	v_mfma_f32_16x16x32_bf16 v[96:99], v[152:155], v[168:171], v[96:99]
	v_mfma_f32_16x16x32_bf16 v[88:91], v[144:147], v[176:179], v[88:91]
	v_mfma_f32_16x16x32_bf16 v[80:83], v[152:155], v[176:179], v[80:83]
	v_mfma_f32_16x16x32_bf16 v[72:75], v[144:147], v[184:187], v[72:75]
	v_mfma_f32_16x16x32_bf16 v[64:67], v[152:155], v[184:187], v[64:67]
	v_mfma_f32_16x16x32_bf16 v[120:123], v[148:151], v[164:167], v[120:123]
	v_mfma_f32_16x16x32_bf16 v[112:115], v[156:159], v[164:167], v[112:115]
	v_mfma_f32_16x16x32_bf16 v[104:107], v[148:151], v[172:175], v[104:107]
	v_mfma_f32_16x16x32_bf16 v[96:99], v[156:159], v[172:175], v[96:99]
	v_mfma_f32_16x16x32_bf16 v[88:91], v[148:151], v[180:183], v[88:91]
	v_mfma_f32_16x16x32_bf16 v[80:83], v[156:159], v[180:183], v[80:83]
	v_mfma_f32_16x16x32_bf16 v[72:75], v[148:151], v[188:191], v[72:75]
	v_mfma_f32_16x16x32_bf16 v[64:67], v[156:159], v[188:191], v[64:67]
	s_barrier
	s_add_i32 s30, s34, s5
	s_mov_b32 m0, s30
	ds_read_b128 v[160:163], v225 offset:49152
	ds_read_b128 v[164:167], v225 offset:50176
	ds_read_b128 v[168:171], v225 offset:51200
	ds_read_b128 v[172:175], v225 offset:52224
	ds_read_b128 v[176:179], v225 offset:53248
	ds_read_b128 v[180:183], v225 offset:54272
	ds_read_b128 v[184:187], v225 offset:55296
	ds_read_b128 v[188:191], v225 offset:56320
	global_load_lds_dwordx4 v196, s[98:99]
	s_add_i32 m0, s30, 0x2000
	s_add_u32 s28, s28, 0x80080
	s_addc_u32 s29, s29, 0
	s_add_i32 s30, s35, s5
	global_load_lds_dwordx4 v192, s[98:99]
	s_mov_b32 m0, s30
	s_nop 0
	global_load_lds_dwordx4 v196, s[28:29]
	s_add_i32 m0, s30, 0x2000
	s_nop 0
	global_load_lds_dwordx4 v192, s[28:29]
	s_waitcnt vmcnt(6)
	s_waitcnt lgkmcnt(0)
	s_barrier
	v_mfma_f32_16x16x32_bf16 v[60:63], v[128:131], v[160:163], v[60:63]
	v_mfma_f32_16x16x32_bf16 v[52:55], v[136:139], v[160:163], v[52:55]
	v_mfma_f32_16x16x32_bf16 v[44:47], v[128:131], v[168:171], v[44:47]
	v_mfma_f32_16x16x32_bf16 v[36:39], v[136:139], v[168:171], v[36:39]
	v_mfma_f32_16x16x32_bf16 v[28:31], v[128:131], v[176:179], v[28:31]
	v_mfma_f32_16x16x32_bf16 v[20:23], v[136:139], v[176:179], v[20:23]
	v_mfma_f32_16x16x32_bf16 v[12:15], v[128:131], v[184:187], v[12:15]
	v_mfma_f32_16x16x32_bf16 v[4:7], v[136:139], v[184:187], v[4:7]
	v_mfma_f32_16x16x32_bf16 v[60:63], v[132:135], v[164:167], v[60:63]
	v_mfma_f32_16x16x32_bf16 v[52:55], v[140:143], v[164:167], v[52:55]
	v_mfma_f32_16x16x32_bf16 v[44:47], v[132:135], v[172:175], v[44:47]
	v_mfma_f32_16x16x32_bf16 v[36:39], v[140:143], v[172:175], v[36:39]
	v_mfma_f32_16x16x32_bf16 v[28:31], v[132:135], v[180:183], v[28:31]
	v_mfma_f32_16x16x32_bf16 v[20:23], v[140:143], v[180:183], v[20:23]
	v_mfma_f32_16x16x32_bf16 v[12:15], v[132:135], v[188:191], v[12:15]
	v_mfma_f32_16x16x32_bf16 v[4:7], v[140:143], v[188:191], v[4:7]
	v_mfma_f32_16x16x32_bf16 v[56:59], v[144:147], v[160:163], v[56:59]
	v_mfma_f32_16x16x32_bf16 v[48:51], v[152:155], v[160:163], v[48:51]
	v_mfma_f32_16x16x32_bf16 v[40:43], v[144:147], v[168:171], v[40:43]
	v_mfma_f32_16x16x32_bf16 v[32:35], v[152:155], v[168:171], v[32:35]
	v_mfma_f32_16x16x32_bf16 v[24:27], v[144:147], v[176:179], v[24:27]
	v_mfma_f32_16x16x32_bf16 v[16:19], v[152:155], v[176:179], v[16:19]
	v_mfma_f32_16x16x32_bf16 v[8:11], v[144:147], v[184:187], v[8:11]
	v_mfma_f32_16x16x32_bf16 v[0:3], v[152:155], v[184:187], v[0:3]
	v_mfma_f32_16x16x32_bf16 v[56:59], v[148:151], v[164:167], v[56:59]
	v_mfma_f32_16x16x32_bf16 v[48:51], v[156:159], v[164:167], v[48:51]
	v_mfma_f32_16x16x32_bf16 v[40:43], v[148:151], v[172:175], v[40:43]
	v_mfma_f32_16x16x32_bf16 v[32:35], v[156:159], v[172:175], v[32:35]
	v_mfma_f32_16x16x32_bf16 v[24:27], v[148:151], v[180:183], v[24:27]
	v_mfma_f32_16x16x32_bf16 v[16:19], v[156:159], v[180:183], v[16:19]
	v_mfma_f32_16x16x32_bf16 v[8:11], v[148:151], v[188:191], v[8:11]
	v_mfma_f32_16x16x32_bf16 v[0:3], v[156:159], v[188:191], v[0:3]
	s_barrier
	s_add_u32 s26, s26, 0x100
	s_addc_u32 s27, s27, 0
	s_add_u32 s59, s59, 0x100
	s_addc_u32 s60, s60, 0
	s_cmp_ge_i32 s61, s49
	s_cbranch_scc1 .Lspx_10

; #define PG8_STAGE(bufoff, gbase, voff) do { _Pragma("unroll") for (int _i = 0; _i < 2; ++_i) \
;         __builtin_amdgcn_global_load_lds((const unsigned*)((const char*)(gbase) + (voff)[_i]), (LAS unsigned*)(lds + (bufoff) + ldsw + _i * 8192), 16, 0, ((voff) == voffA ? AUXA : 0)); } while (0)
; #define PG8_LDA(dst, b, h) do { _Pragma("unroll") for (int m = 0; m < 4; ++m) _Pragma("unroll") for (int k = 0; k < 2; ++k) dst[m][k] = *(const LAS bf16x8*)(lds + PG8_SA(b, h) + aoff + m * 2048 + k * 1024); } while (0)
; #define PG8_LDB(dst, b, h) do { _Pragma("unroll") for (int n = 0; n < 2; ++n) _Pragma("unroll") for (int k = 0; k < 2; ++k) dst[n][k] = *(const LAS bf16x8*)(lds + PG8_SB(b, h) + boff + n * 2048 + k * 1024); } while (0)
; #define PG8_MMA(ai, bj, At, Bt) do { __builtin_amdgcn_s_setprio(1); _Pragma("unroll") for (int m = 0; m < 4; ++m) _Pragma("unroll") for (int n = 0; n < 2; ++n) _Pragma("unroll") for (int k = 0; k < 2; ++k) \
;         acc[ai][bj][m][n] = __builtin_amdgcn_mfma_f32_16x16x32_bf16(Bt[n][k], At[m][k], acc[ai][bj][m][n], 0, 0, 0); __builtin_amdgcn_s_setprio(0); } while (0)
; #define PG8_WAIT_V(n) asm volatile("s_waitcnt vmcnt(" #n ")" ::: "memory")
; #define PG8_WAIT_L(n) asm volatile("s_waitcnt lgkmcnt(" #n ")" ::: "memory")
; #define PG8_BAR __builtin_amdgcn_s_barrier()
; #define PG8_SCHED __builtin_amdgcn_sched_barrier(0)
;     ...
;             const char* a2 = last ? nA : cA + (size_t)(t + 2) * kstep; const char* b2 = last ? nB : cB + (size_t)(t + 2) * kstep;
;             const char* a3 = a2 + kstep; const char* b3 = b2 + kstep;
;             PG8_LDB(B0, 0, 0); PG8_LDB(B1, 0, 1); PG8_SCHED; PG8_LDA(At, 0, 0); PG8_STAGE(PG8_SA(1, 1), a1 + hsA, voffA);
;             if (Epi::NPRE != 0 && last) { E.pre(sv, cur, wr, fr); PG8_WAIT_V(16); } else { PG8_WAIT_V(8); }
;             PG8_WAIT_L(0); PG8_BAR; PG8_MMA(0, 0, At, B0); PG8_MMA(0, 1, At, B1); PG8_BAR; PG8_SCHED;
;             PG8_LDA(At, 0, 1); PG8_STAGE(PG8_SB(0, 0), b2, voffB); PG8_STAGE(PG8_SB(0, 1), b2 + hsB, voffB); PG8_STAGE(PG8_SA(0, 0), a2, voffA);
;             if (Epi::NPRE != 0 && last) { PG8_WAIT_V(16); } else { PG8_WAIT_V(8); }
;             PG8_WAIT_L(0); PG8_BAR; PG8_MMA(1, 0, At, B0); PG8_MMA(1, 1, At, B1); PG8_BAR; PG8_SCHED;
.LBB0_1360:
	s_add_u32 s30, s26, 0xfff80080
	s_addc_u32 s31, s27, -1
	s_waitcnt lgkmcnt(0)
	s_and_b64 s[28:29], s[28:29], exec
	s_cselect_b32 s31, s19, s31
	s_cselect_b32 s30, s21, s30
	s_cselect_b32 s29, s57, s60
	s_cselect_b32 s28, s58, s59
	s_barrier
	v_mfma_f32_16x16x32_bf16 v[124:127], v[144:147], v[184:187], v[124:127]
	v_mfma_f32_16x16x32_bf16 v[116:119], v[152:155], v[184:187], v[116:119]
	v_mfma_f32_16x16x32_bf16 v[108:111], v[144:147], v[176:179], v[108:111]
	v_mfma_f32_16x16x32_bf16 v[100:103], v[152:155], v[176:179], v[100:103]
	v_mfma_f32_16x16x32_bf16 v[92:95], v[144:147], v[168:171], v[92:95]
	v_mfma_f32_16x16x32_bf16 v[84:87], v[152:155], v[168:171], v[84:87]
	v_mfma_f32_16x16x32_bf16 v[76:79], v[144:147], v[160:163], v[76:79]
	v_mfma_f32_16x16x32_bf16 v[68:71], v[152:155], v[160:163], v[68:71]
	v_mfma_f32_16x16x32_bf16 v[124:127], v[148:151], v[188:191], v[124:127]
	v_mfma_f32_16x16x32_bf16 v[116:119], v[156:159], v[188:191], v[116:119]
	v_mfma_f32_16x16x32_bf16 v[108:111], v[148:151], v[180:183], v[108:111]
	v_mfma_f32_16x16x32_bf16 v[100:103], v[156:159], v[180:183], v[100:103]
	v_mfma_f32_16x16x32_bf16 v[92:95], v[148:151], v[172:175], v[92:95]
	v_mfma_f32_16x16x32_bf16 v[84:87], v[156:159], v[172:175], v[84:87]
	v_mfma_f32_16x16x32_bf16 v[76:79], v[148:151], v[164:167], v[76:79]
	v_mfma_f32_16x16x32_bf16 v[68:71], v[156:159], v[164:167], v[68:71]
	v_mfma_f32_16x16x32_bf16 v[120:123], v[128:131], v[184:187], v[120:123]
	v_mfma_f32_16x16x32_bf16 v[112:115], v[136:139], v[184:187], v[112:115]
	v_mfma_f32_16x16x32_bf16 v[104:107], v[128:131], v[176:179], v[104:107]
	v_mfma_f32_16x16x32_bf16 v[96:99], v[136:139], v[176:179], v[96:99]
	v_mfma_f32_16x16x32_bf16 v[88:91], v[128:131], v[168:171], v[88:91]
	v_mfma_f32_16x16x32_bf16 v[80:83], v[136:139], v[168:171], v[80:83]
	v_mfma_f32_16x16x32_bf16 v[72:75], v[128:131], v[160:163], v[72:75]
	v_mfma_f32_16x16x32_bf16 v[64:67], v[136:139], v[160:163], v[64:67]
	v_mfma_f32_16x16x32_bf16 v[120:123], v[132:135], v[188:191], v[120:123]
	v_mfma_f32_16x16x32_bf16 v[112:115], v[140:143], v[188:191], v[112:115]
	v_mfma_f32_16x16x32_bf16 v[104:107], v[132:135], v[180:183], v[104:107]
	v_mfma_f32_16x16x32_bf16 v[96:99], v[140:143], v[180:183], v[96:99]
	v_mfma_f32_16x16x32_bf16 v[88:91], v[132:135], v[172:175], v[88:91]
	v_mfma_f32_16x16x32_bf16 v[80:83], v[140:143], v[172:175], v[80:83]
	v_mfma_f32_16x16x32_bf16 v[72:75], v[132:135], v[164:167], v[72:75]
	v_mfma_f32_16x16x32_bf16 v[64:67], v[140:143], v[164:167], v[64:67]
	s_barrier
	s_add_u32 s98, s28, s14
	s_addc_u32 s99, s29, s15
	s_add_u32 s100, s30, s14
	s_addc_u32 s101, s31, s15
	s_mov_b32 m0, s41
	s_add_u32 s36, s28, 0x80000
	ds_read_b128 v[184:187], v225 offset:16384
	ds_read_b128 v[188:191], v225 offset:17408
	ds_read_b128 v[176:179], v225 offset:18432
	ds_read_b128 v[180:183], v225 offset:19456
	ds_read_b128 v[168:171], v225 offset:20480
	ds_read_b128 v[172:175], v225 offset:21504
	ds_read_b128 v[160:163], v225 offset:22528
	ds_read_b128 v[164:167], v225 offset:23552
	global_load_lds_dwordx4 v196, s[28:29]
	s_mov_b32 m0, s42
	s_addc_u32 s37, s29, 0
	global_load_lds_dwordx4 v192, s[28:29]
	s_mov_b32 m0, s43
	s_nop 0
	global_load_lds_dwordx4 v196, s[36:37]
	s_mov_b32 m0, s44
	s_nop 0
	global_load_lds_dwordx4 v192, s[36:37]
	s_mov_b64 s[36:37], -1
	s_and_b64 vcc, exec, s[34:35]
	s_cbranch_vccz .LBB0_1362
	s_waitcnt vmcnt(6)
	s_mov_b64 s[36:37], 0

; #define PG8_STAGE(bufoff, gbase, voff) do { _Pragma("unroll") for (int _i = 0; _i < 2; ++_i) \
;         __builtin_amdgcn_global_load_lds((const unsigned*)((const char*)(gbase) + (voff)[_i]), (LAS unsigned*)(lds + (bufoff) + ldsw + _i * 8192), 16, 0, ((voff) == voffA ? AUXA : 0)); } while (0)
; #define PG8_LDA(dst, b, h) do { _Pragma("unroll") for (int m = 0; m < 4; ++m) _Pragma("unroll") for (int k = 0; k < 2; ++k) dst[m][k] = *(const LAS bf16x8*)(lds + PG8_SA(b, h) + aoff + m * 2048 + k * 1024); } while (0)
; #define PG8_LDB(dst, b, h) do { _Pragma("unroll") for (int n = 0; n < 2; ++n) _Pragma("unroll") for (int k = 0; k < 2; ++k) dst[n][k] = *(const LAS bf16x8*)(lds + PG8_SB(b, h) + boff + n * 2048 + k * 1024); } while (0)
; #define PG8_MMA(ai, bj, At, Bt) do { __builtin_amdgcn_s_setprio(1); _Pragma("unroll") for (int m = 0; m < 4; ++m) _Pragma("unroll") for (int n = 0; n < 2; ++n) _Pragma("unroll") for (int k = 0; k < 2; ++k) \
;         acc[ai][bj][m][n] = __builtin_amdgcn_mfma_f32_16x16x32_bf16(Bt[n][k], At[m][k], acc[ai][bj][m][n], 0, 0, 0); __builtin_amdgcn_s_setprio(0); } while (0)
; #define PG8_WAIT_V(n) asm volatile("s_waitcnt vmcnt(" #n ")" ::: "memory")
; #define PG8_WAIT_L(n) asm volatile("s_waitcnt lgkmcnt(" #n ")" ::: "memory")
; #define PG8_BAR __builtin_amdgcn_s_barrier()
; #define PG8_SCHED __builtin_amdgcn_sched_barrier(0)
;     ...
;         for (int t = 0; t < nt; t += 2) {
;             const bool last = (t == nt - 2);
;             const char* a1 = cA + (size_t)(t + 1) * kstep;
;             const char* a2 = last ? nA : cA + (size_t)(t + 2) * kstep; const char* b2 = last ? nB : cB + (size_t)(t + 2) * kstep;
;             const char* a3 = a2 + kstep; const char* b3 = b2 + kstep;
;             PG8_LDB(B0, 0, 0); PG8_LDB(B1, 0, 1); PG8_SCHED; PG8_LDA(At, 0, 0); PG8_STAGE(PG8_SA(1, 1), a1 + hsA, voffA);
;             if (Epi::NPRE != 0 && last) { E.pre(sv, cur, wr, fr); PG8_WAIT_V(16); } else { PG8_WAIT_V(8); }
;             PG8_WAIT_L(0); PG8_BAR; PG8_MMA(0, 0, At, B0); PG8_MMA(0, 1, At, B1); PG8_BAR; PG8_SCHED;
;     ...
; #pragma unroll
;         for (int a = 0; a < 2; ++a)
; #pragma unroll
;             for (int b = 0; b < 2; ++b)
; #pragma unroll
;                 for (int m = 0; m < 4; ++m)
; #pragma unroll
;                     for (int n = 0; n < 2; ++n) acc[a][b][m][n] = (f32x4){0.f, 0.f, 0.f, 0.f};
;         cur = nxt; cA = nA; cB = nB; ++ui;
.LBB0_1438:
	v_mov_b32_e32 v127, 0
	s_andn2_b64 vcc, exec, s[10:11]
	v_mov_b32_e32 v126, 0
	v_mov_b64_e32 v[146:147], 0
	v_mov_b64_e32 v[144:145], 0
	v_mov_b64_e32 v[124:125], 0
	v_mov_b64_e32 v[118:119], 0
	v_mov_b64_e32 v[116:117], 0
	v_mov_b64_e32 v[110:111], 0
	v_mov_b64_e32 v[108:109], 0
	v_mov_b64_e32 v[102:103], 0
	v_mov_b64_e32 v[100:101], 0
	v_mov_b64_e32 v[94:95], 0
	v_mov_b64_e32 v[92:93], 0
	v_mov_b64_e32 v[86:87], 0
	v_mov_b64_e32 v[84:85], 0
	v_mov_b64_e32 v[78:79], 0
	v_mov_b64_e32 v[76:77], 0
	v_mov_b64_e32 v[154:155], 0
	v_mov_b64_e32 v[152:153], 0
	v_mov_b64_e32 v[150:151], 0
	v_mov_b64_e32 v[148:149], 0
	v_mov_b64_e32 v[122:123], 0
	v_mov_b64_e32 v[120:121], 0
	v_mov_b64_e32 v[114:115], 0
	v_mov_b64_e32 v[112:113], 0
	v_mov_b64_e32 v[106:107], 0
	v_mov_b64_e32 v[104:105], 0
	v_mov_b64_e32 v[98:99], 0
	v_mov_b64_e32 v[96:97], 0
	v_mov_b64_e32 v[90:91], 0
	v_mov_b64_e32 v[88:89], 0
	v_mov_b64_e32 v[82:83], 0
	v_mov_b64_e32 v[80:81], 0
	v_mov_b64_e32 v[66:67], 0
	v_mov_b64_e32 v[64:65], 0
	v_mov_b64_e32 v[62:63], 0
	v_mov_b64_e32 v[60:61], 0
	v_mov_b64_e32 v[54:55], 0
	v_mov_b64_e32 v[52:53], 0
	v_mov_b64_e32 v[46:47], 0
	v_mov_b64_e32 v[44:45], 0
	v_mov_b64_e32 v[30:31], 0
	v_mov_b64_e32 v[28:29], 0
	v_mov_b64_e32 v[22:23], 0
	v_mov_b64_e32 v[20:21], 0
	v_mov_b64_e32 v[14:15], 0
	v_mov_b64_e32 v[12:13], 0
	v_mov_b64_e32 v[10:11], 0
	v_mov_b64_e32 v[8:9], 0
	v_mov_b64_e32 v[74:75], 0
	v_mov_b64_e32 v[72:73], 0
	v_mov_b64_e32 v[70:71], 0
	v_mov_b64_e32 v[68:69], 0
	v_mov_b64_e32 v[58:59], 0
	v_mov_b64_e32 v[56:57], 0
	v_mov_b64_e32 v[50:51], 0
	v_mov_b64_e32 v[48:49], 0
	v_mov_b64_e32 v[38:39], 0
	v_mov_b64_e32 v[36:37], 0
	v_mov_b64_e32 v[34:35], 0
	v_mov_b64_e32 v[32:33], 0
	v_mov_b64_e32 v[6:7], 0
	v_mov_b64_e32 v[4:5], 0
	v_mov_b64_e32 v[2:3], 0
	v_mov_b64_e32 v[0:1], 0
	s_cbranch_vccnz .LBB0_1442
	s_add_u32 s16, s16, 0x160080
	s_addc_u32 s17, s17, 0
	s_add_u32 s44, s18, 0x100
	v_mov_b32_e32 v0, 0
	s_addc_u32 s45, s19, 0
	s_mov_b32 s18, 0
	v_mov_b32_e32 v1, 0
	v_mov_b64_e32 v[2:3], 0
	v_mov_b64_e32 v[4:5], 0
	v_mov_b64_e32 v[6:7], 0
	v_mov_b64_e32 v[8:9], 0
	v_mov_b64_e32 v[10:11], 0
	v_mov_b64_e32 v[12:13], 0
	v_mov_b64_e32 v[14:15], 0
	v_mov_b64_e32 v[20:21], 0
	v_mov_b64_e32 v[22:23], 0
	v_mov_b64_e32 v[28:29], 0
	v_mov_b64_e32 v[30:31], 0
	v_mov_b64_e32 v[36:37], 0
	v_mov_b64_e32 v[38:39], 0
	v_mov_b64_e32 v[44:45], 0
	v_mov_b64_e32 v[46:47], 0
	v_mov_b64_e32 v[16:17], 0
	v_mov_b64_e32 v[18:19], 0
	v_mov_b64_e32 v[24:25], 0
	v_mov_b64_e32 v[26:27], 0
	v_mov_b64_e32 v[32:33], 0
	v_mov_b64_e32 v[34:35], 0
	v_mov_b64_e32 v[40:41], 0
	v_mov_b64_e32 v[42:43], 0
	v_mov_b64_e32 v[48:49], 0
	v_mov_b64_e32 v[50:51], 0
	v_mov_b64_e32 v[52:53], 0
	v_mov_b64_e32 v[54:55], 0
	v_mov_b64_e32 v[56:57], 0
	v_mov_b64_e32 v[58:59], 0
	v_mov_b64_e32 v[60:61], 0
	v_mov_b64_e32 v[62:63], 0
	v_mov_b64_e32 v[64:65], 0
	v_mov_b64_e32 v[66:67], 0
	v_mov_b64_e32 v[68:69], 0
	v_mov_b64_e32 v[70:71], 0
	v_mov_b64_e32 v[72:73], 0
	v_mov_b64_e32 v[74:75], 0
	v_mov_b64_e32 v[76:77], 0
	v_mov_b64_e32 v[78:79], 0
	v_mov_b64_e32 v[84:85], 0
	v_mov_b64_e32 v[86:87], 0
	v_mov_b64_e32 v[92:93], 0
	v_mov_b64_e32 v[94:95], 0
	v_mov_b64_e32 v[100:101], 0
	v_mov_b64_e32 v[102:103], 0
	v_mov_b64_e32 v[108:109], 0
	v_mov_b64_e32 v[110:111], 0
	v_mov_b64_e32 v[80:81], 0
	v_mov_b64_e32 v[82:83], 0
	v_mov_b64_e32 v[88:89], 0
	v_mov_b64_e32 v[90:91], 0
	v_mov_b64_e32 v[96:97], 0
	v_mov_b64_e32 v[98:99], 0
	v_mov_b64_e32 v[104:105], 0
	v_mov_b64_e32 v[106:107], 0
	v_mov_b64_e32 v[112:113], 0
	v_mov_b64_e32 v[114:115], 0
	v_mov_b64_e32 v[116:117], 0
	v_mov_b64_e32 v[118:119], 0
	v_mov_b64_e32 v[120:121], 0
	v_mov_b64_e32 v[122:123], 0
	v_mov_b64_e32 v[124:125], 0
	v_mov_b64_e32 v[126:127], 0
	v_readfirstlane_b32 s99, v234
	s_nop 0
	s_lshr_b32 s99, s99, 8
	s_cmp_eq_u32 s99, 0
	s_cbranch_scc1 .Lsp_11
	s_setprio 1
.Lsp_11:
.LBB0_1440:
	s_add_u32 s98, s16, 0xffea0000
	s_addc_u32 s99, s17, -1
	s_mov_b32 m0, s34
	s_nop 0
	global_load_lds_dwordx4 v134, s[98:99]
	s_mov_b32 m0, s35
	s_nop 0
	global_load_lds_dwordx4 v130, s[98:99]
	ds_read_b128 v[144:147], v159
	ds_read_b128 v[148:151], v159 offset:1024
	ds_read_b128 v[152:155], v159 offset:2048
	ds_read_b128 v[162:165], v159 offset:3072
	ds_read_b128 v[166:169], v160
	ds_read_b128 v[170:173], v160 offset:1024
	ds_read_b128 v[174:177], v160 offset:2048
	ds_read_b128 v[178:181], v160 offset:3072
	s_add_i32 s46, s18, 2
	s_add_u32 s19, s16, 0xffea0080
	s_addc_u32 s20, s17, -1
	s_cmp_eq_u32 s36, s18
	s_cselect_b32 s18, s14, s44
	s_cselect_b32 s21, s5, s20
	s_cselect_b32 s20, s4, s19
	s_cselect_b32 s19, s15, s45
	s_add_i32 m0, s26, 0xc000
	ds_read_b128 v[182:185], v161
	ds_read_b128 v[186:189], v161 offset:1024
	ds_read_b128 v[190:193], v161 offset:2048
	ds_read_b128 v[194:197], v161 offset:3072
	ds_read_b128 v[198:201], v161 offset:4096
	ds_read_b128 v[202:205], v161 offset:5120
	ds_read_b128 v[206:209], v161 offset:6144
	ds_read_b128 v[210:213], v161 offset:7168
	global_load_lds_dwordx4 v136, s[16:17]
	s_add_i32 m0, s26, 0xe000
	s_nop 0
	global_load_lds_dwordx4 v138, s[16:17]
	s_waitcnt vmcnt(8)
	s_waitcnt lgkmcnt(0)
	s_barrier
; #define PG8_STAGE(bufoff, gbase, voff) do { _Pragma("unroll") for (int _i = 0; _i < 2; ++_i) \
;         __builtin_amdgcn_global_load_lds((const unsigned*)((const char*)(gbase) + (voff)[_i]), (LAS unsigned*)(lds + (bufoff) + ldsw + _i * 8192), 16, 0, ((voff) == voffA ? AUXA : 0)); } while (0)
; #define PG8_LDA(dst, b, h) do { _Pragma("unroll") for (int m = 0; m < 4; ++m) _Pragma("unroll") for (int k = 0; k < 2; ++k) dst[m][k] = *(const LAS bf16x8*)(lds + PG8_SA(b, h) + aoff + m * 2048 + k * 1024); } while (0)
; #define PG8_MMA(ai, bj, At, Bt) do { __builtin_amdgcn_s_setprio(1); _Pragma("unroll") for (int m = 0; m < 4; ++m) _Pragma("unroll") for (int n = 0; n < 2; ++n) _Pragma("unroll") for (int k = 0; k < 2; ++k) \
;         acc[ai][bj][m][n] = __builtin_amdgcn_mfma_f32_16x16x32_bf16(Bt[n][k], At[m][k], acc[ai][bj][m][n], 0, 0, 0); __builtin_amdgcn_s_setprio(0); } while (0)
; #define PG8_WAIT_V(n) asm volatile("s_waitcnt vmcnt(" #n ")" ::: "memory")
; #define PG8_WAIT_L(n) asm volatile("s_waitcnt lgkmcnt(" #n ")" ::: "memory")
; #define PG8_BAR __builtin_amdgcn_s_barrier()
; #define PG8_SCHED __builtin_amdgcn_sched_barrier(0)
;     ...
;             PG8_WAIT_L(0); PG8_BAR; PG8_MMA(0, 0, At, B0); PG8_MMA(0, 1, At, B1); PG8_BAR; PG8_SCHED;
;             PG8_LDA(At, 0, 1); PG8_STAGE(PG8_SB(0, 0), b2, voffB); PG8_STAGE(PG8_SB(0, 1), b2 + hsB, voffB); PG8_STAGE(PG8_SA(0, 0), a2, voffA);
;             if (Epi::NPRE != 0 && last) { PG8_WAIT_V(16); } else { PG8_WAIT_V(8); }
;             PG8_WAIT_L(0); PG8_BAR; PG8_MMA(1, 0, At, B0); PG8_MMA(1, 1, At, B1); PG8_BAR; PG8_SCHED;
	v_mfma_f32_16x16x32_bf16 v[124:127], v[144:147], v[182:185], v[124:127]
	v_mfma_f32_16x16x32_bf16 v[120:123], v[152:155], v[182:185], v[120:123]
	v_mfma_f32_16x16x32_bf16 v[116:119], v[144:147], v[190:193], v[116:119]
	v_mfma_f32_16x16x32_bf16 v[112:115], v[152:155], v[190:193], v[112:115]
	v_mfma_f32_16x16x32_bf16 v[104:107], v[144:147], v[198:201], v[104:107]
	v_mfma_f32_16x16x32_bf16 v[96:99], v[152:155], v[198:201], v[96:99]
	v_mfma_f32_16x16x32_bf16 v[88:91], v[144:147], v[206:209], v[88:91]
	v_mfma_f32_16x16x32_bf16 v[80:83], v[152:155], v[206:209], v[80:83]
	v_mfma_f32_16x16x32_bf16 v[124:127], v[148:151], v[186:189], v[124:127]
	v_mfma_f32_16x16x32_bf16 v[120:123], v[162:165], v[186:189], v[120:123]
	v_mfma_f32_16x16x32_bf16 v[116:119], v[148:151], v[194:197], v[116:119]
	v_mfma_f32_16x16x32_bf16 v[112:115], v[162:165], v[194:197], v[112:115]
	v_mfma_f32_16x16x32_bf16 v[104:107], v[148:151], v[202:205], v[104:107]
	v_mfma_f32_16x16x32_bf16 v[96:99], v[162:165], v[202:205], v[96:99]
	v_mfma_f32_16x16x32_bf16 v[88:91], v[148:151], v[210:213], v[88:91]
	v_mfma_f32_16x16x32_bf16 v[80:83], v[162:165], v[210:213], v[80:83]
	v_mfma_f32_16x16x32_bf16 v[108:111], v[166:169], v[182:185], v[108:111]
	v_mfma_f32_16x16x32_bf16 v[100:103], v[174:177], v[182:185], v[100:103]
	v_mfma_f32_16x16x32_bf16 v[92:95], v[166:169], v[190:193], v[92:95]
	v_mfma_f32_16x16x32_bf16 v[84:87], v[174:177], v[190:193], v[84:87]
	v_mfma_f32_16x16x32_bf16 v[76:79], v[166:169], v[198:201], v[76:79]
	v_mfma_f32_16x16x32_bf16 v[72:75], v[174:177], v[198:201], v[72:75]
	v_mfma_f32_16x16x32_bf16 v[68:71], v[166:169], v[206:209], v[68:71]
	v_mfma_f32_16x16x32_bf16 v[64:67], v[174:177], v[206:209], v[64:67]
	v_mfma_f32_16x16x32_bf16 v[108:111], v[170:173], v[186:189], v[108:111]
	v_mfma_f32_16x16x32_bf16 v[100:103], v[178:181], v[186:189], v[100:103]
	v_mfma_f32_16x16x32_bf16 v[92:95], v[170:173], v[194:197], v[92:95]
	v_mfma_f32_16x16x32_bf16 v[84:87], v[178:181], v[194:197], v[84:87]
	v_mfma_f32_16x16x32_bf16 v[76:79], v[170:173], v[202:205], v[76:79]
	v_mfma_f32_16x16x32_bf16 v[72:75], v[178:181], v[202:205], v[72:75]
	v_mfma_f32_16x16x32_bf16 v[68:71], v[170:173], v[210:213], v[68:71]
	v_mfma_f32_16x16x32_bf16 v[64:67], v[178:181], v[210:213], v[64:67]
	s_barrier
	s_add_u32 s98, s18, s8
	s_addc_u32 s99, s19, s9
	s_add_u32 s100, s20, s8
	s_addc_u32 s101, s21, s9
	s_add_i32 s47, s38, s23
	s_mov_b32 m0, s47
	ds_read_b128 v[182:185], v161 offset:16384
	ds_read_b128 v[186:189], v161 offset:17408
	ds_read_b128 v[190:193], v161 offset:18432
	ds_read_b128 v[194:197], v161 offset:19456
	ds_read_b128 v[198:201], v161 offset:20480
	ds_read_b128 v[202:205], v161 offset:21504
	ds_read_b128 v[206:209], v161 offset:22528
	ds_read_b128 v[210:213], v161 offset:23552
	global_load_lds_dwordx4 v132, s[18:19]
	s_add_i32 m0, s47, 0x2000
	s_add_u32 s48, s18, 0x160000
	s_addc_u32 s49, s19, 0
	s_add_i32 s47, s39, s23
	global_load_lds_dwordx4 v128, s[18:19]
	s_mov_b32 m0, s47
	s_nop 0
	global_load_lds_dwordx4 v132, s[48:49]
	s_add_i32 m0, s47, 0x2000
	s_nop 0
	global_load_lds_dwordx4 v128, s[48:49]
	s_waitcnt vmcnt(6)
	s_waitcnt lgkmcnt(0)
	s_barrier
	v_mfma_f32_16x16x32_bf16 v[60:63], v[144:147], v[182:185], v[60:63]
	v_mfma_f32_16x16x32_bf16 v[56:59], v[152:155], v[182:185], v[56:59]
	v_mfma_f32_16x16x32_bf16 v[52:55], v[144:147], v[190:193], v[52:55]
	v_mfma_f32_16x16x32_bf16 v[48:51], v[152:155], v[190:193], v[48:51]
	v_mfma_f32_16x16x32_bf16 v[40:43], v[144:147], v[198:201], v[40:43]
	v_mfma_f32_16x16x32_bf16 v[32:35], v[152:155], v[198:201], v[32:35]
	v_mfma_f32_16x16x32_bf16 v[24:27], v[144:147], v[206:209], v[24:27]
	v_mfma_f32_16x16x32_bf16 v[16:19], v[152:155], v[206:209], v[16:19]
	v_mfma_f32_16x16x32_bf16 v[60:63], v[148:151], v[186:189], v[60:63]
	v_mfma_f32_16x16x32_bf16 v[56:59], v[162:165], v[186:189], v[56:59]
	v_mfma_f32_16x16x32_bf16 v[52:55], v[148:151], v[194:197], v[52:55]
	v_mfma_f32_16x16x32_bf16 v[48:51], v[162:165], v[194:197], v[48:51]
	v_mfma_f32_16x16x32_bf16 v[40:43], v[148:151], v[202:205], v[40:43]
	v_mfma_f32_16x16x32_bf16 v[32:35], v[162:165], v[202:205], v[32:35]
	v_mfma_f32_16x16x32_bf16 v[24:27], v[148:151], v[210:213], v[24:27]
	v_mfma_f32_16x16x32_bf16 v[16:19], v[162:165], v[210:213], v[16:19]
	v_mfma_f32_16x16x32_bf16 v[44:47], v[166:169], v[182:185], v[44:47]
	v_mfma_f32_16x16x32_bf16 v[36:39], v[174:177], v[182:185], v[36:39]
	v_mfma_f32_16x16x32_bf16 v[28:31], v[166:169], v[190:193], v[28:31]
	v_mfma_f32_16x16x32_bf16 v[20:23], v[174:177], v[190:193], v[20:23]
	v_mfma_f32_16x16x32_bf16 v[12:15], v[166:169], v[198:201], v[12:15]
	v_mfma_f32_16x16x32_bf16 v[8:11], v[174:177], v[198:201], v[8:11]
	v_mfma_f32_16x16x32_bf16 v[4:7], v[166:169], v[206:209], v[4:7]
	v_mfma_f32_16x16x32_bf16 v[0:3], v[174:177], v[206:209], v[0:3]
	v_mfma_f32_16x16x32_bf16 v[44:47], v[170:173], v[186:189], v[44:47]
	v_mfma_f32_16x16x32_bf16 v[36:39], v[178:181], v[186:189], v[36:39]
	v_mfma_f32_16x16x32_bf16 v[28:31], v[170:173], v[194:197], v[28:31]
	v_mfma_f32_16x16x32_bf16 v[20:23], v[178:181], v[194:197], v[20:23]
	v_mfma_f32_16x16x32_bf16 v[12:15], v[170:173], v[202:205], v[12:15]
	v_mfma_f32_16x16x32_bf16 v[8:11], v[178:181], v[202:205], v[8:11]
	v_mfma_f32_16x16x32_bf16 v[4:7], v[170:173], v[210:213], v[4:7]
	v_mfma_f32_16x16x32_bf16 v[0:3], v[178:181], v[210:213], v[0:3]
	s_barrier
; #define PG8_STAGE(bufoff, gbase, voff) do { _Pragma("unroll") for (int _i = 0; _i < 2; ++_i) \
;         __builtin_amdgcn_global_load_lds((const unsigned*)((const char*)(gbase) + (voff)[_i]), (LAS unsigned*)(lds + (bufoff) + ldsw + _i * 8192), 16, 0, ((voff) == voffA ? AUXA : 0)); } while (0)
; #define PG8_LDA(dst, b, h) do { _Pragma("unroll") for (int m = 0; m < 4; ++m) _Pragma("unroll") for (int k = 0; k < 2; ++k) dst[m][k] = *(const LAS bf16x8*)(lds + PG8_SA(b, h) + aoff + m * 2048 + k * 1024); } while (0)
; #define PG8_LDB(dst, b, h) do { _Pragma("unroll") for (int n = 0; n < 2; ++n) _Pragma("unroll") for (int k = 0; k < 2; ++k) dst[n][k] = *(const LAS bf16x8*)(lds + PG8_SB(b, h) + boff + n * 2048 + k * 1024); } while (0)
; #define PG8_MMA(ai, bj, At, Bt) do { __builtin_amdgcn_s_setprio(1); _Pragma("unroll") for (int m = 0; m < 4; ++m) _Pragma("unroll") for (int n = 0; n < 2; ++n) _Pragma("unroll") for (int k = 0; k < 2; ++k) \
;         acc[ai][bj][m][n] = __builtin_amdgcn_mfma_f32_16x16x32_bf16(Bt[n][k], At[m][k], acc[ai][bj][m][n], 0, 0, 0); __builtin_amdgcn_s_setprio(0); } while (0)
; #define PG8_WAIT_V(n) asm volatile("s_waitcnt vmcnt(" #n ")" ::: "memory")
; #define PG8_WAIT_L(n) asm volatile("s_waitcnt lgkmcnt(" #n ")" ::: "memory")
; #define PG8_BAR __builtin_amdgcn_s_barrier()
; #define PG8_SCHED __builtin_amdgcn_sched_barrier(0)
;     ...
;             PG8_LDB(B0, 1, 0); PG8_LDB(B1, 1, 1); PG8_SCHED; PG8_LDA(At, 1, 0); PG8_STAGE(PG8_SA(0, 1), a2 + hsA, voffA);
;             PG8_WAIT_V(8); PG8_WAIT_L(0); PG8_BAR; PG8_MMA(0, 0, At, B0); PG8_MMA(0, 1, At, B1); PG8_BAR; PG8_SCHED;
;             PG8_LDA(At, 1, 1); PG8_STAGE(PG8_SB(1, 0), b3, voffB); PG8_STAGE(PG8_SB(1, 1), b3 + hsB, voffB); PG8_STAGE(PG8_SA(1, 0), a3, voffA);
	s_mov_b32 m0, s26
	s_nop 0
	global_load_lds_dwordx4 v134, s[20:21]
	s_mov_b32 m0, s27
	s_nop 0
	global_load_lds_dwordx4 v130, s[20:21]
	s_add_i32 s47, 0, 0x18000
	s_add_i32 s48, 0, 0x1c000
	v_add_u32_e32 v162, s47, v157
	v_add_u32_e32 v178, s48, v157
	ds_read_b128 v[144:147], v162
	ds_read_b128 v[148:151], v162 offset:1024
	ds_read_b128 v[152:155], v162 offset:2048
	ds_read_b128 v[162:165], v162 offset:3072
	ds_read_b128 v[166:169], v178
	ds_read_b128 v[170:173], v178 offset:1024
	ds_read_b128 v[174:177], v178 offset:2048
	ds_read_b128 v[178:181], v178 offset:3072
	s_add_u32 s20, s20, 0x160000
	s_addc_u32 s21, s21, 0
	s_mov_b32 m0, s28
	ds_read_b128 v[182:185], v161 offset:32768
	ds_read_b128 v[186:189], v161 offset:33792
	ds_read_b128 v[190:193], v161 offset:34816
	ds_read_b128 v[194:197], v161 offset:35840
	ds_read_b128 v[198:201], v161 offset:36864
	ds_read_b128 v[202:205], v161 offset:37888
	ds_read_b128 v[206:209], v161 offset:38912
	ds_read_b128 v[210:213], v161 offset:39936
	global_load_lds_dwordx4 v134, s[20:21]
	s_mov_b32 m0, s29
	s_nop 0
	global_load_lds_dwordx4 v130, s[20:21]
	s_waitcnt vmcnt(8)
	s_waitcnt lgkmcnt(0)
	s_barrier
	v_mfma_f32_16x16x32_bf16 v[124:127], v[144:147], v[182:185], v[124:127]
	v_mfma_f32_16x16x32_bf16 v[120:123], v[152:155], v[182:185], v[120:123]
	v_mfma_f32_16x16x32_bf16 v[116:119], v[144:147], v[190:193], v[116:119]
	v_mfma_f32_16x16x32_bf16 v[112:115], v[152:155], v[190:193], v[112:115]
	v_mfma_f32_16x16x32_bf16 v[104:107], v[144:147], v[198:201], v[104:107]
	v_mfma_f32_16x16x32_bf16 v[96:99], v[152:155], v[198:201], v[96:99]
	v_mfma_f32_16x16x32_bf16 v[88:91], v[144:147], v[206:209], v[88:91]
	v_mfma_f32_16x16x32_bf16 v[80:83], v[152:155], v[206:209], v[80:83]
	v_mfma_f32_16x16x32_bf16 v[124:127], v[148:151], v[186:189], v[124:127]
	v_mfma_f32_16x16x32_bf16 v[120:123], v[162:165], v[186:189], v[120:123]
	v_mfma_f32_16x16x32_bf16 v[116:119], v[148:151], v[194:197], v[116:119]
	v_mfma_f32_16x16x32_bf16 v[112:115], v[162:165], v[194:197], v[112:115]
	v_mfma_f32_16x16x32_bf16 v[104:107], v[148:151], v[202:205], v[104:107]
	v_mfma_f32_16x16x32_bf16 v[96:99], v[162:165], v[202:205], v[96:99]
	v_mfma_f32_16x16x32_bf16 v[88:91], v[148:151], v[210:213], v[88:91]
	v_mfma_f32_16x16x32_bf16 v[80:83], v[162:165], v[210:213], v[80:83]
	v_mfma_f32_16x16x32_bf16 v[108:111], v[166:169], v[182:185], v[108:111]
	v_mfma_f32_16x16x32_bf16 v[100:103], v[174:177], v[182:185], v[100:103]
	v_mfma_f32_16x16x32_bf16 v[92:95], v[166:169], v[190:193], v[92:95]
	v_mfma_f32_16x16x32_bf16 v[84:87], v[174:177], v[190:193], v[84:87]
	v_mfma_f32_16x16x32_bf16 v[76:79], v[166:169], v[198:201], v[76:79]
	v_mfma_f32_16x16x32_bf16 v[72:75], v[174:177], v[198:201], v[72:75]
	v_mfma_f32_16x16x32_bf16 v[68:71], v[166:169], v[206:209], v[68:71]
	v_mfma_f32_16x16x32_bf16 v[64:67], v[174:177], v[206:209], v[64:67]
	v_mfma_f32_16x16x32_bf16 v[108:111], v[170:173], v[186:189], v[108:111]
	v_mfma_f32_16x16x32_bf16 v[100:103], v[178:181], v[186:189], v[100:103]
	v_mfma_f32_16x16x32_bf16 v[92:95], v[170:173], v[194:197], v[92:95]
	v_mfma_f32_16x16x32_bf16 v[84:87], v[178:181], v[194:197], v[84:87]
	v_mfma_f32_16x16x32_bf16 v[76:79], v[170:173], v[202:205], v[76:79]
	v_mfma_f32_16x16x32_bf16 v[72:75], v[178:181], v[202:205], v[72:75]
	v_mfma_f32_16x16x32_bf16 v[68:71], v[170:173], v[210:213], v[68:71]
	v_mfma_f32_16x16x32_bf16 v[64:67], v[178:181], v[210:213], v[64:67]
	s_barrier
	s_add_i32 s20, s47, s23
	s_mov_b32 m0, s20
	ds_read_b128 v[182:185], v161 offset:49152
	ds_read_b128 v[186:189], v161 offset:50176
	ds_read_b128 v[190:193], v161 offset:51200
	ds_read_b128 v[194:197], v161 offset:52224
	ds_read_b128 v[198:201], v161 offset:53248
	ds_read_b128 v[202:205], v161 offset:54272
	ds_read_b128 v[206:209], v161 offset:55296
	ds_read_b128 v[210:213], v161 offset:56320
	global_load_lds_dwordx4 v132, s[98:99]
	s_add_i32 m0, s20, 0x2000
	s_add_u32 s18, s18, 0x160080
	s_addc_u32 s19, s19, 0
	s_add_i32 s20, s48, s23
	global_load_lds_dwordx4 v128, s[98:99]
	s_mov_b32 m0, s20
	s_nop 0
	global_load_lds_dwordx4 v132, s[18:19]
	s_add_i32 m0, s20, 0x2000
	s_nop 0
	global_load_lds_dwordx4 v128, s[18:19]
	s_waitcnt vmcnt(6)
	s_waitcnt lgkmcnt(0)
	s_barrier
; #define PG8_STAGE(bufoff, gbase, voff) do { _Pragma("unroll") for (int _i = 0; _i < 2; ++_i) \
;         __builtin_amdgcn_global_load_lds((const unsigned*)((const char*)(gbase) + (voff)[_i]), (LAS unsigned*)(lds + (bufoff) + ldsw + _i * 8192), 16, 0, ((voff) == voffA ? AUXA : 0)); } while (0)
; #define PG8_LDA(dst, b, h) do { _Pragma("unroll") for (int m = 0; m < 4; ++m) _Pragma("unroll") for (int k = 0; k < 2; ++k) dst[m][k] = *(const LAS bf16x8*)(lds + PG8_SA(b, h) + aoff + m * 2048 + k * 1024); } while (0)
; #define PG8_MMA(ai, bj, At, Bt) do { __builtin_amdgcn_s_setprio(1); _Pragma("unroll") for (int m = 0; m < 4; ++m) _Pragma("unroll") for (int n = 0; n < 2; ++n) _Pragma("unroll") for (int k = 0; k < 2; ++k) \
;         acc[ai][bj][m][n] = __builtin_amdgcn_mfma_f32_16x16x32_bf16(Bt[n][k], At[m][k], acc[ai][bj][m][n], 0, 0, 0); __builtin_amdgcn_s_setprio(0); } while (0)
; #define PG8_WAIT_V(n) asm volatile("s_waitcnt vmcnt(" #n ")" ::: "memory")
; #define PG8_WAIT_L(n) asm volatile("s_waitcnt lgkmcnt(" #n ")" ::: "memory")
; #define PG8_BAR __builtin_amdgcn_s_barrier()
; #define PG8_SCHED __builtin_amdgcn_sched_barrier(0)
;     ...
;             PG8_WAIT_V(8); PG8_WAIT_L(0); PG8_BAR; PG8_MMA(0, 0, At, B0); PG8_MMA(0, 1, At, B1); PG8_BAR; PG8_SCHED;
;             PG8_LDA(At, 1, 1); PG8_STAGE(PG8_SB(1, 0), b3, voffB); PG8_STAGE(PG8_SB(1, 1), b3 + hsB, voffB); PG8_STAGE(PG8_SA(1, 0), a3, voffA);
;             PG8_WAIT_V(8); PG8_WAIT_L(0); PG8_BAR; PG8_MMA(1, 0, At, B0); PG8_MMA(1, 1, At, B1); PG8_BAR; PG8_SCHED;
;         }
;     __device__ __forceinline__ void operator()(const Acc& acc, const Unit& u, int wr, int wc, int fr, int fq, const float (&sv8)[8]) const {
;     ...
;                     const int col = colb + bj * 128;
;                     const f32x4 y0 = xr[m][bj][0] + acc[ai][bj][m][0] * scale, y1 = xr[m][bj][1] + acc[ai][bj][m][1] * scale;
	v_mfma_f32_16x16x32_bf16 v[60:63], v[144:147], v[182:185], v[60:63]
	v_mfma_f32_16x16x32_bf16 v[56:59], v[152:155], v[182:185], v[56:59]
	v_mfma_f32_16x16x32_bf16 v[52:55], v[144:147], v[190:193], v[52:55]
	v_mfma_f32_16x16x32_bf16 v[48:51], v[152:155], v[190:193], v[48:51]
	v_mfma_f32_16x16x32_bf16 v[40:43], v[144:147], v[198:201], v[40:43]
	v_mfma_f32_16x16x32_bf16 v[32:35], v[152:155], v[198:201], v[32:35]
	v_mfma_f32_16x16x32_bf16 v[24:27], v[144:147], v[206:209], v[24:27]
	v_mfma_f32_16x16x32_bf16 v[16:19], v[152:155], v[206:209], v[16:19]
	v_mfma_f32_16x16x32_bf16 v[60:63], v[148:151], v[186:189], v[60:63]
	v_mfma_f32_16x16x32_bf16 v[56:59], v[162:165], v[186:189], v[56:59]
	v_mfma_f32_16x16x32_bf16 v[52:55], v[148:151], v[194:197], v[52:55]
	v_mfma_f32_16x16x32_bf16 v[48:51], v[162:165], v[194:197], v[48:51]
	v_mfma_f32_16x16x32_bf16 v[40:43], v[148:151], v[202:205], v[40:43]
	v_mfma_f32_16x16x32_bf16 v[32:35], v[162:165], v[202:205], v[32:35]
	v_mfma_f32_16x16x32_bf16 v[24:27], v[148:151], v[210:213], v[24:27]
	v_mfma_f32_16x16x32_bf16 v[16:19], v[162:165], v[210:213], v[16:19]
	v_mfma_f32_16x16x32_bf16 v[44:47], v[166:169], v[182:185], v[44:47]
	v_mfma_f32_16x16x32_bf16 v[36:39], v[174:177], v[182:185], v[36:39]
	v_mfma_f32_16x16x32_bf16 v[28:31], v[166:169], v[190:193], v[28:31]
	v_mfma_f32_16x16x32_bf16 v[20:23], v[174:177], v[190:193], v[20:23]
	v_mfma_f32_16x16x32_bf16 v[12:15], v[166:169], v[198:201], v[12:15]
	v_mfma_f32_16x16x32_bf16 v[8:11], v[174:177], v[198:201], v[8:11]
	v_mfma_f32_16x16x32_bf16 v[4:7], v[166:169], v[206:209], v[4:7]
	v_mfma_f32_16x16x32_bf16 v[0:3], v[174:177], v[206:209], v[0:3]
	v_mfma_f32_16x16x32_bf16 v[44:47], v[170:173], v[186:189], v[44:47]
	v_mfma_f32_16x16x32_bf16 v[36:39], v[178:181], v[186:189], v[36:39]
	v_mfma_f32_16x16x32_bf16 v[28:31], v[170:173], v[194:197], v[28:31]
	v_mfma_f32_16x16x32_bf16 v[20:23], v[178:181], v[194:197], v[20:23]
	v_mfma_f32_16x16x32_bf16 v[12:15], v[170:173], v[202:205], v[12:15]
	v_mfma_f32_16x16x32_bf16 v[8:11], v[178:181], v[202:205], v[8:11]
	v_mfma_f32_16x16x32_bf16 v[4:7], v[170:173], v[210:213], v[4:7]
	v_mfma_f32_16x16x32_bf16 v[0:3], v[178:181], v[210:213], v[0:3]
	s_barrier
	s_add_u32 s16, s16, 0x100
	s_addc_u32 s17, s17, 0
	s_add_u32 s44, s44, 0x100
	s_addc_u32 s45, s45, 0
	s_cmp_ge_i32 s46, s31
	s_mov_b32 s18, s46
	s_cbranch_scc0 .LBB0_1440
	s_setprio 0
	v_pk_mul_f32 v[126:127], v[126:127], 0.5 op_sel_hi:[1,0]
	v_pk_mul_f32 v[146:147], v[124:125], 0.5 op_sel_hi:[1,0]
	v_pk_mul_f32 v[144:145], v[122:123], 0.5 op_sel_hi:[1,0]
	v_pk_mul_f32 v[124:125], v[120:121], 0.5 op_sel_hi:[1,0]
	v_pk_mul_f32 v[154:155], v[110:111], 0.5 op_sel_hi:[1,0]
	v_pk_mul_f32 v[152:153], v[108:109], 0.5 op_sel_hi:[1,0]
	v_pk_mul_f32 v[150:151], v[102:103], 0.5 op_sel_hi:[1,0]
	v_pk_mul_f32 v[148:149], v[100:101], 0.5 op_sel_hi:[1,0]
	v_pk_mul_f32 v[118:119], v[118:119], 0.5 op_sel_hi:[1,0]
	v_pk_mul_f32 v[116:117], v[116:117], 0.5 op_sel_hi:[1,0]
	v_pk_mul_f32 v[110:111], v[114:115], 0.5 op_sel_hi:[1,0]
	v_pk_mul_f32 v[108:109], v[112:113], 0.5 op_sel_hi:[1,0]
	v_pk_mul_f32 v[122:123], v[94:95], 0.5 op_sel_hi:[1,0]
	v_pk_mul_f32 v[120:121], v[92:93], 0.5 op_sel_hi:[1,0]
	v_pk_mul_f32 v[114:115], v[86:87], 0.5 op_sel_hi:[1,0]
	v_pk_mul_f32 v[112:113], v[84:85], 0.5 op_sel_hi:[1,0]
	v_pk_mul_f32 v[102:103], v[106:107], 0.5 op_sel_hi:[1,0]
	v_pk_mul_f32 v[100:101], v[104:105], 0.5 op_sel_hi:[1,0]
	v_pk_mul_f32 v[94:95], v[98:99], 0.5 op_sel_hi:[1,0]
	v_pk_mul_f32 v[92:93], v[96:97], 0.5 op_sel_hi:[1,0]
	v_pk_mul_f32 v[106:107], v[78:79], 0.5 op_sel_hi:[1,0]
	v_pk_mul_f32 v[104:105], v[76:77], 0.5 op_sel_hi:[1,0]
	v_pk_mul_f32 v[98:99], v[74:75], 0.5 op_sel_hi:[1,0]
	v_pk_mul_f32 v[96:97], v[72:73], 0.5 op_sel_hi:[1,0]
	v_pk_mul_f32 v[86:87], v[90:91], 0.5 op_sel_hi:[1,0]
	v_pk_mul_f32 v[84:85], v[88:89], 0.5 op_sel_hi:[1,0]
	v_pk_mul_f32 v[78:79], v[82:83], 0.5 op_sel_hi:[1,0]
	v_pk_mul_f32 v[76:77], v[80:81], 0.5 op_sel_hi:[1,0]
	v_pk_mul_f32 v[90:91], v[70:71], 0.5 op_sel_hi:[1,0]
	v_pk_mul_f32 v[88:89], v[68:69], 0.5 op_sel_hi:[1,0]
	v_pk_mul_f32 v[82:83], v[66:67], 0.5 op_sel_hi:[1,0]
	v_pk_mul_f32 v[80:81], v[64:65], 0.5 op_sel_hi:[1,0]
	v_pk_mul_f32 v[66:67], v[62:63], 0.5 op_sel_hi:[1,0]
	v_pk_mul_f32 v[64:65], v[60:61], 0.5 op_sel_hi:[1,0]
	v_pk_mul_f32 v[62:63], v[58:59], 0.5 op_sel_hi:[1,0]
	v_pk_mul_f32 v[60:61], v[56:57], 0.5 op_sel_hi:[1,0]
	v_pk_mul_f32 v[74:75], v[46:47], 0.5 op_sel_hi:[1,0]
	v_pk_mul_f32 v[72:73], v[44:45], 0.5 op_sel_hi:[1,0]
	v_pk_mul_f32 v[70:71], v[38:39], 0.5 op_sel_hi:[1,0]
	v_pk_mul_f32 v[68:69], v[36:37], 0.5 op_sel_hi:[1,0]
	v_pk_mul_f32 v[54:55], v[54:55], 0.5 op_sel_hi:[1,0]
	v_pk_mul_f32 v[52:53], v[52:53], 0.5 op_sel_hi:[1,0]
	v_pk_mul_f32 v[46:47], v[50:51], 0.5 op_sel_hi:[1,0]
	v_pk_mul_f32 v[44:45], v[48:49], 0.5 op_sel_hi:[1,0]
	v_pk_mul_f32 v[58:59], v[30:31], 0.5 op_sel_hi:[1,0]
	v_pk_mul_f32 v[56:57], v[28:29], 0.5 op_sel_hi:[1,0]
	v_pk_mul_f32 v[50:51], v[22:23], 0.5 op_sel_hi:[1,0]
	v_pk_mul_f32 v[48:49], v[20:21], 0.5 op_sel_hi:[1,0]
	v_pk_mul_f32 v[30:31], v[42:43], 0.5 op_sel_hi:[1,0]
	v_pk_mul_f32 v[28:29], v[40:41], 0.5 op_sel_hi:[1,0]
	v_pk_mul_f32 v[22:23], v[34:35], 0.5 op_sel_hi:[1,0]
	v_pk_mul_f32 v[20:21], v[32:33], 0.5 op_sel_hi:[1,0]
	v_pk_mul_f32 v[38:39], v[14:15], 0.5 op_sel_hi:[1,0]
	v_pk_mul_f32 v[36:37], v[12:13], 0.5 op_sel_hi:[1,0]
	v_pk_mul_f32 v[34:35], v[10:11], 0.5 op_sel_hi:[1,0]
	v_pk_mul_f32 v[32:33], v[8:9], 0.5 op_sel_hi:[1,0]
	v_pk_mul_f32 v[14:15], v[26:27], 0.5 op_sel_hi:[1,0]
	v_pk_mul_f32 v[12:13], v[24:25], 0.5 op_sel_hi:[1,0]
	v_pk_mul_f32 v[10:11], v[18:19], 0.5 op_sel_hi:[1,0]
	v_pk_mul_f32 v[8:9], v[16:17], 0.5 op_sel_hi:[1,0]
	v_pk_mul_f32 v[6:7], v[6:7], 0.5 op_sel_hi:[1,0]
	v_pk_mul_f32 v[4:5], v[4:5], 0.5 op_sel_hi:[1,0]
	v_pk_mul_f32 v[2:3], v[2:3], 0.5 op_sel_hi:[1,0]
	v_pk_mul_f32 v[0:1], v[0:1], 0.5 op_sel_hi:[1,0]
